# GEMM K-loops: s_setprio 1 moved in front of the barrier that opens the MFMA block
# speedup vs baseline: 1.0208x; 1.0105x over previous
; #define PG8_STAGE(bufoff, gbase, voff) do { _Pragma("unroll") for (int _i = 0; _i < 2; ++_i) \
;         __builtin_amdgcn_global_load_lds((const unsigned*)((const char*)(gbase) + (voff)[_i]), (PG8_LAS unsigned*)(lds + (bufoff) + ldsw + _i * 8192), 16, 0, 0); } while (0)
; #define PG8_LDA(dst, b, h) do { _Pragma("unroll") for (int m = 0; m < 4; ++m) _Pragma("unroll") for (int k = 0; k < 2; ++k) dst[m][k] = *(const PG8_LAS bf16x8*)(lds + PG8_SA(b, h) + aoff + m * 2048 + k * 1024); } while (0)
; #define PG8_LDB(dst, b, h) do { _Pragma("unroll") for (int n = 0; n < 2; ++n) _Pragma("unroll") for (int k = 0; k < 2; ++k) dst[n][k] = *(const PG8_LAS bf16x8*)(lds + PG8_SB(b, h) + boff + n * 2048 + k * 1024); } while (0)
; #define PG8_MMA(ai, bj, At, Bt) do { __builtin_amdgcn_s_setprio(1); _Pragma("unroll") for (int m = 0; m < 4; ++m) _Pragma("unroll") for (int n = 0; n < 2; ++n) _Pragma("unroll") for (int k = 0; k < 2; ++k) \
;         acc[ai][bj][m][n] = __builtin_amdgcn_mfma_f32_16x16x32_bf16(Bt[n][k], At[m][k], acc[ai][bj][m][n], 0, 0, 0); __builtin_amdgcn_s_setprio(0); } while (0)
; #define PG8_WAIT_V(n) asm volatile("s_waitcnt vmcnt(" #n ")" ::: "memory")
; #define PG8_WAIT_L(n) asm volatile("s_waitcnt lgkmcnt(" #n ")" ::: "memory")
; template <class Epi, class Sched, bool ALIGN_EPI = false, bool SP2 = false>
; __device__ __forceinline__ void gemm_phase(PG8_LAS unsigned char* lds, const Gemm g, const Sched& S, const Epi& E) {
;     ...
;             const bool last = (t == nt - 2);
;             const char* a1 = cA + (size_t)(t + 1) * kstep;
;             const char* a2 = last ? nA : cA + (size_t)(t + 2) * kstep; const char* b2 = last ? nB : cB + (size_t)(t + 2) * kstep;
;             const char* a3 = a2 + kstep; const char* b3 = b2 + kstep;
;             if (last && has_next) S.a_ready(nxt);
;             if constexpr (SP2) {
;             PG8_LDB(B0, 0, 0); PG8_LDB(B1, 0, 1); PG8_SCHED; PG8_LDA(At, 0, 0); PG8_STAGE(PG8_SA(1, 1), a1 + hstepA, voffA);
;             PG8_WAIT_V(8); PG8_WAIT_L(0); PG8_BAR; PG8_MMA(0, 0, At, B0); PG8_MMA(0, 1, At, B1); PG8_BAR; PG8_SCHED;
;             PG8_LDA(At, 0, 1); PG8_STAGE(PG8_SB(0, 0), b2, voffB); PG8_STAGE(PG8_SB(0, 1), b2 + hstep, voffB); PG8_STAGE(PG8_SA(0, 0), a2, voffA);
;             PG8_WAIT_V(8); PG8_WAIT_L(0); PG8_BAR; PG8_MMA(1, 0, At, B0); PG8_MMA(1, 1, At, B1); PG8_BAR; PG8_SCHED;
.LBB0_258:
	ds_read_b128 v[164:167], v161
	ds_read_b128 v[168:171], v161 offset:1024
	ds_read_b128 v[172:175], v161 offset:2048
	ds_read_b128 v[176:179], v161 offset:3072
	ds_read_b128 v[180:183], v162
	ds_read_b128 v[184:187], v162 offset:1024
	ds_read_b128 v[190:193], v162 offset:2048
	ds_read_b128 v[194:197], v162 offset:3072
	s_add_i32 s65, s36, 2
	s_add_u32 s66, s10, 0xfffc0080
	s_addc_u32 s37, s11, -1
	s_cmp_eq_u32 s56, s36
	s_cselect_b32 s36, s64, s66
	s_cselect_b32 s37, s29, s37
	s_cselect_b32 s67, s31, s39
	s_cselect_b32 s66, s30, s38
	s_add_i32 m0, s48, 0xc000
	ds_read_b128 v[198:201], v163
	ds_read_b128 v[202:205], v163 offset:1024
	ds_read_b128 v[206:209], v163 offset:2048
	ds_read_b128 v[210:213], v163 offset:3072
	ds_read_b128 v[214:217], v163 offset:4096
	ds_read_b128 v[218:221], v163 offset:5120
	ds_read_b128 v[222:225], v163 offset:6144
	global_load_lds_dwordx4 v138, s[10:11]
	s_add_i32 m0, s48, 0xe000
	ds_read_b128 v[226:229], v163 offset:7168
	global_load_lds_dwordx4 v142, s[10:11]
	s_waitcnt vmcnt(8) lgkmcnt(0)
	s_setprio 1
	s_barrier
	v_mfma_f32_16x16x32_bf16 v[124:127], v[164:167], v[198:201], v[124:127]
	v_mfma_f32_16x16x32_bf16 v[120:123], v[172:175], v[198:201], v[120:123]
	v_mfma_f32_16x16x32_bf16 v[108:111], v[164:167], v[206:209], v[108:111]
	v_mfma_f32_16x16x32_bf16 v[104:107], v[172:175], v[206:209], v[104:107]
	v_mfma_f32_16x16x32_bf16 v[92:95], v[164:167], v[214:217], v[92:95]
	v_mfma_f32_16x16x32_bf16 v[88:91], v[172:175], v[214:217], v[88:91]
	v_mfma_f32_16x16x32_bf16 v[76:79], v[164:167], v[222:225], v[76:79]
	v_mfma_f32_16x16x32_bf16 v[72:75], v[172:175], v[222:225], v[72:75]
	v_mfma_f32_16x16x32_bf16 v[124:127], v[168:171], v[202:205], v[124:127]
	v_mfma_f32_16x16x32_bf16 v[120:123], v[176:179], v[202:205], v[120:123]
	v_mfma_f32_16x16x32_bf16 v[108:111], v[168:171], v[210:213], v[108:111]
	v_mfma_f32_16x16x32_bf16 v[104:107], v[176:179], v[210:213], v[104:107]
	v_mfma_f32_16x16x32_bf16 v[92:95], v[168:171], v[218:221], v[92:95]
	v_mfma_f32_16x16x32_bf16 v[88:91], v[176:179], v[218:221], v[88:91]
	v_mfma_f32_16x16x32_bf16 v[76:79], v[168:171], v[226:229], v[76:79]
	v_mfma_f32_16x16x32_bf16 v[72:75], v[176:179], v[226:229], v[72:75]
	v_mfma_f32_16x16x32_bf16 v[116:119], v[180:183], v[198:201], v[116:119]
	v_mfma_f32_16x16x32_bf16 v[112:115], v[190:193], v[198:201], v[112:115]
	v_mfma_f32_16x16x32_bf16 v[100:103], v[180:183], v[206:209], v[100:103]
	v_mfma_f32_16x16x32_bf16 v[96:99], v[190:193], v[206:209], v[96:99]
	v_mfma_f32_16x16x32_bf16 v[84:87], v[180:183], v[214:217], v[84:87]
	v_mfma_f32_16x16x32_bf16 v[80:83], v[190:193], v[214:217], v[80:83]
	v_mfma_f32_16x16x32_bf16 v[68:71], v[180:183], v[222:225], v[68:71]
	v_mfma_f32_16x16x32_bf16 v[64:67], v[190:193], v[222:225], v[64:67]
	v_mfma_f32_16x16x32_bf16 v[116:119], v[184:187], v[202:205], v[116:119]
	v_mfma_f32_16x16x32_bf16 v[112:115], v[194:197], v[202:205], v[112:115]
	v_mfma_f32_16x16x32_bf16 v[100:103], v[184:187], v[210:213], v[100:103]
	v_mfma_f32_16x16x32_bf16 v[96:99], v[194:197], v[210:213], v[96:99]
	v_mfma_f32_16x16x32_bf16 v[84:87], v[184:187], v[218:221], v[84:87]
	v_mfma_f32_16x16x32_bf16 v[80:83], v[194:197], v[218:221], v[80:83]
	v_mfma_f32_16x16x32_bf16 v[68:71], v[184:187], v[226:229], v[68:71]
	v_mfma_f32_16x16x32_bf16 v[64:67], v[194:197], v[226:229], v[64:67]
	s_setprio 0
	s_barrier
	s_add_i32 s68, s57, s47
	s_mov_b32 m0, s68
	ds_read_b128 v[198:201], v163 offset:16384
	ds_read_b128 v[202:205], v163 offset:17408
	ds_read_b128 v[206:209], v163 offset:18432
	ds_read_b128 v[210:213], v163 offset:19456
	global_load_lds_dwordx4 v136, s[66:67]
	s_add_i32 m0, s68, 0x2000
	s_mov_b64 s[100:101], s[66:67]
	s_add_i32 s68, s58, s47
	global_load_lds_dwordx4 v134, s[66:67]
	s_add_u32 s66, s66, s16
	s_addc_u32 s67, s67, s17
	s_mov_b32 m0, s68
	ds_read_b128 v[226:229], v163 offset:23552
	global_load_lds_dwordx4 v136, s[66:67]
	s_add_i32 m0, s68, 0x2000
	ds_read_b128 v[222:225], v163 offset:22528
	global_load_lds_dwordx4 v134, s[66:67]
	s_mov_b32 m0, s48
	ds_read_b128 v[218:221], v163 offset:21504
	global_load_lds_dwordx4 v128, s[36:37]
	s_mov_b32 m0, s49
	ds_read_b128 v[214:217], v163 offset:20480
	global_load_lds_dwordx4 v130, s[36:37]
	s_waitcnt vmcnt(8) lgkmcnt(0)
	s_setprio 1
	s_barrier
	v_mfma_f32_16x16x32_bf16 v[60:63], v[164:167], v[198:201], v[60:63]
	v_mfma_f32_16x16x32_bf16 v[56:59], v[172:175], v[198:201], v[56:59]
	v_mfma_f32_16x16x32_bf16 v[44:47], v[164:167], v[206:209], v[44:47]
	v_mfma_f32_16x16x32_bf16 v[40:43], v[172:175], v[206:209], v[40:43]
	v_mfma_f32_16x16x32_bf16 v[28:31], v[164:167], v[214:217], v[28:31]
	v_mfma_f32_16x16x32_bf16 v[24:27], v[172:175], v[214:217], v[24:27]
	v_mfma_f32_16x16x32_bf16 v[12:15], v[164:167], v[222:225], v[12:15]
	v_mfma_f32_16x16x32_bf16 v[8:11], v[172:175], v[222:225], v[8:11]
	v_mfma_f32_16x16x32_bf16 v[60:63], v[168:171], v[202:205], v[60:63]
	v_mfma_f32_16x16x32_bf16 v[56:59], v[176:179], v[202:205], v[56:59]
	v_mfma_f32_16x16x32_bf16 v[44:47], v[168:171], v[210:213], v[44:47]
	v_mfma_f32_16x16x32_bf16 v[40:43], v[176:179], v[210:213], v[40:43]
	v_mfma_f32_16x16x32_bf16 v[28:31], v[168:171], v[218:221], v[28:31]
	v_mfma_f32_16x16x32_bf16 v[24:27], v[176:179], v[218:221], v[24:27]
	v_mfma_f32_16x16x32_bf16 v[12:15], v[168:171], v[226:229], v[12:15]
	v_mfma_f32_16x16x32_bf16 v[8:11], v[176:179], v[226:229], v[8:11]
	v_mfma_f32_16x16x32_bf16 v[52:55], v[180:183], v[198:201], v[52:55]
	v_mfma_f32_16x16x32_bf16 v[48:51], v[190:193], v[198:201], v[48:51]
	v_mfma_f32_16x16x32_bf16 v[36:39], v[180:183], v[206:209], v[36:39]
	v_mfma_f32_16x16x32_bf16 v[32:35], v[190:193], v[206:209], v[32:35]
	v_mfma_f32_16x16x32_bf16 v[20:23], v[180:183], v[214:217], v[20:23]
	v_mfma_f32_16x16x32_bf16 v[16:19], v[190:193], v[214:217], v[16:19]
	v_mfma_f32_16x16x32_bf16 v[4:7], v[180:183], v[222:225], v[4:7]
	v_mfma_f32_16x16x32_bf16 v[0:3], v[190:193], v[222:225], v[0:3]
	v_mfma_f32_16x16x32_bf16 v[52:55], v[184:187], v[202:205], v[52:55]
	v_mfma_f32_16x16x32_bf16 v[48:51], v[194:197], v[202:205], v[48:51]
	v_mfma_f32_16x16x32_bf16 v[36:39], v[184:187], v[210:213], v[36:39]
	v_mfma_f32_16x16x32_bf16 v[32:35], v[194:197], v[210:213], v[32:35]
	v_mfma_f32_16x16x32_bf16 v[20:23], v[184:187], v[218:221], v[20:23]
	v_mfma_f32_16x16x32_bf16 v[16:19], v[194:197], v[218:221], v[16:19]
	v_mfma_f32_16x16x32_bf16 v[4:7], v[184:187], v[226:229], v[4:7]
	v_mfma_f32_16x16x32_bf16 v[0:3], v[194:197], v[226:229], v[0:3]
	s_setprio 0
	s_barrier
; #define PG8_STAGE(bufoff, gbase, voff) do { _Pragma("unroll") for (int _i = 0; _i < 2; ++_i) \
;         __builtin_amdgcn_global_load_lds((const unsigned*)((const char*)(gbase) + (voff)[_i]), (PG8_LAS unsigned*)(lds + (bufoff) + ldsw + _i * 8192), 16, 0, 0); } while (0)
; #define PG8_LDA(dst, b, h) do { _Pragma("unroll") for (int m = 0; m < 4; ++m) _Pragma("unroll") for (int k = 0; k < 2; ++k) dst[m][k] = *(const PG8_LAS bf16x8*)(lds + PG8_SA(b, h) + aoff + m * 2048 + k * 1024); } while (0)
; #define PG8_LDB(dst, b, h) do { _Pragma("unroll") for (int n = 0; n < 2; ++n) _Pragma("unroll") for (int k = 0; k < 2; ++k) dst[n][k] = *(const PG8_LAS bf16x8*)(lds + PG8_SB(b, h) + boff + n * 2048 + k * 1024); } while (0)
; #define PG8_MMA(ai, bj, At, Bt) do { __builtin_amdgcn_s_setprio(1); _Pragma("unroll") for (int m = 0; m < 4; ++m) _Pragma("unroll") for (int n = 0; n < 2; ++n) _Pragma("unroll") for (int k = 0; k < 2; ++k) \
;         acc[ai][bj][m][n] = __builtin_amdgcn_mfma_f32_16x16x32_bf16(Bt[n][k], At[m][k], acc[ai][bj][m][n], 0, 0, 0); __builtin_amdgcn_s_setprio(0); } while (0)
; #define PG8_WAIT_V(n) asm volatile("s_waitcnt vmcnt(" #n ")" ::: "memory")
; #define PG8_WAIT_L(n) asm volatile("s_waitcnt lgkmcnt(" #n ")" ::: "memory")
; #define PG8_BAR __builtin_amdgcn_s_barrier()
; #define PG8_SCHED __builtin_amdgcn_sched_barrier(0)
; template <class Epi, class Sched, bool ALIGN_EPI = false, bool SP2 = false>
; __device__ __forceinline__ void gemm_phase(PG8_LAS unsigned char* lds, const Gemm g, const Sched& S, const Epi& E) {
;     ...
;             PG8_LDB(B0, 1, 0); PG8_LDB(B1, 1, 1); PG8_SCHED; PG8_LDA(At, 1, 0); PG8_STAGE(PG8_SA(0, 1), a2 + hstepA, voffA);
;             PG8_WAIT_V(8); PG8_WAIT_L(0); PG8_BAR; PG8_MMA(0, 0, At, B0); PG8_MMA(0, 1, At, B1); PG8_BAR; PG8_SCHED;
;             PG8_LDA(At, 1, 1); PG8_STAGE(PG8_SB(1, 0), b3, voffB); PG8_STAGE(PG8_SB(1, 1), b3 + hstep, voffB); PG8_STAGE(PG8_SA(1, 0), a3, voffA);
;             PG8_WAIT_V(8); PG8_WAIT_L(0); PG8_BAR; PG8_MMA(1, 0, At, B0); PG8_MMA(1, 1, At, B1); PG8_BAR; PG8_SCHED;
	s_add_i32 s66, 0, 0x18000
	s_add_i32 s67, 0, 0x1c000
	v_add_u32_e32 v176, s66, v159
	v_add_u32_e32 v189, s67, v159
	ds_read_b128 v[164:167], v176
	ds_read_b128 v[168:171], v176 offset:1024
	ds_read_b128 v[172:175], v176 offset:2048
	ds_read_b128 v[176:179], v176 offset:3072
	ds_read_b128 v[180:183], v189
	ds_read_b128 v[184:187], v189 offset:1024
	ds_read_b128 v[190:193], v189 offset:2048
	ds_read_b128 v[194:197], v189 offset:3072
	s_mov_b64 vcc, s[36:37]
	s_add_u32 s36, s36, 0x40000
	s_addc_u32 s37, s37, 0
	s_mov_b32 m0, s50
	ds_read_b128 v[198:201], v163 offset:32768
	ds_read_b128 v[202:205], v163 offset:33792
	ds_read_b128 v[206:209], v163 offset:34816
	ds_read_b128 v[210:213], v163 offset:35840
	ds_read_b128 v[214:217], v163 offset:36864
	ds_read_b128 v[218:221], v163 offset:37888
	ds_read_b128 v[222:225], v163 offset:38912
	global_load_lds_dwordx4 v128, s[36:37]
	s_mov_b32 m0, s51
	ds_read_b128 v[226:229], v163 offset:39936
	global_load_lds_dwordx4 v130, s[36:37]
	s_waitcnt vmcnt(8) lgkmcnt(0)
	s_setprio 1
	s_barrier
	v_mfma_f32_16x16x32_bf16 v[124:127], v[164:167], v[198:201], v[124:127]
	v_mfma_f32_16x16x32_bf16 v[120:123], v[172:175], v[198:201], v[120:123]
	v_mfma_f32_16x16x32_bf16 v[108:111], v[164:167], v[206:209], v[108:111]
	v_mfma_f32_16x16x32_bf16 v[104:107], v[172:175], v[206:209], v[104:107]
	v_mfma_f32_16x16x32_bf16 v[92:95], v[164:167], v[214:217], v[92:95]
	v_mfma_f32_16x16x32_bf16 v[88:91], v[172:175], v[214:217], v[88:91]
	v_mfma_f32_16x16x32_bf16 v[76:79], v[164:167], v[222:225], v[76:79]
	v_mfma_f32_16x16x32_bf16 v[72:75], v[172:175], v[222:225], v[72:75]
	v_mfma_f32_16x16x32_bf16 v[124:127], v[168:171], v[202:205], v[124:127]
	v_mfma_f32_16x16x32_bf16 v[120:123], v[176:179], v[202:205], v[120:123]
	v_mfma_f32_16x16x32_bf16 v[108:111], v[168:171], v[210:213], v[108:111]
	v_mfma_f32_16x16x32_bf16 v[104:107], v[176:179], v[210:213], v[104:107]
	v_mfma_f32_16x16x32_bf16 v[92:95], v[168:171], v[218:221], v[92:95]
	v_mfma_f32_16x16x32_bf16 v[88:91], v[176:179], v[218:221], v[88:91]
	v_mfma_f32_16x16x32_bf16 v[76:79], v[168:171], v[226:229], v[76:79]
	v_mfma_f32_16x16x32_bf16 v[72:75], v[176:179], v[226:229], v[72:75]
	v_mfma_f32_16x16x32_bf16 v[116:119], v[180:183], v[198:201], v[116:119]
	v_mfma_f32_16x16x32_bf16 v[112:115], v[190:193], v[198:201], v[112:115]
	v_mfma_f32_16x16x32_bf16 v[100:103], v[180:183], v[206:209], v[100:103]
	v_mfma_f32_16x16x32_bf16 v[96:99], v[190:193], v[206:209], v[96:99]
	v_mfma_f32_16x16x32_bf16 v[84:87], v[180:183], v[214:217], v[84:87]
	v_mfma_f32_16x16x32_bf16 v[80:83], v[190:193], v[214:217], v[80:83]
	v_mfma_f32_16x16x32_bf16 v[68:71], v[180:183], v[222:225], v[68:71]
	v_mfma_f32_16x16x32_bf16 v[64:67], v[190:193], v[222:225], v[64:67]
	v_mfma_f32_16x16x32_bf16 v[116:119], v[184:187], v[202:205], v[116:119]
	v_mfma_f32_16x16x32_bf16 v[112:115], v[194:197], v[202:205], v[112:115]
	v_mfma_f32_16x16x32_bf16 v[100:103], v[184:187], v[210:213], v[100:103]
	v_mfma_f32_16x16x32_bf16 v[96:99], v[194:197], v[210:213], v[96:99]
	v_mfma_f32_16x16x32_bf16 v[84:87], v[184:187], v[218:221], v[84:87]
	v_mfma_f32_16x16x32_bf16 v[80:83], v[194:197], v[218:221], v[80:83]
	v_mfma_f32_16x16x32_bf16 v[68:71], v[184:187], v[226:229], v[68:71]
	v_mfma_f32_16x16x32_bf16 v[64:67], v[194:197], v[226:229], v[64:67]
	s_setprio 0
	s_barrier
	s_add_i32 s36, s66, s47
	s_add_i32 m0, s36, 0xffffff80
	ds_read_b128 v[198:201], v163 offset:49152
	ds_read_b128 v[202:205], v163 offset:50176
	ds_read_b128 v[206:209], v163 offset:51200
	ds_read_b128 v[210:213], v163 offset:52224
	global_load_lds_dwordx4 v136, s[100:101] offset:128
	s_add_i32 m0, s36, 0x1f80
	s_add_i32 s36, s67, s47
	global_load_lds_dwordx4 v134, s[100:101] offset:128
	s_add_u32 s100, s100, s16
	s_addc_u32 s101, s101, s17
	s_add_i32 m0, s36, 0xffffff80
	ds_read_b128 v[226:229], v163 offset:56320
	global_load_lds_dwordx4 v136, s[100:101] offset:128
	s_add_i32 m0, s36, 0x1f80
	ds_read_b128 v[222:225], v163 offset:55296
	global_load_lds_dwordx4 v134, s[100:101] offset:128
	s_add_i32 m0, s52, 0xffffff80
	ds_read_b128 v[218:221], v163 offset:54272
	global_load_lds_dwordx4 v128, vcc offset:128
	s_add_i32 m0, s53, 0xffffff80
	ds_read_b128 v[214:217], v163 offset:53248
	global_load_lds_dwordx4 v130, vcc offset:128
	s_waitcnt vmcnt(8) lgkmcnt(0)
	s_setprio 1
	s_barrier
	v_mfma_f32_16x16x32_bf16 v[60:63], v[164:167], v[198:201], v[60:63]
	v_mfma_f32_16x16x32_bf16 v[56:59], v[172:175], v[198:201], v[56:59]
	v_mfma_f32_16x16x32_bf16 v[44:47], v[164:167], v[206:209], v[44:47]
	v_mfma_f32_16x16x32_bf16 v[40:43], v[172:175], v[206:209], v[40:43]
	v_mfma_f32_16x16x32_bf16 v[28:31], v[164:167], v[214:217], v[28:31]
	v_mfma_f32_16x16x32_bf16 v[24:27], v[172:175], v[214:217], v[24:27]
	v_mfma_f32_16x16x32_bf16 v[12:15], v[164:167], v[222:225], v[12:15]
	v_mfma_f32_16x16x32_bf16 v[8:11], v[172:175], v[222:225], v[8:11]
	v_mfma_f32_16x16x32_bf16 v[60:63], v[168:171], v[202:205], v[60:63]
	v_mfma_f32_16x16x32_bf16 v[56:59], v[176:179], v[202:205], v[56:59]
	v_mfma_f32_16x16x32_bf16 v[44:47], v[168:171], v[210:213], v[44:47]
	v_mfma_f32_16x16x32_bf16 v[40:43], v[176:179], v[210:213], v[40:43]
	v_mfma_f32_16x16x32_bf16 v[28:31], v[168:171], v[218:221], v[28:31]
	v_mfma_f32_16x16x32_bf16 v[24:27], v[176:179], v[218:221], v[24:27]
	v_mfma_f32_16x16x32_bf16 v[12:15], v[168:171], v[226:229], v[12:15]
	v_mfma_f32_16x16x32_bf16 v[8:11], v[176:179], v[226:229], v[8:11]
	v_mfma_f32_16x16x32_bf16 v[52:55], v[180:183], v[198:201], v[52:55]
	v_mfma_f32_16x16x32_bf16 v[48:51], v[190:193], v[198:201], v[48:51]
	v_mfma_f32_16x16x32_bf16 v[36:39], v[180:183], v[206:209], v[36:39]
	v_mfma_f32_16x16x32_bf16 v[32:35], v[190:193], v[206:209], v[32:35]
	v_mfma_f32_16x16x32_bf16 v[20:23], v[180:183], v[214:217], v[20:23]
	v_mfma_f32_16x16x32_bf16 v[16:19], v[190:193], v[214:217], v[16:19]
	v_mfma_f32_16x16x32_bf16 v[4:7], v[180:183], v[222:225], v[4:7]
	v_mfma_f32_16x16x32_bf16 v[0:3], v[190:193], v[222:225], v[0:3]
	v_mfma_f32_16x16x32_bf16 v[52:55], v[184:187], v[202:205], v[52:55]
	v_mfma_f32_16x16x32_bf16 v[48:51], v[194:197], v[202:205], v[48:51]
	v_mfma_f32_16x16x32_bf16 v[36:39], v[184:187], v[210:213], v[36:39]
	v_mfma_f32_16x16x32_bf16 v[32:35], v[194:197], v[210:213], v[32:35]
	v_mfma_f32_16x16x32_bf16 v[20:23], v[184:187], v[218:221], v[20:23]
	v_mfma_f32_16x16x32_bf16 v[16:19], v[194:197], v[218:221], v[16:19]
	v_mfma_f32_16x16x32_bf16 v[4:7], v[184:187], v[226:229], v[4:7]
	v_mfma_f32_16x16x32_bf16 v[0:3], v[194:197], v[226:229], v[0:3]
	s_setprio 0
	s_barrier
	s_add_u32 s10, s10, 0x100
	s_addc_u32 s11, s11, 0
	s_add_u32 s38, s38, 0x100
	s_addc_u32 s39, s39, 0
	s_cmp_ge_i32 s65, s54
	s_mov_b32 s36, s65
	s_cbranch_scc0 .LBB0_258

; #define PG8_STAGE(bufoff, gbase, voff) do { _Pragma("unroll") for (int _i = 0; _i < 2; ++_i) \
;         __builtin_amdgcn_global_load_lds((const unsigned*)((const char*)(gbase) + (voff)[_i]), (PG8_LAS unsigned*)(lds + (bufoff) + ldsw + _i * 8192), 16, 0, 0); } while (0)
; #define PG8_LDA(dst, b, h) do { _Pragma("unroll") for (int m = 0; m < 4; ++m) _Pragma("unroll") for (int k = 0; k < 2; ++k) dst[m][k] = *(const PG8_LAS bf16x8*)(lds + PG8_SA(b, h) + aoff + m * 2048 + k * 1024); } while (0)
; #define PG8_LDB(dst, b, h) do { _Pragma("unroll") for (int n = 0; n < 2; ++n) _Pragma("unroll") for (int k = 0; k < 2; ++k) dst[n][k] = *(const PG8_LAS bf16x8*)(lds + PG8_SB(b, h) + boff + n * 2048 + k * 1024); } while (0)
; #define PG8_MMA(ai, bj, At, Bt) do { __builtin_amdgcn_s_setprio(1); _Pragma("unroll") for (int m = 0; m < 4; ++m) _Pragma("unroll") for (int n = 0; n < 2; ++n) _Pragma("unroll") for (int k = 0; k < 2; ++k) \
;         acc[ai][bj][m][n] = __builtin_amdgcn_mfma_f32_16x16x32_bf16(Bt[n][k], At[m][k], acc[ai][bj][m][n], 0, 0, 0); __builtin_amdgcn_s_setprio(0); } while (0)
; #define PG8_WAIT_V(n) asm volatile("s_waitcnt vmcnt(" #n ")" ::: "memory")
; #define PG8_WAIT_L(n) asm volatile("s_waitcnt lgkmcnt(" #n ")" ::: "memory")
; template <class Epi, class Sched, bool ALIGN_EPI = false, bool SP2 = false>
; __device__ __forceinline__ void gemm_phase(PG8_LAS unsigned char* lds, const Gemm g, const Sched& S, const Epi& E) {
;     ...
;             const bool last = (t == nt - 2);
;             const char* a1 = cA + (size_t)(t + 1) * kstep;
;             const char* a2 = last ? nA : cA + (size_t)(t + 2) * kstep; const char* b2 = last ? nB : cB + (size_t)(t + 2) * kstep;
;             const char* a3 = a2 + kstep; const char* b3 = b2 + kstep;
;             if (last && has_next) S.a_ready(nxt);
;             if constexpr (SP2) {
;             PG8_LDB(B0, 0, 0); PG8_LDB(B1, 0, 1); PG8_SCHED; PG8_LDA(At, 0, 0); PG8_STAGE(PG8_SA(1, 1), a1 + hstepA, voffA);
;             PG8_WAIT_V(8); PG8_WAIT_L(0); PG8_BAR; PG8_MMA(0, 0, At, B0); PG8_MMA(0, 1, At, B1); PG8_BAR; PG8_SCHED;
;             PG8_LDA(At, 0, 1); PG8_STAGE(PG8_SB(0, 0), b2, voffB); PG8_STAGE(PG8_SB(0, 1), b2 + hstep, voffB); PG8_STAGE(PG8_SA(0, 0), a2, voffA);
;             PG8_WAIT_V(8); PG8_WAIT_L(0); PG8_BAR; PG8_MMA(1, 0, At, B0); PG8_MMA(1, 1, At, B1); PG8_BAR; PG8_SCHED;
.LBB0_282:
	ds_read_b128 v[148:151], v144
	ds_read_b128 v[152:155], v144 offset:1024
	ds_read_b128 v[156:159], v144 offset:2048
	ds_read_b128 v[160:163], v144 offset:3072
	ds_read_b128 v[164:167], v145
	ds_read_b128 v[168:171], v145 offset:1024
	ds_read_b128 v[172:175], v145 offset:2048
	ds_read_b128 v[176:179], v145 offset:3072
	s_add_i32 s61, s34, 2
	s_add_u32 s62, s30, 0xfffc0080
	s_addc_u32 s35, s31, -1
	s_cmp_eq_u32 s52, s34
	s_cselect_b32 s34, s36, s62
	s_cselect_b32 s35, s5, s35
	s_cselect_b32 s63, s27, s60
	s_cselect_b32 s62, s26, s37
	s_add_i32 m0, s33, 0xc000
	ds_read_b128 v[180:183], v146
	ds_read_b128 v[184:187], v146 offset:1024
	ds_read_b128 v[190:193], v146 offset:2048
	ds_read_b128 v[194:197], v146 offset:3072
	ds_read_b128 v[198:201], v146 offset:4096
	ds_read_b128 v[202:205], v146 offset:5120
	ds_read_b128 v[206:209], v146 offset:6144
	global_load_lds_dwordx4 v138, s[30:31]
	s_add_i32 m0, s33, 0xe000
	ds_read_b128 v[210:213], v146 offset:7168
	global_load_lds_dwordx4 v140, s[30:31]
	s_waitcnt vmcnt(8) lgkmcnt(0)
	s_setprio 1
	s_barrier
	v_mfma_f32_16x16x32_bf16 v[124:127], v[148:151], v[180:183], v[124:127]
	v_mfma_f32_16x16x32_bf16 v[120:123], v[156:159], v[180:183], v[120:123]
	v_mfma_f32_16x16x32_bf16 v[108:111], v[148:151], v[190:193], v[108:111]
	v_mfma_f32_16x16x32_bf16 v[104:107], v[156:159], v[190:193], v[104:107]
	v_mfma_f32_16x16x32_bf16 v[92:95], v[148:151], v[198:201], v[92:95]
	v_mfma_f32_16x16x32_bf16 v[88:91], v[156:159], v[198:201], v[88:91]
	v_mfma_f32_16x16x32_bf16 v[76:79], v[148:151], v[206:209], v[76:79]
	v_mfma_f32_16x16x32_bf16 v[72:75], v[156:159], v[206:209], v[72:75]
	v_mfma_f32_16x16x32_bf16 v[124:127], v[152:155], v[184:187], v[124:127]
	v_mfma_f32_16x16x32_bf16 v[120:123], v[160:163], v[184:187], v[120:123]
	v_mfma_f32_16x16x32_bf16 v[108:111], v[152:155], v[194:197], v[108:111]
	v_mfma_f32_16x16x32_bf16 v[104:107], v[160:163], v[194:197], v[104:107]
	v_mfma_f32_16x16x32_bf16 v[92:95], v[152:155], v[202:205], v[92:95]
	v_mfma_f32_16x16x32_bf16 v[88:91], v[160:163], v[202:205], v[88:91]
	v_mfma_f32_16x16x32_bf16 v[76:79], v[152:155], v[210:213], v[76:79]
	v_mfma_f32_16x16x32_bf16 v[72:75], v[160:163], v[210:213], v[72:75]
	v_mfma_f32_16x16x32_bf16 v[116:119], v[164:167], v[180:183], v[116:119]
	v_mfma_f32_16x16x32_bf16 v[112:115], v[172:175], v[180:183], v[112:115]
	v_mfma_f32_16x16x32_bf16 v[100:103], v[164:167], v[190:193], v[100:103]
	v_mfma_f32_16x16x32_bf16 v[96:99], v[172:175], v[190:193], v[96:99]
	v_mfma_f32_16x16x32_bf16 v[84:87], v[164:167], v[198:201], v[84:87]
	v_mfma_f32_16x16x32_bf16 v[80:83], v[172:175], v[198:201], v[80:83]
	v_mfma_f32_16x16x32_bf16 v[68:71], v[164:167], v[206:209], v[68:71]
	v_mfma_f32_16x16x32_bf16 v[64:67], v[172:175], v[206:209], v[64:67]
	v_mfma_f32_16x16x32_bf16 v[116:119], v[168:171], v[184:187], v[116:119]
	v_mfma_f32_16x16x32_bf16 v[112:115], v[176:179], v[184:187], v[112:115]
	v_mfma_f32_16x16x32_bf16 v[100:103], v[168:171], v[194:197], v[100:103]
	v_mfma_f32_16x16x32_bf16 v[96:99], v[176:179], v[194:197], v[96:99]
	v_mfma_f32_16x16x32_bf16 v[84:87], v[168:171], v[202:205], v[84:87]
	v_mfma_f32_16x16x32_bf16 v[80:83], v[176:179], v[202:205], v[80:83]
	v_mfma_f32_16x16x32_bf16 v[68:71], v[168:171], v[210:213], v[68:71]
	v_mfma_f32_16x16x32_bf16 v[64:67], v[176:179], v[210:213], v[64:67]
	s_setprio 0
	s_barrier
	s_add_i32 s64, s53, s44
	s_mov_b32 m0, s64
	ds_read_b128 v[180:183], v146 offset:16384
	ds_read_b128 v[184:187], v146 offset:17408
	ds_read_b128 v[190:193], v146 offset:18432
	ds_read_b128 v[194:197], v146 offset:19456
	global_load_lds_dwordx4 v132, s[62:63]
	s_add_i32 m0, s64, 0x2000
	s_mov_b64 s[100:101], s[62:63]
	s_add_i32 s64, s54, s44
	global_load_lds_dwordx4 v134, s[62:63]
	s_add_u32 s62, s62, s16
	s_addc_u32 s63, s63, s17
	s_mov_b32 m0, s64
	ds_read_b128 v[210:213], v146 offset:23552
	global_load_lds_dwordx4 v132, s[62:63]
	s_add_i32 m0, s64, 0x2000
	ds_read_b128 v[206:209], v146 offset:22528
	global_load_lds_dwordx4 v134, s[62:63]
	s_mov_b32 m0, s33
	ds_read_b128 v[202:205], v146 offset:21504
	global_load_lds_dwordx4 v128, s[34:35]
	s_mov_b32 m0, s43
	ds_read_b128 v[198:201], v146 offset:20480
	global_load_lds_dwordx4 v130, s[34:35]
	s_waitcnt vmcnt(8) lgkmcnt(0)
	s_setprio 1
	s_barrier
	v_mfma_f32_16x16x32_bf16 v[60:63], v[148:151], v[180:183], v[60:63]
	v_mfma_f32_16x16x32_bf16 v[56:59], v[156:159], v[180:183], v[56:59]
	v_mfma_f32_16x16x32_bf16 v[44:47], v[148:151], v[190:193], v[44:47]
	v_mfma_f32_16x16x32_bf16 v[40:43], v[156:159], v[190:193], v[40:43]
	v_mfma_f32_16x16x32_bf16 v[28:31], v[148:151], v[198:201], v[28:31]
	v_mfma_f32_16x16x32_bf16 v[24:27], v[156:159], v[198:201], v[24:27]
	v_mfma_f32_16x16x32_bf16 v[12:15], v[148:151], v[206:209], v[12:15]
	v_mfma_f32_16x16x32_bf16 v[8:11], v[156:159], v[206:209], v[8:11]
	v_mfma_f32_16x16x32_bf16 v[60:63], v[152:155], v[184:187], v[60:63]
	v_mfma_f32_16x16x32_bf16 v[56:59], v[160:163], v[184:187], v[56:59]
	v_mfma_f32_16x16x32_bf16 v[44:47], v[152:155], v[194:197], v[44:47]
	v_mfma_f32_16x16x32_bf16 v[40:43], v[160:163], v[194:197], v[40:43]
	v_mfma_f32_16x16x32_bf16 v[28:31], v[152:155], v[202:205], v[28:31]
	v_mfma_f32_16x16x32_bf16 v[24:27], v[160:163], v[202:205], v[24:27]
	v_mfma_f32_16x16x32_bf16 v[12:15], v[152:155], v[210:213], v[12:15]
	v_mfma_f32_16x16x32_bf16 v[8:11], v[160:163], v[210:213], v[8:11]
	v_mfma_f32_16x16x32_bf16 v[52:55], v[164:167], v[180:183], v[52:55]
	v_mfma_f32_16x16x32_bf16 v[48:51], v[172:175], v[180:183], v[48:51]
	v_mfma_f32_16x16x32_bf16 v[36:39], v[164:167], v[190:193], v[36:39]
	v_mfma_f32_16x16x32_bf16 v[32:35], v[172:175], v[190:193], v[32:35]
	v_mfma_f32_16x16x32_bf16 v[20:23], v[164:167], v[198:201], v[20:23]
	v_mfma_f32_16x16x32_bf16 v[16:19], v[172:175], v[198:201], v[16:19]
	v_mfma_f32_16x16x32_bf16 v[4:7], v[164:167], v[206:209], v[4:7]
	v_mfma_f32_16x16x32_bf16 v[0:3], v[172:175], v[206:209], v[0:3]
	v_mfma_f32_16x16x32_bf16 v[52:55], v[168:171], v[184:187], v[52:55]
	v_mfma_f32_16x16x32_bf16 v[48:51], v[176:179], v[184:187], v[48:51]
	v_mfma_f32_16x16x32_bf16 v[36:39], v[168:171], v[194:197], v[36:39]
	v_mfma_f32_16x16x32_bf16 v[32:35], v[176:179], v[194:197], v[32:35]
	v_mfma_f32_16x16x32_bf16 v[20:23], v[168:171], v[202:205], v[20:23]
	v_mfma_f32_16x16x32_bf16 v[16:19], v[176:179], v[202:205], v[16:19]
	v_mfma_f32_16x16x32_bf16 v[4:7], v[168:171], v[210:213], v[4:7]
	v_mfma_f32_16x16x32_bf16 v[0:3], v[176:179], v[210:213], v[0:3]
	s_setprio 0
	s_barrier
; #define PG8_STAGE(bufoff, gbase, voff) do { _Pragma("unroll") for (int _i = 0; _i < 2; ++_i) \
;         __builtin_amdgcn_global_load_lds((const unsigned*)((const char*)(gbase) + (voff)[_i]), (PG8_LAS unsigned*)(lds + (bufoff) + ldsw + _i * 8192), 16, 0, 0); } while (0)
; #define PG8_LDA(dst, b, h) do { _Pragma("unroll") for (int m = 0; m < 4; ++m) _Pragma("unroll") for (int k = 0; k < 2; ++k) dst[m][k] = *(const PG8_LAS bf16x8*)(lds + PG8_SA(b, h) + aoff + m * 2048 + k * 1024); } while (0)
; #define PG8_LDB(dst, b, h) do { _Pragma("unroll") for (int n = 0; n < 2; ++n) _Pragma("unroll") for (int k = 0; k < 2; ++k) dst[n][k] = *(const PG8_LAS bf16x8*)(lds + PG8_SB(b, h) + boff + n * 2048 + k * 1024); } while (0)
; #define PG8_MMA(ai, bj, At, Bt) do { __builtin_amdgcn_s_setprio(1); _Pragma("unroll") for (int m = 0; m < 4; ++m) _Pragma("unroll") for (int n = 0; n < 2; ++n) _Pragma("unroll") for (int k = 0; k < 2; ++k) \
;         acc[ai][bj][m][n] = __builtin_amdgcn_mfma_f32_16x16x32_bf16(Bt[n][k], At[m][k], acc[ai][bj][m][n], 0, 0, 0); __builtin_amdgcn_s_setprio(0); } while (0)
; #define PG8_WAIT_V(n) asm volatile("s_waitcnt vmcnt(" #n ")" ::: "memory")
; #define PG8_WAIT_L(n) asm volatile("s_waitcnt lgkmcnt(" #n ")" ::: "memory")
; #define PG8_BAR __builtin_amdgcn_s_barrier()
; #define PG8_SCHED __builtin_amdgcn_sched_barrier(0)
; template <class Epi, class Sched, bool ALIGN_EPI = false, bool SP2 = false>
; __device__ __forceinline__ void gemm_phase(PG8_LAS unsigned char* lds, const Gemm g, const Sched& S, const Epi& E) {
;     ...
;             PG8_LDB(B0, 1, 0); PG8_LDB(B1, 1, 1); PG8_SCHED; PG8_LDA(At, 1, 0); PG8_STAGE(PG8_SA(0, 1), a2 + hstepA, voffA);
;             PG8_WAIT_V(8); PG8_WAIT_L(0); PG8_BAR; PG8_MMA(0, 0, At, B0); PG8_MMA(0, 1, At, B1); PG8_BAR; PG8_SCHED;
;             PG8_LDA(At, 1, 1); PG8_STAGE(PG8_SB(1, 0), b3, voffB); PG8_STAGE(PG8_SB(1, 1), b3 + hstep, voffB); PG8_STAGE(PG8_SA(1, 0), a3, voffA);
;             PG8_WAIT_V(8); PG8_WAIT_L(0); PG8_BAR; PG8_MMA(1, 0, At, B0); PG8_MMA(1, 1, At, B1); PG8_BAR; PG8_SCHED;
	s_add_i32 s62, 0, 0x18000
	v_add_u32_e32 v147, s62, v142
	s_add_i32 s63, 0, 0x1c000
	ds_read_b128 v[148:151], v147
	ds_read_b128 v[152:155], v147 offset:1024
	ds_read_b128 v[156:159], v147 offset:2048
	ds_read_b128 v[160:163], v147 offset:3072
	v_add_u32_e32 v147, s63, v142
	ds_read_b128 v[164:167], v147
	ds_read_b128 v[168:171], v147 offset:1024
	ds_read_b128 v[172:175], v147 offset:2048
	ds_read_b128 v[176:179], v147 offset:3072
	s_mov_b64 vcc, s[34:35]
	s_add_u32 s34, s34, 0x40000
	s_addc_u32 s35, s35, 0
	s_mov_b32 m0, s45
	ds_read_b128 v[180:183], v146 offset:32768
	ds_read_b128 v[184:187], v146 offset:33792
	ds_read_b128 v[190:193], v146 offset:34816
	ds_read_b128 v[194:197], v146 offset:35840
	ds_read_b128 v[198:201], v146 offset:36864
	ds_read_b128 v[202:205], v146 offset:37888
	ds_read_b128 v[206:209], v146 offset:38912
	global_load_lds_dwordx4 v128, s[34:35]
	s_mov_b32 m0, s47
	ds_read_b128 v[210:213], v146 offset:39936
	global_load_lds_dwordx4 v130, s[34:35]
	s_waitcnt vmcnt(8) lgkmcnt(0)
	s_setprio 1
	s_barrier
	v_mfma_f32_16x16x32_bf16 v[124:127], v[148:151], v[180:183], v[124:127]
	v_mfma_f32_16x16x32_bf16 v[120:123], v[156:159], v[180:183], v[120:123]
	v_mfma_f32_16x16x32_bf16 v[108:111], v[148:151], v[190:193], v[108:111]
	v_mfma_f32_16x16x32_bf16 v[104:107], v[156:159], v[190:193], v[104:107]
	v_mfma_f32_16x16x32_bf16 v[92:95], v[148:151], v[198:201], v[92:95]
	v_mfma_f32_16x16x32_bf16 v[88:91], v[156:159], v[198:201], v[88:91]
	v_mfma_f32_16x16x32_bf16 v[76:79], v[148:151], v[206:209], v[76:79]
	v_mfma_f32_16x16x32_bf16 v[72:75], v[156:159], v[206:209], v[72:75]
	v_mfma_f32_16x16x32_bf16 v[124:127], v[152:155], v[184:187], v[124:127]
	v_mfma_f32_16x16x32_bf16 v[120:123], v[160:163], v[184:187], v[120:123]
	v_mfma_f32_16x16x32_bf16 v[108:111], v[152:155], v[194:197], v[108:111]
	v_mfma_f32_16x16x32_bf16 v[104:107], v[160:163], v[194:197], v[104:107]
	v_mfma_f32_16x16x32_bf16 v[92:95], v[152:155], v[202:205], v[92:95]
	v_mfma_f32_16x16x32_bf16 v[88:91], v[160:163], v[202:205], v[88:91]
	v_mfma_f32_16x16x32_bf16 v[76:79], v[152:155], v[210:213], v[76:79]
	v_mfma_f32_16x16x32_bf16 v[72:75], v[160:163], v[210:213], v[72:75]
	v_mfma_f32_16x16x32_bf16 v[116:119], v[164:167], v[180:183], v[116:119]
	v_mfma_f32_16x16x32_bf16 v[112:115], v[172:175], v[180:183], v[112:115]
	v_mfma_f32_16x16x32_bf16 v[100:103], v[164:167], v[190:193], v[100:103]
	v_mfma_f32_16x16x32_bf16 v[96:99], v[172:175], v[190:193], v[96:99]
	v_mfma_f32_16x16x32_bf16 v[84:87], v[164:167], v[198:201], v[84:87]
	v_mfma_f32_16x16x32_bf16 v[80:83], v[172:175], v[198:201], v[80:83]
	v_mfma_f32_16x16x32_bf16 v[68:71], v[164:167], v[206:209], v[68:71]
	v_mfma_f32_16x16x32_bf16 v[64:67], v[172:175], v[206:209], v[64:67]
	v_mfma_f32_16x16x32_bf16 v[116:119], v[168:171], v[184:187], v[116:119]
	v_mfma_f32_16x16x32_bf16 v[112:115], v[176:179], v[184:187], v[112:115]
	v_mfma_f32_16x16x32_bf16 v[100:103], v[168:171], v[194:197], v[100:103]
	v_mfma_f32_16x16x32_bf16 v[96:99], v[176:179], v[194:197], v[96:99]
	v_mfma_f32_16x16x32_bf16 v[84:87], v[168:171], v[202:205], v[84:87]
	v_mfma_f32_16x16x32_bf16 v[80:83], v[176:179], v[202:205], v[80:83]
	v_mfma_f32_16x16x32_bf16 v[68:71], v[168:171], v[210:213], v[68:71]
	v_mfma_f32_16x16x32_bf16 v[64:67], v[176:179], v[210:213], v[64:67]
	s_setprio 0
	s_barrier
	s_add_i32 s34, s62, s44
	s_add_i32 m0, s34, 0xffffff80
	ds_read_b128 v[180:183], v146 offset:49152
	ds_read_b128 v[184:187], v146 offset:50176
	ds_read_b128 v[190:193], v146 offset:51200
	ds_read_b128 v[194:197], v146 offset:52224
	global_load_lds_dwordx4 v132, s[100:101] offset:128
	s_add_i32 m0, s34, 0x1f80
	s_add_i32 s34, s63, s44
	global_load_lds_dwordx4 v134, s[100:101] offset:128
	s_add_u32 s100, s100, s16
	s_addc_u32 s101, s101, s17
	s_add_i32 m0, s34, 0xffffff80
	ds_read_b128 v[210:213], v146 offset:56320
	global_load_lds_dwordx4 v132, s[100:101] offset:128
	s_add_i32 m0, s34, 0x1f80
	ds_read_b128 v[206:209], v146 offset:55296
	global_load_lds_dwordx4 v134, s[100:101] offset:128
	s_add_i32 m0, s48, 0xffffff80
	ds_read_b128 v[202:205], v146 offset:54272
	global_load_lds_dwordx4 v128, vcc offset:128
	s_add_i32 m0, s49, 0xffffff80
	ds_read_b128 v[198:201], v146 offset:53248
	global_load_lds_dwordx4 v130, vcc offset:128
	s_waitcnt vmcnt(8) lgkmcnt(0)
	s_setprio 1
	s_barrier
	v_mfma_f32_16x16x32_bf16 v[60:63], v[148:151], v[180:183], v[60:63]
	v_mfma_f32_16x16x32_bf16 v[56:59], v[156:159], v[180:183], v[56:59]
	v_mfma_f32_16x16x32_bf16 v[44:47], v[148:151], v[190:193], v[44:47]
	v_mfma_f32_16x16x32_bf16 v[40:43], v[156:159], v[190:193], v[40:43]
	v_mfma_f32_16x16x32_bf16 v[28:31], v[148:151], v[198:201], v[28:31]
	v_mfma_f32_16x16x32_bf16 v[24:27], v[156:159], v[198:201], v[24:27]
	v_mfma_f32_16x16x32_bf16 v[12:15], v[148:151], v[206:209], v[12:15]
	v_mfma_f32_16x16x32_bf16 v[8:11], v[156:159], v[206:209], v[8:11]
	v_mfma_f32_16x16x32_bf16 v[60:63], v[152:155], v[184:187], v[60:63]
	v_mfma_f32_16x16x32_bf16 v[56:59], v[160:163], v[184:187], v[56:59]
	v_mfma_f32_16x16x32_bf16 v[44:47], v[152:155], v[194:197], v[44:47]
	v_mfma_f32_16x16x32_bf16 v[40:43], v[160:163], v[194:197], v[40:43]
	v_mfma_f32_16x16x32_bf16 v[28:31], v[152:155], v[202:205], v[28:31]
	v_mfma_f32_16x16x32_bf16 v[24:27], v[160:163], v[202:205], v[24:27]
	v_mfma_f32_16x16x32_bf16 v[12:15], v[152:155], v[210:213], v[12:15]
	v_mfma_f32_16x16x32_bf16 v[8:11], v[160:163], v[210:213], v[8:11]
	v_mfma_f32_16x16x32_bf16 v[52:55], v[164:167], v[180:183], v[52:55]
	v_mfma_f32_16x16x32_bf16 v[48:51], v[172:175], v[180:183], v[48:51]
	v_mfma_f32_16x16x32_bf16 v[36:39], v[164:167], v[190:193], v[36:39]
	v_mfma_f32_16x16x32_bf16 v[32:35], v[172:175], v[190:193], v[32:35]
	v_mfma_f32_16x16x32_bf16 v[20:23], v[164:167], v[198:201], v[20:23]
	v_mfma_f32_16x16x32_bf16 v[16:19], v[172:175], v[198:201], v[16:19]
	v_mfma_f32_16x16x32_bf16 v[4:7], v[164:167], v[206:209], v[4:7]
	v_mfma_f32_16x16x32_bf16 v[0:3], v[172:175], v[206:209], v[0:3]
	v_mfma_f32_16x16x32_bf16 v[52:55], v[168:171], v[184:187], v[52:55]
	v_mfma_f32_16x16x32_bf16 v[48:51], v[176:179], v[184:187], v[48:51]
	v_mfma_f32_16x16x32_bf16 v[36:39], v[168:171], v[194:197], v[36:39]
	v_mfma_f32_16x16x32_bf16 v[32:35], v[176:179], v[194:197], v[32:35]
	v_mfma_f32_16x16x32_bf16 v[20:23], v[168:171], v[202:205], v[20:23]
	v_mfma_f32_16x16x32_bf16 v[16:19], v[176:179], v[202:205], v[16:19]
	v_mfma_f32_16x16x32_bf16 v[4:7], v[168:171], v[210:213], v[4:7]
	v_mfma_f32_16x16x32_bf16 v[0:3], v[176:179], v[210:213], v[0:3]
	s_setprio 0
	s_barrier
	s_add_u32 s30, s30, 0x100
	s_addc_u32 s31, s31, 0
	s_add_u32 s37, s37, 0x100
	s_addc_u32 s60, s60, 0
	s_cmp_ge_i32 s61, s50
	s_mov_b32 s34, s61
	s_cbranch_scc0 .LBB0_282

; #define PG8_STAGE(bufoff, gbase, voff) do { _Pragma("unroll") for (int _i = 0; _i < 2; ++_i) \
;         __builtin_amdgcn_global_load_lds((const unsigned*)((const char*)(gbase) + (voff)[_i]), (PG8_LAS unsigned*)(lds + (bufoff) + ldsw + _i * 8192), 16, 0, 0); } while (0)
; #define PG8_LDA(dst, b, h) do { _Pragma("unroll") for (int m = 0; m < 4; ++m) _Pragma("unroll") for (int k = 0; k < 2; ++k) dst[m][k] = *(const PG8_LAS bf16x8*)(lds + PG8_SA(b, h) + aoff + m * 2048 + k * 1024); } while (0)
; #define PG8_LDB(dst, b, h) do { _Pragma("unroll") for (int n = 0; n < 2; ++n) _Pragma("unroll") for (int k = 0; k < 2; ++k) dst[n][k] = *(const PG8_LAS bf16x8*)(lds + PG8_SB(b, h) + boff + n * 2048 + k * 1024); } while (0)
; #define PG8_MMA(ai, bj, At, Bt) do { __builtin_amdgcn_s_setprio(1); _Pragma("unroll") for (int m = 0; m < 4; ++m) _Pragma("unroll") for (int n = 0; n < 2; ++n) _Pragma("unroll") for (int k = 0; k < 2; ++k) \
;         acc[ai][bj][m][n] = __builtin_amdgcn_mfma_f32_16x16x32_bf16(Bt[n][k], At[m][k], acc[ai][bj][m][n], 0, 0, 0); __builtin_amdgcn_s_setprio(0); } while (0)
; #define PG8_WAIT_V(n) asm volatile("s_waitcnt vmcnt(" #n ")" ::: "memory")
; #define PG8_WAIT_L(n) asm volatile("s_waitcnt lgkmcnt(" #n ")" ::: "memory")
; template <class Epi, class Sched, bool ALIGN_EPI = false, bool SP2 = false>
; __device__ __forceinline__ void gemm_phase(PG8_LAS unsigned char* lds, const Gemm g, const Sched& S, const Epi& E) {
;     ...
;             const bool last = (t == nt - 2);
;             const char* a1 = cA + (size_t)(t + 1) * kstep;
;             const char* a2 = last ? nA : cA + (size_t)(t + 2) * kstep; const char* b2 = last ? nB : cB + (size_t)(t + 2) * kstep;
;             const char* a3 = a2 + kstep; const char* b3 = b2 + kstep;
;             if (last && has_next) S.a_ready(nxt);
;             if constexpr (SP2) {
;             PG8_LDB(B0, 0, 0); PG8_LDB(B1, 0, 1); PG8_SCHED; PG8_LDA(At, 0, 0); PG8_STAGE(PG8_SA(1, 1), a1 + hstepA, voffA);
;             PG8_WAIT_V(8); PG8_WAIT_L(0); PG8_BAR; PG8_MMA(0, 0, At, B0); PG8_MMA(0, 1, At, B1); PG8_BAR; PG8_SCHED;
;             PG8_LDA(At, 0, 1); PG8_STAGE(PG8_SB(0, 0), b2, voffB); PG8_STAGE(PG8_SB(0, 1), b2 + hstep, voffB); PG8_STAGE(PG8_SA(0, 0), a2, voffA);
;             PG8_WAIT_V(8); PG8_WAIT_L(0); PG8_BAR; PG8_MMA(1, 0, At, B0); PG8_MMA(1, 1, At, B1); PG8_BAR; PG8_SCHED;
.LBB0_368:
	ds_read_b128 v[154:157], v150
	ds_read_b128 v[158:161], v150 offset:1024
	ds_read_b128 v[162:165], v150 offset:2048
	ds_read_b128 v[166:169], v150 offset:3072
	ds_read_b128 v[170:173], v151
	ds_read_b128 v[174:177], v151 offset:1024
	ds_read_b128 v[178:181], v151 offset:2048
	ds_read_b128 v[182:185], v151 offset:3072
	s_add_i32 s64, s28, 2
	s_add_u32 s65, s26, 0xfffe0080
	s_addc_u32 s29, s27, -1
	s_cmp_eq_u32 s50, s28
	s_cselect_b32 s28, s30, s65
	s_cselect_b32 s29, s13, s29
	s_cselect_b32 s67, s21, s63
	s_cselect_b32 s66, s20, s62
	s_mov_b32 m0, s54
	ds_read_b128 v[190:193], v152
	ds_read_b128 v[194:197], v152 offset:1024
	ds_read_b128 v[198:201], v152 offset:2048
	ds_read_b128 v[202:205], v152 offset:3072
	ds_read_b128 v[206:209], v152 offset:4096
	ds_read_b128 v[210:213], v152 offset:5120
	ds_read_b128 v[214:217], v152 offset:6144
	global_load_lds_dwordx4 v138, s[26:27]
	s_mov_b32 m0, s55
	ds_read_b128 v[218:221], v152 offset:7168
	global_load_lds_dwordx4 v140, s[26:27]
	s_waitcnt vmcnt(8) lgkmcnt(0)
	s_setprio 1
	s_barrier
	v_mfma_f32_16x16x32_bf16 v[124:127], v[154:157], v[190:193], v[124:127]
	v_mfma_f32_16x16x32_bf16 v[120:123], v[162:165], v[190:193], v[120:123]
	v_mfma_f32_16x16x32_bf16 v[108:111], v[154:157], v[198:201], v[108:111]
	v_mfma_f32_16x16x32_bf16 v[104:107], v[162:165], v[198:201], v[104:107]
	v_mfma_f32_16x16x32_bf16 v[92:95], v[154:157], v[206:209], v[92:95]
	v_mfma_f32_16x16x32_bf16 v[88:91], v[162:165], v[206:209], v[88:91]
	v_mfma_f32_16x16x32_bf16 v[76:79], v[154:157], v[214:217], v[76:79]
	v_mfma_f32_16x16x32_bf16 v[72:75], v[162:165], v[214:217], v[72:75]
	v_mfma_f32_16x16x32_bf16 v[124:127], v[158:161], v[194:197], v[124:127]
	v_mfma_f32_16x16x32_bf16 v[120:123], v[166:169], v[194:197], v[120:123]
	v_mfma_f32_16x16x32_bf16 v[108:111], v[158:161], v[202:205], v[108:111]
	v_mfma_f32_16x16x32_bf16 v[104:107], v[166:169], v[202:205], v[104:107]
	v_mfma_f32_16x16x32_bf16 v[92:95], v[158:161], v[210:213], v[92:95]
	v_mfma_f32_16x16x32_bf16 v[88:91], v[166:169], v[210:213], v[88:91]
	v_mfma_f32_16x16x32_bf16 v[76:79], v[158:161], v[218:221], v[76:79]
	v_mfma_f32_16x16x32_bf16 v[72:75], v[166:169], v[218:221], v[72:75]
	v_mfma_f32_16x16x32_bf16 v[116:119], v[170:173], v[190:193], v[116:119]
	v_mfma_f32_16x16x32_bf16 v[112:115], v[178:181], v[190:193], v[112:115]
	v_mfma_f32_16x16x32_bf16 v[100:103], v[170:173], v[198:201], v[100:103]
	v_mfma_f32_16x16x32_bf16 v[96:99], v[178:181], v[198:201], v[96:99]
	v_mfma_f32_16x16x32_bf16 v[84:87], v[170:173], v[206:209], v[84:87]
	v_mfma_f32_16x16x32_bf16 v[80:83], v[178:181], v[206:209], v[80:83]
	v_mfma_f32_16x16x32_bf16 v[68:71], v[170:173], v[214:217], v[68:71]
	v_mfma_f32_16x16x32_bf16 v[64:67], v[178:181], v[214:217], v[64:67]
	v_mfma_f32_16x16x32_bf16 v[116:119], v[174:177], v[194:197], v[116:119]
	v_mfma_f32_16x16x32_bf16 v[112:115], v[182:185], v[194:197], v[112:115]
	v_mfma_f32_16x16x32_bf16 v[100:103], v[174:177], v[202:205], v[100:103]
	v_mfma_f32_16x16x32_bf16 v[96:99], v[182:185], v[202:205], v[96:99]
	v_mfma_f32_16x16x32_bf16 v[84:87], v[174:177], v[210:213], v[84:87]
	v_mfma_f32_16x16x32_bf16 v[80:83], v[182:185], v[210:213], v[80:83]
	v_mfma_f32_16x16x32_bf16 v[68:71], v[174:177], v[218:221], v[68:71]
	v_mfma_f32_16x16x32_bf16 v[64:67], v[182:185], v[218:221], v[64:67]
	s_setprio 0
	s_barrier
	s_mov_b32 m0, s56
	s_mov_b64 s[100:101], s[66:67]
	ds_read_b128 v[190:193], v152 offset:16384
	ds_read_b128 v[194:197], v152 offset:17408
	ds_read_b128 v[198:201], v152 offset:18432
	global_load_lds_dwordx4 v134, s[66:67]
	s_mov_b32 m0, s57
	ds_read_b128 v[218:221], v152 offset:23552
	global_load_lds_dwordx4 v132, s[66:67]
	s_add_u32 s66, s66, s4
	s_addc_u32 s67, s67, s5
	s_mov_b32 m0, s58
	ds_read_b128 v[214:217], v152 offset:22528
	global_load_lds_dwordx4 v134, s[66:67]
	s_mov_b32 m0, s59
	ds_read_b128 v[210:213], v152 offset:21504
	global_load_lds_dwordx4 v132, s[66:67]
	s_mov_b32 m0, s38
	ds_read_b128 v[206:209], v152 offset:20480
	global_load_lds_dwordx4 v130, s[28:29]
	s_mov_b32 m0, s39
	ds_read_b128 v[202:205], v152 offset:19456
	global_load_lds_dwordx4 v128, s[28:29]
	s_waitcnt vmcnt(8) lgkmcnt(0)
	s_setprio 1
	s_barrier
	v_mfma_f32_16x16x32_bf16 v[60:63], v[154:157], v[190:193], v[60:63]
	v_mfma_f32_16x16x32_bf16 v[56:59], v[162:165], v[190:193], v[56:59]
	v_mfma_f32_16x16x32_bf16 v[44:47], v[154:157], v[198:201], v[44:47]
	v_mfma_f32_16x16x32_bf16 v[40:43], v[162:165], v[198:201], v[40:43]
	v_mfma_f32_16x16x32_bf16 v[28:31], v[154:157], v[206:209], v[28:31]
	v_mfma_f32_16x16x32_bf16 v[24:27], v[162:165], v[206:209], v[24:27]
	v_mfma_f32_16x16x32_bf16 v[12:15], v[154:157], v[214:217], v[12:15]
	v_mfma_f32_16x16x32_bf16 v[8:11], v[162:165], v[214:217], v[8:11]
	v_mfma_f32_16x16x32_bf16 v[60:63], v[158:161], v[194:197], v[60:63]
	v_mfma_f32_16x16x32_bf16 v[56:59], v[166:169], v[194:197], v[56:59]
	v_mfma_f32_16x16x32_bf16 v[44:47], v[158:161], v[202:205], v[44:47]
	v_mfma_f32_16x16x32_bf16 v[40:43], v[166:169], v[202:205], v[40:43]
	v_mfma_f32_16x16x32_bf16 v[28:31], v[158:161], v[210:213], v[28:31]
	v_mfma_f32_16x16x32_bf16 v[24:27], v[166:169], v[210:213], v[24:27]
	v_mfma_f32_16x16x32_bf16 v[12:15], v[158:161], v[218:221], v[12:15]
	v_mfma_f32_16x16x32_bf16 v[8:11], v[166:169], v[218:221], v[8:11]
	v_mfma_f32_16x16x32_bf16 v[52:55], v[170:173], v[190:193], v[52:55]
	v_mfma_f32_16x16x32_bf16 v[48:51], v[178:181], v[190:193], v[48:51]
	v_mfma_f32_16x16x32_bf16 v[36:39], v[170:173], v[198:201], v[36:39]
	v_mfma_f32_16x16x32_bf16 v[32:35], v[178:181], v[198:201], v[32:35]
	v_mfma_f32_16x16x32_bf16 v[20:23], v[170:173], v[206:209], v[20:23]
	v_mfma_f32_16x16x32_bf16 v[16:19], v[178:181], v[206:209], v[16:19]
	v_mfma_f32_16x16x32_bf16 v[4:7], v[170:173], v[214:217], v[4:7]
	v_mfma_f32_16x16x32_bf16 v[0:3], v[178:181], v[214:217], v[0:3]
	v_mfma_f32_16x16x32_bf16 v[52:55], v[174:177], v[194:197], v[52:55]
	v_mfma_f32_16x16x32_bf16 v[48:51], v[182:185], v[194:197], v[48:51]
	v_mfma_f32_16x16x32_bf16 v[36:39], v[174:177], v[202:205], v[36:39]
	v_mfma_f32_16x16x32_bf16 v[32:35], v[182:185], v[202:205], v[32:35]
	v_mfma_f32_16x16x32_bf16 v[20:23], v[174:177], v[210:213], v[20:23]
	v_mfma_f32_16x16x32_bf16 v[16:19], v[182:185], v[210:213], v[16:19]
	v_mfma_f32_16x16x32_bf16 v[4:7], v[174:177], v[218:221], v[4:7]
	v_mfma_f32_16x16x32_bf16 v[0:3], v[182:185], v[218:221], v[0:3]
	s_setprio 0
	s_barrier
; #define PG8_STAGE(bufoff, gbase, voff) do { _Pragma("unroll") for (int _i = 0; _i < 2; ++_i) \
;         __builtin_amdgcn_global_load_lds((const unsigned*)((const char*)(gbase) + (voff)[_i]), (PG8_LAS unsigned*)(lds + (bufoff) + ldsw + _i * 8192), 16, 0, 0); } while (0)
; #define PG8_LDA(dst, b, h) do { _Pragma("unroll") for (int m = 0; m < 4; ++m) _Pragma("unroll") for (int k = 0; k < 2; ++k) dst[m][k] = *(const PG8_LAS bf16x8*)(lds + PG8_SA(b, h) + aoff + m * 2048 + k * 1024); } while (0)
; #define PG8_LDB(dst, b, h) do { _Pragma("unroll") for (int n = 0; n < 2; ++n) _Pragma("unroll") for (int k = 0; k < 2; ++k) dst[n][k] = *(const PG8_LAS bf16x8*)(lds + PG8_SB(b, h) + boff + n * 2048 + k * 1024); } while (0)
; #define PG8_MMA(ai, bj, At, Bt) do { __builtin_amdgcn_s_setprio(1); _Pragma("unroll") for (int m = 0; m < 4; ++m) _Pragma("unroll") for (int n = 0; n < 2; ++n) _Pragma("unroll") for (int k = 0; k < 2; ++k) \
;         acc[ai][bj][m][n] = __builtin_amdgcn_mfma_f32_16x16x32_bf16(Bt[n][k], At[m][k], acc[ai][bj][m][n], 0, 0, 0); __builtin_amdgcn_s_setprio(0); } while (0)
; #define PG8_WAIT_V(n) asm volatile("s_waitcnt vmcnt(" #n ")" ::: "memory")
; #define PG8_WAIT_L(n) asm volatile("s_waitcnt lgkmcnt(" #n ")" ::: "memory")
; #define PG8_BAR __builtin_amdgcn_s_barrier()
; #define PG8_SCHED __builtin_amdgcn_sched_barrier(0)
; template <class Epi, class Sched, bool ALIGN_EPI = false, bool SP2 = false>
; __device__ __forceinline__ void gemm_phase(PG8_LAS unsigned char* lds, const Gemm g, const Sched& S, const Epi& E) {
;     ...
;             PG8_LDB(B0, 1, 0); PG8_LDB(B1, 1, 1); PG8_SCHED; PG8_LDA(At, 1, 0); PG8_STAGE(PG8_SA(0, 1), a2 + hstepA, voffA);
;             PG8_WAIT_V(8); PG8_WAIT_L(0); PG8_BAR; PG8_MMA(0, 0, At, B0); PG8_MMA(0, 1, At, B1); PG8_BAR; PG8_SCHED;
;             PG8_LDA(At, 1, 1); PG8_STAGE(PG8_SB(1, 0), b3, voffB); PG8_STAGE(PG8_SB(1, 1), b3 + hstep, voffB); PG8_STAGE(PG8_SA(1, 0), a3, voffA);
;             PG8_WAIT_V(8); PG8_WAIT_L(0); PG8_BAR; PG8_MMA(1, 0, At, B0); PG8_MMA(1, 1, At, B1); PG8_BAR; PG8_SCHED;
	s_add_i32 s65, 0, 0x18000
	s_add_i32 s66, 0, 0x1c000
	v_add_u32_e32 v166, s65, v149
	v_add_u32_e32 v182, s66, v149
	ds_read_b128 v[154:157], v166
	ds_read_b128 v[158:161], v166 offset:1024
	ds_read_b128 v[162:165], v166 offset:2048
	ds_read_b128 v[166:169], v166 offset:3072
	ds_read_b128 v[170:173], v182
	ds_read_b128 v[174:177], v182 offset:1024
	ds_read_b128 v[178:181], v182 offset:2048
	ds_read_b128 v[182:185], v182 offset:3072
	s_mov_b64 vcc, s[28:29]
	s_add_u32 s28, s28, 0x20000
	s_addc_u32 s29, s29, 0
	s_mov_b32 m0, s40
	ds_read_b128 v[190:193], v152 offset:32768
	ds_read_b128 v[194:197], v152 offset:33792
	ds_read_b128 v[198:201], v152 offset:34816
	ds_read_b128 v[202:205], v152 offset:35840
	ds_read_b128 v[206:209], v152 offset:36864
	ds_read_b128 v[210:213], v152 offset:37888
	ds_read_b128 v[214:217], v152 offset:38912
	global_load_lds_dwordx4 v130, s[28:29]
	s_mov_b32 m0, s41
	ds_read_b128 v[218:221], v152 offset:39936
	global_load_lds_dwordx4 v128, s[28:29]
	s_waitcnt vmcnt(8) lgkmcnt(0)
	s_setprio 1
	s_barrier
	v_mfma_f32_16x16x32_bf16 v[124:127], v[154:157], v[190:193], v[124:127]
	v_mfma_f32_16x16x32_bf16 v[120:123], v[162:165], v[190:193], v[120:123]
	v_mfma_f32_16x16x32_bf16 v[108:111], v[154:157], v[198:201], v[108:111]
	v_mfma_f32_16x16x32_bf16 v[104:107], v[162:165], v[198:201], v[104:107]
	v_mfma_f32_16x16x32_bf16 v[92:95], v[154:157], v[206:209], v[92:95]
	v_mfma_f32_16x16x32_bf16 v[88:91], v[162:165], v[206:209], v[88:91]
	v_mfma_f32_16x16x32_bf16 v[76:79], v[154:157], v[214:217], v[76:79]
	v_mfma_f32_16x16x32_bf16 v[72:75], v[162:165], v[214:217], v[72:75]
	v_mfma_f32_16x16x32_bf16 v[124:127], v[158:161], v[194:197], v[124:127]
	v_mfma_f32_16x16x32_bf16 v[120:123], v[166:169], v[194:197], v[120:123]
	v_mfma_f32_16x16x32_bf16 v[108:111], v[158:161], v[202:205], v[108:111]
	v_mfma_f32_16x16x32_bf16 v[104:107], v[166:169], v[202:205], v[104:107]
	v_mfma_f32_16x16x32_bf16 v[92:95], v[158:161], v[210:213], v[92:95]
	v_mfma_f32_16x16x32_bf16 v[88:91], v[166:169], v[210:213], v[88:91]
	v_mfma_f32_16x16x32_bf16 v[76:79], v[158:161], v[218:221], v[76:79]
	v_mfma_f32_16x16x32_bf16 v[72:75], v[166:169], v[218:221], v[72:75]
	v_mfma_f32_16x16x32_bf16 v[116:119], v[170:173], v[190:193], v[116:119]
	v_mfma_f32_16x16x32_bf16 v[112:115], v[178:181], v[190:193], v[112:115]
	v_mfma_f32_16x16x32_bf16 v[100:103], v[170:173], v[198:201], v[100:103]
	v_mfma_f32_16x16x32_bf16 v[96:99], v[178:181], v[198:201], v[96:99]
	v_mfma_f32_16x16x32_bf16 v[84:87], v[170:173], v[206:209], v[84:87]
	v_mfma_f32_16x16x32_bf16 v[80:83], v[178:181], v[206:209], v[80:83]
	v_mfma_f32_16x16x32_bf16 v[68:71], v[170:173], v[214:217], v[68:71]
	v_mfma_f32_16x16x32_bf16 v[64:67], v[178:181], v[214:217], v[64:67]
	v_mfma_f32_16x16x32_bf16 v[116:119], v[174:177], v[194:197], v[116:119]
	v_mfma_f32_16x16x32_bf16 v[112:115], v[182:185], v[194:197], v[112:115]
	v_mfma_f32_16x16x32_bf16 v[100:103], v[174:177], v[202:205], v[100:103]
	v_mfma_f32_16x16x32_bf16 v[96:99], v[182:185], v[202:205], v[96:99]
	v_mfma_f32_16x16x32_bf16 v[84:87], v[174:177], v[210:213], v[84:87]
	v_mfma_f32_16x16x32_bf16 v[80:83], v[182:185], v[210:213], v[80:83]
	v_mfma_f32_16x16x32_bf16 v[68:71], v[174:177], v[218:221], v[68:71]
	v_mfma_f32_16x16x32_bf16 v[64:67], v[182:185], v[218:221], v[64:67]
	s_setprio 0
	s_barrier
	s_add_i32 s28, s65, s37
	s_add_i32 m0, s28, 0xffffff80
	ds_read_b128 v[190:193], v152 offset:49152
	ds_read_b128 v[194:197], v152 offset:50176
	ds_read_b128 v[198:201], v152 offset:51200
	ds_read_b128 v[202:205], v152 offset:52224
	global_load_lds_dwordx4 v134, s[100:101] offset:128
	s_add_i32 m0, s28, 0x1f80
	s_add_i32 s28, s66, s37
	global_load_lds_dwordx4 v132, s[100:101] offset:128
	s_add_u32 s100, s100, s4
	s_addc_u32 s101, s101, s5
	s_add_i32 m0, s28, 0xffffff80
	ds_read_b128 v[218:221], v152 offset:56320
	global_load_lds_dwordx4 v134, s[100:101] offset:128
	s_add_i32 m0, s28, 0x1f80
	ds_read_b128 v[214:217], v152 offset:55296
	global_load_lds_dwordx4 v132, s[100:101] offset:128
	s_add_i32 m0, s43, 0xffffff80
	ds_read_b128 v[210:213], v152 offset:54272
	global_load_lds_dwordx4 v130, vcc offset:128
	s_add_i32 m0, s44, 0xffffff80
	ds_read_b128 v[206:209], v152 offset:53248
	global_load_lds_dwordx4 v128, vcc offset:128
	s_waitcnt vmcnt(8) lgkmcnt(0)
	s_setprio 1
	s_barrier
	v_mfma_f32_16x16x32_bf16 v[60:63], v[154:157], v[190:193], v[60:63]
	v_mfma_f32_16x16x32_bf16 v[56:59], v[162:165], v[190:193], v[56:59]
	v_mfma_f32_16x16x32_bf16 v[44:47], v[154:157], v[198:201], v[44:47]
	v_mfma_f32_16x16x32_bf16 v[40:43], v[162:165], v[198:201], v[40:43]
	v_mfma_f32_16x16x32_bf16 v[28:31], v[154:157], v[206:209], v[28:31]
	v_mfma_f32_16x16x32_bf16 v[24:27], v[162:165], v[206:209], v[24:27]
	v_mfma_f32_16x16x32_bf16 v[12:15], v[154:157], v[214:217], v[12:15]
	v_mfma_f32_16x16x32_bf16 v[8:11], v[162:165], v[214:217], v[8:11]
	v_mfma_f32_16x16x32_bf16 v[60:63], v[158:161], v[194:197], v[60:63]
	v_mfma_f32_16x16x32_bf16 v[56:59], v[166:169], v[194:197], v[56:59]
	v_mfma_f32_16x16x32_bf16 v[44:47], v[158:161], v[202:205], v[44:47]
	v_mfma_f32_16x16x32_bf16 v[40:43], v[166:169], v[202:205], v[40:43]
	v_mfma_f32_16x16x32_bf16 v[28:31], v[158:161], v[210:213], v[28:31]
	v_mfma_f32_16x16x32_bf16 v[24:27], v[166:169], v[210:213], v[24:27]
	v_mfma_f32_16x16x32_bf16 v[12:15], v[158:161], v[218:221], v[12:15]
	v_mfma_f32_16x16x32_bf16 v[8:11], v[166:169], v[218:221], v[8:11]
	v_mfma_f32_16x16x32_bf16 v[52:55], v[170:173], v[190:193], v[52:55]
	v_mfma_f32_16x16x32_bf16 v[48:51], v[178:181], v[190:193], v[48:51]
	v_mfma_f32_16x16x32_bf16 v[36:39], v[170:173], v[198:201], v[36:39]
	v_mfma_f32_16x16x32_bf16 v[32:35], v[178:181], v[198:201], v[32:35]
	v_mfma_f32_16x16x32_bf16 v[20:23], v[170:173], v[206:209], v[20:23]
	v_mfma_f32_16x16x32_bf16 v[16:19], v[178:181], v[206:209], v[16:19]
	v_mfma_f32_16x16x32_bf16 v[4:7], v[170:173], v[214:217], v[4:7]
	v_mfma_f32_16x16x32_bf16 v[0:3], v[178:181], v[214:217], v[0:3]
	v_mfma_f32_16x16x32_bf16 v[52:55], v[174:177], v[194:197], v[52:55]
	v_mfma_f32_16x16x32_bf16 v[48:51], v[182:185], v[194:197], v[48:51]
	v_mfma_f32_16x16x32_bf16 v[36:39], v[174:177], v[202:205], v[36:39]
	v_mfma_f32_16x16x32_bf16 v[32:35], v[182:185], v[202:205], v[32:35]
	v_mfma_f32_16x16x32_bf16 v[20:23], v[174:177], v[210:213], v[20:23]
	v_mfma_f32_16x16x32_bf16 v[16:19], v[182:185], v[210:213], v[16:19]
	v_mfma_f32_16x16x32_bf16 v[4:7], v[174:177], v[218:221], v[4:7]
	v_mfma_f32_16x16x32_bf16 v[0:3], v[182:185], v[218:221], v[0:3]
	s_setprio 0
	s_barrier
	s_add_u32 s26, s26, 0x100
	s_addc_u32 s27, s27, 0
	s_add_u32 s62, s62, 0x100
	s_addc_u32 s63, s63, 0
	s_cmp_ge_i32 s64, s48
	s_mov_b32 s28, s64
	s_cbranch_scc0 .LBB0_368

; #define PG8_STAGE(bufoff, gbase, voff) do { _Pragma("unroll") for (int _i = 0; _i < 2; ++_i) \
;         __builtin_amdgcn_global_load_lds((const unsigned*)((const char*)(gbase) + (voff)[_i]), (PG8_LAS unsigned*)(lds + (bufoff) + ldsw + _i * 8192), 16, 0, 0); } while (0)
; #define PG8_LDA(dst, b, h) do { _Pragma("unroll") for (int m = 0; m < 4; ++m) _Pragma("unroll") for (int k = 0; k < 2; ++k) dst[m][k] = *(const PG8_LAS bf16x8*)(lds + PG8_SA(b, h) + aoff + m * 2048 + k * 1024); } while (0)
; #define PG8_LDB(dst, b, h) do { _Pragma("unroll") for (int n = 0; n < 2; ++n) _Pragma("unroll") for (int k = 0; k < 2; ++k) dst[n][k] = *(const PG8_LAS bf16x8*)(lds + PG8_SB(b, h) + boff + n * 2048 + k * 1024); } while (0)
; #define PG8_MMA(ai, bj, At, Bt) do { __builtin_amdgcn_s_setprio(1); _Pragma("unroll") for (int m = 0; m < 4; ++m) _Pragma("unroll") for (int n = 0; n < 2; ++n) _Pragma("unroll") for (int k = 0; k < 2; ++k) \
;         acc[ai][bj][m][n] = __builtin_amdgcn_mfma_f32_16x16x32_bf16(Bt[n][k], At[m][k], acc[ai][bj][m][n], 0, 0, 0); __builtin_amdgcn_s_setprio(0); } while (0)
; #define PG8_WAIT_V(n) asm volatile("s_waitcnt vmcnt(" #n ")" ::: "memory")
; #define PG8_WAIT_L(n) asm volatile("s_waitcnt lgkmcnt(" #n ")" ::: "memory")
; template <class Epi, class Sched, bool ALIGN_EPI = false, bool SP2 = false>
; __device__ __forceinline__ void gemm_phase(PG8_LAS unsigned char* lds, const Gemm g, const Sched& S, const Epi& E) {
;     ...
;             const bool last = (t == nt - 2);
;             const char* a1 = cA + (size_t)(t + 1) * kstep;
;             const char* a2 = last ? nA : cA + (size_t)(t + 2) * kstep; const char* b2 = last ? nB : cB + (size_t)(t + 2) * kstep;
;             const char* a3 = a2 + kstep; const char* b3 = b2 + kstep;
;             if (last && has_next) S.a_ready(nxt);
;             if constexpr (SP2) {
;             PG8_LDB(B0, 0, 0); PG8_LDB(B1, 0, 1); PG8_SCHED; PG8_LDA(At, 0, 0); PG8_STAGE(PG8_SA(1, 1), a1 + hstepA, voffA);
;             PG8_WAIT_V(8); PG8_WAIT_L(0); PG8_BAR; PG8_MMA(0, 0, At, B0); PG8_MMA(0, 1, At, B1); PG8_BAR; PG8_SCHED;
;             PG8_LDA(At, 0, 1); PG8_STAGE(PG8_SB(0, 0), b2, voffB); PG8_STAGE(PG8_SB(0, 1), b2 + hstep, voffB); PG8_STAGE(PG8_SA(0, 0), a2, voffA);
;             PG8_WAIT_V(8); PG8_WAIT_L(0); PG8_BAR; PG8_MMA(1, 0, At, B0); PG8_MMA(1, 1, At, B1); PG8_BAR; PG8_SCHED;
.LBB0_523:
	ds_read_b128 v[154:157], v149
	ds_read_b128 v[158:161], v149 offset:1024
	ds_read_b128 v[162:165], v149 offset:2048
	ds_read_b128 v[166:169], v149 offset:3072
	ds_read_b128 v[170:173], v150
	ds_read_b128 v[174:177], v150 offset:1024
	ds_read_b128 v[178:181], v150 offset:2048
	ds_read_b128 v[182:185], v150 offset:3072
	s_add_i32 s61, s30, 2
	s_add_u32 s62, s4, 0xfffe0080
	s_addc_u32 s31, s5, -1
	s_cmp_eq_u32 s52, s30
	s_cselect_b32 s30, s34, s62
	s_cselect_b32 s31, s15, s31
	s_cselect_b32 s63, s25, s60
	s_cselect_b32 s62, s24, s59
	s_add_i32 m0, s41, 0xc000
	ds_read_b128 v[190:193], v151
	ds_read_b128 v[194:197], v151 offset:1024
	ds_read_b128 v[198:201], v151 offset:2048
	ds_read_b128 v[202:205], v151 offset:3072
	ds_read_b128 v[206:209], v151 offset:4096
	ds_read_b128 v[210:213], v151 offset:5120
	ds_read_b128 v[214:217], v151 offset:6144
	global_load_lds_dwordx4 v138, s[4:5]
	s_add_i32 m0, s41, 0xe000
	ds_read_b128 v[218:221], v151 offset:7168
	global_load_lds_dwordx4 v140, s[4:5]
	s_waitcnt vmcnt(8) lgkmcnt(0)
	s_setprio 1
	s_barrier
	v_mfma_f32_16x16x32_bf16 v[124:127], v[154:157], v[190:193], v[124:127]
	v_mfma_f32_16x16x32_bf16 v[120:123], v[162:165], v[190:193], v[120:123]
	v_mfma_f32_16x16x32_bf16 v[108:111], v[154:157], v[198:201], v[108:111]
	v_mfma_f32_16x16x32_bf16 v[104:107], v[162:165], v[198:201], v[104:107]
	v_mfma_f32_16x16x32_bf16 v[92:95], v[154:157], v[206:209], v[92:95]
	v_mfma_f32_16x16x32_bf16 v[88:91], v[162:165], v[206:209], v[88:91]
	v_mfma_f32_16x16x32_bf16 v[76:79], v[154:157], v[214:217], v[76:79]
	v_mfma_f32_16x16x32_bf16 v[72:75], v[162:165], v[214:217], v[72:75]
	v_mfma_f32_16x16x32_bf16 v[124:127], v[158:161], v[194:197], v[124:127]
	v_mfma_f32_16x16x32_bf16 v[120:123], v[166:169], v[194:197], v[120:123]
	v_mfma_f32_16x16x32_bf16 v[108:111], v[158:161], v[202:205], v[108:111]
	v_mfma_f32_16x16x32_bf16 v[104:107], v[166:169], v[202:205], v[104:107]
	v_mfma_f32_16x16x32_bf16 v[92:95], v[158:161], v[210:213], v[92:95]
	v_mfma_f32_16x16x32_bf16 v[88:91], v[166:169], v[210:213], v[88:91]
	v_mfma_f32_16x16x32_bf16 v[76:79], v[158:161], v[218:221], v[76:79]
	v_mfma_f32_16x16x32_bf16 v[72:75], v[166:169], v[218:221], v[72:75]
	v_mfma_f32_16x16x32_bf16 v[116:119], v[170:173], v[190:193], v[116:119]
	v_mfma_f32_16x16x32_bf16 v[112:115], v[178:181], v[190:193], v[112:115]
	v_mfma_f32_16x16x32_bf16 v[100:103], v[170:173], v[198:201], v[100:103]
	v_mfma_f32_16x16x32_bf16 v[96:99], v[178:181], v[198:201], v[96:99]
	v_mfma_f32_16x16x32_bf16 v[84:87], v[170:173], v[206:209], v[84:87]
	v_mfma_f32_16x16x32_bf16 v[80:83], v[178:181], v[206:209], v[80:83]
	v_mfma_f32_16x16x32_bf16 v[68:71], v[170:173], v[214:217], v[68:71]
	v_mfma_f32_16x16x32_bf16 v[64:67], v[178:181], v[214:217], v[64:67]
	v_mfma_f32_16x16x32_bf16 v[116:119], v[174:177], v[194:197], v[116:119]
	v_mfma_f32_16x16x32_bf16 v[112:115], v[182:185], v[194:197], v[112:115]
	v_mfma_f32_16x16x32_bf16 v[100:103], v[174:177], v[202:205], v[100:103]
	v_mfma_f32_16x16x32_bf16 v[96:99], v[182:185], v[202:205], v[96:99]
	v_mfma_f32_16x16x32_bf16 v[84:87], v[174:177], v[210:213], v[84:87]
	v_mfma_f32_16x16x32_bf16 v[80:83], v[182:185], v[210:213], v[80:83]
	v_mfma_f32_16x16x32_bf16 v[68:71], v[174:177], v[218:221], v[68:71]
	v_mfma_f32_16x16x32_bf16 v[64:67], v[182:185], v[218:221], v[64:67]
	s_setprio 0
	s_barrier
	s_add_i32 s64, s54, s40
	s_mov_b32 m0, s64
	ds_read_b128 v[190:193], v151 offset:16384
	ds_read_b128 v[194:197], v151 offset:17408
	ds_read_b128 v[198:201], v151 offset:18432
	ds_read_b128 v[202:205], v151 offset:19456
	global_load_lds_dwordx4 v134, s[62:63]
	s_add_i32 m0, s64, 0x2000
	s_mov_b64 s[100:101], s[62:63]
	s_add_i32 s64, s55, s40
	global_load_lds_dwordx4 v132, s[62:63]
	s_add_u32 s62, s62, s10
	s_addc_u32 s63, s63, s11
	s_mov_b32 m0, s64
	ds_read_b128 v[218:221], v151 offset:23552
	global_load_lds_dwordx4 v134, s[62:63]
	s_add_i32 m0, s64, 0x2000
	ds_read_b128 v[214:217], v151 offset:22528
	global_load_lds_dwordx4 v132, s[62:63]
	s_mov_b32 m0, s41
	ds_read_b128 v[210:213], v151 offset:21504
	global_load_lds_dwordx4 v130, s[30:31]
	s_mov_b32 m0, s42
	ds_read_b128 v[206:209], v151 offset:20480
	global_load_lds_dwordx4 v128, s[30:31]
	s_waitcnt vmcnt(8) lgkmcnt(0)
	s_setprio 1
	s_barrier
	v_mfma_f32_16x16x32_bf16 v[60:63], v[154:157], v[190:193], v[60:63]
	v_mfma_f32_16x16x32_bf16 v[56:59], v[162:165], v[190:193], v[56:59]
	v_mfma_f32_16x16x32_bf16 v[44:47], v[154:157], v[198:201], v[44:47]
	v_mfma_f32_16x16x32_bf16 v[40:43], v[162:165], v[198:201], v[40:43]
	v_mfma_f32_16x16x32_bf16 v[28:31], v[154:157], v[206:209], v[28:31]
	v_mfma_f32_16x16x32_bf16 v[24:27], v[162:165], v[206:209], v[24:27]
	v_mfma_f32_16x16x32_bf16 v[12:15], v[154:157], v[214:217], v[12:15]
	v_mfma_f32_16x16x32_bf16 v[8:11], v[162:165], v[214:217], v[8:11]
	v_mfma_f32_16x16x32_bf16 v[60:63], v[158:161], v[194:197], v[60:63]
	v_mfma_f32_16x16x32_bf16 v[56:59], v[166:169], v[194:197], v[56:59]
	v_mfma_f32_16x16x32_bf16 v[44:47], v[158:161], v[202:205], v[44:47]
	v_mfma_f32_16x16x32_bf16 v[40:43], v[166:169], v[202:205], v[40:43]
	v_mfma_f32_16x16x32_bf16 v[28:31], v[158:161], v[210:213], v[28:31]
	v_mfma_f32_16x16x32_bf16 v[24:27], v[166:169], v[210:213], v[24:27]
	v_mfma_f32_16x16x32_bf16 v[12:15], v[158:161], v[218:221], v[12:15]
	v_mfma_f32_16x16x32_bf16 v[8:11], v[166:169], v[218:221], v[8:11]
	v_mfma_f32_16x16x32_bf16 v[52:55], v[170:173], v[190:193], v[52:55]
	v_mfma_f32_16x16x32_bf16 v[48:51], v[178:181], v[190:193], v[48:51]
	v_mfma_f32_16x16x32_bf16 v[36:39], v[170:173], v[198:201], v[36:39]
	v_mfma_f32_16x16x32_bf16 v[32:35], v[178:181], v[198:201], v[32:35]
	v_mfma_f32_16x16x32_bf16 v[20:23], v[170:173], v[206:209], v[20:23]
	v_mfma_f32_16x16x32_bf16 v[16:19], v[178:181], v[206:209], v[16:19]
	v_mfma_f32_16x16x32_bf16 v[4:7], v[170:173], v[214:217], v[4:7]
	v_mfma_f32_16x16x32_bf16 v[0:3], v[178:181], v[214:217], v[0:3]
	v_mfma_f32_16x16x32_bf16 v[52:55], v[174:177], v[194:197], v[52:55]
	v_mfma_f32_16x16x32_bf16 v[48:51], v[182:185], v[194:197], v[48:51]
	v_mfma_f32_16x16x32_bf16 v[36:39], v[174:177], v[202:205], v[36:39]
	v_mfma_f32_16x16x32_bf16 v[32:35], v[182:185], v[202:205], v[32:35]
	v_mfma_f32_16x16x32_bf16 v[20:23], v[174:177], v[210:213], v[20:23]
	v_mfma_f32_16x16x32_bf16 v[16:19], v[182:185], v[210:213], v[16:19]
	v_mfma_f32_16x16x32_bf16 v[4:7], v[174:177], v[218:221], v[4:7]
	v_mfma_f32_16x16x32_bf16 v[0:3], v[182:185], v[218:221], v[0:3]
	s_setprio 0
	s_barrier
; #define PG8_STAGE(bufoff, gbase, voff) do { _Pragma("unroll") for (int _i = 0; _i < 2; ++_i) \
;         __builtin_amdgcn_global_load_lds((const unsigned*)((const char*)(gbase) + (voff)[_i]), (PG8_LAS unsigned*)(lds + (bufoff) + ldsw + _i * 8192), 16, 0, 0); } while (0)
; #define PG8_LDA(dst, b, h) do { _Pragma("unroll") for (int m = 0; m < 4; ++m) _Pragma("unroll") for (int k = 0; k < 2; ++k) dst[m][k] = *(const PG8_LAS bf16x8*)(lds + PG8_SA(b, h) + aoff + m * 2048 + k * 1024); } while (0)
; #define PG8_LDB(dst, b, h) do { _Pragma("unroll") for (int n = 0; n < 2; ++n) _Pragma("unroll") for (int k = 0; k < 2; ++k) dst[n][k] = *(const PG8_LAS bf16x8*)(lds + PG8_SB(b, h) + boff + n * 2048 + k * 1024); } while (0)
; #define PG8_MMA(ai, bj, At, Bt) do { __builtin_amdgcn_s_setprio(1); _Pragma("unroll") for (int m = 0; m < 4; ++m) _Pragma("unroll") for (int n = 0; n < 2; ++n) _Pragma("unroll") for (int k = 0; k < 2; ++k) \
;         acc[ai][bj][m][n] = __builtin_amdgcn_mfma_f32_16x16x32_bf16(Bt[n][k], At[m][k], acc[ai][bj][m][n], 0, 0, 0); __builtin_amdgcn_s_setprio(0); } while (0)
; #define PG8_WAIT_V(n) asm volatile("s_waitcnt vmcnt(" #n ")" ::: "memory")
; #define PG8_WAIT_L(n) asm volatile("s_waitcnt lgkmcnt(" #n ")" ::: "memory")
; #define PG8_BAR __builtin_amdgcn_s_barrier()
; #define PG8_SCHED __builtin_amdgcn_sched_barrier(0)
; template <class Epi, class Sched, bool ALIGN_EPI = false, bool SP2 = false>
; __device__ __forceinline__ void gemm_phase(PG8_LAS unsigned char* lds, const Gemm g, const Sched& S, const Epi& E) {
;     ...
;             PG8_LDB(B0, 1, 0); PG8_LDB(B1, 1, 1); PG8_SCHED; PG8_LDA(At, 1, 0); PG8_STAGE(PG8_SA(0, 1), a2 + hstepA, voffA);
;             PG8_WAIT_V(8); PG8_WAIT_L(0); PG8_BAR; PG8_MMA(0, 0, At, B0); PG8_MMA(0, 1, At, B1); PG8_BAR; PG8_SCHED;
;             PG8_LDA(At, 1, 1); PG8_STAGE(PG8_SB(1, 0), b3, voffB); PG8_STAGE(PG8_SB(1, 1), b3 + hstep, voffB); PG8_STAGE(PG8_SA(1, 0), a3, voffA);
;             PG8_WAIT_V(8); PG8_WAIT_L(0); PG8_BAR; PG8_MMA(1, 0, At, B0); PG8_MMA(1, 1, At, B1); PG8_BAR; PG8_SCHED;
	s_add_i32 s62, 0, 0x18000
	s_add_i32 s63, 0, 0x1c000
	v_add_u32_e32 v166, s62, v147
	v_add_u32_e32 v182, s63, v147
	ds_read_b128 v[154:157], v166
	ds_read_b128 v[158:161], v166 offset:1024
	ds_read_b128 v[162:165], v166 offset:2048
	ds_read_b128 v[166:169], v166 offset:3072
	ds_read_b128 v[170:173], v182
	ds_read_b128 v[174:177], v182 offset:1024
	ds_read_b128 v[178:181], v182 offset:2048
	ds_read_b128 v[182:185], v182 offset:3072
	s_mov_b64 vcc, s[30:31]
	s_add_u32 s30, s30, 0x20000
	s_addc_u32 s31, s31, 0
	s_mov_b32 m0, s43
	ds_read_b128 v[190:193], v151 offset:32768
	ds_read_b128 v[194:197], v151 offset:33792
	ds_read_b128 v[198:201], v151 offset:34816
	ds_read_b128 v[202:205], v151 offset:35840
	ds_read_b128 v[206:209], v151 offset:36864
	ds_read_b128 v[210:213], v151 offset:37888
	ds_read_b128 v[214:217], v151 offset:38912
	global_load_lds_dwordx4 v130, s[30:31]
	s_mov_b32 m0, s44
	ds_read_b128 v[218:221], v151 offset:39936
	global_load_lds_dwordx4 v128, s[30:31]
	s_waitcnt vmcnt(8) lgkmcnt(0)
	s_setprio 1
	s_barrier
	v_mfma_f32_16x16x32_bf16 v[124:127], v[154:157], v[190:193], v[124:127]
	v_mfma_f32_16x16x32_bf16 v[120:123], v[162:165], v[190:193], v[120:123]
	v_mfma_f32_16x16x32_bf16 v[108:111], v[154:157], v[198:201], v[108:111]
	v_mfma_f32_16x16x32_bf16 v[104:107], v[162:165], v[198:201], v[104:107]
	v_mfma_f32_16x16x32_bf16 v[92:95], v[154:157], v[206:209], v[92:95]
	v_mfma_f32_16x16x32_bf16 v[88:91], v[162:165], v[206:209], v[88:91]
	v_mfma_f32_16x16x32_bf16 v[76:79], v[154:157], v[214:217], v[76:79]
	v_mfma_f32_16x16x32_bf16 v[72:75], v[162:165], v[214:217], v[72:75]
	v_mfma_f32_16x16x32_bf16 v[124:127], v[158:161], v[194:197], v[124:127]
	v_mfma_f32_16x16x32_bf16 v[120:123], v[166:169], v[194:197], v[120:123]
	v_mfma_f32_16x16x32_bf16 v[108:111], v[158:161], v[202:205], v[108:111]
	v_mfma_f32_16x16x32_bf16 v[104:107], v[166:169], v[202:205], v[104:107]
	v_mfma_f32_16x16x32_bf16 v[92:95], v[158:161], v[210:213], v[92:95]
	v_mfma_f32_16x16x32_bf16 v[88:91], v[166:169], v[210:213], v[88:91]
	v_mfma_f32_16x16x32_bf16 v[76:79], v[158:161], v[218:221], v[76:79]
	v_mfma_f32_16x16x32_bf16 v[72:75], v[166:169], v[218:221], v[72:75]
	v_mfma_f32_16x16x32_bf16 v[116:119], v[170:173], v[190:193], v[116:119]
	v_mfma_f32_16x16x32_bf16 v[112:115], v[178:181], v[190:193], v[112:115]
	v_mfma_f32_16x16x32_bf16 v[100:103], v[170:173], v[198:201], v[100:103]
	v_mfma_f32_16x16x32_bf16 v[96:99], v[178:181], v[198:201], v[96:99]
	v_mfma_f32_16x16x32_bf16 v[84:87], v[170:173], v[206:209], v[84:87]
	v_mfma_f32_16x16x32_bf16 v[80:83], v[178:181], v[206:209], v[80:83]
	v_mfma_f32_16x16x32_bf16 v[68:71], v[170:173], v[214:217], v[68:71]
	v_mfma_f32_16x16x32_bf16 v[64:67], v[178:181], v[214:217], v[64:67]
	v_mfma_f32_16x16x32_bf16 v[116:119], v[174:177], v[194:197], v[116:119]
	v_mfma_f32_16x16x32_bf16 v[112:115], v[182:185], v[194:197], v[112:115]
	v_mfma_f32_16x16x32_bf16 v[100:103], v[174:177], v[202:205], v[100:103]
	v_mfma_f32_16x16x32_bf16 v[96:99], v[182:185], v[202:205], v[96:99]
	v_mfma_f32_16x16x32_bf16 v[84:87], v[174:177], v[210:213], v[84:87]
	v_mfma_f32_16x16x32_bf16 v[80:83], v[182:185], v[210:213], v[80:83]
	v_mfma_f32_16x16x32_bf16 v[68:71], v[174:177], v[218:221], v[68:71]
	v_mfma_f32_16x16x32_bf16 v[64:67], v[182:185], v[218:221], v[64:67]
	s_setprio 0
	s_barrier
	s_add_i32 s30, s62, s40
	s_add_i32 m0, s30, 0xffffff80
	ds_read_b128 v[190:193], v151 offset:49152
	ds_read_b128 v[194:197], v151 offset:50176
	ds_read_b128 v[198:201], v151 offset:51200
	ds_read_b128 v[202:205], v151 offset:52224
	global_load_lds_dwordx4 v134, s[100:101] offset:128
	s_add_i32 m0, s30, 0x1f80
	s_add_i32 s30, s63, s40
	global_load_lds_dwordx4 v132, s[100:101] offset:128
	s_add_u32 s100, s100, s10
	s_addc_u32 s101, s101, s11
	s_add_i32 m0, s30, 0xffffff80
	ds_read_b128 v[218:221], v151 offset:56320
	global_load_lds_dwordx4 v134, s[100:101] offset:128
	s_add_i32 m0, s30, 0x1f80
	ds_read_b128 v[214:217], v151 offset:55296
	global_load_lds_dwordx4 v132, s[100:101] offset:128
	s_add_i32 m0, s48, 0xffffff80
	ds_read_b128 v[210:213], v151 offset:54272
	global_load_lds_dwordx4 v130, vcc offset:128
	s_add_i32 m0, s49, 0xffffff80
	ds_read_b128 v[206:209], v151 offset:53248
	global_load_lds_dwordx4 v128, vcc offset:128
	s_waitcnt vmcnt(8) lgkmcnt(0)
	s_setprio 1
	s_barrier
	v_mfma_f32_16x16x32_bf16 v[60:63], v[154:157], v[190:193], v[60:63]
	v_mfma_f32_16x16x32_bf16 v[56:59], v[162:165], v[190:193], v[56:59]
	v_mfma_f32_16x16x32_bf16 v[44:47], v[154:157], v[198:201], v[44:47]
	v_mfma_f32_16x16x32_bf16 v[40:43], v[162:165], v[198:201], v[40:43]
	v_mfma_f32_16x16x32_bf16 v[28:31], v[154:157], v[206:209], v[28:31]
	v_mfma_f32_16x16x32_bf16 v[24:27], v[162:165], v[206:209], v[24:27]
	v_mfma_f32_16x16x32_bf16 v[12:15], v[154:157], v[214:217], v[12:15]
	v_mfma_f32_16x16x32_bf16 v[8:11], v[162:165], v[214:217], v[8:11]
	v_mfma_f32_16x16x32_bf16 v[60:63], v[158:161], v[194:197], v[60:63]
	v_mfma_f32_16x16x32_bf16 v[56:59], v[166:169], v[194:197], v[56:59]
	v_mfma_f32_16x16x32_bf16 v[44:47], v[158:161], v[202:205], v[44:47]
	v_mfma_f32_16x16x32_bf16 v[40:43], v[166:169], v[202:205], v[40:43]
	v_mfma_f32_16x16x32_bf16 v[28:31], v[158:161], v[210:213], v[28:31]
	v_mfma_f32_16x16x32_bf16 v[24:27], v[166:169], v[210:213], v[24:27]
	v_mfma_f32_16x16x32_bf16 v[12:15], v[158:161], v[218:221], v[12:15]
	v_mfma_f32_16x16x32_bf16 v[8:11], v[166:169], v[218:221], v[8:11]
	v_mfma_f32_16x16x32_bf16 v[52:55], v[170:173], v[190:193], v[52:55]
	v_mfma_f32_16x16x32_bf16 v[48:51], v[178:181], v[190:193], v[48:51]
	v_mfma_f32_16x16x32_bf16 v[36:39], v[170:173], v[198:201], v[36:39]
	v_mfma_f32_16x16x32_bf16 v[32:35], v[178:181], v[198:201], v[32:35]
	v_mfma_f32_16x16x32_bf16 v[20:23], v[170:173], v[206:209], v[20:23]
	v_mfma_f32_16x16x32_bf16 v[16:19], v[178:181], v[206:209], v[16:19]
	v_mfma_f32_16x16x32_bf16 v[4:7], v[170:173], v[214:217], v[4:7]
	v_mfma_f32_16x16x32_bf16 v[0:3], v[178:181], v[214:217], v[0:3]
	v_mfma_f32_16x16x32_bf16 v[52:55], v[174:177], v[194:197], v[52:55]
	v_mfma_f32_16x16x32_bf16 v[48:51], v[182:185], v[194:197], v[48:51]
	v_mfma_f32_16x16x32_bf16 v[36:39], v[174:177], v[202:205], v[36:39]
	v_mfma_f32_16x16x32_bf16 v[32:35], v[182:185], v[202:205], v[32:35]
	v_mfma_f32_16x16x32_bf16 v[20:23], v[174:177], v[210:213], v[20:23]
	v_mfma_f32_16x16x32_bf16 v[16:19], v[182:185], v[210:213], v[16:19]
	v_mfma_f32_16x16x32_bf16 v[4:7], v[174:177], v[218:221], v[4:7]
	v_mfma_f32_16x16x32_bf16 v[0:3], v[182:185], v[218:221], v[0:3]
	s_setprio 0
	s_barrier
	s_add_u32 s4, s4, 0x100
	s_addc_u32 s5, s5, 0
	s_add_u32 s59, s59, 0x100
	s_addc_u32 s60, s60, 0
	s_cmp_ge_i32 s61, s51
	s_mov_b32 s30, s61
	s_cbranch_scc0 .LBB0_523

; #define PG8_STAGE(bufoff, gbase, voff) do { _Pragma("unroll") for (int _i = 0; _i < 2; ++_i) \
;         __builtin_amdgcn_global_load_lds((const unsigned*)((const char*)(gbase) + (voff)[_i]), (PG8_LAS unsigned*)(lds + (bufoff) + ldsw + _i * 8192), 16, 0, 0); } while (0)
; #define PG8_LDA(dst, b, h) do { _Pragma("unroll") for (int m = 0; m < 4; ++m) _Pragma("unroll") for (int k = 0; k < 2; ++k) dst[m][k] = *(const PG8_LAS bf16x8*)(lds + PG8_SA(b, h) + aoff + m * 2048 + k * 1024); } while (0)
; #define PG8_LDB(dst, b, h) do { _Pragma("unroll") for (int n = 0; n < 2; ++n) _Pragma("unroll") for (int k = 0; k < 2; ++k) dst[n][k] = *(const PG8_LAS bf16x8*)(lds + PG8_SB(b, h) + boff + n * 2048 + k * 1024); } while (0)
; #define PG8_MMA(ai, bj, At, Bt) do { __builtin_amdgcn_s_setprio(1); _Pragma("unroll") for (int m = 0; m < 4; ++m) _Pragma("unroll") for (int n = 0; n < 2; ++n) _Pragma("unroll") for (int k = 0; k < 2; ++k) \
;         acc[ai][bj][m][n] = __builtin_amdgcn_mfma_f32_16x16x32_bf16(Bt[n][k], At[m][k], acc[ai][bj][m][n], 0, 0, 0); __builtin_amdgcn_s_setprio(0); } while (0)
; #define PG8_WAIT_V(n) asm volatile("s_waitcnt vmcnt(" #n ")" ::: "memory")
; #define PG8_WAIT_L(n) asm volatile("s_waitcnt lgkmcnt(" #n ")" ::: "memory")
; template <class Epi, class Sched, bool ALIGN_EPI = false, bool SP2 = false>
; __device__ __forceinline__ void gemm_phase(PG8_LAS unsigned char* lds, const Gemm g, const Sched& S, const Epi& E) {
;     ...
;             const bool last = (t == nt - 2);
;             const char* a1 = cA + (size_t)(t + 1) * kstep;
;             const char* a2 = last ? nA : cA + (size_t)(t + 2) * kstep; const char* b2 = last ? nB : cB + (size_t)(t + 2) * kstep;
;             const char* a3 = a2 + kstep; const char* b3 = b2 + kstep;
;             if (last && has_next) S.a_ready(nxt);
;             if constexpr (SP2) {
;             PG8_LDB(B0, 0, 0); PG8_LDB(B1, 0, 1); PG8_SCHED; PG8_LDA(At, 0, 0); PG8_STAGE(PG8_SA(1, 1), a1 + hstepA, voffA);
;             PG8_WAIT_V(8); PG8_WAIT_L(0); PG8_BAR; PG8_MMA(0, 0, At, B0); PG8_MMA(0, 1, At, B1); PG8_BAR; PG8_SCHED;
;             PG8_LDA(At, 0, 1); PG8_STAGE(PG8_SB(0, 0), b2, voffB); PG8_STAGE(PG8_SB(0, 1), b2 + hstep, voffB); PG8_STAGE(PG8_SA(0, 0), a2, voffA);
;             PG8_WAIT_V(8); PG8_WAIT_L(0); PG8_BAR; PG8_MMA(1, 0, At, B0); PG8_MMA(1, 1, At, B1); PG8_BAR; PG8_SCHED;
.LBB0_601:
	ds_read_b128 v[150:153], v147
	ds_read_b128 v[154:157], v147 offset:1024
	ds_read_b128 v[158:161], v147 offset:2048
	ds_read_b128 v[162:165], v147 offset:3072
	ds_read_b128 v[166:169], v148
	ds_read_b128 v[170:173], v148 offset:1024
	ds_read_b128 v[174:177], v148 offset:2048
	ds_read_b128 v[178:181], v148 offset:3072
	s_add_i32 s60, s30, 2
	s_add_u32 s61, s10, 0xfffc0080
	s_addc_u32 s31, s11, -1
	s_cmp_eq_u32 s51, s30
	s_cselect_b32 s30, s59, s61
	s_cselect_b32 s31, s23, s31
	s_cselect_b32 s63, s25, s35
	s_cselect_b32 s62, s24, s34
	s_add_i32 m0, s29, 0xc000
	ds_read_b128 v[182:185], v149
	ds_read_b128 v[190:193], v149 offset:1024
	ds_read_b128 v[194:197], v149 offset:2048
	ds_read_b128 v[198:201], v149 offset:3072
	ds_read_b128 v[202:205], v149 offset:4096
	ds_read_b128 v[206:209], v149 offset:5120
	ds_read_b128 v[210:213], v149 offset:6144
	global_load_lds_dwordx4 v136, s[10:11]
	s_add_i32 m0, s29, 0xe000
	ds_read_b128 v[214:217], v149 offset:7168
	global_load_lds_dwordx4 v138, s[10:11]
	s_waitcnt vmcnt(8) lgkmcnt(0)
	s_setprio 1
	s_barrier
	v_mfma_f32_16x16x32_bf16 v[120:123], v[150:153], v[182:185], v[120:123]
	v_mfma_f32_16x16x32_bf16 v[112:115], v[158:161], v[182:185], v[112:115]
	v_mfma_f32_16x16x32_bf16 v[104:107], v[150:153], v[194:197], v[104:107]
	v_mfma_f32_16x16x32_bf16 v[96:99], v[158:161], v[194:197], v[96:99]
	v_mfma_f32_16x16x32_bf16 v[88:91], v[150:153], v[202:205], v[88:91]
	v_mfma_f32_16x16x32_bf16 v[80:83], v[158:161], v[202:205], v[80:83]
	v_mfma_f32_16x16x32_bf16 v[72:75], v[150:153], v[210:213], v[72:75]
	v_mfma_f32_16x16x32_bf16 v[64:67], v[158:161], v[210:213], v[64:67]
	v_mfma_f32_16x16x32_bf16 v[120:123], v[154:157], v[190:193], v[120:123]
	v_mfma_f32_16x16x32_bf16 v[112:115], v[162:165], v[190:193], v[112:115]
	v_mfma_f32_16x16x32_bf16 v[104:107], v[154:157], v[198:201], v[104:107]
	v_mfma_f32_16x16x32_bf16 v[96:99], v[162:165], v[198:201], v[96:99]
	v_mfma_f32_16x16x32_bf16 v[88:91], v[154:157], v[206:209], v[88:91]
	v_mfma_f32_16x16x32_bf16 v[80:83], v[162:165], v[206:209], v[80:83]
	v_mfma_f32_16x16x32_bf16 v[72:75], v[154:157], v[214:217], v[72:75]
	v_mfma_f32_16x16x32_bf16 v[64:67], v[162:165], v[214:217], v[64:67]
	v_mfma_f32_16x16x32_bf16 v[124:127], v[166:169], v[182:185], v[124:127]
	v_mfma_f32_16x16x32_bf16 v[116:119], v[174:177], v[182:185], v[116:119]
	v_mfma_f32_16x16x32_bf16 v[108:111], v[166:169], v[194:197], v[108:111]
	v_mfma_f32_16x16x32_bf16 v[100:103], v[174:177], v[194:197], v[100:103]
	v_mfma_f32_16x16x32_bf16 v[92:95], v[166:169], v[202:205], v[92:95]
	v_mfma_f32_16x16x32_bf16 v[84:87], v[174:177], v[202:205], v[84:87]
	v_mfma_f32_16x16x32_bf16 v[76:79], v[166:169], v[210:213], v[76:79]
	v_mfma_f32_16x16x32_bf16 v[68:71], v[174:177], v[210:213], v[68:71]
	v_mfma_f32_16x16x32_bf16 v[124:127], v[170:173], v[190:193], v[124:127]
	v_mfma_f32_16x16x32_bf16 v[116:119], v[178:181], v[190:193], v[116:119]
	v_mfma_f32_16x16x32_bf16 v[108:111], v[170:173], v[198:201], v[108:111]
	v_mfma_f32_16x16x32_bf16 v[100:103], v[178:181], v[198:201], v[100:103]
	v_mfma_f32_16x16x32_bf16 v[92:95], v[170:173], v[206:209], v[92:95]
	v_mfma_f32_16x16x32_bf16 v[84:87], v[178:181], v[206:209], v[84:87]
	v_mfma_f32_16x16x32_bf16 v[76:79], v[170:173], v[214:217], v[76:79]
	v_mfma_f32_16x16x32_bf16 v[68:71], v[178:181], v[214:217], v[68:71]
	s_setprio 0
	s_barrier
	s_add_i32 s61, s52, s38
	s_mov_b32 m0, s61
	ds_read_b128 v[182:185], v149 offset:16384
	ds_read_b128 v[190:193], v149 offset:17408
	ds_read_b128 v[194:197], v149 offset:18432
	ds_read_b128 v[198:201], v149 offset:19456
	global_load_lds_dwordx4 v134, s[62:63]
	s_add_i32 m0, s61, 0x2000
	s_mov_b64 s[100:101], s[62:63]
	s_add_i32 s61, s53, s38
	global_load_lds_dwordx4 v132, s[62:63]
	s_add_u32 s62, s62, s4
	s_addc_u32 s63, s63, s5
	s_mov_b32 m0, s61
	ds_read_b128 v[214:217], v149 offset:23552
	global_load_lds_dwordx4 v134, s[62:63]
	s_add_i32 m0, s61, 0x2000
	ds_read_b128 v[210:213], v149 offset:22528
	global_load_lds_dwordx4 v132, s[62:63]
	s_mov_b32 m0, s29
	ds_read_b128 v[206:209], v149 offset:21504
	global_load_lds_dwordx4 v128, s[30:31]
	s_mov_b32 m0, s41
	ds_read_b128 v[202:205], v149 offset:20480
	global_load_lds_dwordx4 v130, s[30:31]
	s_waitcnt vmcnt(8) lgkmcnt(0)
	s_setprio 1
	s_barrier
	v_mfma_f32_16x16x32_bf16 v[56:59], v[150:153], v[182:185], v[56:59]
	v_mfma_f32_16x16x32_bf16 v[48:51], v[158:161], v[182:185], v[48:51]
	v_mfma_f32_16x16x32_bf16 v[40:43], v[150:153], v[194:197], v[40:43]
	v_mfma_f32_16x16x32_bf16 v[32:35], v[158:161], v[194:197], v[32:35]
	v_mfma_f32_16x16x32_bf16 v[24:27], v[150:153], v[202:205], v[24:27]
	v_mfma_f32_16x16x32_bf16 v[16:19], v[158:161], v[202:205], v[16:19]
	v_mfma_f32_16x16x32_bf16 v[8:11], v[150:153], v[210:213], v[8:11]
	v_mfma_f32_16x16x32_bf16 v[0:3], v[158:161], v[210:213], v[0:3]
	v_mfma_f32_16x16x32_bf16 v[56:59], v[154:157], v[190:193], v[56:59]
	v_mfma_f32_16x16x32_bf16 v[48:51], v[162:165], v[190:193], v[48:51]
	v_mfma_f32_16x16x32_bf16 v[40:43], v[154:157], v[198:201], v[40:43]
	v_mfma_f32_16x16x32_bf16 v[32:35], v[162:165], v[198:201], v[32:35]
	v_mfma_f32_16x16x32_bf16 v[24:27], v[154:157], v[206:209], v[24:27]
	v_mfma_f32_16x16x32_bf16 v[16:19], v[162:165], v[206:209], v[16:19]
	v_mfma_f32_16x16x32_bf16 v[8:11], v[154:157], v[214:217], v[8:11]
	v_mfma_f32_16x16x32_bf16 v[0:3], v[162:165], v[214:217], v[0:3]
	v_mfma_f32_16x16x32_bf16 v[60:63], v[166:169], v[182:185], v[60:63]
	v_mfma_f32_16x16x32_bf16 v[52:55], v[174:177], v[182:185], v[52:55]
	v_mfma_f32_16x16x32_bf16 v[44:47], v[166:169], v[194:197], v[44:47]
	v_mfma_f32_16x16x32_bf16 v[36:39], v[174:177], v[194:197], v[36:39]
	v_mfma_f32_16x16x32_bf16 v[28:31], v[166:169], v[202:205], v[28:31]
	v_mfma_f32_16x16x32_bf16 v[20:23], v[174:177], v[202:205], v[20:23]
	v_mfma_f32_16x16x32_bf16 v[12:15], v[166:169], v[210:213], v[12:15]
	v_mfma_f32_16x16x32_bf16 v[4:7], v[174:177], v[210:213], v[4:7]
	v_mfma_f32_16x16x32_bf16 v[60:63], v[170:173], v[190:193], v[60:63]
	v_mfma_f32_16x16x32_bf16 v[52:55], v[178:181], v[190:193], v[52:55]
	v_mfma_f32_16x16x32_bf16 v[44:47], v[170:173], v[198:201], v[44:47]
	v_mfma_f32_16x16x32_bf16 v[36:39], v[178:181], v[198:201], v[36:39]
	v_mfma_f32_16x16x32_bf16 v[28:31], v[170:173], v[206:209], v[28:31]
	v_mfma_f32_16x16x32_bf16 v[20:23], v[178:181], v[206:209], v[20:23]
	v_mfma_f32_16x16x32_bf16 v[12:15], v[170:173], v[214:217], v[12:15]
	v_mfma_f32_16x16x32_bf16 v[4:7], v[178:181], v[214:217], v[4:7]
	s_setprio 0
	s_barrier
; #define PG8_STAGE(bufoff, gbase, voff) do { _Pragma("unroll") for (int _i = 0; _i < 2; ++_i) \
;         __builtin_amdgcn_global_load_lds((const unsigned*)((const char*)(gbase) + (voff)[_i]), (PG8_LAS unsigned*)(lds + (bufoff) + ldsw + _i * 8192), 16, 0, 0); } while (0)
; #define PG8_LDA(dst, b, h) do { _Pragma("unroll") for (int m = 0; m < 4; ++m) _Pragma("unroll") for (int k = 0; k < 2; ++k) dst[m][k] = *(const PG8_LAS bf16x8*)(lds + PG8_SA(b, h) + aoff + m * 2048 + k * 1024); } while (0)
; #define PG8_LDB(dst, b, h) do { _Pragma("unroll") for (int n = 0; n < 2; ++n) _Pragma("unroll") for (int k = 0; k < 2; ++k) dst[n][k] = *(const PG8_LAS bf16x8*)(lds + PG8_SB(b, h) + boff + n * 2048 + k * 1024); } while (0)
; #define PG8_MMA(ai, bj, At, Bt) do { __builtin_amdgcn_s_setprio(1); _Pragma("unroll") for (int m = 0; m < 4; ++m) _Pragma("unroll") for (int n = 0; n < 2; ++n) _Pragma("unroll") for (int k = 0; k < 2; ++k) \
;         acc[ai][bj][m][n] = __builtin_amdgcn_mfma_f32_16x16x32_bf16(Bt[n][k], At[m][k], acc[ai][bj][m][n], 0, 0, 0); __builtin_amdgcn_s_setprio(0); } while (0)
; #define PG8_WAIT_V(n) asm volatile("s_waitcnt vmcnt(" #n ")" ::: "memory")
; #define PG8_WAIT_L(n) asm volatile("s_waitcnt lgkmcnt(" #n ")" ::: "memory")
; #define PG8_BAR __builtin_amdgcn_s_barrier()
; #define PG8_SCHED __builtin_amdgcn_sched_barrier(0)
; template <class Epi, class Sched, bool ALIGN_EPI = false, bool SP2 = false>
; __device__ __forceinline__ void gemm_phase(PG8_LAS unsigned char* lds, const Gemm g, const Sched& S, const Epi& E) {
;     ...
;             PG8_LDB(B0, 1, 0); PG8_LDB(B1, 1, 1); PG8_SCHED; PG8_LDA(At, 1, 0); PG8_STAGE(PG8_SA(0, 1), a2 + hstepA, voffA);
;             PG8_WAIT_V(8); PG8_WAIT_L(0); PG8_BAR; PG8_MMA(0, 0, At, B0); PG8_MMA(0, 1, At, B1); PG8_BAR; PG8_SCHED;
;             PG8_LDA(At, 1, 1); PG8_STAGE(PG8_SB(1, 0), b3, voffB); PG8_STAGE(PG8_SB(1, 1), b3 + hstep, voffB); PG8_STAGE(PG8_SA(1, 0), a3, voffA);
;             PG8_WAIT_V(8); PG8_WAIT_L(0); PG8_BAR; PG8_MMA(1, 0, At, B0); PG8_MMA(1, 1, At, B1); PG8_BAR; PG8_SCHED;
	s_add_i32 s61, 0, 0x18000
	s_add_i32 s62, 0, 0x1c000
	v_add_u32_e32 v162, s61, v145
	v_add_u32_e32 v178, s62, v145
	ds_read_b128 v[150:153], v162
	ds_read_b128 v[154:157], v162 offset:1024
	ds_read_b128 v[158:161], v162 offset:2048
	ds_read_b128 v[162:165], v162 offset:3072
	ds_read_b128 v[166:169], v178
	ds_read_b128 v[170:173], v178 offset:1024
	ds_read_b128 v[174:177], v178 offset:2048
	ds_read_b128 v[178:181], v178 offset:3072
	s_mov_b64 vcc, s[30:31]
	s_add_u32 s30, s30, 0x40000
	s_addc_u32 s31, s31, 0
	s_mov_b32 m0, s42
	ds_read_b128 v[182:185], v149 offset:32768
	ds_read_b128 v[190:193], v149 offset:33792
	ds_read_b128 v[194:197], v149 offset:34816
	ds_read_b128 v[198:201], v149 offset:35840
	ds_read_b128 v[202:205], v149 offset:36864
	ds_read_b128 v[206:209], v149 offset:37888
	ds_read_b128 v[210:213], v149 offset:38912
	global_load_lds_dwordx4 v128, s[30:31]
	s_mov_b32 m0, s43
	ds_read_b128 v[214:217], v149 offset:39936
	global_load_lds_dwordx4 v130, s[30:31]
	s_waitcnt vmcnt(8) lgkmcnt(0)
	s_setprio 1
	s_barrier
	v_mfma_f32_16x16x32_bf16 v[120:123], v[150:153], v[182:185], v[120:123]
	v_mfma_f32_16x16x32_bf16 v[112:115], v[158:161], v[182:185], v[112:115]
	v_mfma_f32_16x16x32_bf16 v[104:107], v[150:153], v[194:197], v[104:107]
	v_mfma_f32_16x16x32_bf16 v[96:99], v[158:161], v[194:197], v[96:99]
	v_mfma_f32_16x16x32_bf16 v[88:91], v[150:153], v[202:205], v[88:91]
	v_mfma_f32_16x16x32_bf16 v[80:83], v[158:161], v[202:205], v[80:83]
	v_mfma_f32_16x16x32_bf16 v[72:75], v[150:153], v[210:213], v[72:75]
	v_mfma_f32_16x16x32_bf16 v[64:67], v[158:161], v[210:213], v[64:67]
	v_mfma_f32_16x16x32_bf16 v[120:123], v[154:157], v[190:193], v[120:123]
	v_mfma_f32_16x16x32_bf16 v[112:115], v[162:165], v[190:193], v[112:115]
	v_mfma_f32_16x16x32_bf16 v[104:107], v[154:157], v[198:201], v[104:107]
	v_mfma_f32_16x16x32_bf16 v[96:99], v[162:165], v[198:201], v[96:99]
	v_mfma_f32_16x16x32_bf16 v[88:91], v[154:157], v[206:209], v[88:91]
	v_mfma_f32_16x16x32_bf16 v[80:83], v[162:165], v[206:209], v[80:83]
	v_mfma_f32_16x16x32_bf16 v[72:75], v[154:157], v[214:217], v[72:75]
	v_mfma_f32_16x16x32_bf16 v[64:67], v[162:165], v[214:217], v[64:67]
	v_mfma_f32_16x16x32_bf16 v[124:127], v[166:169], v[182:185], v[124:127]
	v_mfma_f32_16x16x32_bf16 v[116:119], v[174:177], v[182:185], v[116:119]
	v_mfma_f32_16x16x32_bf16 v[108:111], v[166:169], v[194:197], v[108:111]
	v_mfma_f32_16x16x32_bf16 v[100:103], v[174:177], v[194:197], v[100:103]
	v_mfma_f32_16x16x32_bf16 v[92:95], v[166:169], v[202:205], v[92:95]
	v_mfma_f32_16x16x32_bf16 v[84:87], v[174:177], v[202:205], v[84:87]
	v_mfma_f32_16x16x32_bf16 v[76:79], v[166:169], v[210:213], v[76:79]
	v_mfma_f32_16x16x32_bf16 v[68:71], v[174:177], v[210:213], v[68:71]
	v_mfma_f32_16x16x32_bf16 v[124:127], v[170:173], v[190:193], v[124:127]
	v_mfma_f32_16x16x32_bf16 v[116:119], v[178:181], v[190:193], v[116:119]
	v_mfma_f32_16x16x32_bf16 v[108:111], v[170:173], v[198:201], v[108:111]
	v_mfma_f32_16x16x32_bf16 v[100:103], v[178:181], v[198:201], v[100:103]
	v_mfma_f32_16x16x32_bf16 v[92:95], v[170:173], v[206:209], v[92:95]
	v_mfma_f32_16x16x32_bf16 v[84:87], v[178:181], v[206:209], v[84:87]
	v_mfma_f32_16x16x32_bf16 v[76:79], v[170:173], v[214:217], v[76:79]
	v_mfma_f32_16x16x32_bf16 v[68:71], v[178:181], v[214:217], v[68:71]
	s_setprio 0
	s_barrier
	s_add_i32 s30, s61, s38
	s_add_i32 m0, s30, 0xffffff80
	ds_read_b128 v[182:185], v149 offset:49152
	ds_read_b128 v[190:193], v149 offset:50176
	ds_read_b128 v[194:197], v149 offset:51200
	ds_read_b128 v[198:201], v149 offset:52224
	global_load_lds_dwordx4 v134, s[100:101] offset:128
	s_add_i32 m0, s30, 0x1f80
	s_add_i32 s30, s62, s38
	global_load_lds_dwordx4 v132, s[100:101] offset:128
	s_add_u32 s100, s100, s4
	s_addc_u32 s101, s101, s5
	s_add_i32 m0, s30, 0xffffff80
	ds_read_b128 v[214:217], v149 offset:56320
	global_load_lds_dwordx4 v134, s[100:101] offset:128
	s_add_i32 m0, s30, 0x1f80
	ds_read_b128 v[210:213], v149 offset:55296
	global_load_lds_dwordx4 v132, s[100:101] offset:128
	s_add_i32 m0, s47, 0xffffff80
	ds_read_b128 v[206:209], v149 offset:54272
	global_load_lds_dwordx4 v128, vcc offset:128
	s_add_i32 m0, s48, 0xffffff80
	ds_read_b128 v[202:205], v149 offset:53248
	global_load_lds_dwordx4 v130, vcc offset:128
	s_waitcnt vmcnt(8) lgkmcnt(0)
	s_setprio 1
	s_barrier
	v_mfma_f32_16x16x32_bf16 v[56:59], v[150:153], v[182:185], v[56:59]
	v_mfma_f32_16x16x32_bf16 v[48:51], v[158:161], v[182:185], v[48:51]
	v_mfma_f32_16x16x32_bf16 v[40:43], v[150:153], v[194:197], v[40:43]
	v_mfma_f32_16x16x32_bf16 v[32:35], v[158:161], v[194:197], v[32:35]
	v_mfma_f32_16x16x32_bf16 v[24:27], v[150:153], v[202:205], v[24:27]
	v_mfma_f32_16x16x32_bf16 v[16:19], v[158:161], v[202:205], v[16:19]
	v_mfma_f32_16x16x32_bf16 v[8:11], v[150:153], v[210:213], v[8:11]
	v_mfma_f32_16x16x32_bf16 v[0:3], v[158:161], v[210:213], v[0:3]
	v_mfma_f32_16x16x32_bf16 v[56:59], v[154:157], v[190:193], v[56:59]
	v_mfma_f32_16x16x32_bf16 v[48:51], v[162:165], v[190:193], v[48:51]
	v_mfma_f32_16x16x32_bf16 v[40:43], v[154:157], v[198:201], v[40:43]
	v_mfma_f32_16x16x32_bf16 v[32:35], v[162:165], v[198:201], v[32:35]
	v_mfma_f32_16x16x32_bf16 v[24:27], v[154:157], v[206:209], v[24:27]
	v_mfma_f32_16x16x32_bf16 v[16:19], v[162:165], v[206:209], v[16:19]
	v_mfma_f32_16x16x32_bf16 v[8:11], v[154:157], v[214:217], v[8:11]
	v_mfma_f32_16x16x32_bf16 v[0:3], v[162:165], v[214:217], v[0:3]
	v_mfma_f32_16x16x32_bf16 v[60:63], v[166:169], v[182:185], v[60:63]
	v_mfma_f32_16x16x32_bf16 v[52:55], v[174:177], v[182:185], v[52:55]
	v_mfma_f32_16x16x32_bf16 v[44:47], v[166:169], v[194:197], v[44:47]
	v_mfma_f32_16x16x32_bf16 v[36:39], v[174:177], v[194:197], v[36:39]
	v_mfma_f32_16x16x32_bf16 v[28:31], v[166:169], v[202:205], v[28:31]
	v_mfma_f32_16x16x32_bf16 v[20:23], v[174:177], v[202:205], v[20:23]
	v_mfma_f32_16x16x32_bf16 v[12:15], v[166:169], v[210:213], v[12:15]
	v_mfma_f32_16x16x32_bf16 v[4:7], v[174:177], v[210:213], v[4:7]
	v_mfma_f32_16x16x32_bf16 v[60:63], v[170:173], v[190:193], v[60:63]
	v_mfma_f32_16x16x32_bf16 v[52:55], v[178:181], v[190:193], v[52:55]
	v_mfma_f32_16x16x32_bf16 v[44:47], v[170:173], v[198:201], v[44:47]
	v_mfma_f32_16x16x32_bf16 v[36:39], v[178:181], v[198:201], v[36:39]
	v_mfma_f32_16x16x32_bf16 v[28:31], v[170:173], v[206:209], v[28:31]
	v_mfma_f32_16x16x32_bf16 v[20:23], v[178:181], v[206:209], v[20:23]
	v_mfma_f32_16x16x32_bf16 v[12:15], v[170:173], v[214:217], v[12:15]
	v_mfma_f32_16x16x32_bf16 v[4:7], v[178:181], v[214:217], v[4:7]
	s_setprio 0
	s_barrier
	s_add_u32 s10, s10, 0x100
	s_addc_u32 s11, s11, 0
	s_add_u32 s34, s34, 0x100
	s_addc_u32 s35, s35, 0
	s_cmp_ge_i32 s60, s50
	s_mov_b32 s30, s60
	s_cbranch_scc0 .LBB0_601

; #define PG8_STAGE(bufoff, gbase, voff) do { _Pragma("unroll") for (int _i = 0; _i < 2; ++_i) \
;         __builtin_amdgcn_global_load_lds((const unsigned*)((const char*)(gbase) + (voff)[_i]), (PG8_LAS unsigned*)(lds + (bufoff) + ldsw + _i * 8192), 16, 0, 0); } while (0)
; #define PG8_LDA(dst, b, h) do { _Pragma("unroll") for (int m = 0; m < 4; ++m) _Pragma("unroll") for (int k = 0; k < 2; ++k) dst[m][k] = *(const PG8_LAS bf16x8*)(lds + PG8_SA(b, h) + aoff + m * 2048 + k * 1024); } while (0)
; #define PG8_LDB(dst, b, h) do { _Pragma("unroll") for (int n = 0; n < 2; ++n) _Pragma("unroll") for (int k = 0; k < 2; ++k) dst[n][k] = *(const PG8_LAS bf16x8*)(lds + PG8_SB(b, h) + boff + n * 2048 + k * 1024); } while (0)
; #define PG8_MMA(ai, bj, At, Bt) do { __builtin_amdgcn_s_setprio(1); _Pragma("unroll") for (int m = 0; m < 4; ++m) _Pragma("unroll") for (int n = 0; n < 2; ++n) _Pragma("unroll") for (int k = 0; k < 2; ++k) \
;         acc[ai][bj][m][n] = __builtin_amdgcn_mfma_f32_16x16x32_bf16(Bt[n][k], At[m][k], acc[ai][bj][m][n], 0, 0, 0); __builtin_amdgcn_s_setprio(0); } while (0)
; #define PG8_WAIT_V(n) asm volatile("s_waitcnt vmcnt(" #n ")" ::: "memory")
; #define PG8_WAIT_L(n) asm volatile("s_waitcnt lgkmcnt(" #n ")" ::: "memory")
; template <class Epi, class Sched, bool ALIGN_EPI = false, bool SP2 = false>
; __device__ __forceinline__ void gemm_phase(PG8_LAS unsigned char* lds, const Gemm g, const Sched& S, const Epi& E) {
;     ...
;             const bool last = (t == nt - 2);
;             const char* a1 = cA + (size_t)(t + 1) * kstep;
;             const char* a2 = last ? nA : cA + (size_t)(t + 2) * kstep; const char* b2 = last ? nB : cB + (size_t)(t + 2) * kstep;
;             const char* a3 = a2 + kstep; const char* b3 = b2 + kstep;
;             if (last && has_next) S.a_ready(nxt);
;             if constexpr (SP2) {
;             PG8_LDB(B0, 0, 0); PG8_LDB(B1, 0, 1); PG8_SCHED; PG8_LDA(At, 0, 0); PG8_STAGE(PG8_SA(1, 1), a1 + hstepA, voffA);
;             PG8_WAIT_V(8); PG8_WAIT_L(0); PG8_BAR; PG8_MMA(0, 0, At, B0); PG8_MMA(0, 1, At, B1); PG8_BAR; PG8_SCHED;
;             PG8_LDA(At, 0, 1); PG8_STAGE(PG8_SB(0, 0), b2, voffB); PG8_STAGE(PG8_SB(0, 1), b2 + hstep, voffB); PG8_STAGE(PG8_SA(0, 0), a2, voffA);
;             PG8_WAIT_V(8); PG8_WAIT_L(0); PG8_BAR; PG8_MMA(1, 0, At, B0); PG8_MMA(1, 1, At, B1); PG8_BAR; PG8_SCHED;
.LBB0_681:
	ds_read_b128 v[128:131], v175
	ds_read_b128 v[132:135], v175 offset:1024
	ds_read_b128 v[136:139], v175 offset:2048
	ds_read_b128 v[140:143], v175 offset:3072
	ds_read_b128 v[162:165], v176
	ds_read_b128 v[166:169], v176 offset:1024
	ds_read_b128 v[180:183], v176 offset:2048
	ds_read_b128 v[184:187], v176 offset:3072
	s_add_i32 s71, s48, 2
	s_add_u32 s72, s8, 0xfffc0080
	s_addc_u32 s49, s9, -1
	s_cmp_eq_u32 s64, s48
	s_cselect_b32 s48, s70, s72
	s_cselect_b32 s49, s39, s49
	s_cselect_b32 s73, s41, s51
	s_cselect_b32 s72, s40, s50
	s_add_i32 m0, s45, 0xc000
	ds_read_b128 v[190:193], v177
	ds_read_b128 v[194:197], v177 offset:1024
	ds_read_b128 v[198:201], v177 offset:2048
	ds_read_b128 v[202:205], v177 offset:3072
	ds_read_b128 v[206:209], v177 offset:4096
	ds_read_b128 v[210:213], v177 offset:5120
	ds_read_b128 v[214:217], v177 offset:6144
	global_load_lds_dwordx4 v154, s[8:9]
	s_add_i32 m0, s45, 0xe000
	ds_read_b128 v[218:221], v177 offset:7168
	global_load_lds_dwordx4 v156, s[8:9]
	s_waitcnt vmcnt(8) lgkmcnt(0)
	s_setprio 1
	s_barrier
	v_mfma_f32_16x16x32_bf16 v[124:127], v[128:131], v[190:193], v[124:127]
	v_mfma_f32_16x16x32_bf16 v[120:123], v[136:139], v[190:193], v[120:123]
	v_mfma_f32_16x16x32_bf16 v[108:111], v[128:131], v[198:201], v[108:111]
	v_mfma_f32_16x16x32_bf16 v[104:107], v[136:139], v[198:201], v[104:107]
	v_mfma_f32_16x16x32_bf16 v[92:95], v[128:131], v[206:209], v[92:95]
	v_mfma_f32_16x16x32_bf16 v[88:91], v[136:139], v[206:209], v[88:91]
	v_mfma_f32_16x16x32_bf16 v[76:79], v[128:131], v[214:217], v[76:79]
	v_mfma_f32_16x16x32_bf16 v[72:75], v[136:139], v[214:217], v[72:75]
	v_mfma_f32_16x16x32_bf16 v[124:127], v[132:135], v[194:197], v[124:127]
	v_mfma_f32_16x16x32_bf16 v[120:123], v[140:143], v[194:197], v[120:123]
	v_mfma_f32_16x16x32_bf16 v[108:111], v[132:135], v[202:205], v[108:111]
	v_mfma_f32_16x16x32_bf16 v[104:107], v[140:143], v[202:205], v[104:107]
	v_mfma_f32_16x16x32_bf16 v[92:95], v[132:135], v[210:213], v[92:95]
	v_mfma_f32_16x16x32_bf16 v[88:91], v[140:143], v[210:213], v[88:91]
	v_mfma_f32_16x16x32_bf16 v[76:79], v[132:135], v[218:221], v[76:79]
	v_mfma_f32_16x16x32_bf16 v[72:75], v[140:143], v[218:221], v[72:75]
	v_mfma_f32_16x16x32_bf16 v[116:119], v[162:165], v[190:193], v[116:119]
	v_mfma_f32_16x16x32_bf16 v[112:115], v[180:183], v[190:193], v[112:115]
	v_mfma_f32_16x16x32_bf16 v[100:103], v[162:165], v[198:201], v[100:103]
	v_mfma_f32_16x16x32_bf16 v[96:99], v[180:183], v[198:201], v[96:99]
	v_mfma_f32_16x16x32_bf16 v[84:87], v[162:165], v[206:209], v[84:87]
	v_mfma_f32_16x16x32_bf16 v[80:83], v[180:183], v[206:209], v[80:83]
	v_mfma_f32_16x16x32_bf16 v[68:71], v[162:165], v[214:217], v[68:71]
	v_mfma_f32_16x16x32_bf16 v[64:67], v[180:183], v[214:217], v[64:67]
	v_mfma_f32_16x16x32_bf16 v[116:119], v[166:169], v[194:197], v[116:119]
	v_mfma_f32_16x16x32_bf16 v[112:115], v[184:187], v[194:197], v[112:115]
	v_mfma_f32_16x16x32_bf16 v[100:103], v[166:169], v[202:205], v[100:103]
	v_mfma_f32_16x16x32_bf16 v[96:99], v[184:187], v[202:205], v[96:99]
	v_mfma_f32_16x16x32_bf16 v[84:87], v[166:169], v[210:213], v[84:87]
	v_mfma_f32_16x16x32_bf16 v[80:83], v[184:187], v[210:213], v[80:83]
	v_mfma_f32_16x16x32_bf16 v[68:71], v[166:169], v[218:221], v[68:71]
	v_mfma_f32_16x16x32_bf16 v[64:67], v[184:187], v[218:221], v[64:67]
	s_setprio 0
	s_barrier
	s_add_i32 s74, s65, s53
	s_mov_b32 m0, s74
	ds_read_b128 v[190:193], v177 offset:16384
	ds_read_b128 v[194:197], v177 offset:17408
	ds_read_b128 v[198:201], v177 offset:18432
	ds_read_b128 v[202:205], v177 offset:19456
	global_load_lds_dwordx4 v150, s[72:73]
	s_add_i32 m0, s74, 0x2000
	s_mov_b64 s[100:101], s[72:73]
	s_add_i32 s74, s66, s53
	global_load_lds_dwordx4 v148, s[72:73]
	s_add_u32 s72, s72, s10
	s_addc_u32 s73, s73, s11
	s_mov_b32 m0, s74
	ds_read_b128 v[218:221], v177 offset:23552
	global_load_lds_dwordx4 v150, s[72:73]
	s_add_i32 m0, s74, 0x2000
	ds_read_b128 v[214:217], v177 offset:22528
	global_load_lds_dwordx4 v148, s[72:73]
	s_mov_b32 m0, s45
	ds_read_b128 v[210:213], v177 offset:21504
	global_load_lds_dwordx4 v144, s[48:49]
	s_mov_b32 m0, s55
	ds_read_b128 v[206:209], v177 offset:20480
	global_load_lds_dwordx4 v146, s[48:49]
	s_waitcnt vmcnt(8) lgkmcnt(0)
	s_setprio 1
	s_barrier
	v_mfma_f32_16x16x32_bf16 v[60:63], v[128:131], v[190:193], v[60:63]
	v_mfma_f32_16x16x32_bf16 v[56:59], v[136:139], v[190:193], v[56:59]
	v_mfma_f32_16x16x32_bf16 v[44:47], v[128:131], v[198:201], v[44:47]
	v_mfma_f32_16x16x32_bf16 v[40:43], v[136:139], v[198:201], v[40:43]
	v_mfma_f32_16x16x32_bf16 v[28:31], v[128:131], v[206:209], v[28:31]
	v_mfma_f32_16x16x32_bf16 v[24:27], v[136:139], v[206:209], v[24:27]
	v_mfma_f32_16x16x32_bf16 v[12:15], v[128:131], v[214:217], v[12:15]
	v_mfma_f32_16x16x32_bf16 v[8:11], v[136:139], v[214:217], v[8:11]
	v_mfma_f32_16x16x32_bf16 v[60:63], v[132:135], v[194:197], v[60:63]
	v_mfma_f32_16x16x32_bf16 v[56:59], v[140:143], v[194:197], v[56:59]
	v_mfma_f32_16x16x32_bf16 v[44:47], v[132:135], v[202:205], v[44:47]
	v_mfma_f32_16x16x32_bf16 v[40:43], v[140:143], v[202:205], v[40:43]
	v_mfma_f32_16x16x32_bf16 v[28:31], v[132:135], v[210:213], v[28:31]
	v_mfma_f32_16x16x32_bf16 v[24:27], v[140:143], v[210:213], v[24:27]
	v_mfma_f32_16x16x32_bf16 v[12:15], v[132:135], v[218:221], v[12:15]
	v_mfma_f32_16x16x32_bf16 v[8:11], v[140:143], v[218:221], v[8:11]
	v_mfma_f32_16x16x32_bf16 v[52:55], v[162:165], v[190:193], v[52:55]
	v_mfma_f32_16x16x32_bf16 v[48:51], v[180:183], v[190:193], v[48:51]
	v_mfma_f32_16x16x32_bf16 v[36:39], v[162:165], v[198:201], v[36:39]
	v_mfma_f32_16x16x32_bf16 v[32:35], v[180:183], v[198:201], v[32:35]
	v_mfma_f32_16x16x32_bf16 v[20:23], v[162:165], v[206:209], v[20:23]
	v_mfma_f32_16x16x32_bf16 v[16:19], v[180:183], v[206:209], v[16:19]
	v_mfma_f32_16x16x32_bf16 v[4:7], v[162:165], v[214:217], v[4:7]
	v_mfma_f32_16x16x32_bf16 v[0:3], v[180:183], v[214:217], v[0:3]
	v_mfma_f32_16x16x32_bf16 v[52:55], v[166:169], v[194:197], v[52:55]
	v_mfma_f32_16x16x32_bf16 v[48:51], v[184:187], v[194:197], v[48:51]
	v_mfma_f32_16x16x32_bf16 v[36:39], v[166:169], v[202:205], v[36:39]
	v_mfma_f32_16x16x32_bf16 v[32:35], v[184:187], v[202:205], v[32:35]
	v_mfma_f32_16x16x32_bf16 v[20:23], v[166:169], v[210:213], v[20:23]
	v_mfma_f32_16x16x32_bf16 v[16:19], v[184:187], v[210:213], v[16:19]
	v_mfma_f32_16x16x32_bf16 v[4:7], v[166:169], v[218:221], v[4:7]
	v_mfma_f32_16x16x32_bf16 v[0:3], v[184:187], v[218:221], v[0:3]
	s_setprio 0
	s_barrier
; #define PG8_STAGE(bufoff, gbase, voff) do { _Pragma("unroll") for (int _i = 0; _i < 2; ++_i) \
;         __builtin_amdgcn_global_load_lds((const unsigned*)((const char*)(gbase) + (voff)[_i]), (PG8_LAS unsigned*)(lds + (bufoff) + ldsw + _i * 8192), 16, 0, 0); } while (0)
; #define PG8_LDA(dst, b, h) do { _Pragma("unroll") for (int m = 0; m < 4; ++m) _Pragma("unroll") for (int k = 0; k < 2; ++k) dst[m][k] = *(const PG8_LAS bf16x8*)(lds + PG8_SA(b, h) + aoff + m * 2048 + k * 1024); } while (0)
; #define PG8_LDB(dst, b, h) do { _Pragma("unroll") for (int n = 0; n < 2; ++n) _Pragma("unroll") for (int k = 0; k < 2; ++k) dst[n][k] = *(const PG8_LAS bf16x8*)(lds + PG8_SB(b, h) + boff + n * 2048 + k * 1024); } while (0)
; #define PG8_MMA(ai, bj, At, Bt) do { __builtin_amdgcn_s_setprio(1); _Pragma("unroll") for (int m = 0; m < 4; ++m) _Pragma("unroll") for (int n = 0; n < 2; ++n) _Pragma("unroll") for (int k = 0; k < 2; ++k) \
;         acc[ai][bj][m][n] = __builtin_amdgcn_mfma_f32_16x16x32_bf16(Bt[n][k], At[m][k], acc[ai][bj][m][n], 0, 0, 0); __builtin_amdgcn_s_setprio(0); } while (0)
; #define PG8_WAIT_V(n) asm volatile("s_waitcnt vmcnt(" #n ")" ::: "memory")
; #define PG8_WAIT_L(n) asm volatile("s_waitcnt lgkmcnt(" #n ")" ::: "memory")
; #define PG8_BAR __builtin_amdgcn_s_barrier()
; #define PG8_SCHED __builtin_amdgcn_sched_barrier(0)
; template <class Epi, class Sched, bool ALIGN_EPI = false, bool SP2 = false>
; __device__ __forceinline__ void gemm_phase(PG8_LAS unsigned char* lds, const Gemm g, const Sched& S, const Epi& E) {
;     ...
;             PG8_LDB(B0, 1, 0); PG8_LDB(B1, 1, 1); PG8_SCHED; PG8_LDA(At, 1, 0); PG8_STAGE(PG8_SA(0, 1), a2 + hstepA, voffA);
;             PG8_WAIT_V(8); PG8_WAIT_L(0); PG8_BAR; PG8_MMA(0, 0, At, B0); PG8_MMA(0, 1, At, B1); PG8_BAR; PG8_SCHED;
;             PG8_LDA(At, 1, 1); PG8_STAGE(PG8_SB(1, 0), b3, voffB); PG8_STAGE(PG8_SB(1, 1), b3 + hstep, voffB); PG8_STAGE(PG8_SA(1, 0), a3, voffA);
;             PG8_WAIT_V(8); PG8_WAIT_L(0); PG8_BAR; PG8_MMA(1, 0, At, B0); PG8_MMA(1, 1, At, B1); PG8_BAR; PG8_SCHED;
	s_add_i32 s72, 0, 0x18000
	s_add_i32 s73, 0, 0x1c000
	v_add_u32_e32 v140, s72, v173
	v_add_u32_e32 v152, s73, v173
	ds_read_b128 v[128:131], v140
	ds_read_b128 v[132:135], v140 offset:1024
	ds_read_b128 v[136:139], v140 offset:2048
	ds_read_b128 v[140:143], v140 offset:3072
	ds_read_b128 v[162:165], v152
	ds_read_b128 v[166:169], v152 offset:1024
	ds_read_b128 v[180:183], v152 offset:2048
	ds_read_b128 v[184:187], v152 offset:3072
	s_mov_b64 vcc, s[48:49]
	s_add_u32 s48, s48, 0x40000
	s_addc_u32 s49, s49, 0
	s_mov_b32 m0, s56
	ds_read_b128 v[190:193], v177 offset:32768
	ds_read_b128 v[194:197], v177 offset:33792
	ds_read_b128 v[198:201], v177 offset:34816
	ds_read_b128 v[202:205], v177 offset:35840
	ds_read_b128 v[206:209], v177 offset:36864
	ds_read_b128 v[210:213], v177 offset:37888
	ds_read_b128 v[214:217], v177 offset:38912
	global_load_lds_dwordx4 v144, s[48:49]
	s_mov_b32 m0, s57
	ds_read_b128 v[218:221], v177 offset:39936
	global_load_lds_dwordx4 v146, s[48:49]
	s_waitcnt vmcnt(8) lgkmcnt(0)
	s_setprio 1
	s_barrier
	v_mfma_f32_16x16x32_bf16 v[124:127], v[128:131], v[190:193], v[124:127]
	v_mfma_f32_16x16x32_bf16 v[120:123], v[136:139], v[190:193], v[120:123]
	v_mfma_f32_16x16x32_bf16 v[108:111], v[128:131], v[198:201], v[108:111]
	v_mfma_f32_16x16x32_bf16 v[104:107], v[136:139], v[198:201], v[104:107]
	v_mfma_f32_16x16x32_bf16 v[92:95], v[128:131], v[206:209], v[92:95]
	v_mfma_f32_16x16x32_bf16 v[88:91], v[136:139], v[206:209], v[88:91]
	v_mfma_f32_16x16x32_bf16 v[76:79], v[128:131], v[214:217], v[76:79]
	v_mfma_f32_16x16x32_bf16 v[72:75], v[136:139], v[214:217], v[72:75]
	v_mfma_f32_16x16x32_bf16 v[124:127], v[132:135], v[194:197], v[124:127]
	v_mfma_f32_16x16x32_bf16 v[120:123], v[140:143], v[194:197], v[120:123]
	v_mfma_f32_16x16x32_bf16 v[108:111], v[132:135], v[202:205], v[108:111]
	v_mfma_f32_16x16x32_bf16 v[104:107], v[140:143], v[202:205], v[104:107]
	v_mfma_f32_16x16x32_bf16 v[92:95], v[132:135], v[210:213], v[92:95]
	v_mfma_f32_16x16x32_bf16 v[88:91], v[140:143], v[210:213], v[88:91]
	v_mfma_f32_16x16x32_bf16 v[76:79], v[132:135], v[218:221], v[76:79]
	v_mfma_f32_16x16x32_bf16 v[72:75], v[140:143], v[218:221], v[72:75]
	v_mfma_f32_16x16x32_bf16 v[116:119], v[162:165], v[190:193], v[116:119]
	v_mfma_f32_16x16x32_bf16 v[112:115], v[180:183], v[190:193], v[112:115]
	v_mfma_f32_16x16x32_bf16 v[100:103], v[162:165], v[198:201], v[100:103]
	v_mfma_f32_16x16x32_bf16 v[96:99], v[180:183], v[198:201], v[96:99]
	v_mfma_f32_16x16x32_bf16 v[84:87], v[162:165], v[206:209], v[84:87]
	v_mfma_f32_16x16x32_bf16 v[80:83], v[180:183], v[206:209], v[80:83]
	v_mfma_f32_16x16x32_bf16 v[68:71], v[162:165], v[214:217], v[68:71]
	v_mfma_f32_16x16x32_bf16 v[64:67], v[180:183], v[214:217], v[64:67]
	v_mfma_f32_16x16x32_bf16 v[116:119], v[166:169], v[194:197], v[116:119]
	v_mfma_f32_16x16x32_bf16 v[112:115], v[184:187], v[194:197], v[112:115]
	v_mfma_f32_16x16x32_bf16 v[100:103], v[166:169], v[202:205], v[100:103]
	v_mfma_f32_16x16x32_bf16 v[96:99], v[184:187], v[202:205], v[96:99]
	v_mfma_f32_16x16x32_bf16 v[84:87], v[166:169], v[210:213], v[84:87]
	v_mfma_f32_16x16x32_bf16 v[80:83], v[184:187], v[210:213], v[80:83]
	v_mfma_f32_16x16x32_bf16 v[68:71], v[166:169], v[218:221], v[68:71]
	v_mfma_f32_16x16x32_bf16 v[64:67], v[184:187], v[218:221], v[64:67]
	s_setprio 0
	s_barrier
	s_add_i32 s48, s72, s53
	s_add_i32 m0, s48, 0xffffff80
	ds_read_b128 v[190:193], v177 offset:49152
	ds_read_b128 v[194:197], v177 offset:50176
	ds_read_b128 v[198:201], v177 offset:51200
	ds_read_b128 v[202:205], v177 offset:52224
	global_load_lds_dwordx4 v150, s[100:101] offset:128
	s_add_i32 m0, s48, 0x1f80
	s_add_i32 s48, s73, s53
	global_load_lds_dwordx4 v148, s[100:101] offset:128
	s_add_u32 s100, s100, s10
	s_addc_u32 s101, s101, s11
	s_add_i32 m0, s48, 0xffffff80
	ds_read_b128 v[218:221], v177 offset:56320
	global_load_lds_dwordx4 v150, s[100:101] offset:128
	s_add_i32 m0, s48, 0x1f80
	ds_read_b128 v[214:217], v177 offset:55296
	global_load_lds_dwordx4 v148, s[100:101] offset:128
	s_add_i32 m0, s60, 0xffffff80
	ds_read_b128 v[210:213], v177 offset:54272
	global_load_lds_dwordx4 v144, vcc offset:128
	s_add_i32 m0, s61, 0xffffff80
	ds_read_b128 v[206:209], v177 offset:53248
	global_load_lds_dwordx4 v146, vcc offset:128
	s_waitcnt vmcnt(8) lgkmcnt(0)
	s_setprio 1
	s_barrier
	v_mfma_f32_16x16x32_bf16 v[60:63], v[128:131], v[190:193], v[60:63]
	v_mfma_f32_16x16x32_bf16 v[56:59], v[136:139], v[190:193], v[56:59]
	v_mfma_f32_16x16x32_bf16 v[44:47], v[128:131], v[198:201], v[44:47]
	v_mfma_f32_16x16x32_bf16 v[40:43], v[136:139], v[198:201], v[40:43]
	v_mfma_f32_16x16x32_bf16 v[28:31], v[128:131], v[206:209], v[28:31]
	v_mfma_f32_16x16x32_bf16 v[24:27], v[136:139], v[206:209], v[24:27]
	v_mfma_f32_16x16x32_bf16 v[12:15], v[128:131], v[214:217], v[12:15]
	v_mfma_f32_16x16x32_bf16 v[8:11], v[136:139], v[214:217], v[8:11]
	v_mfma_f32_16x16x32_bf16 v[60:63], v[132:135], v[194:197], v[60:63]
	v_mfma_f32_16x16x32_bf16 v[56:59], v[140:143], v[194:197], v[56:59]
	v_mfma_f32_16x16x32_bf16 v[44:47], v[132:135], v[202:205], v[44:47]
	v_mfma_f32_16x16x32_bf16 v[40:43], v[140:143], v[202:205], v[40:43]
	v_mfma_f32_16x16x32_bf16 v[28:31], v[132:135], v[210:213], v[28:31]
	v_mfma_f32_16x16x32_bf16 v[24:27], v[140:143], v[210:213], v[24:27]
	v_mfma_f32_16x16x32_bf16 v[12:15], v[132:135], v[218:221], v[12:15]
	v_mfma_f32_16x16x32_bf16 v[8:11], v[140:143], v[218:221], v[8:11]
	v_mfma_f32_16x16x32_bf16 v[52:55], v[162:165], v[190:193], v[52:55]
	v_mfma_f32_16x16x32_bf16 v[48:51], v[180:183], v[190:193], v[48:51]
	v_mfma_f32_16x16x32_bf16 v[36:39], v[162:165], v[198:201], v[36:39]
	v_mfma_f32_16x16x32_bf16 v[32:35], v[180:183], v[198:201], v[32:35]
	v_mfma_f32_16x16x32_bf16 v[20:23], v[162:165], v[206:209], v[20:23]
	v_mfma_f32_16x16x32_bf16 v[16:19], v[180:183], v[206:209], v[16:19]
	v_mfma_f32_16x16x32_bf16 v[4:7], v[162:165], v[214:217], v[4:7]
	v_mfma_f32_16x16x32_bf16 v[0:3], v[180:183], v[214:217], v[0:3]
	v_mfma_f32_16x16x32_bf16 v[52:55], v[166:169], v[194:197], v[52:55]
	v_mfma_f32_16x16x32_bf16 v[48:51], v[184:187], v[194:197], v[48:51]
	v_mfma_f32_16x16x32_bf16 v[36:39], v[166:169], v[202:205], v[36:39]
	v_mfma_f32_16x16x32_bf16 v[32:35], v[184:187], v[202:205], v[32:35]
	v_mfma_f32_16x16x32_bf16 v[20:23], v[166:169], v[210:213], v[20:23]
	v_mfma_f32_16x16x32_bf16 v[16:19], v[184:187], v[210:213], v[16:19]
	v_mfma_f32_16x16x32_bf16 v[4:7], v[166:169], v[218:221], v[4:7]
	v_mfma_f32_16x16x32_bf16 v[0:3], v[184:187], v[218:221], v[0:3]
	s_setprio 0
	s_barrier
	s_add_u32 s8, s8, 0x100
	s_addc_u32 s9, s9, 0
	s_add_u32 s50, s50, 0x100
	s_addc_u32 s51, s51, 0
	s_cmp_ge_i32 s71, s63
	s_mov_b32 s48, s71
	s_cbranch_scc0 .LBB0_681

; #define PG8_STAGE(bufoff, gbase, voff) do { _Pragma("unroll") for (int _i = 0; _i < 2; ++_i) \
;         __builtin_amdgcn_global_load_lds((const unsigned*)((const char*)(gbase) + (voff)[_i]), (PG8_LAS unsigned*)(lds + (bufoff) + ldsw + _i * 8192), 16, 0, 0); } while (0)
; #define PG8_LDA(dst, b, h) do { _Pragma("unroll") for (int m = 0; m < 4; ++m) _Pragma("unroll") for (int k = 0; k < 2; ++k) dst[m][k] = *(const PG8_LAS bf16x8*)(lds + PG8_SA(b, h) + aoff + m * 2048 + k * 1024); } while (0)
; #define PG8_LDB(dst, b, h) do { _Pragma("unroll") for (int n = 0; n < 2; ++n) _Pragma("unroll") for (int k = 0; k < 2; ++k) dst[n][k] = *(const PG8_LAS bf16x8*)(lds + PG8_SB(b, h) + boff + n * 2048 + k * 1024); } while (0)
; #define PG8_MMA(ai, bj, At, Bt) do { __builtin_amdgcn_s_setprio(1); _Pragma("unroll") for (int m = 0; m < 4; ++m) _Pragma("unroll") for (int n = 0; n < 2; ++n) _Pragma("unroll") for (int k = 0; k < 2; ++k) \
;         acc[ai][bj][m][n] = __builtin_amdgcn_mfma_f32_16x16x32_bf16(Bt[n][k], At[m][k], acc[ai][bj][m][n], 0, 0, 0); __builtin_amdgcn_s_setprio(0); } while (0)
; #define PG8_WAIT_V(n) asm volatile("s_waitcnt vmcnt(" #n ")" ::: "memory")
; #define PG8_WAIT_L(n) asm volatile("s_waitcnt lgkmcnt(" #n ")" ::: "memory")
; template <class Epi, class Sched, bool ALIGN_EPI = false, bool SP2 = false>
; __device__ __forceinline__ void gemm_phase(PG8_LAS unsigned char* lds, const Gemm g, const Sched& S, const Epi& E) {
;     ...
;             const bool last = (t == nt - 2);
;             const char* a1 = cA + (size_t)(t + 1) * kstep;
;             const char* a2 = last ? nA : cA + (size_t)(t + 2) * kstep; const char* b2 = last ? nB : cB + (size_t)(t + 2) * kstep;
;             const char* a3 = a2 + kstep; const char* b3 = b2 + kstep;
;             if (last && has_next) S.a_ready(nxt);
;             if constexpr (SP2) {
;             PG8_LDB(B0, 0, 0); PG8_LDB(B1, 0, 1); PG8_SCHED; PG8_LDA(At, 0, 0); PG8_STAGE(PG8_SA(1, 1), a1 + hstepA, voffA);
;             PG8_WAIT_V(8); PG8_WAIT_L(0); PG8_BAR; PG8_MMA(0, 0, At, B0); PG8_MMA(0, 1, At, B1); PG8_BAR; PG8_SCHED;
;             PG8_LDA(At, 0, 1); PG8_STAGE(PG8_SB(0, 0), b2, voffB); PG8_STAGE(PG8_SB(0, 1), b2 + hstep, voffB); PG8_STAGE(PG8_SA(0, 0), a2, voffA);
;             PG8_WAIT_V(8); PG8_WAIT_L(0); PG8_BAR; PG8_MMA(1, 0, At, B0); PG8_MMA(1, 1, At, B1); PG8_BAR; PG8_SCHED;
.LBB0_762:
	ds_read_b128 v[128:131], v169
	ds_read_b128 v[132:135], v169 offset:1024
	ds_read_b128 v[136:139], v169 offset:2048
	ds_read_b128 v[140:143], v169 offset:3072
	ds_read_b128 v[156:159], v170
	ds_read_b128 v[160:163], v170 offset:1024
	ds_read_b128 v[172:175], v170 offset:2048
	ds_read_b128 v[176:179], v170 offset:3072
	s_add_i32 s76, s48, 2
	s_add_u32 s77, s44, 0xfffc0080
	s_addc_u32 s49, s45, -1
	s_cmp_eq_u32 s70, s48
	s_cselect_b32 s48, s50, s77
	s_cselect_b32 s49, s37, s49
	s_cselect_b32 s79, s39, s75
	s_cselect_b32 s78, s38, s51
	s_add_i32 m0, s43, 0xc000
	ds_read_b128 v[180:183], v171
	ds_read_b128 v[184:187], v171 offset:1024
	ds_read_b128 v[190:193], v171 offset:2048
	ds_read_b128 v[194:197], v171 offset:3072
	ds_read_b128 v[198:201], v171 offset:4096
	ds_read_b128 v[202:205], v171 offset:5120
	ds_read_b128 v[206:209], v171 offset:6144
	global_load_lds_dwordx4 v152, s[44:45]
	s_add_i32 m0, s43, 0xe000
	ds_read_b128 v[210:213], v171 offset:7168
	global_load_lds_dwordx4 v154, s[44:45]
	s_waitcnt vmcnt(8) lgkmcnt(0)
	s_setprio 1
	s_barrier
	v_mfma_f32_16x16x32_bf16 v[124:127], v[128:131], v[180:183], v[124:127]
	v_mfma_f32_16x16x32_bf16 v[120:123], v[136:139], v[180:183], v[120:123]
	v_mfma_f32_16x16x32_bf16 v[108:111], v[128:131], v[190:193], v[108:111]
	v_mfma_f32_16x16x32_bf16 v[104:107], v[136:139], v[190:193], v[104:107]
	v_mfma_f32_16x16x32_bf16 v[92:95], v[128:131], v[198:201], v[92:95]
	v_mfma_f32_16x16x32_bf16 v[88:91], v[136:139], v[198:201], v[88:91]
	v_mfma_f32_16x16x32_bf16 v[76:79], v[128:131], v[206:209], v[76:79]
	v_mfma_f32_16x16x32_bf16 v[72:75], v[136:139], v[206:209], v[72:75]
	v_mfma_f32_16x16x32_bf16 v[124:127], v[132:135], v[184:187], v[124:127]
	v_mfma_f32_16x16x32_bf16 v[120:123], v[140:143], v[184:187], v[120:123]
	v_mfma_f32_16x16x32_bf16 v[108:111], v[132:135], v[194:197], v[108:111]
	v_mfma_f32_16x16x32_bf16 v[104:107], v[140:143], v[194:197], v[104:107]
	v_mfma_f32_16x16x32_bf16 v[92:95], v[132:135], v[202:205], v[92:95]
	v_mfma_f32_16x16x32_bf16 v[88:91], v[140:143], v[202:205], v[88:91]
	v_mfma_f32_16x16x32_bf16 v[76:79], v[132:135], v[210:213], v[76:79]
	v_mfma_f32_16x16x32_bf16 v[72:75], v[140:143], v[210:213], v[72:75]
	v_mfma_f32_16x16x32_bf16 v[116:119], v[156:159], v[180:183], v[116:119]
	v_mfma_f32_16x16x32_bf16 v[112:115], v[172:175], v[180:183], v[112:115]
	v_mfma_f32_16x16x32_bf16 v[100:103], v[156:159], v[190:193], v[100:103]
	v_mfma_f32_16x16x32_bf16 v[96:99], v[172:175], v[190:193], v[96:99]
	v_mfma_f32_16x16x32_bf16 v[84:87], v[156:159], v[198:201], v[84:87]
	v_mfma_f32_16x16x32_bf16 v[80:83], v[172:175], v[198:201], v[80:83]
	v_mfma_f32_16x16x32_bf16 v[68:71], v[156:159], v[206:209], v[68:71]
	v_mfma_f32_16x16x32_bf16 v[64:67], v[172:175], v[206:209], v[64:67]
	v_mfma_f32_16x16x32_bf16 v[116:119], v[160:163], v[184:187], v[116:119]
	v_mfma_f32_16x16x32_bf16 v[112:115], v[176:179], v[184:187], v[112:115]
	v_mfma_f32_16x16x32_bf16 v[100:103], v[160:163], v[194:197], v[100:103]
	v_mfma_f32_16x16x32_bf16 v[96:99], v[176:179], v[194:197], v[96:99]
	v_mfma_f32_16x16x32_bf16 v[84:87], v[160:163], v[202:205], v[84:87]
	v_mfma_f32_16x16x32_bf16 v[80:83], v[176:179], v[202:205], v[80:83]
	v_mfma_f32_16x16x32_bf16 v[68:71], v[160:163], v[210:213], v[68:71]
	v_mfma_f32_16x16x32_bf16 v[64:67], v[176:179], v[210:213], v[64:67]
	s_setprio 0
	s_barrier
	s_add_i32 s77, s71, s57
	s_mov_b32 m0, s77
	ds_read_b128 v[180:183], v171 offset:16384
	ds_read_b128 v[184:187], v171 offset:17408
	ds_read_b128 v[190:193], v171 offset:18432
	ds_read_b128 v[194:197], v171 offset:19456
	global_load_lds_dwordx4 v150, s[78:79]
	s_add_i32 m0, s77, 0x2000
	s_mov_b64 s[100:101], s[78:79]
	s_add_i32 s77, s72, s57
	global_load_lds_dwordx4 v148, s[78:79]
	s_add_u32 s78, s78, s8
	s_addc_u32 s79, s79, s9
	s_mov_b32 m0, s77
	ds_read_b128 v[210:213], v171 offset:23552
	global_load_lds_dwordx4 v150, s[78:79]
	s_add_i32 m0, s77, 0x2000
	ds_read_b128 v[206:209], v171 offset:22528
	global_load_lds_dwordx4 v148, s[78:79]
	s_mov_b32 m0, s43
	ds_read_b128 v[202:205], v171 offset:21504
	global_load_lds_dwordx4 v144, s[48:49]
	s_mov_b32 m0, s59
	ds_read_b128 v[198:201], v171 offset:20480
	global_load_lds_dwordx4 v146, s[48:49]
	s_waitcnt vmcnt(8) lgkmcnt(0)
	s_setprio 1
	s_barrier
	v_mfma_f32_16x16x32_bf16 v[60:63], v[128:131], v[180:183], v[60:63]
	v_mfma_f32_16x16x32_bf16 v[56:59], v[136:139], v[180:183], v[56:59]
	v_mfma_f32_16x16x32_bf16 v[44:47], v[128:131], v[190:193], v[44:47]
	v_mfma_f32_16x16x32_bf16 v[40:43], v[136:139], v[190:193], v[40:43]
	v_mfma_f32_16x16x32_bf16 v[28:31], v[128:131], v[198:201], v[28:31]
	v_mfma_f32_16x16x32_bf16 v[24:27], v[136:139], v[198:201], v[24:27]
	v_mfma_f32_16x16x32_bf16 v[12:15], v[128:131], v[206:209], v[12:15]
	v_mfma_f32_16x16x32_bf16 v[8:11], v[136:139], v[206:209], v[8:11]
	v_mfma_f32_16x16x32_bf16 v[60:63], v[132:135], v[184:187], v[60:63]
	v_mfma_f32_16x16x32_bf16 v[56:59], v[140:143], v[184:187], v[56:59]
	v_mfma_f32_16x16x32_bf16 v[44:47], v[132:135], v[194:197], v[44:47]
	v_mfma_f32_16x16x32_bf16 v[40:43], v[140:143], v[194:197], v[40:43]
	v_mfma_f32_16x16x32_bf16 v[28:31], v[132:135], v[202:205], v[28:31]
	v_mfma_f32_16x16x32_bf16 v[24:27], v[140:143], v[202:205], v[24:27]
	v_mfma_f32_16x16x32_bf16 v[12:15], v[132:135], v[210:213], v[12:15]
	v_mfma_f32_16x16x32_bf16 v[8:11], v[140:143], v[210:213], v[8:11]
	v_mfma_f32_16x16x32_bf16 v[52:55], v[156:159], v[180:183], v[52:55]
	v_mfma_f32_16x16x32_bf16 v[48:51], v[172:175], v[180:183], v[48:51]
	v_mfma_f32_16x16x32_bf16 v[36:39], v[156:159], v[190:193], v[36:39]
	v_mfma_f32_16x16x32_bf16 v[32:35], v[172:175], v[190:193], v[32:35]
	v_mfma_f32_16x16x32_bf16 v[20:23], v[156:159], v[198:201], v[20:23]
	v_mfma_f32_16x16x32_bf16 v[16:19], v[172:175], v[198:201], v[16:19]
	v_mfma_f32_16x16x32_bf16 v[4:7], v[156:159], v[206:209], v[4:7]
	v_mfma_f32_16x16x32_bf16 v[0:3], v[172:175], v[206:209], v[0:3]
	v_mfma_f32_16x16x32_bf16 v[52:55], v[160:163], v[184:187], v[52:55]
	v_mfma_f32_16x16x32_bf16 v[48:51], v[176:179], v[184:187], v[48:51]
	v_mfma_f32_16x16x32_bf16 v[36:39], v[160:163], v[194:197], v[36:39]
	v_mfma_f32_16x16x32_bf16 v[32:35], v[176:179], v[194:197], v[32:35]
	v_mfma_f32_16x16x32_bf16 v[20:23], v[160:163], v[202:205], v[20:23]
	v_mfma_f32_16x16x32_bf16 v[16:19], v[176:179], v[202:205], v[16:19]
	v_mfma_f32_16x16x32_bf16 v[4:7], v[160:163], v[210:213], v[4:7]
	v_mfma_f32_16x16x32_bf16 v[0:3], v[176:179], v[210:213], v[0:3]
	s_setprio 0
	s_barrier
; #define PG8_STAGE(bufoff, gbase, voff) do { _Pragma("unroll") for (int _i = 0; _i < 2; ++_i) \
;         __builtin_amdgcn_global_load_lds((const unsigned*)((const char*)(gbase) + (voff)[_i]), (PG8_LAS unsigned*)(lds + (bufoff) + ldsw + _i * 8192), 16, 0, 0); } while (0)
; #define PG8_LDA(dst, b, h) do { _Pragma("unroll") for (int m = 0; m < 4; ++m) _Pragma("unroll") for (int k = 0; k < 2; ++k) dst[m][k] = *(const PG8_LAS bf16x8*)(lds + PG8_SA(b, h) + aoff + m * 2048 + k * 1024); } while (0)
; #define PG8_LDB(dst, b, h) do { _Pragma("unroll") for (int n = 0; n < 2; ++n) _Pragma("unroll") for (int k = 0; k < 2; ++k) dst[n][k] = *(const PG8_LAS bf16x8*)(lds + PG8_SB(b, h) + boff + n * 2048 + k * 1024); } while (0)
; #define PG8_MMA(ai, bj, At, Bt) do { __builtin_amdgcn_s_setprio(1); _Pragma("unroll") for (int m = 0; m < 4; ++m) _Pragma("unroll") for (int n = 0; n < 2; ++n) _Pragma("unroll") for (int k = 0; k < 2; ++k) \
;         acc[ai][bj][m][n] = __builtin_amdgcn_mfma_f32_16x16x32_bf16(Bt[n][k], At[m][k], acc[ai][bj][m][n], 0, 0, 0); __builtin_amdgcn_s_setprio(0); } while (0)
; #define PG8_WAIT_V(n) asm volatile("s_waitcnt vmcnt(" #n ")" ::: "memory")
; #define PG8_WAIT_L(n) asm volatile("s_waitcnt lgkmcnt(" #n ")" ::: "memory")
; #define PG8_BAR __builtin_amdgcn_s_barrier()
; #define PG8_SCHED __builtin_amdgcn_sched_barrier(0)
; template <class Epi, class Sched, bool ALIGN_EPI = false, bool SP2 = false>
; __device__ __forceinline__ void gemm_phase(PG8_LAS unsigned char* lds, const Gemm g, const Sched& S, const Epi& E) {
;     ...
;             PG8_LDB(B0, 1, 0); PG8_LDB(B1, 1, 1); PG8_SCHED; PG8_LDA(At, 1, 0); PG8_STAGE(PG8_SA(0, 1), a2 + hstepA, voffA);
;             PG8_WAIT_V(8); PG8_WAIT_L(0); PG8_BAR; PG8_MMA(0, 0, At, B0); PG8_MMA(0, 1, At, B1); PG8_BAR; PG8_SCHED;
;             PG8_LDA(At, 1, 1); PG8_STAGE(PG8_SB(1, 0), b3, voffB); PG8_STAGE(PG8_SB(1, 1), b3 + hstep, voffB); PG8_STAGE(PG8_SA(1, 0), a3, voffA);
;             PG8_WAIT_V(8); PG8_WAIT_L(0); PG8_BAR; PG8_MMA(1, 0, At, B0); PG8_MMA(1, 1, At, B1); PG8_BAR; PG8_SCHED;
	s_add_i32 s77, 0, 0x18000
	s_add_i32 s78, 0, 0x1c000
	v_add_u32_e32 v140, s77, v167
	v_add_u32_e32 v176, s78, v167
	ds_read_b128 v[128:131], v140
	ds_read_b128 v[132:135], v140 offset:1024
	ds_read_b128 v[136:139], v140 offset:2048
	ds_read_b128 v[140:143], v140 offset:3072
	ds_read_b128 v[156:159], v176
	ds_read_b128 v[160:163], v176 offset:1024
	ds_read_b128 v[172:175], v176 offset:2048
	ds_read_b128 v[176:179], v176 offset:3072
	s_mov_b64 vcc, s[48:49]
	s_add_u32 s48, s48, 0x40000
	s_addc_u32 s49, s49, 0
	s_mov_b32 m0, s60
	ds_read_b128 v[180:183], v171 offset:32768
	ds_read_b128 v[184:187], v171 offset:33792
	ds_read_b128 v[190:193], v171 offset:34816
	ds_read_b128 v[194:197], v171 offset:35840
	ds_read_b128 v[198:201], v171 offset:36864
	ds_read_b128 v[202:205], v171 offset:37888
	ds_read_b128 v[206:209], v171 offset:38912
	global_load_lds_dwordx4 v144, s[48:49]
	s_mov_b32 m0, s61
	ds_read_b128 v[210:213], v171 offset:39936
	global_load_lds_dwordx4 v146, s[48:49]
	s_waitcnt vmcnt(8) lgkmcnt(0)
	s_setprio 1
	s_barrier
	v_mfma_f32_16x16x32_bf16 v[124:127], v[128:131], v[180:183], v[124:127]
	v_mfma_f32_16x16x32_bf16 v[120:123], v[136:139], v[180:183], v[120:123]
	v_mfma_f32_16x16x32_bf16 v[108:111], v[128:131], v[190:193], v[108:111]
	v_mfma_f32_16x16x32_bf16 v[104:107], v[136:139], v[190:193], v[104:107]
	v_mfma_f32_16x16x32_bf16 v[92:95], v[128:131], v[198:201], v[92:95]
	v_mfma_f32_16x16x32_bf16 v[88:91], v[136:139], v[198:201], v[88:91]
	v_mfma_f32_16x16x32_bf16 v[76:79], v[128:131], v[206:209], v[76:79]
	v_mfma_f32_16x16x32_bf16 v[72:75], v[136:139], v[206:209], v[72:75]
	v_mfma_f32_16x16x32_bf16 v[124:127], v[132:135], v[184:187], v[124:127]
	v_mfma_f32_16x16x32_bf16 v[120:123], v[140:143], v[184:187], v[120:123]
	v_mfma_f32_16x16x32_bf16 v[108:111], v[132:135], v[194:197], v[108:111]
	v_mfma_f32_16x16x32_bf16 v[104:107], v[140:143], v[194:197], v[104:107]
	v_mfma_f32_16x16x32_bf16 v[92:95], v[132:135], v[202:205], v[92:95]
	v_mfma_f32_16x16x32_bf16 v[88:91], v[140:143], v[202:205], v[88:91]
	v_mfma_f32_16x16x32_bf16 v[76:79], v[132:135], v[210:213], v[76:79]
	v_mfma_f32_16x16x32_bf16 v[72:75], v[140:143], v[210:213], v[72:75]
	v_mfma_f32_16x16x32_bf16 v[116:119], v[156:159], v[180:183], v[116:119]
	v_mfma_f32_16x16x32_bf16 v[112:115], v[172:175], v[180:183], v[112:115]
	v_mfma_f32_16x16x32_bf16 v[100:103], v[156:159], v[190:193], v[100:103]
	v_mfma_f32_16x16x32_bf16 v[96:99], v[172:175], v[190:193], v[96:99]
	v_mfma_f32_16x16x32_bf16 v[84:87], v[156:159], v[198:201], v[84:87]
	v_mfma_f32_16x16x32_bf16 v[80:83], v[172:175], v[198:201], v[80:83]
	v_mfma_f32_16x16x32_bf16 v[68:71], v[156:159], v[206:209], v[68:71]
	v_mfma_f32_16x16x32_bf16 v[64:67], v[172:175], v[206:209], v[64:67]
	v_mfma_f32_16x16x32_bf16 v[116:119], v[160:163], v[184:187], v[116:119]
	v_mfma_f32_16x16x32_bf16 v[112:115], v[176:179], v[184:187], v[112:115]
	v_mfma_f32_16x16x32_bf16 v[100:103], v[160:163], v[194:197], v[100:103]
	v_mfma_f32_16x16x32_bf16 v[96:99], v[176:179], v[194:197], v[96:99]
	v_mfma_f32_16x16x32_bf16 v[84:87], v[160:163], v[202:205], v[84:87]
	v_mfma_f32_16x16x32_bf16 v[80:83], v[176:179], v[202:205], v[80:83]
	v_mfma_f32_16x16x32_bf16 v[68:71], v[160:163], v[210:213], v[68:71]
	v_mfma_f32_16x16x32_bf16 v[64:67], v[176:179], v[210:213], v[64:67]
	s_setprio 0
	s_barrier
	s_add_i32 s48, s77, s57
	s_add_i32 m0, s48, 0xffffff80
	ds_read_b128 v[180:183], v171 offset:49152
	ds_read_b128 v[184:187], v171 offset:50176
	ds_read_b128 v[190:193], v171 offset:51200
	ds_read_b128 v[194:197], v171 offset:52224
	global_load_lds_dwordx4 v150, s[100:101] offset:128
	s_add_i32 m0, s48, 0x1f80
	s_add_i32 s48, s78, s57
	global_load_lds_dwordx4 v148, s[100:101] offset:128
	s_add_u32 s100, s100, s8
	s_addc_u32 s101, s101, s9
	s_add_i32 m0, s48, 0xffffff80
	ds_read_b128 v[210:213], v171 offset:56320
	global_load_lds_dwordx4 v150, s[100:101] offset:128
	s_add_i32 m0, s48, 0x1f80
	ds_read_b128 v[206:209], v171 offset:55296
	global_load_lds_dwordx4 v148, s[100:101] offset:128
	s_add_i32 m0, s65, 0xffffff80
	ds_read_b128 v[202:205], v171 offset:54272
	global_load_lds_dwordx4 v144, vcc offset:128
	s_add_i32 m0, s66, 0xffffff80
	ds_read_b128 v[198:201], v171 offset:53248
	global_load_lds_dwordx4 v146, vcc offset:128
	s_waitcnt vmcnt(8) lgkmcnt(0)
	s_setprio 1
	s_barrier
	v_mfma_f32_16x16x32_bf16 v[60:63], v[128:131], v[180:183], v[60:63]
	v_mfma_f32_16x16x32_bf16 v[56:59], v[136:139], v[180:183], v[56:59]
	v_mfma_f32_16x16x32_bf16 v[44:47], v[128:131], v[190:193], v[44:47]
	v_mfma_f32_16x16x32_bf16 v[40:43], v[136:139], v[190:193], v[40:43]
	v_mfma_f32_16x16x32_bf16 v[28:31], v[128:131], v[198:201], v[28:31]
	v_mfma_f32_16x16x32_bf16 v[24:27], v[136:139], v[198:201], v[24:27]
	v_mfma_f32_16x16x32_bf16 v[12:15], v[128:131], v[206:209], v[12:15]
	v_mfma_f32_16x16x32_bf16 v[8:11], v[136:139], v[206:209], v[8:11]
	v_mfma_f32_16x16x32_bf16 v[60:63], v[132:135], v[184:187], v[60:63]
	v_mfma_f32_16x16x32_bf16 v[56:59], v[140:143], v[184:187], v[56:59]
	v_mfma_f32_16x16x32_bf16 v[44:47], v[132:135], v[194:197], v[44:47]
	v_mfma_f32_16x16x32_bf16 v[40:43], v[140:143], v[194:197], v[40:43]
	v_mfma_f32_16x16x32_bf16 v[28:31], v[132:135], v[202:205], v[28:31]
	v_mfma_f32_16x16x32_bf16 v[24:27], v[140:143], v[202:205], v[24:27]
	v_mfma_f32_16x16x32_bf16 v[12:15], v[132:135], v[210:213], v[12:15]
	v_mfma_f32_16x16x32_bf16 v[8:11], v[140:143], v[210:213], v[8:11]
	v_mfma_f32_16x16x32_bf16 v[52:55], v[156:159], v[180:183], v[52:55]
	v_mfma_f32_16x16x32_bf16 v[48:51], v[172:175], v[180:183], v[48:51]
	v_mfma_f32_16x16x32_bf16 v[36:39], v[156:159], v[190:193], v[36:39]
	v_mfma_f32_16x16x32_bf16 v[32:35], v[172:175], v[190:193], v[32:35]
	v_mfma_f32_16x16x32_bf16 v[20:23], v[156:159], v[198:201], v[20:23]
	v_mfma_f32_16x16x32_bf16 v[16:19], v[172:175], v[198:201], v[16:19]
	v_mfma_f32_16x16x32_bf16 v[4:7], v[156:159], v[206:209], v[4:7]
	v_mfma_f32_16x16x32_bf16 v[0:3], v[172:175], v[206:209], v[0:3]
	v_mfma_f32_16x16x32_bf16 v[52:55], v[160:163], v[184:187], v[52:55]
	v_mfma_f32_16x16x32_bf16 v[48:51], v[176:179], v[184:187], v[48:51]
	v_mfma_f32_16x16x32_bf16 v[36:39], v[160:163], v[194:197], v[36:39]
	v_mfma_f32_16x16x32_bf16 v[32:35], v[176:179], v[194:197], v[32:35]
	v_mfma_f32_16x16x32_bf16 v[20:23], v[160:163], v[202:205], v[20:23]
	v_mfma_f32_16x16x32_bf16 v[16:19], v[176:179], v[202:205], v[16:19]
	v_mfma_f32_16x16x32_bf16 v[4:7], v[160:163], v[210:213], v[4:7]
	v_mfma_f32_16x16x32_bf16 v[0:3], v[176:179], v[210:213], v[0:3]
	s_setprio 0
	s_barrier
	s_add_u32 s44, s44, 0x100
	s_addc_u32 s45, s45, 0
	s_add_u32 s51, s51, 0x100
	s_addc_u32 s75, s75, 0
	s_cmp_ge_i32 s76, s67
	s_mov_b32 s48, s76
	s_cbranch_scc0 .LBB0_762

; #define PG8_STAGE(bufoff, gbase, voff) do { _Pragma("unroll") for (int _i = 0; _i < 2; ++_i) \
;         __builtin_amdgcn_global_load_lds((const unsigned*)((const char*)(gbase) + (voff)[_i]), (PG8_LAS unsigned*)(lds + (bufoff) + ldsw + _i * 8192), 16, 0, 0); } while (0)
; #define PG8_LDA(dst, b, h) do { _Pragma("unroll") for (int m = 0; m < 4; ++m) _Pragma("unroll") for (int k = 0; k < 2; ++k) dst[m][k] = *(const PG8_LAS bf16x8*)(lds + PG8_SA(b, h) + aoff + m * 2048 + k * 1024); } while (0)
; #define PG8_LDB(dst, b, h) do { _Pragma("unroll") for (int n = 0; n < 2; ++n) _Pragma("unroll") for (int k = 0; k < 2; ++k) dst[n][k] = *(const PG8_LAS bf16x8*)(lds + PG8_SB(b, h) + boff + n * 2048 + k * 1024); } while (0)
; #define PG8_MMA(ai, bj, At, Bt) do { __builtin_amdgcn_s_setprio(1); _Pragma("unroll") for (int m = 0; m < 4; ++m) _Pragma("unroll") for (int n = 0; n < 2; ++n) _Pragma("unroll") for (int k = 0; k < 2; ++k) \
;         acc[ai][bj][m][n] = __builtin_amdgcn_mfma_f32_16x16x32_bf16(Bt[n][k], At[m][k], acc[ai][bj][m][n], 0, 0, 0); __builtin_amdgcn_s_setprio(0); } while (0)
; #define PG8_WAIT_V(n) asm volatile("s_waitcnt vmcnt(" #n ")" ::: "memory")
; #define PG8_WAIT_L(n) asm volatile("s_waitcnt lgkmcnt(" #n ")" ::: "memory")
; template <class Epi, class Sched, bool ALIGN_EPI = false, bool SP2 = false>
; __device__ __forceinline__ void gemm_phase(PG8_LAS unsigned char* lds, const Gemm g, const Sched& S, const Epi& E) {
;     ...
;             const bool last = (t == nt - 2);
;             const char* a1 = cA + (size_t)(t + 1) * kstep;
;             const char* a2 = last ? nA : cA + (size_t)(t + 2) * kstep; const char* b2 = last ? nB : cB + (size_t)(t + 2) * kstep;
;             const char* a3 = a2 + kstep; const char* b3 = b2 + kstep;
;             if (last && has_next) S.a_ready(nxt);
;             if constexpr (SP2) {
;             PG8_LDB(B0, 0, 0); PG8_LDB(B1, 0, 1); PG8_SCHED; PG8_LDA(At, 0, 0); PG8_STAGE(PG8_SA(1, 1), a1 + hstepA, voffA);
;             PG8_WAIT_V(8); PG8_WAIT_L(0); PG8_BAR; PG8_MMA(0, 0, At, B0); PG8_MMA(0, 1, At, B1); PG8_BAR; PG8_SCHED;
;             PG8_LDA(At, 0, 1); PG8_STAGE(PG8_SB(0, 0), b2, voffB); PG8_STAGE(PG8_SB(0, 1), b2 + hstep, voffB); PG8_STAGE(PG8_SA(0, 0), a2, voffA);
;             PG8_WAIT_V(8); PG8_WAIT_L(0); PG8_BAR; PG8_MMA(1, 0, At, B0); PG8_MMA(1, 1, At, B1); PG8_BAR; PG8_SCHED;
.LBB0_898:
	ds_read_b128 v[150:153], v147
	ds_read_b128 v[154:157], v147 offset:1024
	ds_read_b128 v[158:161], v147 offset:2048
	ds_read_b128 v[162:165], v147 offset:3072
	ds_read_b128 v[166:169], v148
	ds_read_b128 v[170:173], v148 offset:1024
	ds_read_b128 v[174:177], v148 offset:2048
	ds_read_b128 v[178:181], v148 offset:3072
	s_add_i32 s58, s30, 2
	s_add_u32 s59, s10, 0xfffc0080
	s_addc_u32 s31, s11, -1
	s_cmp_eq_u32 s51, s30
	s_cselect_b32 s30, s57, s59
	s_cselect_b32 s31, s23, s31
	s_cselect_b32 s61, s25, s35
	s_cselect_b32 s60, s24, s34
	s_add_i32 m0, s29, 0xc000
	ds_read_b128 v[182:185], v149
	ds_read_b128 v[190:193], v149 offset:1024
	ds_read_b128 v[194:197], v149 offset:2048
	ds_read_b128 v[198:201], v149 offset:3072
	ds_read_b128 v[202:205], v149 offset:4096
	ds_read_b128 v[206:209], v149 offset:5120
	ds_read_b128 v[210:213], v149 offset:6144
	global_load_lds_dwordx4 v136, s[10:11]
	s_add_i32 m0, s29, 0xe000
	ds_read_b128 v[214:217], v149 offset:7168
	global_load_lds_dwordx4 v138, s[10:11]
	s_waitcnt vmcnt(8) lgkmcnt(0)
	s_setprio 1
	s_barrier
	v_mfma_f32_16x16x32_bf16 v[124:127], v[150:153], v[182:185], v[124:127]
	v_mfma_f32_16x16x32_bf16 v[116:119], v[158:161], v[182:185], v[116:119]
	v_mfma_f32_16x16x32_bf16 v[108:111], v[150:153], v[194:197], v[108:111]
	v_mfma_f32_16x16x32_bf16 v[100:103], v[158:161], v[194:197], v[100:103]
	v_mfma_f32_16x16x32_bf16 v[92:95], v[150:153], v[202:205], v[92:95]
	v_mfma_f32_16x16x32_bf16 v[84:87], v[158:161], v[202:205], v[84:87]
	v_mfma_f32_16x16x32_bf16 v[76:79], v[150:153], v[210:213], v[76:79]
	v_mfma_f32_16x16x32_bf16 v[68:71], v[158:161], v[210:213], v[68:71]
	v_mfma_f32_16x16x32_bf16 v[124:127], v[154:157], v[190:193], v[124:127]
	v_mfma_f32_16x16x32_bf16 v[116:119], v[162:165], v[190:193], v[116:119]
	v_mfma_f32_16x16x32_bf16 v[108:111], v[154:157], v[198:201], v[108:111]
	v_mfma_f32_16x16x32_bf16 v[100:103], v[162:165], v[198:201], v[100:103]
	v_mfma_f32_16x16x32_bf16 v[92:95], v[154:157], v[206:209], v[92:95]
	v_mfma_f32_16x16x32_bf16 v[84:87], v[162:165], v[206:209], v[84:87]
	v_mfma_f32_16x16x32_bf16 v[76:79], v[154:157], v[214:217], v[76:79]
	v_mfma_f32_16x16x32_bf16 v[68:71], v[162:165], v[214:217], v[68:71]
	v_mfma_f32_16x16x32_bf16 v[120:123], v[166:169], v[182:185], v[120:123]
	v_mfma_f32_16x16x32_bf16 v[112:115], v[174:177], v[182:185], v[112:115]
	v_mfma_f32_16x16x32_bf16 v[104:107], v[166:169], v[194:197], v[104:107]
	v_mfma_f32_16x16x32_bf16 v[96:99], v[174:177], v[194:197], v[96:99]
	v_mfma_f32_16x16x32_bf16 v[88:91], v[166:169], v[202:205], v[88:91]
	v_mfma_f32_16x16x32_bf16 v[80:83], v[174:177], v[202:205], v[80:83]
	v_mfma_f32_16x16x32_bf16 v[72:75], v[166:169], v[210:213], v[72:75]
	v_mfma_f32_16x16x32_bf16 v[64:67], v[174:177], v[210:213], v[64:67]
	v_mfma_f32_16x16x32_bf16 v[120:123], v[170:173], v[190:193], v[120:123]
	v_mfma_f32_16x16x32_bf16 v[112:115], v[178:181], v[190:193], v[112:115]
	v_mfma_f32_16x16x32_bf16 v[104:107], v[170:173], v[198:201], v[104:107]
	v_mfma_f32_16x16x32_bf16 v[96:99], v[178:181], v[198:201], v[96:99]
	v_mfma_f32_16x16x32_bf16 v[88:91], v[170:173], v[206:209], v[88:91]
	v_mfma_f32_16x16x32_bf16 v[80:83], v[178:181], v[206:209], v[80:83]
	v_mfma_f32_16x16x32_bf16 v[72:75], v[170:173], v[214:217], v[72:75]
	v_mfma_f32_16x16x32_bf16 v[64:67], v[178:181], v[214:217], v[64:67]
	s_setprio 0
	s_barrier
	s_add_i32 s59, s52, s38
	s_mov_b32 m0, s59
	ds_read_b128 v[182:185], v149 offset:16384
	ds_read_b128 v[190:193], v149 offset:17408
	ds_read_b128 v[194:197], v149 offset:18432
	ds_read_b128 v[198:201], v149 offset:19456
	global_load_lds_dwordx4 v134, s[60:61]
	s_add_i32 m0, s59, 0x2000
	s_mov_b64 s[100:101], s[60:61]
	s_add_i32 s59, s53, s38
	global_load_lds_dwordx4 v132, s[60:61]
	s_add_u32 s60, s60, s4
	s_addc_u32 s61, s61, s5
	s_mov_b32 m0, s59
	ds_read_b128 v[214:217], v149 offset:23552
	global_load_lds_dwordx4 v134, s[60:61]
	s_add_i32 m0, s59, 0x2000
	ds_read_b128 v[210:213], v149 offset:22528
	global_load_lds_dwordx4 v132, s[60:61]
	s_mov_b32 m0, s29
	ds_read_b128 v[206:209], v149 offset:21504
	global_load_lds_dwordx4 v128, s[30:31]
	s_mov_b32 m0, s41
	ds_read_b128 v[202:205], v149 offset:20480
	global_load_lds_dwordx4 v130, s[30:31]
	s_waitcnt vmcnt(8) lgkmcnt(0)
	s_setprio 1
	s_barrier
	v_mfma_f32_16x16x32_bf16 v[60:63], v[150:153], v[182:185], v[60:63]
	v_mfma_f32_16x16x32_bf16 v[52:55], v[158:161], v[182:185], v[52:55]
	v_mfma_f32_16x16x32_bf16 v[44:47], v[150:153], v[194:197], v[44:47]
	v_mfma_f32_16x16x32_bf16 v[36:39], v[158:161], v[194:197], v[36:39]
	v_mfma_f32_16x16x32_bf16 v[28:31], v[150:153], v[202:205], v[28:31]
	v_mfma_f32_16x16x32_bf16 v[20:23], v[158:161], v[202:205], v[20:23]
	v_mfma_f32_16x16x32_bf16 v[12:15], v[150:153], v[210:213], v[12:15]
	v_mfma_f32_16x16x32_bf16 v[4:7], v[158:161], v[210:213], v[4:7]
	v_mfma_f32_16x16x32_bf16 v[60:63], v[154:157], v[190:193], v[60:63]
	v_mfma_f32_16x16x32_bf16 v[52:55], v[162:165], v[190:193], v[52:55]
	v_mfma_f32_16x16x32_bf16 v[44:47], v[154:157], v[198:201], v[44:47]
	v_mfma_f32_16x16x32_bf16 v[36:39], v[162:165], v[198:201], v[36:39]
	v_mfma_f32_16x16x32_bf16 v[28:31], v[154:157], v[206:209], v[28:31]
	v_mfma_f32_16x16x32_bf16 v[20:23], v[162:165], v[206:209], v[20:23]
	v_mfma_f32_16x16x32_bf16 v[12:15], v[154:157], v[214:217], v[12:15]
	v_mfma_f32_16x16x32_bf16 v[4:7], v[162:165], v[214:217], v[4:7]
	v_mfma_f32_16x16x32_bf16 v[56:59], v[166:169], v[182:185], v[56:59]
	v_mfma_f32_16x16x32_bf16 v[48:51], v[174:177], v[182:185], v[48:51]
	v_mfma_f32_16x16x32_bf16 v[40:43], v[166:169], v[194:197], v[40:43]
	v_mfma_f32_16x16x32_bf16 v[32:35], v[174:177], v[194:197], v[32:35]
	v_mfma_f32_16x16x32_bf16 v[24:27], v[166:169], v[202:205], v[24:27]
	v_mfma_f32_16x16x32_bf16 v[16:19], v[174:177], v[202:205], v[16:19]
	v_mfma_f32_16x16x32_bf16 v[8:11], v[166:169], v[210:213], v[8:11]
	v_mfma_f32_16x16x32_bf16 v[0:3], v[174:177], v[210:213], v[0:3]
	v_mfma_f32_16x16x32_bf16 v[56:59], v[170:173], v[190:193], v[56:59]
	v_mfma_f32_16x16x32_bf16 v[48:51], v[178:181], v[190:193], v[48:51]
	v_mfma_f32_16x16x32_bf16 v[40:43], v[170:173], v[198:201], v[40:43]
	v_mfma_f32_16x16x32_bf16 v[32:35], v[178:181], v[198:201], v[32:35]
	v_mfma_f32_16x16x32_bf16 v[24:27], v[170:173], v[206:209], v[24:27]
	v_mfma_f32_16x16x32_bf16 v[16:19], v[178:181], v[206:209], v[16:19]
	v_mfma_f32_16x16x32_bf16 v[8:11], v[170:173], v[214:217], v[8:11]
	v_mfma_f32_16x16x32_bf16 v[0:3], v[178:181], v[214:217], v[0:3]
	s_setprio 0
	s_barrier
; #define PG8_STAGE(bufoff, gbase, voff) do { _Pragma("unroll") for (int _i = 0; _i < 2; ++_i) \
;         __builtin_amdgcn_global_load_lds((const unsigned*)((const char*)(gbase) + (voff)[_i]), (PG8_LAS unsigned*)(lds + (bufoff) + ldsw + _i * 8192), 16, 0, 0); } while (0)
; #define PG8_LDA(dst, b, h) do { _Pragma("unroll") for (int m = 0; m < 4; ++m) _Pragma("unroll") for (int k = 0; k < 2; ++k) dst[m][k] = *(const PG8_LAS bf16x8*)(lds + PG8_SA(b, h) + aoff + m * 2048 + k * 1024); } while (0)
; #define PG8_LDB(dst, b, h) do { _Pragma("unroll") for (int n = 0; n < 2; ++n) _Pragma("unroll") for (int k = 0; k < 2; ++k) dst[n][k] = *(const PG8_LAS bf16x8*)(lds + PG8_SB(b, h) + boff + n * 2048 + k * 1024); } while (0)
; #define PG8_MMA(ai, bj, At, Bt) do { __builtin_amdgcn_s_setprio(1); _Pragma("unroll") for (int m = 0; m < 4; ++m) _Pragma("unroll") for (int n = 0; n < 2; ++n) _Pragma("unroll") for (int k = 0; k < 2; ++k) \
;         acc[ai][bj][m][n] = __builtin_amdgcn_mfma_f32_16x16x32_bf16(Bt[n][k], At[m][k], acc[ai][bj][m][n], 0, 0, 0); __builtin_amdgcn_s_setprio(0); } while (0)
; #define PG8_WAIT_V(n) asm volatile("s_waitcnt vmcnt(" #n ")" ::: "memory")
; #define PG8_WAIT_L(n) asm volatile("s_waitcnt lgkmcnt(" #n ")" ::: "memory")
; #define PG8_BAR __builtin_amdgcn_s_barrier()
; #define PG8_SCHED __builtin_amdgcn_sched_barrier(0)
; template <class Epi, class Sched, bool ALIGN_EPI = false, bool SP2 = false>
; __device__ __forceinline__ void gemm_phase(PG8_LAS unsigned char* lds, const Gemm g, const Sched& S, const Epi& E) {
;     ...
;             PG8_LDB(B0, 1, 0); PG8_LDB(B1, 1, 1); PG8_SCHED; PG8_LDA(At, 1, 0); PG8_STAGE(PG8_SA(0, 1), a2 + hstepA, voffA);
;             PG8_WAIT_V(8); PG8_WAIT_L(0); PG8_BAR; PG8_MMA(0, 0, At, B0); PG8_MMA(0, 1, At, B1); PG8_BAR; PG8_SCHED;
;             PG8_LDA(At, 1, 1); PG8_STAGE(PG8_SB(1, 0), b3, voffB); PG8_STAGE(PG8_SB(1, 1), b3 + hstep, voffB); PG8_STAGE(PG8_SA(1, 0), a3, voffA);
;             PG8_WAIT_V(8); PG8_WAIT_L(0); PG8_BAR; PG8_MMA(1, 0, At, B0); PG8_MMA(1, 1, At, B1); PG8_BAR; PG8_SCHED;
	s_add_i32 s59, 0, 0x18000
	s_add_i32 s60, 0, 0x1c000
	v_add_u32_e32 v162, s59, v145
	v_add_u32_e32 v178, s60, v145
	ds_read_b128 v[150:153], v162
	ds_read_b128 v[154:157], v162 offset:1024
	ds_read_b128 v[158:161], v162 offset:2048
	ds_read_b128 v[162:165], v162 offset:3072
	ds_read_b128 v[166:169], v178
	ds_read_b128 v[170:173], v178 offset:1024
	ds_read_b128 v[174:177], v178 offset:2048
	ds_read_b128 v[178:181], v178 offset:3072
	s_mov_b64 vcc, s[30:31]
	s_add_u32 s30, s30, 0x40000
	s_addc_u32 s31, s31, 0
	s_mov_b32 m0, s42
	ds_read_b128 v[182:185], v149 offset:32768
	ds_read_b128 v[190:193], v149 offset:33792
	ds_read_b128 v[194:197], v149 offset:34816
	ds_read_b128 v[198:201], v149 offset:35840
	ds_read_b128 v[202:205], v149 offset:36864
	ds_read_b128 v[206:209], v149 offset:37888
	ds_read_b128 v[210:213], v149 offset:38912
	global_load_lds_dwordx4 v128, s[30:31]
	s_mov_b32 m0, s43
	ds_read_b128 v[214:217], v149 offset:39936
	global_load_lds_dwordx4 v130, s[30:31]
	s_waitcnt vmcnt(8) lgkmcnt(0)
	s_setprio 1
	s_barrier
	v_mfma_f32_16x16x32_bf16 v[124:127], v[150:153], v[182:185], v[124:127]
	v_mfma_f32_16x16x32_bf16 v[116:119], v[158:161], v[182:185], v[116:119]
	v_mfma_f32_16x16x32_bf16 v[108:111], v[150:153], v[194:197], v[108:111]
	v_mfma_f32_16x16x32_bf16 v[100:103], v[158:161], v[194:197], v[100:103]
	v_mfma_f32_16x16x32_bf16 v[92:95], v[150:153], v[202:205], v[92:95]
	v_mfma_f32_16x16x32_bf16 v[84:87], v[158:161], v[202:205], v[84:87]
	v_mfma_f32_16x16x32_bf16 v[76:79], v[150:153], v[210:213], v[76:79]
	v_mfma_f32_16x16x32_bf16 v[68:71], v[158:161], v[210:213], v[68:71]
	v_mfma_f32_16x16x32_bf16 v[124:127], v[154:157], v[190:193], v[124:127]
	v_mfma_f32_16x16x32_bf16 v[116:119], v[162:165], v[190:193], v[116:119]
	v_mfma_f32_16x16x32_bf16 v[108:111], v[154:157], v[198:201], v[108:111]
	v_mfma_f32_16x16x32_bf16 v[100:103], v[162:165], v[198:201], v[100:103]
	v_mfma_f32_16x16x32_bf16 v[92:95], v[154:157], v[206:209], v[92:95]
	v_mfma_f32_16x16x32_bf16 v[84:87], v[162:165], v[206:209], v[84:87]
	v_mfma_f32_16x16x32_bf16 v[76:79], v[154:157], v[214:217], v[76:79]
	v_mfma_f32_16x16x32_bf16 v[68:71], v[162:165], v[214:217], v[68:71]
	v_mfma_f32_16x16x32_bf16 v[120:123], v[166:169], v[182:185], v[120:123]
	v_mfma_f32_16x16x32_bf16 v[112:115], v[174:177], v[182:185], v[112:115]
	v_mfma_f32_16x16x32_bf16 v[104:107], v[166:169], v[194:197], v[104:107]
	v_mfma_f32_16x16x32_bf16 v[96:99], v[174:177], v[194:197], v[96:99]
	v_mfma_f32_16x16x32_bf16 v[88:91], v[166:169], v[202:205], v[88:91]
	v_mfma_f32_16x16x32_bf16 v[80:83], v[174:177], v[202:205], v[80:83]
	v_mfma_f32_16x16x32_bf16 v[72:75], v[166:169], v[210:213], v[72:75]
	v_mfma_f32_16x16x32_bf16 v[64:67], v[174:177], v[210:213], v[64:67]
	v_mfma_f32_16x16x32_bf16 v[120:123], v[170:173], v[190:193], v[120:123]
	v_mfma_f32_16x16x32_bf16 v[112:115], v[178:181], v[190:193], v[112:115]
	v_mfma_f32_16x16x32_bf16 v[104:107], v[170:173], v[198:201], v[104:107]
	v_mfma_f32_16x16x32_bf16 v[96:99], v[178:181], v[198:201], v[96:99]
	v_mfma_f32_16x16x32_bf16 v[88:91], v[170:173], v[206:209], v[88:91]
	v_mfma_f32_16x16x32_bf16 v[80:83], v[178:181], v[206:209], v[80:83]
	v_mfma_f32_16x16x32_bf16 v[72:75], v[170:173], v[214:217], v[72:75]
	v_mfma_f32_16x16x32_bf16 v[64:67], v[178:181], v[214:217], v[64:67]
	s_setprio 0
	s_barrier
	s_add_i32 s30, s59, s38
	s_add_i32 m0, s30, 0xffffff80
	ds_read_b128 v[182:185], v149 offset:49152
	ds_read_b128 v[190:193], v149 offset:50176
	ds_read_b128 v[194:197], v149 offset:51200
	ds_read_b128 v[198:201], v149 offset:52224
	global_load_lds_dwordx4 v134, s[100:101] offset:128
	s_add_i32 m0, s30, 0x1f80
	s_add_i32 s30, s60, s38
	global_load_lds_dwordx4 v132, s[100:101] offset:128
	s_add_u32 s100, s100, s4
	s_addc_u32 s101, s101, s5
	s_add_i32 m0, s30, 0xffffff80
	ds_read_b128 v[214:217], v149 offset:56320
	global_load_lds_dwordx4 v134, s[100:101] offset:128
	s_add_i32 m0, s30, 0x1f80
	ds_read_b128 v[210:213], v149 offset:55296
	global_load_lds_dwordx4 v132, s[100:101] offset:128
	s_add_i32 m0, s47, 0xffffff80
	ds_read_b128 v[206:209], v149 offset:54272
	global_load_lds_dwordx4 v128, vcc offset:128
	s_add_i32 m0, s48, 0xffffff80
	ds_read_b128 v[202:205], v149 offset:53248
	global_load_lds_dwordx4 v130, vcc offset:128
	s_waitcnt vmcnt(8) lgkmcnt(0)
	s_setprio 1
	s_barrier
	v_mfma_f32_16x16x32_bf16 v[60:63], v[150:153], v[182:185], v[60:63]
	v_mfma_f32_16x16x32_bf16 v[52:55], v[158:161], v[182:185], v[52:55]
	v_mfma_f32_16x16x32_bf16 v[44:47], v[150:153], v[194:197], v[44:47]
	v_mfma_f32_16x16x32_bf16 v[36:39], v[158:161], v[194:197], v[36:39]
	v_mfma_f32_16x16x32_bf16 v[28:31], v[150:153], v[202:205], v[28:31]
	v_mfma_f32_16x16x32_bf16 v[20:23], v[158:161], v[202:205], v[20:23]
	v_mfma_f32_16x16x32_bf16 v[12:15], v[150:153], v[210:213], v[12:15]
	v_mfma_f32_16x16x32_bf16 v[4:7], v[158:161], v[210:213], v[4:7]
	v_mfma_f32_16x16x32_bf16 v[60:63], v[154:157], v[190:193], v[60:63]
	v_mfma_f32_16x16x32_bf16 v[52:55], v[162:165], v[190:193], v[52:55]
	v_mfma_f32_16x16x32_bf16 v[44:47], v[154:157], v[198:201], v[44:47]
	v_mfma_f32_16x16x32_bf16 v[36:39], v[162:165], v[198:201], v[36:39]
	v_mfma_f32_16x16x32_bf16 v[28:31], v[154:157], v[206:209], v[28:31]
	v_mfma_f32_16x16x32_bf16 v[20:23], v[162:165], v[206:209], v[20:23]
	v_mfma_f32_16x16x32_bf16 v[12:15], v[154:157], v[214:217], v[12:15]
	v_mfma_f32_16x16x32_bf16 v[4:7], v[162:165], v[214:217], v[4:7]
	v_mfma_f32_16x16x32_bf16 v[56:59], v[166:169], v[182:185], v[56:59]
	v_mfma_f32_16x16x32_bf16 v[48:51], v[174:177], v[182:185], v[48:51]
	v_mfma_f32_16x16x32_bf16 v[40:43], v[166:169], v[194:197], v[40:43]
	v_mfma_f32_16x16x32_bf16 v[32:35], v[174:177], v[194:197], v[32:35]
	v_mfma_f32_16x16x32_bf16 v[24:27], v[166:169], v[202:205], v[24:27]
	v_mfma_f32_16x16x32_bf16 v[16:19], v[174:177], v[202:205], v[16:19]
	v_mfma_f32_16x16x32_bf16 v[8:11], v[166:169], v[210:213], v[8:11]
	v_mfma_f32_16x16x32_bf16 v[0:3], v[174:177], v[210:213], v[0:3]
	v_mfma_f32_16x16x32_bf16 v[56:59], v[170:173], v[190:193], v[56:59]
	v_mfma_f32_16x16x32_bf16 v[48:51], v[178:181], v[190:193], v[48:51]
	v_mfma_f32_16x16x32_bf16 v[40:43], v[170:173], v[198:201], v[40:43]
	v_mfma_f32_16x16x32_bf16 v[32:35], v[178:181], v[198:201], v[32:35]
	v_mfma_f32_16x16x32_bf16 v[24:27], v[170:173], v[206:209], v[24:27]
	v_mfma_f32_16x16x32_bf16 v[16:19], v[178:181], v[206:209], v[16:19]
	v_mfma_f32_16x16x32_bf16 v[8:11], v[170:173], v[214:217], v[8:11]
	v_mfma_f32_16x16x32_bf16 v[0:3], v[178:181], v[214:217], v[0:3]
	s_setprio 0
	s_barrier
	s_add_u32 s10, s10, 0x100
	s_addc_u32 s11, s11, 0
	s_add_u32 s34, s34, 0x100
	s_addc_u32 s35, s35, 0
	s_cmp_ge_i32 s58, s50
	s_mov_b32 s30, s58
	s_cbranch_scc0 .LBB0_898

; #define PG8_STAGE(bufoff, gbase, voff) do { _Pragma("unroll") for (int _i = 0; _i < 2; ++_i) \
;         __builtin_amdgcn_global_load_lds((const unsigned*)((const char*)(gbase) + (voff)[_i]), (PG8_LAS unsigned*)(lds + (bufoff) + ldsw + _i * 8192), 16, 0, 0); } while (0)
; #define PG8_LDA(dst, b, h) do { _Pragma("unroll") for (int m = 0; m < 4; ++m) _Pragma("unroll") for (int k = 0; k < 2; ++k) dst[m][k] = *(const PG8_LAS bf16x8*)(lds + PG8_SA(b, h) + aoff + m * 2048 + k * 1024); } while (0)
; #define PG8_LDB(dst, b, h) do { _Pragma("unroll") for (int n = 0; n < 2; ++n) _Pragma("unroll") for (int k = 0; k < 2; ++k) dst[n][k] = *(const PG8_LAS bf16x8*)(lds + PG8_SB(b, h) + boff + n * 2048 + k * 1024); } while (0)
; #define PG8_MMA(ai, bj, At, Bt) do { __builtin_amdgcn_s_setprio(1); _Pragma("unroll") for (int m = 0; m < 4; ++m) _Pragma("unroll") for (int n = 0; n < 2; ++n) _Pragma("unroll") for (int k = 0; k < 2; ++k) \
;         acc[ai][bj][m][n] = __builtin_amdgcn_mfma_f32_16x16x32_bf16(Bt[n][k], At[m][k], acc[ai][bj][m][n], 0, 0, 0); __builtin_amdgcn_s_setprio(0); } while (0)
; #define PG8_WAIT_V(n) asm volatile("s_waitcnt vmcnt(" #n ")" ::: "memory")
; #define PG8_WAIT_L(n) asm volatile("s_waitcnt lgkmcnt(" #n ")" ::: "memory")
; template <class Epi, class Sched, bool ALIGN_EPI = false, bool SP2 = false>
; __device__ __forceinline__ void gemm_phase(PG8_LAS unsigned char* lds, const Gemm g, const Sched& S, const Epi& E) {
;     ...
;             const bool last = (t == nt - 2);
;             const char* a1 = cA + (size_t)(t + 1) * kstep;
;             const char* a2 = last ? nA : cA + (size_t)(t + 2) * kstep; const char* b2 = last ? nB : cB + (size_t)(t + 2) * kstep;
;             const char* a3 = a2 + kstep; const char* b3 = b2 + kstep;
;             if (last && has_next) S.a_ready(nxt);
;             if constexpr (SP2) {
;             PG8_LDB(B0, 0, 0); PG8_LDB(B1, 0, 1); PG8_SCHED; PG8_LDA(At, 0, 0); PG8_STAGE(PG8_SA(1, 1), a1 + hstepA, voffA);
;             PG8_WAIT_V(8); PG8_WAIT_L(0); PG8_BAR; PG8_MMA(0, 0, At, B0); PG8_MMA(0, 1, At, B1); PG8_BAR; PG8_SCHED;
;             PG8_LDA(At, 0, 1); PG8_STAGE(PG8_SB(0, 0), b2, voffB); PG8_STAGE(PG8_SB(0, 1), b2 + hstep, voffB); PG8_STAGE(PG8_SA(0, 0), a2, voffA);
;             PG8_WAIT_V(8); PG8_WAIT_L(0); PG8_BAR; PG8_MMA(1, 0, At, B0); PG8_MMA(1, 1, At, B1); PG8_BAR; PG8_SCHED;
.LBB0_980:
	ds_read_b128 v[128:131], v169
	ds_read_b128 v[132:135], v169 offset:1024
	ds_read_b128 v[136:139], v169 offset:2048
	ds_read_b128 v[140:143], v169 offset:3072
	ds_read_b128 v[160:163], v170
	ds_read_b128 v[172:175], v170 offset:1024
	ds_read_b128 v[176:179], v170 offset:2048
	ds_read_b128 v[180:183], v170 offset:3072
	s_add_i32 s69, s38, 2
	s_add_u32 s70, s36, 0xfff50080
	s_addc_u32 s39, s37, -1
	s_cmp_eq_u32 s55, s38
	s_cselect_b32 s38, s8, s70
	s_cselect_b32 s39, s9, s39
	s_cselect_b32 s71, s35, s68
	s_cselect_b32 s70, s34, s67
	s_add_i32 m0, s44, 0xc000
	ds_read_b128 v[184:187], v171
	ds_read_b128 v[190:193], v171 offset:1024
	ds_read_b128 v[194:197], v171 offset:2048
	ds_read_b128 v[198:201], v171 offset:3072
	ds_read_b128 v[202:205], v171 offset:4096
	ds_read_b128 v[206:209], v171 offset:5120
	ds_read_b128 v[210:213], v171 offset:6144
	global_load_lds_dwordx4 v152, s[36:37]
	s_add_i32 m0, s44, 0xe000
	ds_read_b128 v[214:217], v171 offset:7168
	global_load_lds_dwordx4 v154, s[36:37]
	s_waitcnt vmcnt(8) lgkmcnt(0)
	s_setprio 1
	s_barrier
	v_mfma_f32_16x16x32_bf16 v[124:127], v[128:131], v[184:187], v[124:127]
	v_mfma_f32_16x16x32_bf16 v[120:123], v[136:139], v[184:187], v[120:123]
	v_mfma_f32_16x16x32_bf16 v[108:111], v[128:131], v[194:197], v[108:111]
	v_mfma_f32_16x16x32_bf16 v[104:107], v[136:139], v[194:197], v[104:107]
	v_mfma_f32_16x16x32_bf16 v[92:95], v[128:131], v[202:205], v[92:95]
	v_mfma_f32_16x16x32_bf16 v[88:91], v[136:139], v[202:205], v[88:91]
	v_mfma_f32_16x16x32_bf16 v[76:79], v[128:131], v[210:213], v[76:79]
	v_mfma_f32_16x16x32_bf16 v[72:75], v[136:139], v[210:213], v[72:75]
	v_mfma_f32_16x16x32_bf16 v[124:127], v[132:135], v[190:193], v[124:127]
	v_mfma_f32_16x16x32_bf16 v[120:123], v[140:143], v[190:193], v[120:123]
	v_mfma_f32_16x16x32_bf16 v[108:111], v[132:135], v[198:201], v[108:111]
	v_mfma_f32_16x16x32_bf16 v[104:107], v[140:143], v[198:201], v[104:107]
	v_mfma_f32_16x16x32_bf16 v[92:95], v[132:135], v[206:209], v[92:95]
	v_mfma_f32_16x16x32_bf16 v[88:91], v[140:143], v[206:209], v[88:91]
	v_mfma_f32_16x16x32_bf16 v[76:79], v[132:135], v[214:217], v[76:79]
	v_mfma_f32_16x16x32_bf16 v[72:75], v[140:143], v[214:217], v[72:75]
	v_mfma_f32_16x16x32_bf16 v[116:119], v[160:163], v[184:187], v[116:119]
	v_mfma_f32_16x16x32_bf16 v[112:115], v[176:179], v[184:187], v[112:115]
	v_mfma_f32_16x16x32_bf16 v[100:103], v[160:163], v[194:197], v[100:103]
	v_mfma_f32_16x16x32_bf16 v[96:99], v[176:179], v[194:197], v[96:99]
	v_mfma_f32_16x16x32_bf16 v[84:87], v[160:163], v[202:205], v[84:87]
	v_mfma_f32_16x16x32_bf16 v[80:83], v[176:179], v[202:205], v[80:83]
	v_mfma_f32_16x16x32_bf16 v[68:71], v[160:163], v[210:213], v[68:71]
	v_mfma_f32_16x16x32_bf16 v[64:67], v[176:179], v[210:213], v[64:67]
	v_mfma_f32_16x16x32_bf16 v[116:119], v[172:175], v[190:193], v[116:119]
	v_mfma_f32_16x16x32_bf16 v[112:115], v[180:183], v[190:193], v[112:115]
	v_mfma_f32_16x16x32_bf16 v[100:103], v[172:175], v[198:201], v[100:103]
	v_mfma_f32_16x16x32_bf16 v[96:99], v[180:183], v[198:201], v[96:99]
	v_mfma_f32_16x16x32_bf16 v[84:87], v[172:175], v[206:209], v[84:87]
	v_mfma_f32_16x16x32_bf16 v[80:83], v[180:183], v[206:209], v[80:83]
	v_mfma_f32_16x16x32_bf16 v[68:71], v[172:175], v[214:217], v[68:71]
	v_mfma_f32_16x16x32_bf16 v[64:67], v[180:183], v[214:217], v[64:67]
	s_setprio 0
	s_barrier
	s_add_i32 s72, s56, s42
	s_mov_b32 m0, s72
	ds_read_b128 v[184:187], v171 offset:16384
	ds_read_b128 v[190:193], v171 offset:17408
	ds_read_b128 v[194:197], v171 offset:18432
	ds_read_b128 v[198:201], v171 offset:19456
	global_load_lds_dwordx4 v150, s[70:71]
	s_add_i32 m0, s72, 0x2000
	s_mov_b64 s[100:101], s[70:71]
	s_add_i32 s72, s57, s42
	global_load_lds_dwordx4 v148, s[70:71]
	s_add_u32 s70, s70, s4
	s_addc_u32 s71, s71, s5
	s_mov_b32 m0, s72
	ds_read_b128 v[214:217], v171 offset:23552
	global_load_lds_dwordx4 v150, s[70:71]
	s_add_i32 m0, s72, 0x2000
	ds_read_b128 v[210:213], v171 offset:22528
	global_load_lds_dwordx4 v148, s[70:71]
	s_mov_b32 m0, s44
	ds_read_b128 v[206:209], v171 offset:21504
	global_load_lds_dwordx4 v144, s[38:39]
	s_mov_b32 m0, s45
	ds_read_b128 v[202:205], v171 offset:20480
	global_load_lds_dwordx4 v146, s[38:39]
	s_waitcnt vmcnt(8) lgkmcnt(0)
	s_setprio 1
	s_barrier
	v_mfma_f32_16x16x32_bf16 v[60:63], v[128:131], v[184:187], v[60:63]
	v_mfma_f32_16x16x32_bf16 v[56:59], v[136:139], v[184:187], v[56:59]
	v_mfma_f32_16x16x32_bf16 v[44:47], v[128:131], v[194:197], v[44:47]
	v_mfma_f32_16x16x32_bf16 v[40:43], v[136:139], v[194:197], v[40:43]
	v_mfma_f32_16x16x32_bf16 v[28:31], v[128:131], v[202:205], v[28:31]
	v_mfma_f32_16x16x32_bf16 v[24:27], v[136:139], v[202:205], v[24:27]
	v_mfma_f32_16x16x32_bf16 v[12:15], v[128:131], v[210:213], v[12:15]
	v_mfma_f32_16x16x32_bf16 v[8:11], v[136:139], v[210:213], v[8:11]
	v_mfma_f32_16x16x32_bf16 v[60:63], v[132:135], v[190:193], v[60:63]
	v_mfma_f32_16x16x32_bf16 v[56:59], v[140:143], v[190:193], v[56:59]
	v_mfma_f32_16x16x32_bf16 v[44:47], v[132:135], v[198:201], v[44:47]
	v_mfma_f32_16x16x32_bf16 v[40:43], v[140:143], v[198:201], v[40:43]
	v_mfma_f32_16x16x32_bf16 v[28:31], v[132:135], v[206:209], v[28:31]
	v_mfma_f32_16x16x32_bf16 v[24:27], v[140:143], v[206:209], v[24:27]
	v_mfma_f32_16x16x32_bf16 v[12:15], v[132:135], v[214:217], v[12:15]
	v_mfma_f32_16x16x32_bf16 v[8:11], v[140:143], v[214:217], v[8:11]
	v_mfma_f32_16x16x32_bf16 v[52:55], v[160:163], v[184:187], v[52:55]
	v_mfma_f32_16x16x32_bf16 v[48:51], v[176:179], v[184:187], v[48:51]
	v_mfma_f32_16x16x32_bf16 v[36:39], v[160:163], v[194:197], v[36:39]
	v_mfma_f32_16x16x32_bf16 v[32:35], v[176:179], v[194:197], v[32:35]
	v_mfma_f32_16x16x32_bf16 v[20:23], v[160:163], v[202:205], v[20:23]
	v_mfma_f32_16x16x32_bf16 v[16:19], v[176:179], v[202:205], v[16:19]
	v_mfma_f32_16x16x32_bf16 v[4:7], v[160:163], v[210:213], v[4:7]
	v_mfma_f32_16x16x32_bf16 v[0:3], v[176:179], v[210:213], v[0:3]
	v_mfma_f32_16x16x32_bf16 v[52:55], v[172:175], v[190:193], v[52:55]
	v_mfma_f32_16x16x32_bf16 v[48:51], v[180:183], v[190:193], v[48:51]
	v_mfma_f32_16x16x32_bf16 v[36:39], v[172:175], v[198:201], v[36:39]
	v_mfma_f32_16x16x32_bf16 v[32:35], v[180:183], v[198:201], v[32:35]
	v_mfma_f32_16x16x32_bf16 v[20:23], v[172:175], v[206:209], v[20:23]
	v_mfma_f32_16x16x32_bf16 v[16:19], v[180:183], v[206:209], v[16:19]
	v_mfma_f32_16x16x32_bf16 v[4:7], v[172:175], v[214:217], v[4:7]
	v_mfma_f32_16x16x32_bf16 v[0:3], v[180:183], v[214:217], v[0:3]
	s_setprio 0
	s_barrier
; #define PG8_STAGE(bufoff, gbase, voff) do { _Pragma("unroll") for (int _i = 0; _i < 2; ++_i) \
;         __builtin_amdgcn_global_load_lds((const unsigned*)((const char*)(gbase) + (voff)[_i]), (PG8_LAS unsigned*)(lds + (bufoff) + ldsw + _i * 8192), 16, 0, 0); } while (0)
; #define PG8_LDA(dst, b, h) do { _Pragma("unroll") for (int m = 0; m < 4; ++m) _Pragma("unroll") for (int k = 0; k < 2; ++k) dst[m][k] = *(const PG8_LAS bf16x8*)(lds + PG8_SA(b, h) + aoff + m * 2048 + k * 1024); } while (0)
; #define PG8_LDB(dst, b, h) do { _Pragma("unroll") for (int n = 0; n < 2; ++n) _Pragma("unroll") for (int k = 0; k < 2; ++k) dst[n][k] = *(const PG8_LAS bf16x8*)(lds + PG8_SB(b, h) + boff + n * 2048 + k * 1024); } while (0)
; #define PG8_MMA(ai, bj, At, Bt) do { __builtin_amdgcn_s_setprio(1); _Pragma("unroll") for (int m = 0; m < 4; ++m) _Pragma("unroll") for (int n = 0; n < 2; ++n) _Pragma("unroll") for (int k = 0; k < 2; ++k) \
;         acc[ai][bj][m][n] = __builtin_amdgcn_mfma_f32_16x16x32_bf16(Bt[n][k], At[m][k], acc[ai][bj][m][n], 0, 0, 0); __builtin_amdgcn_s_setprio(0); } while (0)
; #define PG8_WAIT_V(n) asm volatile("s_waitcnt vmcnt(" #n ")" ::: "memory")
; #define PG8_WAIT_L(n) asm volatile("s_waitcnt lgkmcnt(" #n ")" ::: "memory")
; #define PG8_BAR __builtin_amdgcn_s_barrier()
; #define PG8_SCHED __builtin_amdgcn_sched_barrier(0)
; template <class Epi, class Sched, bool ALIGN_EPI = false, bool SP2 = false>
; __device__ __forceinline__ void gemm_phase(PG8_LAS unsigned char* lds, const Gemm g, const Sched& S, const Epi& E) {
;     ...
;             PG8_LDB(B0, 1, 0); PG8_LDB(B1, 1, 1); PG8_SCHED; PG8_LDA(At, 1, 0); PG8_STAGE(PG8_SA(0, 1), a2 + hstepA, voffA);
;             PG8_WAIT_V(8); PG8_WAIT_L(0); PG8_BAR; PG8_MMA(0, 0, At, B0); PG8_MMA(0, 1, At, B1); PG8_BAR; PG8_SCHED;
;             PG8_LDA(At, 1, 1); PG8_STAGE(PG8_SB(1, 0), b3, voffB); PG8_STAGE(PG8_SB(1, 1), b3 + hstep, voffB); PG8_STAGE(PG8_SA(1, 0), a3, voffA);
;             PG8_WAIT_V(8); PG8_WAIT_L(0); PG8_BAR; PG8_MMA(1, 0, At, B0); PG8_MMA(1, 1, At, B1); PG8_BAR; PG8_SCHED;
	s_add_i32 s70, 0, 0x18000
	s_add_i32 s71, 0, 0x1c000
	v_add_u32_e32 v140, s70, v167
	v_add_u32_e32 v180, s71, v167
	ds_read_b128 v[128:131], v140
	ds_read_b128 v[132:135], v140 offset:1024
	ds_read_b128 v[136:139], v140 offset:2048
	ds_read_b128 v[140:143], v140 offset:3072
	ds_read_b128 v[160:163], v180
	ds_read_b128 v[172:175], v180 offset:1024
	ds_read_b128 v[176:179], v180 offset:2048
	ds_read_b128 v[180:183], v180 offset:3072
	s_mov_b64 vcc, s[38:39]
	s_add_u32 s38, s38, 0xb0000
	s_addc_u32 s39, s39, 0
	s_mov_b32 m0, s47
	ds_read_b128 v[184:187], v171 offset:32768
	ds_read_b128 v[190:193], v171 offset:33792
	ds_read_b128 v[194:197], v171 offset:34816
	ds_read_b128 v[198:201], v171 offset:35840
	ds_read_b128 v[202:205], v171 offset:36864
	ds_read_b128 v[206:209], v171 offset:37888
	ds_read_b128 v[210:213], v171 offset:38912
	global_load_lds_dwordx4 v144, s[38:39]
	s_mov_b32 m0, s48
	ds_read_b128 v[214:217], v171 offset:39936
	global_load_lds_dwordx4 v146, s[38:39]
	s_waitcnt vmcnt(8) lgkmcnt(0)
	s_setprio 1
	s_barrier
	v_mfma_f32_16x16x32_bf16 v[124:127], v[128:131], v[184:187], v[124:127]
	v_mfma_f32_16x16x32_bf16 v[120:123], v[136:139], v[184:187], v[120:123]
	v_mfma_f32_16x16x32_bf16 v[108:111], v[128:131], v[194:197], v[108:111]
	v_mfma_f32_16x16x32_bf16 v[104:107], v[136:139], v[194:197], v[104:107]
	v_mfma_f32_16x16x32_bf16 v[92:95], v[128:131], v[202:205], v[92:95]
	v_mfma_f32_16x16x32_bf16 v[88:91], v[136:139], v[202:205], v[88:91]
	v_mfma_f32_16x16x32_bf16 v[76:79], v[128:131], v[210:213], v[76:79]
	v_mfma_f32_16x16x32_bf16 v[72:75], v[136:139], v[210:213], v[72:75]
	v_mfma_f32_16x16x32_bf16 v[124:127], v[132:135], v[190:193], v[124:127]
	v_mfma_f32_16x16x32_bf16 v[120:123], v[140:143], v[190:193], v[120:123]
	v_mfma_f32_16x16x32_bf16 v[108:111], v[132:135], v[198:201], v[108:111]
	v_mfma_f32_16x16x32_bf16 v[104:107], v[140:143], v[198:201], v[104:107]
	v_mfma_f32_16x16x32_bf16 v[92:95], v[132:135], v[206:209], v[92:95]
	v_mfma_f32_16x16x32_bf16 v[88:91], v[140:143], v[206:209], v[88:91]
	v_mfma_f32_16x16x32_bf16 v[76:79], v[132:135], v[214:217], v[76:79]
	v_mfma_f32_16x16x32_bf16 v[72:75], v[140:143], v[214:217], v[72:75]
	v_mfma_f32_16x16x32_bf16 v[116:119], v[160:163], v[184:187], v[116:119]
	v_mfma_f32_16x16x32_bf16 v[112:115], v[176:179], v[184:187], v[112:115]
	v_mfma_f32_16x16x32_bf16 v[100:103], v[160:163], v[194:197], v[100:103]
	v_mfma_f32_16x16x32_bf16 v[96:99], v[176:179], v[194:197], v[96:99]
	v_mfma_f32_16x16x32_bf16 v[84:87], v[160:163], v[202:205], v[84:87]
	v_mfma_f32_16x16x32_bf16 v[80:83], v[176:179], v[202:205], v[80:83]
	v_mfma_f32_16x16x32_bf16 v[68:71], v[160:163], v[210:213], v[68:71]
	v_mfma_f32_16x16x32_bf16 v[64:67], v[176:179], v[210:213], v[64:67]
	v_mfma_f32_16x16x32_bf16 v[116:119], v[172:175], v[190:193], v[116:119]
	v_mfma_f32_16x16x32_bf16 v[112:115], v[180:183], v[190:193], v[112:115]
	v_mfma_f32_16x16x32_bf16 v[100:103], v[172:175], v[198:201], v[100:103]
	v_mfma_f32_16x16x32_bf16 v[96:99], v[180:183], v[198:201], v[96:99]
	v_mfma_f32_16x16x32_bf16 v[84:87], v[172:175], v[206:209], v[84:87]
	v_mfma_f32_16x16x32_bf16 v[80:83], v[180:183], v[206:209], v[80:83]
	v_mfma_f32_16x16x32_bf16 v[68:71], v[172:175], v[214:217], v[68:71]
	v_mfma_f32_16x16x32_bf16 v[64:67], v[180:183], v[214:217], v[64:67]
	s_setprio 0
	s_barrier
	s_add_i32 s38, s70, s42
	s_add_i32 m0, s38, 0xffffff80
	ds_read_b128 v[184:187], v171 offset:49152
	ds_read_b128 v[190:193], v171 offset:50176
	ds_read_b128 v[194:197], v171 offset:51200
	ds_read_b128 v[198:201], v171 offset:52224
	global_load_lds_dwordx4 v150, s[100:101] offset:128
	s_add_i32 m0, s38, 0x1f80
	s_add_i32 s38, s71, s42
	global_load_lds_dwordx4 v148, s[100:101] offset:128
	s_add_u32 s100, s100, s4
	s_addc_u32 s101, s101, s5
	s_add_i32 m0, s38, 0xffffff80
	ds_read_b128 v[214:217], v171 offset:56320
	global_load_lds_dwordx4 v150, s[100:101] offset:128
	s_add_i32 m0, s38, 0x1f80
	ds_read_b128 v[210:213], v171 offset:55296
	global_load_lds_dwordx4 v148, s[100:101] offset:128
	s_add_i32 m0, s51, 0xffffff80
	ds_read_b128 v[206:209], v171 offset:54272
	global_load_lds_dwordx4 v144, vcc offset:128
	s_add_i32 m0, s52, 0xffffff80
	ds_read_b128 v[202:205], v171 offset:53248
	global_load_lds_dwordx4 v146, vcc offset:128
	s_waitcnt vmcnt(8) lgkmcnt(0)
	s_setprio 1
	s_barrier
	v_mfma_f32_16x16x32_bf16 v[60:63], v[128:131], v[184:187], v[60:63]
	v_mfma_f32_16x16x32_bf16 v[56:59], v[136:139], v[184:187], v[56:59]
	v_mfma_f32_16x16x32_bf16 v[44:47], v[128:131], v[194:197], v[44:47]
	v_mfma_f32_16x16x32_bf16 v[40:43], v[136:139], v[194:197], v[40:43]
	v_mfma_f32_16x16x32_bf16 v[28:31], v[128:131], v[202:205], v[28:31]
	v_mfma_f32_16x16x32_bf16 v[24:27], v[136:139], v[202:205], v[24:27]
	v_mfma_f32_16x16x32_bf16 v[12:15], v[128:131], v[210:213], v[12:15]
	v_mfma_f32_16x16x32_bf16 v[8:11], v[136:139], v[210:213], v[8:11]
	v_mfma_f32_16x16x32_bf16 v[60:63], v[132:135], v[190:193], v[60:63]
	v_mfma_f32_16x16x32_bf16 v[56:59], v[140:143], v[190:193], v[56:59]
	v_mfma_f32_16x16x32_bf16 v[44:47], v[132:135], v[198:201], v[44:47]
	v_mfma_f32_16x16x32_bf16 v[40:43], v[140:143], v[198:201], v[40:43]
	v_mfma_f32_16x16x32_bf16 v[28:31], v[132:135], v[206:209], v[28:31]
	v_mfma_f32_16x16x32_bf16 v[24:27], v[140:143], v[206:209], v[24:27]
	v_mfma_f32_16x16x32_bf16 v[12:15], v[132:135], v[214:217], v[12:15]
	v_mfma_f32_16x16x32_bf16 v[8:11], v[140:143], v[214:217], v[8:11]
	v_mfma_f32_16x16x32_bf16 v[52:55], v[160:163], v[184:187], v[52:55]
	v_mfma_f32_16x16x32_bf16 v[48:51], v[176:179], v[184:187], v[48:51]
	v_mfma_f32_16x16x32_bf16 v[36:39], v[160:163], v[194:197], v[36:39]
	v_mfma_f32_16x16x32_bf16 v[32:35], v[176:179], v[194:197], v[32:35]
	v_mfma_f32_16x16x32_bf16 v[20:23], v[160:163], v[202:205], v[20:23]
	v_mfma_f32_16x16x32_bf16 v[16:19], v[176:179], v[202:205], v[16:19]
	v_mfma_f32_16x16x32_bf16 v[4:7], v[160:163], v[210:213], v[4:7]
	v_mfma_f32_16x16x32_bf16 v[0:3], v[176:179], v[210:213], v[0:3]
	v_mfma_f32_16x16x32_bf16 v[52:55], v[172:175], v[190:193], v[52:55]
	v_mfma_f32_16x16x32_bf16 v[48:51], v[180:183], v[190:193], v[48:51]
	v_mfma_f32_16x16x32_bf16 v[36:39], v[172:175], v[198:201], v[36:39]
	v_mfma_f32_16x16x32_bf16 v[32:35], v[180:183], v[198:201], v[32:35]
	v_mfma_f32_16x16x32_bf16 v[20:23], v[172:175], v[206:209], v[20:23]
	v_mfma_f32_16x16x32_bf16 v[16:19], v[180:183], v[206:209], v[16:19]
	v_mfma_f32_16x16x32_bf16 v[4:7], v[172:175], v[214:217], v[4:7]
	v_mfma_f32_16x16x32_bf16 v[0:3], v[180:183], v[214:217], v[0:3]
	s_setprio 0
	s_barrier
	s_add_u32 s36, s36, 0x100
	s_addc_u32 s37, s37, 0
	s_add_u32 s67, s67, 0x100
	s_addc_u32 s68, s68, 0
	s_cmp_ge_i32 s69, s54
	s_mov_b32 s38, s69
	s_cbranch_scc0 .LBB0_980

; #define PG8_STAGE(bufoff, gbase, voff) do { _Pragma("unroll") for (int _i = 0; _i < 2; ++_i) \
;         __builtin_amdgcn_global_load_lds((const unsigned*)((const char*)(gbase) + (voff)[_i]), (PG8_LAS unsigned*)(lds + (bufoff) + ldsw + _i * 8192), 16, 0, 0); } while (0)
; #define PG8_LDA(dst, b, h) do { _Pragma("unroll") for (int m = 0; m < 4; ++m) _Pragma("unroll") for (int k = 0; k < 2; ++k) dst[m][k] = *(const PG8_LAS bf16x8*)(lds + PG8_SA(b, h) + aoff + m * 2048 + k * 1024); } while (0)
; #define PG8_LDB(dst, b, h) do { _Pragma("unroll") for (int n = 0; n < 2; ++n) _Pragma("unroll") for (int k = 0; k < 2; ++k) dst[n][k] = *(const PG8_LAS bf16x8*)(lds + PG8_SB(b, h) + boff + n * 2048 + k * 1024); } while (0)
; #define PG8_MMA(ai, bj, At, Bt) do { __builtin_amdgcn_s_setprio(1); _Pragma("unroll") for (int m = 0; m < 4; ++m) _Pragma("unroll") for (int n = 0; n < 2; ++n) _Pragma("unroll") for (int k = 0; k < 2; ++k) \
;         acc[ai][bj][m][n] = __builtin_amdgcn_mfma_f32_16x16x32_bf16(Bt[n][k], At[m][k], acc[ai][bj][m][n], 0, 0, 0); __builtin_amdgcn_s_setprio(0); } while (0)
; #define PG8_WAIT_V(n) asm volatile("s_waitcnt vmcnt(" #n ")" ::: "memory")
; #define PG8_WAIT_L(n) asm volatile("s_waitcnt lgkmcnt(" #n ")" ::: "memory")
; template <class Epi, class Sched, bool ALIGN_EPI = false, bool SP2 = false>
; __device__ __forceinline__ void gemm_phase(PG8_LAS unsigned char* lds, const Gemm g, const Sched& S, const Epi& E) {
;     ...
;             const bool last = (t == nt - 2);
;             const char* a1 = cA + (size_t)(t + 1) * kstep;
;             const char* a2 = last ? nA : cA + (size_t)(t + 2) * kstep; const char* b2 = last ? nB : cB + (size_t)(t + 2) * kstep;
;             const char* a3 = a2 + kstep; const char* b3 = b2 + kstep;
;             if (last && has_next) S.a_ready(nxt);
;             if constexpr (SP2) {
;             PG8_LDB(B0, 0, 0); PG8_LDB(B1, 0, 1); PG8_SCHED; PG8_LDA(At, 0, 0); PG8_STAGE(PG8_SA(1, 1), a1 + hstepA, voffA);
;             PG8_WAIT_V(8); PG8_WAIT_L(0); PG8_BAR; PG8_MMA(0, 0, At, B0); PG8_MMA(0, 1, At, B1); PG8_BAR; PG8_SCHED;
;             PG8_LDA(At, 0, 1); PG8_STAGE(PG8_SB(0, 0), b2, voffB); PG8_STAGE(PG8_SB(0, 1), b2 + hstep, voffB); PG8_STAGE(PG8_SA(0, 0), a2, voffA);
;             PG8_WAIT_V(8); PG8_WAIT_L(0); PG8_BAR; PG8_MMA(1, 0, At, B0); PG8_MMA(1, 1, At, B1); PG8_BAR; PG8_SCHED;
.LBB0_1068:
	ds_read_b128 v[152:155], v148
	ds_read_b128 v[156:159], v148 offset:1024
	ds_read_b128 v[160:163], v148 offset:2048
	ds_read_b128 v[164:167], v148 offset:3072
	ds_read_b128 v[168:171], v149
	ds_read_b128 v[172:175], v149 offset:1024
	ds_read_b128 v[176:179], v149 offset:2048
	ds_read_b128 v[180:183], v149 offset:3072
	s_add_i32 s69, s26, 2
	s_add_u32 s27, s24, 0xfff50080
	s_addc_u32 s28, s25, -1
	s_cmp_eq_u32 s51, s26
	s_cselect_b32 s26, s22, s67
	s_cselect_b32 s29, s21, s28
	s_cselect_b32 s28, s20, s27
	s_cselect_b32 s27, s23, s68
	s_add_i32 m0, s42, 0xc000
	ds_read_b128 v[184:187], v150
	ds_read_b128 v[190:193], v150 offset:1024
	ds_read_b128 v[194:197], v150 offset:2048
	ds_read_b128 v[198:201], v150 offset:3072
	ds_read_b128 v[202:205], v150 offset:4096
	ds_read_b128 v[206:209], v150 offset:5120
	ds_read_b128 v[210:213], v150 offset:6144
	global_load_lds_dwordx4 v132, s[24:25]
	s_add_i32 m0, s42, 0xe000
	ds_read_b128 v[214:217], v150 offset:7168
	global_load_lds_dwordx4 v136, s[24:25]
	s_waitcnt vmcnt(8) lgkmcnt(0)
	s_setprio 1
	s_barrier
	v_mfma_f32_16x16x32_bf16 v[124:127], v[152:155], v[184:187], v[124:127]
	v_mfma_f32_16x16x32_bf16 v[120:123], v[160:163], v[184:187], v[120:123]
	v_mfma_f32_16x16x32_bf16 v[108:111], v[152:155], v[194:197], v[108:111]
	v_mfma_f32_16x16x32_bf16 v[104:107], v[160:163], v[194:197], v[104:107]
	v_mfma_f32_16x16x32_bf16 v[92:95], v[152:155], v[202:205], v[92:95]
	v_mfma_f32_16x16x32_bf16 v[88:91], v[160:163], v[202:205], v[88:91]
	v_mfma_f32_16x16x32_bf16 v[76:79], v[152:155], v[210:213], v[76:79]
	v_mfma_f32_16x16x32_bf16 v[72:75], v[160:163], v[210:213], v[72:75]
	v_mfma_f32_16x16x32_bf16 v[124:127], v[156:159], v[190:193], v[124:127]
	v_mfma_f32_16x16x32_bf16 v[120:123], v[164:167], v[190:193], v[120:123]
	v_mfma_f32_16x16x32_bf16 v[108:111], v[156:159], v[198:201], v[108:111]
	v_mfma_f32_16x16x32_bf16 v[104:107], v[164:167], v[198:201], v[104:107]
	v_mfma_f32_16x16x32_bf16 v[92:95], v[156:159], v[206:209], v[92:95]
	v_mfma_f32_16x16x32_bf16 v[88:91], v[164:167], v[206:209], v[88:91]
	v_mfma_f32_16x16x32_bf16 v[76:79], v[156:159], v[214:217], v[76:79]
	v_mfma_f32_16x16x32_bf16 v[72:75], v[164:167], v[214:217], v[72:75]
	v_mfma_f32_16x16x32_bf16 v[116:119], v[168:171], v[184:187], v[116:119]
	v_mfma_f32_16x16x32_bf16 v[112:115], v[176:179], v[184:187], v[112:115]
	v_mfma_f32_16x16x32_bf16 v[100:103], v[168:171], v[194:197], v[100:103]
	v_mfma_f32_16x16x32_bf16 v[96:99], v[176:179], v[194:197], v[96:99]
	v_mfma_f32_16x16x32_bf16 v[84:87], v[168:171], v[202:205], v[84:87]
	v_mfma_f32_16x16x32_bf16 v[80:83], v[176:179], v[202:205], v[80:83]
	v_mfma_f32_16x16x32_bf16 v[68:71], v[168:171], v[210:213], v[68:71]
	v_mfma_f32_16x16x32_bf16 v[64:67], v[176:179], v[210:213], v[64:67]
	v_mfma_f32_16x16x32_bf16 v[116:119], v[172:175], v[190:193], v[116:119]
	v_mfma_f32_16x16x32_bf16 v[112:115], v[180:183], v[190:193], v[112:115]
	v_mfma_f32_16x16x32_bf16 v[100:103], v[172:175], v[198:201], v[100:103]
	v_mfma_f32_16x16x32_bf16 v[96:99], v[180:183], v[198:201], v[96:99]
	v_mfma_f32_16x16x32_bf16 v[84:87], v[172:175], v[206:209], v[84:87]
	v_mfma_f32_16x16x32_bf16 v[80:83], v[180:183], v[206:209], v[80:83]
	v_mfma_f32_16x16x32_bf16 v[68:71], v[172:175], v[214:217], v[68:71]
	v_mfma_f32_16x16x32_bf16 v[64:67], v[180:183], v[214:217], v[64:67]
	s_setprio 0
	s_barrier
	s_add_i32 s70, s54, s41
	s_mov_b32 m0, s70
	ds_read_b128 v[184:187], v150 offset:16384
	ds_read_b128 v[190:193], v150 offset:17408
	ds_read_b128 v[194:197], v150 offset:18432
	ds_read_b128 v[198:201], v150 offset:19456
	global_load_lds_dwordx4 v128, s[26:27]
	s_add_i32 m0, s70, 0x2000
	s_add_u32 s70, s26, 0xb0000
	s_addc_u32 s71, s27, 0
	s_add_i32 s72, s55, s41
	global_load_lds_dwordx4 v130, s[26:27]
	s_mov_b32 m0, s72
	ds_read_b128 v[214:217], v150 offset:23552
	global_load_lds_dwordx4 v128, s[70:71]
	s_add_i32 m0, s72, 0x2000
	ds_read_b128 v[210:213], v150 offset:22528
	global_load_lds_dwordx4 v130, s[70:71]
	s_mov_b32 m0, s42
	ds_read_b128 v[206:209], v150 offset:21504
	global_load_lds_dwordx4 v128, s[28:29]
	s_mov_b32 m0, s43
	ds_read_b128 v[202:205], v150 offset:20480
	global_load_lds_dwordx4 v130, s[28:29]
	s_waitcnt vmcnt(8) lgkmcnt(0)
	s_setprio 1
	s_barrier
	v_mfma_f32_16x16x32_bf16 v[60:63], v[152:155], v[184:187], v[60:63]
	v_mfma_f32_16x16x32_bf16 v[56:59], v[160:163], v[184:187], v[56:59]
	v_mfma_f32_16x16x32_bf16 v[44:47], v[152:155], v[194:197], v[44:47]
	v_mfma_f32_16x16x32_bf16 v[40:43], v[160:163], v[194:197], v[40:43]
	v_mfma_f32_16x16x32_bf16 v[28:31], v[152:155], v[202:205], v[28:31]
	v_mfma_f32_16x16x32_bf16 v[24:27], v[160:163], v[202:205], v[24:27]
	v_mfma_f32_16x16x32_bf16 v[12:15], v[152:155], v[210:213], v[12:15]
	v_mfma_f32_16x16x32_bf16 v[8:11], v[160:163], v[210:213], v[8:11]
	v_mfma_f32_16x16x32_bf16 v[60:63], v[156:159], v[190:193], v[60:63]
	v_mfma_f32_16x16x32_bf16 v[56:59], v[164:167], v[190:193], v[56:59]
	v_mfma_f32_16x16x32_bf16 v[44:47], v[156:159], v[198:201], v[44:47]
	v_mfma_f32_16x16x32_bf16 v[40:43], v[164:167], v[198:201], v[40:43]
	v_mfma_f32_16x16x32_bf16 v[28:31], v[156:159], v[206:209], v[28:31]
	v_mfma_f32_16x16x32_bf16 v[24:27], v[164:167], v[206:209], v[24:27]
	v_mfma_f32_16x16x32_bf16 v[12:15], v[156:159], v[214:217], v[12:15]
	v_mfma_f32_16x16x32_bf16 v[8:11], v[164:167], v[214:217], v[8:11]
	v_mfma_f32_16x16x32_bf16 v[52:55], v[168:171], v[184:187], v[52:55]
	v_mfma_f32_16x16x32_bf16 v[48:51], v[176:179], v[184:187], v[48:51]
	v_mfma_f32_16x16x32_bf16 v[36:39], v[168:171], v[194:197], v[36:39]
	v_mfma_f32_16x16x32_bf16 v[32:35], v[176:179], v[194:197], v[32:35]
	v_mfma_f32_16x16x32_bf16 v[20:23], v[168:171], v[202:205], v[20:23]
	v_mfma_f32_16x16x32_bf16 v[16:19], v[176:179], v[202:205], v[16:19]
	v_mfma_f32_16x16x32_bf16 v[4:7], v[168:171], v[210:213], v[4:7]
	v_mfma_f32_16x16x32_bf16 v[0:3], v[176:179], v[210:213], v[0:3]
	v_mfma_f32_16x16x32_bf16 v[52:55], v[172:175], v[190:193], v[52:55]
	v_mfma_f32_16x16x32_bf16 v[48:51], v[180:183], v[190:193], v[48:51]
	v_mfma_f32_16x16x32_bf16 v[36:39], v[172:175], v[198:201], v[36:39]
	v_mfma_f32_16x16x32_bf16 v[32:35], v[180:183], v[198:201], v[32:35]
	v_mfma_f32_16x16x32_bf16 v[20:23], v[172:175], v[206:209], v[20:23]
	v_mfma_f32_16x16x32_bf16 v[16:19], v[180:183], v[206:209], v[16:19]
	v_mfma_f32_16x16x32_bf16 v[4:7], v[172:175], v[214:217], v[4:7]
	v_mfma_f32_16x16x32_bf16 v[0:3], v[180:183], v[214:217], v[0:3]
	s_setprio 0
	s_barrier
; #define PG8_STAGE(bufoff, gbase, voff) do { _Pragma("unroll") for (int _i = 0; _i < 2; ++_i) \
;         __builtin_amdgcn_global_load_lds((const unsigned*)((const char*)(gbase) + (voff)[_i]), (PG8_LAS unsigned*)(lds + (bufoff) + ldsw + _i * 8192), 16, 0, 0); } while (0)
; #define PG8_LDA(dst, b, h) do { _Pragma("unroll") for (int m = 0; m < 4; ++m) _Pragma("unroll") for (int k = 0; k < 2; ++k) dst[m][k] = *(const PG8_LAS bf16x8*)(lds + PG8_SA(b, h) + aoff + m * 2048 + k * 1024); } while (0)
; #define PG8_LDB(dst, b, h) do { _Pragma("unroll") for (int n = 0; n < 2; ++n) _Pragma("unroll") for (int k = 0; k < 2; ++k) dst[n][k] = *(const PG8_LAS bf16x8*)(lds + PG8_SB(b, h) + boff + n * 2048 + k * 1024); } while (0)
; #define PG8_MMA(ai, bj, At, Bt) do { __builtin_amdgcn_s_setprio(1); _Pragma("unroll") for (int m = 0; m < 4; ++m) _Pragma("unroll") for (int n = 0; n < 2; ++n) _Pragma("unroll") for (int k = 0; k < 2; ++k) \
;         acc[ai][bj][m][n] = __builtin_amdgcn_mfma_f32_16x16x32_bf16(Bt[n][k], At[m][k], acc[ai][bj][m][n], 0, 0, 0); __builtin_amdgcn_s_setprio(0); } while (0)
; #define PG8_WAIT_V(n) asm volatile("s_waitcnt vmcnt(" #n ")" ::: "memory")
; #define PG8_WAIT_L(n) asm volatile("s_waitcnt lgkmcnt(" #n ")" ::: "memory")
; #define PG8_BAR __builtin_amdgcn_s_barrier()
; #define PG8_SCHED __builtin_amdgcn_sched_barrier(0)
; template <class Epi, class Sched, bool ALIGN_EPI = false, bool SP2 = false>
; __device__ __forceinline__ void gemm_phase(PG8_LAS unsigned char* lds, const Gemm g, const Sched& S, const Epi& E) {
;     ...
;             PG8_LDB(B0, 1, 0); PG8_LDB(B1, 1, 1); PG8_SCHED; PG8_LDA(At, 1, 0); PG8_STAGE(PG8_SA(0, 1), a2 + hstepA, voffA);
;             PG8_WAIT_V(8); PG8_WAIT_L(0); PG8_BAR; PG8_MMA(0, 0, At, B0); PG8_MMA(0, 1, At, B1); PG8_BAR; PG8_SCHED;
;             PG8_LDA(At, 1, 1); PG8_STAGE(PG8_SB(1, 0), b3, voffB); PG8_STAGE(PG8_SB(1, 1), b3 + hstep, voffB); PG8_STAGE(PG8_SA(1, 0), a3, voffA);
;             PG8_WAIT_V(8); PG8_WAIT_L(0); PG8_BAR; PG8_MMA(1, 0, At, B0); PG8_MMA(1, 1, At, B1); PG8_BAR; PG8_SCHED;
	s_add_i32 s70, 0, 0x18000
	v_add_u32_e32 v151, s70, v147
	s_add_i32 s71, 0, 0x1c000
	ds_read_b128 v[152:155], v151
	ds_read_b128 v[156:159], v151 offset:1024
	ds_read_b128 v[160:163], v151 offset:2048
	ds_read_b128 v[164:167], v151 offset:3072
	v_add_u32_e32 v151, s71, v147
	ds_read_b128 v[168:171], v151
	ds_read_b128 v[172:175], v151 offset:1024
	ds_read_b128 v[176:179], v151 offset:2048
	ds_read_b128 v[180:183], v151 offset:3072
	s_mov_b64 vcc, s[28:29]
	s_add_u32 s28, s28, 0xb0000
	s_addc_u32 s29, s29, 0
	s_mov_b32 m0, s44
	ds_read_b128 v[184:187], v150 offset:32768
	ds_read_b128 v[190:193], v150 offset:33792
	ds_read_b128 v[194:197], v150 offset:34816
	ds_read_b128 v[198:201], v150 offset:35840
	ds_read_b128 v[202:205], v150 offset:36864
	ds_read_b128 v[206:209], v150 offset:37888
	ds_read_b128 v[210:213], v150 offset:38912
	global_load_lds_dwordx4 v128, s[28:29]
	s_mov_b32 m0, s45
	ds_read_b128 v[214:217], v150 offset:39936
	global_load_lds_dwordx4 v130, s[28:29]
	s_waitcnt vmcnt(8) lgkmcnt(0)
	s_setprio 1
	s_barrier
	v_mfma_f32_16x16x32_bf16 v[124:127], v[152:155], v[184:187], v[124:127]
	v_mfma_f32_16x16x32_bf16 v[120:123], v[160:163], v[184:187], v[120:123]
	v_mfma_f32_16x16x32_bf16 v[108:111], v[152:155], v[194:197], v[108:111]
	v_mfma_f32_16x16x32_bf16 v[104:107], v[160:163], v[194:197], v[104:107]
	v_mfma_f32_16x16x32_bf16 v[92:95], v[152:155], v[202:205], v[92:95]
	v_mfma_f32_16x16x32_bf16 v[88:91], v[160:163], v[202:205], v[88:91]
	v_mfma_f32_16x16x32_bf16 v[76:79], v[152:155], v[210:213], v[76:79]
	v_mfma_f32_16x16x32_bf16 v[72:75], v[160:163], v[210:213], v[72:75]
	v_mfma_f32_16x16x32_bf16 v[124:127], v[156:159], v[190:193], v[124:127]
	v_mfma_f32_16x16x32_bf16 v[120:123], v[164:167], v[190:193], v[120:123]
	v_mfma_f32_16x16x32_bf16 v[108:111], v[156:159], v[198:201], v[108:111]
	v_mfma_f32_16x16x32_bf16 v[104:107], v[164:167], v[198:201], v[104:107]
	v_mfma_f32_16x16x32_bf16 v[92:95], v[156:159], v[206:209], v[92:95]
	v_mfma_f32_16x16x32_bf16 v[88:91], v[164:167], v[206:209], v[88:91]
	v_mfma_f32_16x16x32_bf16 v[76:79], v[156:159], v[214:217], v[76:79]
	v_mfma_f32_16x16x32_bf16 v[72:75], v[164:167], v[214:217], v[72:75]
	v_mfma_f32_16x16x32_bf16 v[116:119], v[168:171], v[184:187], v[116:119]
	v_mfma_f32_16x16x32_bf16 v[112:115], v[176:179], v[184:187], v[112:115]
	v_mfma_f32_16x16x32_bf16 v[100:103], v[168:171], v[194:197], v[100:103]
	v_mfma_f32_16x16x32_bf16 v[96:99], v[176:179], v[194:197], v[96:99]
	v_mfma_f32_16x16x32_bf16 v[84:87], v[168:171], v[202:205], v[84:87]
	v_mfma_f32_16x16x32_bf16 v[80:83], v[176:179], v[202:205], v[80:83]
	v_mfma_f32_16x16x32_bf16 v[68:71], v[168:171], v[210:213], v[68:71]
	v_mfma_f32_16x16x32_bf16 v[64:67], v[176:179], v[210:213], v[64:67]
	v_mfma_f32_16x16x32_bf16 v[116:119], v[172:175], v[190:193], v[116:119]
	v_mfma_f32_16x16x32_bf16 v[112:115], v[180:183], v[190:193], v[112:115]
	v_mfma_f32_16x16x32_bf16 v[100:103], v[172:175], v[198:201], v[100:103]
	v_mfma_f32_16x16x32_bf16 v[96:99], v[180:183], v[198:201], v[96:99]
	v_mfma_f32_16x16x32_bf16 v[84:87], v[172:175], v[206:209], v[84:87]
	v_mfma_f32_16x16x32_bf16 v[80:83], v[180:183], v[206:209], v[80:83]
	v_mfma_f32_16x16x32_bf16 v[68:71], v[172:175], v[214:217], v[68:71]
	v_mfma_f32_16x16x32_bf16 v[64:67], v[180:183], v[214:217], v[64:67]
	s_setprio 0
	s_barrier
	s_add_i32 s28, s70, s41
	s_add_i32 m0, s28, 0xffffff80
	ds_read_b128 v[184:187], v150 offset:49152
	ds_read_b128 v[190:193], v150 offset:50176
	ds_read_b128 v[194:197], v150 offset:51200
	ds_read_b128 v[198:201], v150 offset:52224
	global_load_lds_dwordx4 v128, s[26:27] offset:128
	s_add_i32 m0, s28, 0x1f80
	s_mov_b64 s[100:101], s[26:27]
	s_add_u32 s26, s26, 0xb0080
	s_addc_u32 s27, s27, 0
	s_add_i32 s28, s71, s41
	global_load_lds_dwordx4 v130, s[100:101] offset:128
	s_mov_b32 m0, s28
	ds_read_b128 v[214:217], v150 offset:56320
	global_load_lds_dwordx4 v128, s[26:27]
	s_add_i32 m0, s28, 0x2000
	ds_read_b128 v[210:213], v150 offset:55296
	global_load_lds_dwordx4 v130, s[26:27]
	s_add_i32 m0, s49, 0xffffff80
	ds_read_b128 v[206:209], v150 offset:54272
	global_load_lds_dwordx4 v128, vcc offset:128
	s_add_i32 m0, s50, 0xffffff80
	ds_read_b128 v[202:205], v150 offset:53248
	global_load_lds_dwordx4 v130, vcc offset:128
	s_waitcnt vmcnt(8) lgkmcnt(0)
	s_setprio 1
	s_barrier
	v_mfma_f32_16x16x32_bf16 v[60:63], v[152:155], v[184:187], v[60:63]
	v_mfma_f32_16x16x32_bf16 v[56:59], v[160:163], v[184:187], v[56:59]
	v_mfma_f32_16x16x32_bf16 v[44:47], v[152:155], v[194:197], v[44:47]
	v_mfma_f32_16x16x32_bf16 v[40:43], v[160:163], v[194:197], v[40:43]
	v_mfma_f32_16x16x32_bf16 v[28:31], v[152:155], v[202:205], v[28:31]
	v_mfma_f32_16x16x32_bf16 v[24:27], v[160:163], v[202:205], v[24:27]
	v_mfma_f32_16x16x32_bf16 v[12:15], v[152:155], v[210:213], v[12:15]
	v_mfma_f32_16x16x32_bf16 v[8:11], v[160:163], v[210:213], v[8:11]
	v_mfma_f32_16x16x32_bf16 v[60:63], v[156:159], v[190:193], v[60:63]
	v_mfma_f32_16x16x32_bf16 v[56:59], v[164:167], v[190:193], v[56:59]
	v_mfma_f32_16x16x32_bf16 v[44:47], v[156:159], v[198:201], v[44:47]
	v_mfma_f32_16x16x32_bf16 v[40:43], v[164:167], v[198:201], v[40:43]
	v_mfma_f32_16x16x32_bf16 v[28:31], v[156:159], v[206:209], v[28:31]
	v_mfma_f32_16x16x32_bf16 v[24:27], v[164:167], v[206:209], v[24:27]
	v_mfma_f32_16x16x32_bf16 v[12:15], v[156:159], v[214:217], v[12:15]
	v_mfma_f32_16x16x32_bf16 v[8:11], v[164:167], v[214:217], v[8:11]
	v_mfma_f32_16x16x32_bf16 v[52:55], v[168:171], v[184:187], v[52:55]
	v_mfma_f32_16x16x32_bf16 v[48:51], v[176:179], v[184:187], v[48:51]
	v_mfma_f32_16x16x32_bf16 v[36:39], v[168:171], v[194:197], v[36:39]
	v_mfma_f32_16x16x32_bf16 v[32:35], v[176:179], v[194:197], v[32:35]
	v_mfma_f32_16x16x32_bf16 v[20:23], v[168:171], v[202:205], v[20:23]
	v_mfma_f32_16x16x32_bf16 v[16:19], v[176:179], v[202:205], v[16:19]
	v_mfma_f32_16x16x32_bf16 v[4:7], v[168:171], v[210:213], v[4:7]
	v_mfma_f32_16x16x32_bf16 v[0:3], v[176:179], v[210:213], v[0:3]
	v_mfma_f32_16x16x32_bf16 v[52:55], v[172:175], v[190:193], v[52:55]
	v_mfma_f32_16x16x32_bf16 v[48:51], v[180:183], v[190:193], v[48:51]
	v_mfma_f32_16x16x32_bf16 v[36:39], v[172:175], v[198:201], v[36:39]
	v_mfma_f32_16x16x32_bf16 v[32:35], v[180:183], v[198:201], v[32:35]
	v_mfma_f32_16x16x32_bf16 v[20:23], v[172:175], v[206:209], v[20:23]
	v_mfma_f32_16x16x32_bf16 v[16:19], v[180:183], v[206:209], v[16:19]
	v_mfma_f32_16x16x32_bf16 v[4:7], v[172:175], v[214:217], v[4:7]
	v_mfma_f32_16x16x32_bf16 v[0:3], v[180:183], v[214:217], v[0:3]
	s_setprio 0
	s_barrier
	s_add_u32 s24, s24, 0x100
	s_addc_u32 s25, s25, 0
	s_add_u32 s67, s67, 0x100
	s_addc_u32 s68, s68, 0
	s_cmp_ge_i32 s69, s48
	s_mov_b32 s26, s69
	s_cbranch_scc0 .LBB0_1068

; #define PG8_STAGE(bufoff, gbase, voff) do { _Pragma("unroll") for (int _i = 0; _i < 2; ++_i) \
;         __builtin_amdgcn_global_load_lds((const unsigned*)((const char*)(gbase) + (voff)[_i]), (PG8_LAS unsigned*)(lds + (bufoff) + ldsw + _i * 8192), 16, 0, 0); } while (0)
; #define PG8_LDA(dst, b, h) do { _Pragma("unroll") for (int m = 0; m < 4; ++m) _Pragma("unroll") for (int k = 0; k < 2; ++k) dst[m][k] = *(const PG8_LAS bf16x8*)(lds + PG8_SA(b, h) + aoff + m * 2048 + k * 1024); } while (0)
; #define PG8_LDB(dst, b, h) do { _Pragma("unroll") for (int n = 0; n < 2; ++n) _Pragma("unroll") for (int k = 0; k < 2; ++k) dst[n][k] = *(const PG8_LAS bf16x8*)(lds + PG8_SB(b, h) + boff + n * 2048 + k * 1024); } while (0)
; #define PG8_MMA(ai, bj, At, Bt) do { __builtin_amdgcn_s_setprio(1); _Pragma("unroll") for (int m = 0; m < 4; ++m) _Pragma("unroll") for (int n = 0; n < 2; ++n) _Pragma("unroll") for (int k = 0; k < 2; ++k) \
;         acc[ai][bj][m][n] = __builtin_amdgcn_mfma_f32_16x16x32_bf16(Bt[n][k], At[m][k], acc[ai][bj][m][n], 0, 0, 0); __builtin_amdgcn_s_setprio(0); } while (0)
; #define PG8_WAIT_V(n) asm volatile("s_waitcnt vmcnt(" #n ")" ::: "memory")
; #define PG8_WAIT_L(n) asm volatile("s_waitcnt lgkmcnt(" #n ")" ::: "memory")
; template <class Epi, class Sched, bool ALIGN_EPI = false, bool SP2 = false>
; __device__ __forceinline__ void gemm_phase(PG8_LAS unsigned char* lds, const Gemm g, const Sched& S, const Epi& E) {
;     ...
;             const bool last = (t == nt - 2);
;             const char* a1 = cA + (size_t)(t + 1) * kstep;
;             const char* a2 = last ? nA : cA + (size_t)(t + 2) * kstep; const char* b2 = last ? nB : cB + (size_t)(t + 2) * kstep;
;             const char* a3 = a2 + kstep; const char* b3 = b2 + kstep;
;             if (last && has_next) S.a_ready(nxt);
;             if constexpr (SP2) {
;             PG8_LDB(B0, 0, 0); PG8_LDB(B1, 0, 1); PG8_SCHED; PG8_LDA(At, 0, 0); PG8_STAGE(PG8_SA(1, 1), a1 + hstepA, voffA);
;             PG8_WAIT_V(8); PG8_WAIT_L(0); PG8_BAR; PG8_MMA(0, 0, At, B0); PG8_MMA(0, 1, At, B1); PG8_BAR; PG8_SCHED;
;             PG8_LDA(At, 0, 1); PG8_STAGE(PG8_SB(0, 0), b2, voffB); PG8_STAGE(PG8_SB(0, 1), b2 + hstep, voffB); PG8_STAGE(PG8_SA(0, 0), a2, voffA);
;             PG8_WAIT_V(8); PG8_WAIT_L(0); PG8_BAR; PG8_MMA(1, 0, At, B0); PG8_MMA(1, 1, At, B1); PG8_BAR; PG8_SCHED;
.LBB0_1236:
	ds_read_b128 v[150:153], v147
	ds_read_b128 v[154:157], v147 offset:1024
	ds_read_b128 v[158:161], v147 offset:2048
	ds_read_b128 v[162:165], v147 offset:3072
	ds_read_b128 v[166:169], v148
	ds_read_b128 v[170:173], v148 offset:1024
	ds_read_b128 v[174:177], v148 offset:2048
	ds_read_b128 v[178:181], v148 offset:3072
	s_add_i32 s68, s40, 2
	s_add_u32 s69, s8, 0xfffc0080
	s_addc_u32 s41, s9, -1
	s_cmp_eq_u32 s59, s40
	s_cselect_b32 s40, s67, s69
	s_cselect_b32 s41, s35, s41
	s_cselect_b32 s71, s37, s43
	s_cselect_b32 s70, s36, s42
	s_add_i32 m0, s31, 0xc000
	ds_read_b128 v[182:185], v149
	ds_read_b128 v[190:193], v149 offset:1024
	ds_read_b128 v[194:197], v149 offset:2048
	ds_read_b128 v[198:201], v149 offset:3072
	ds_read_b128 v[202:205], v149 offset:4096
	ds_read_b128 v[206:209], v149 offset:5120
	ds_read_b128 v[210:213], v149 offset:6144
	global_load_lds_dwordx4 v136, s[8:9]
	s_add_i32 m0, s31, 0xe000
	ds_read_b128 v[214:217], v149 offset:7168
	global_load_lds_dwordx4 v138, s[8:9]
	s_waitcnt vmcnt(8) lgkmcnt(0)
	s_setprio 1
	s_barrier
	v_mfma_f32_16x16x32_bf16 v[120:123], v[150:153], v[182:185], v[120:123]
	v_mfma_f32_16x16x32_bf16 v[124:127], v[158:161], v[182:185], v[124:127]
	v_mfma_f32_16x16x32_bf16 v[108:111], v[150:153], v[194:197], v[108:111]
	v_mfma_f32_16x16x32_bf16 v[104:107], v[158:161], v[194:197], v[104:107]
	v_mfma_f32_16x16x32_bf16 v[92:95], v[150:153], v[202:205], v[92:95]
	v_mfma_f32_16x16x32_bf16 v[88:91], v[158:161], v[202:205], v[88:91]
	v_mfma_f32_16x16x32_bf16 v[76:79], v[150:153], v[210:213], v[76:79]
	v_mfma_f32_16x16x32_bf16 v[72:75], v[158:161], v[210:213], v[72:75]
	v_mfma_f32_16x16x32_bf16 v[120:123], v[154:157], v[190:193], v[120:123]
	v_mfma_f32_16x16x32_bf16 v[124:127], v[162:165], v[190:193], v[124:127]
	v_mfma_f32_16x16x32_bf16 v[108:111], v[154:157], v[198:201], v[108:111]
	v_mfma_f32_16x16x32_bf16 v[104:107], v[162:165], v[198:201], v[104:107]
	v_mfma_f32_16x16x32_bf16 v[92:95], v[154:157], v[206:209], v[92:95]
	v_mfma_f32_16x16x32_bf16 v[88:91], v[162:165], v[206:209], v[88:91]
	v_mfma_f32_16x16x32_bf16 v[76:79], v[154:157], v[214:217], v[76:79]
	v_mfma_f32_16x16x32_bf16 v[72:75], v[162:165], v[214:217], v[72:75]
	v_mfma_f32_16x16x32_bf16 v[116:119], v[166:169], v[182:185], v[116:119]
	v_mfma_f32_16x16x32_bf16 v[112:115], v[174:177], v[182:185], v[112:115]
	v_mfma_f32_16x16x32_bf16 v[100:103], v[166:169], v[194:197], v[100:103]
	v_mfma_f32_16x16x32_bf16 v[96:99], v[174:177], v[194:197], v[96:99]
	v_mfma_f32_16x16x32_bf16 v[84:87], v[166:169], v[202:205], v[84:87]
	v_mfma_f32_16x16x32_bf16 v[80:83], v[174:177], v[202:205], v[80:83]
	v_mfma_f32_16x16x32_bf16 v[68:71], v[166:169], v[210:213], v[68:71]
	v_mfma_f32_16x16x32_bf16 v[64:67], v[174:177], v[210:213], v[64:67]
	v_mfma_f32_16x16x32_bf16 v[116:119], v[170:173], v[190:193], v[116:119]
	v_mfma_f32_16x16x32_bf16 v[112:115], v[178:181], v[190:193], v[112:115]
	v_mfma_f32_16x16x32_bf16 v[100:103], v[170:173], v[198:201], v[100:103]
	v_mfma_f32_16x16x32_bf16 v[96:99], v[178:181], v[198:201], v[96:99]
	v_mfma_f32_16x16x32_bf16 v[84:87], v[170:173], v[206:209], v[84:87]
	v_mfma_f32_16x16x32_bf16 v[80:83], v[178:181], v[206:209], v[80:83]
	v_mfma_f32_16x16x32_bf16 v[68:71], v[170:173], v[214:217], v[68:71]
	v_mfma_f32_16x16x32_bf16 v[64:67], v[178:181], v[214:217], v[64:67]
	s_setprio 0
	s_barrier
	s_add_i32 s69, s60, s47
	s_mov_b32 m0, s69
	ds_read_b128 v[182:185], v149 offset:16384
	ds_read_b128 v[190:193], v149 offset:17408
	ds_read_b128 v[194:197], v149 offset:18432
	ds_read_b128 v[198:201], v149 offset:19456
	global_load_lds_dwordx4 v134, s[70:71]
	s_add_i32 m0, s69, 0x2000
	s_mov_b64 s[100:101], s[70:71]
	s_add_i32 s69, s61, s47
	global_load_lds_dwordx4 v132, s[70:71]
	s_add_u32 s70, s70, s4
	s_addc_u32 s71, s71, s5
	s_mov_b32 m0, s69
	ds_read_b128 v[214:217], v149 offset:23552
	global_load_lds_dwordx4 v134, s[70:71]
	s_add_i32 m0, s69, 0x2000
	ds_read_b128 v[210:213], v149 offset:22528
	global_load_lds_dwordx4 v132, s[70:71]
	s_mov_b32 m0, s31
	ds_read_b128 v[206:209], v149 offset:21504
	global_load_lds_dwordx4 v128, s[40:41]
	s_mov_b32 m0, s50
	ds_read_b128 v[202:205], v149 offset:20480
	global_load_lds_dwordx4 v130, s[40:41]
	s_waitcnt vmcnt(8) lgkmcnt(0)
	s_setprio 1
	s_barrier
	v_mfma_f32_16x16x32_bf16 v[60:63], v[150:153], v[182:185], v[60:63]
	v_mfma_f32_16x16x32_bf16 v[56:59], v[158:161], v[182:185], v[56:59]
	v_mfma_f32_16x16x32_bf16 v[44:47], v[150:153], v[194:197], v[44:47]
	v_mfma_f32_16x16x32_bf16 v[40:43], v[158:161], v[194:197], v[40:43]
	v_mfma_f32_16x16x32_bf16 v[28:31], v[150:153], v[202:205], v[28:31]
	v_mfma_f32_16x16x32_bf16 v[24:27], v[158:161], v[202:205], v[24:27]
	v_mfma_f32_16x16x32_bf16 v[12:15], v[150:153], v[210:213], v[12:15]
	v_mfma_f32_16x16x32_bf16 v[8:11], v[158:161], v[210:213], v[8:11]
	v_mfma_f32_16x16x32_bf16 v[60:63], v[154:157], v[190:193], v[60:63]
	v_mfma_f32_16x16x32_bf16 v[56:59], v[162:165], v[190:193], v[56:59]
	v_mfma_f32_16x16x32_bf16 v[44:47], v[154:157], v[198:201], v[44:47]
	v_mfma_f32_16x16x32_bf16 v[40:43], v[162:165], v[198:201], v[40:43]
	v_mfma_f32_16x16x32_bf16 v[28:31], v[154:157], v[206:209], v[28:31]
	v_mfma_f32_16x16x32_bf16 v[24:27], v[162:165], v[206:209], v[24:27]
	v_mfma_f32_16x16x32_bf16 v[12:15], v[154:157], v[214:217], v[12:15]
	v_mfma_f32_16x16x32_bf16 v[8:11], v[162:165], v[214:217], v[8:11]
	v_mfma_f32_16x16x32_bf16 v[52:55], v[166:169], v[182:185], v[52:55]
	v_mfma_f32_16x16x32_bf16 v[48:51], v[174:177], v[182:185], v[48:51]
	v_mfma_f32_16x16x32_bf16 v[36:39], v[166:169], v[194:197], v[36:39]
	v_mfma_f32_16x16x32_bf16 v[32:35], v[174:177], v[194:197], v[32:35]
	v_mfma_f32_16x16x32_bf16 v[20:23], v[166:169], v[202:205], v[20:23]
	v_mfma_f32_16x16x32_bf16 v[16:19], v[174:177], v[202:205], v[16:19]
	v_mfma_f32_16x16x32_bf16 v[4:7], v[166:169], v[210:213], v[4:7]
	v_mfma_f32_16x16x32_bf16 v[0:3], v[174:177], v[210:213], v[0:3]
	v_mfma_f32_16x16x32_bf16 v[52:55], v[170:173], v[190:193], v[52:55]
	v_mfma_f32_16x16x32_bf16 v[48:51], v[178:181], v[190:193], v[48:51]
	v_mfma_f32_16x16x32_bf16 v[36:39], v[170:173], v[198:201], v[36:39]
	v_mfma_f32_16x16x32_bf16 v[32:35], v[178:181], v[198:201], v[32:35]
	v_mfma_f32_16x16x32_bf16 v[20:23], v[170:173], v[206:209], v[20:23]
	v_mfma_f32_16x16x32_bf16 v[16:19], v[178:181], v[206:209], v[16:19]
	v_mfma_f32_16x16x32_bf16 v[4:7], v[170:173], v[214:217], v[4:7]
	v_mfma_f32_16x16x32_bf16 v[0:3], v[178:181], v[214:217], v[0:3]
	s_setprio 0
	s_barrier
; #define PG8_STAGE(bufoff, gbase, voff) do { _Pragma("unroll") for (int _i = 0; _i < 2; ++_i) \
;         __builtin_amdgcn_global_load_lds((const unsigned*)((const char*)(gbase) + (voff)[_i]), (PG8_LAS unsigned*)(lds + (bufoff) + ldsw + _i * 8192), 16, 0, 0); } while (0)
; #define PG8_LDA(dst, b, h) do { _Pragma("unroll") for (int m = 0; m < 4; ++m) _Pragma("unroll") for (int k = 0; k < 2; ++k) dst[m][k] = *(const PG8_LAS bf16x8*)(lds + PG8_SA(b, h) + aoff + m * 2048 + k * 1024); } while (0)
; #define PG8_LDB(dst, b, h) do { _Pragma("unroll") for (int n = 0; n < 2; ++n) _Pragma("unroll") for (int k = 0; k < 2; ++k) dst[n][k] = *(const PG8_LAS bf16x8*)(lds + PG8_SB(b, h) + boff + n * 2048 + k * 1024); } while (0)
; #define PG8_MMA(ai, bj, At, Bt) do { __builtin_amdgcn_s_setprio(1); _Pragma("unroll") for (int m = 0; m < 4; ++m) _Pragma("unroll") for (int n = 0; n < 2; ++n) _Pragma("unroll") for (int k = 0; k < 2; ++k) \
;         acc[ai][bj][m][n] = __builtin_amdgcn_mfma_f32_16x16x32_bf16(Bt[n][k], At[m][k], acc[ai][bj][m][n], 0, 0, 0); __builtin_amdgcn_s_setprio(0); } while (0)
; #define PG8_WAIT_V(n) asm volatile("s_waitcnt vmcnt(" #n ")" ::: "memory")
; #define PG8_WAIT_L(n) asm volatile("s_waitcnt lgkmcnt(" #n ")" ::: "memory")
; #define PG8_BAR __builtin_amdgcn_s_barrier()
; #define PG8_SCHED __builtin_amdgcn_sched_barrier(0)
; template <class Epi, class Sched, bool ALIGN_EPI = false, bool SP2 = false>
; __device__ __forceinline__ void gemm_phase(PG8_LAS unsigned char* lds, const Gemm g, const Sched& S, const Epi& E) {
;     ...
;             PG8_LDB(B0, 1, 0); PG8_LDB(B1, 1, 1); PG8_SCHED; PG8_LDA(At, 1, 0); PG8_STAGE(PG8_SA(0, 1), a2 + hstepA, voffA);
;             PG8_WAIT_V(8); PG8_WAIT_L(0); PG8_BAR; PG8_MMA(0, 0, At, B0); PG8_MMA(0, 1, At, B1); PG8_BAR; PG8_SCHED;
;             PG8_LDA(At, 1, 1); PG8_STAGE(PG8_SB(1, 0), b3, voffB); PG8_STAGE(PG8_SB(1, 1), b3 + hstep, voffB); PG8_STAGE(PG8_SA(1, 0), a3, voffA);
;             PG8_WAIT_V(8); PG8_WAIT_L(0); PG8_BAR; PG8_MMA(1, 0, At, B0); PG8_MMA(1, 1, At, B1); PG8_BAR; PG8_SCHED;
	s_add_i32 s69, 0, 0x18000
	s_add_i32 s70, 0, 0x1c000
	v_add_u32_e32 v162, s69, v145
	v_add_u32_e32 v178, s70, v145
	ds_read_b128 v[150:153], v162
	ds_read_b128 v[154:157], v162 offset:1024
	ds_read_b128 v[158:161], v162 offset:2048
	ds_read_b128 v[162:165], v162 offset:3072
	ds_read_b128 v[166:169], v178
	ds_read_b128 v[170:173], v178 offset:1024
	ds_read_b128 v[174:177], v178 offset:2048
	ds_read_b128 v[178:181], v178 offset:3072
	s_mov_b64 vcc, s[40:41]
	s_add_u32 s40, s40, 0x40000
	s_addc_u32 s41, s41, 0
	s_mov_b32 m0, s51
	ds_read_b128 v[182:185], v149 offset:32768
	ds_read_b128 v[190:193], v149 offset:33792
	ds_read_b128 v[194:197], v149 offset:34816
	ds_read_b128 v[198:201], v149 offset:35840
	ds_read_b128 v[202:205], v149 offset:36864
	ds_read_b128 v[206:209], v149 offset:37888
	ds_read_b128 v[210:213], v149 offset:38912
	global_load_lds_dwordx4 v128, s[40:41]
	s_mov_b32 m0, s52
	ds_read_b128 v[214:217], v149 offset:39936
	global_load_lds_dwordx4 v130, s[40:41]
	s_waitcnt vmcnt(8) lgkmcnt(0)
	s_setprio 1
	s_barrier
	v_mfma_f32_16x16x32_bf16 v[120:123], v[150:153], v[182:185], v[120:123]
	v_mfma_f32_16x16x32_bf16 v[124:127], v[158:161], v[182:185], v[124:127]
	v_mfma_f32_16x16x32_bf16 v[108:111], v[150:153], v[194:197], v[108:111]
	v_mfma_f32_16x16x32_bf16 v[104:107], v[158:161], v[194:197], v[104:107]
	v_mfma_f32_16x16x32_bf16 v[92:95], v[150:153], v[202:205], v[92:95]
	v_mfma_f32_16x16x32_bf16 v[88:91], v[158:161], v[202:205], v[88:91]
	v_mfma_f32_16x16x32_bf16 v[76:79], v[150:153], v[210:213], v[76:79]
	v_mfma_f32_16x16x32_bf16 v[72:75], v[158:161], v[210:213], v[72:75]
	v_mfma_f32_16x16x32_bf16 v[120:123], v[154:157], v[190:193], v[120:123]
	v_mfma_f32_16x16x32_bf16 v[124:127], v[162:165], v[190:193], v[124:127]
	v_mfma_f32_16x16x32_bf16 v[108:111], v[154:157], v[198:201], v[108:111]
	v_mfma_f32_16x16x32_bf16 v[104:107], v[162:165], v[198:201], v[104:107]
	v_mfma_f32_16x16x32_bf16 v[92:95], v[154:157], v[206:209], v[92:95]
	v_mfma_f32_16x16x32_bf16 v[88:91], v[162:165], v[206:209], v[88:91]
	v_mfma_f32_16x16x32_bf16 v[76:79], v[154:157], v[214:217], v[76:79]
	v_mfma_f32_16x16x32_bf16 v[72:75], v[162:165], v[214:217], v[72:75]
	v_mfma_f32_16x16x32_bf16 v[116:119], v[166:169], v[182:185], v[116:119]
	v_mfma_f32_16x16x32_bf16 v[112:115], v[174:177], v[182:185], v[112:115]
	v_mfma_f32_16x16x32_bf16 v[100:103], v[166:169], v[194:197], v[100:103]
	v_mfma_f32_16x16x32_bf16 v[96:99], v[174:177], v[194:197], v[96:99]
	v_mfma_f32_16x16x32_bf16 v[84:87], v[166:169], v[202:205], v[84:87]
	v_mfma_f32_16x16x32_bf16 v[80:83], v[174:177], v[202:205], v[80:83]
	v_mfma_f32_16x16x32_bf16 v[68:71], v[166:169], v[210:213], v[68:71]
	v_mfma_f32_16x16x32_bf16 v[64:67], v[174:177], v[210:213], v[64:67]
	v_mfma_f32_16x16x32_bf16 v[116:119], v[170:173], v[190:193], v[116:119]
	v_mfma_f32_16x16x32_bf16 v[112:115], v[178:181], v[190:193], v[112:115]
	v_mfma_f32_16x16x32_bf16 v[100:103], v[170:173], v[198:201], v[100:103]
	v_mfma_f32_16x16x32_bf16 v[96:99], v[178:181], v[198:201], v[96:99]
	v_mfma_f32_16x16x32_bf16 v[84:87], v[170:173], v[206:209], v[84:87]
	v_mfma_f32_16x16x32_bf16 v[80:83], v[178:181], v[206:209], v[80:83]
	v_mfma_f32_16x16x32_bf16 v[68:71], v[170:173], v[214:217], v[68:71]
	v_mfma_f32_16x16x32_bf16 v[64:67], v[178:181], v[214:217], v[64:67]
	s_setprio 0
	s_barrier
	s_add_i32 s40, s69, s47
	s_add_i32 m0, s40, 0xffffff80
	ds_read_b128 v[182:185], v149 offset:49152
	ds_read_b128 v[190:193], v149 offset:50176
	ds_read_b128 v[194:197], v149 offset:51200
	ds_read_b128 v[198:201], v149 offset:52224
	global_load_lds_dwordx4 v134, s[100:101] offset:128
	s_add_i32 m0, s40, 0x1f80
	s_add_i32 s40, s70, s47
	global_load_lds_dwordx4 v132, s[100:101] offset:128
	s_add_u32 s100, s100, s4
	s_addc_u32 s101, s101, s5
	s_add_i32 m0, s40, 0xffffff80
	ds_read_b128 v[214:217], v149 offset:56320
	global_load_lds_dwordx4 v134, s[100:101] offset:128
	s_add_i32 m0, s40, 0x1f80
	ds_read_b128 v[210:213], v149 offset:55296
	global_load_lds_dwordx4 v132, s[100:101] offset:128
	s_add_i32 m0, s55, 0xffffff80
	ds_read_b128 v[206:209], v149 offset:54272
	global_load_lds_dwordx4 v128, vcc offset:128
	s_add_i32 m0, s56, 0xffffff80
	ds_read_b128 v[202:205], v149 offset:53248
	global_load_lds_dwordx4 v130, vcc offset:128
	s_waitcnt vmcnt(8) lgkmcnt(0)
	s_setprio 1
	s_barrier
	v_mfma_f32_16x16x32_bf16 v[60:63], v[150:153], v[182:185], v[60:63]
	v_mfma_f32_16x16x32_bf16 v[56:59], v[158:161], v[182:185], v[56:59]
	v_mfma_f32_16x16x32_bf16 v[44:47], v[150:153], v[194:197], v[44:47]
	v_mfma_f32_16x16x32_bf16 v[40:43], v[158:161], v[194:197], v[40:43]
	v_mfma_f32_16x16x32_bf16 v[28:31], v[150:153], v[202:205], v[28:31]
	v_mfma_f32_16x16x32_bf16 v[24:27], v[158:161], v[202:205], v[24:27]
	v_mfma_f32_16x16x32_bf16 v[12:15], v[150:153], v[210:213], v[12:15]
	v_mfma_f32_16x16x32_bf16 v[8:11], v[158:161], v[210:213], v[8:11]
	v_mfma_f32_16x16x32_bf16 v[60:63], v[154:157], v[190:193], v[60:63]
	v_mfma_f32_16x16x32_bf16 v[56:59], v[162:165], v[190:193], v[56:59]
	v_mfma_f32_16x16x32_bf16 v[44:47], v[154:157], v[198:201], v[44:47]
	v_mfma_f32_16x16x32_bf16 v[40:43], v[162:165], v[198:201], v[40:43]
	v_mfma_f32_16x16x32_bf16 v[28:31], v[154:157], v[206:209], v[28:31]
	v_mfma_f32_16x16x32_bf16 v[24:27], v[162:165], v[206:209], v[24:27]
	v_mfma_f32_16x16x32_bf16 v[12:15], v[154:157], v[214:217], v[12:15]
	v_mfma_f32_16x16x32_bf16 v[8:11], v[162:165], v[214:217], v[8:11]
	v_mfma_f32_16x16x32_bf16 v[52:55], v[166:169], v[182:185], v[52:55]
	v_mfma_f32_16x16x32_bf16 v[48:51], v[174:177], v[182:185], v[48:51]
	v_mfma_f32_16x16x32_bf16 v[36:39], v[166:169], v[194:197], v[36:39]
	v_mfma_f32_16x16x32_bf16 v[32:35], v[174:177], v[194:197], v[32:35]
	v_mfma_f32_16x16x32_bf16 v[20:23], v[166:169], v[202:205], v[20:23]
	v_mfma_f32_16x16x32_bf16 v[16:19], v[174:177], v[202:205], v[16:19]
	v_mfma_f32_16x16x32_bf16 v[4:7], v[166:169], v[210:213], v[4:7]
	v_mfma_f32_16x16x32_bf16 v[0:3], v[174:177], v[210:213], v[0:3]
	v_mfma_f32_16x16x32_bf16 v[52:55], v[170:173], v[190:193], v[52:55]
	v_mfma_f32_16x16x32_bf16 v[48:51], v[178:181], v[190:193], v[48:51]
	v_mfma_f32_16x16x32_bf16 v[36:39], v[170:173], v[198:201], v[36:39]
	v_mfma_f32_16x16x32_bf16 v[32:35], v[178:181], v[198:201], v[32:35]
	v_mfma_f32_16x16x32_bf16 v[20:23], v[170:173], v[206:209], v[20:23]
	v_mfma_f32_16x16x32_bf16 v[16:19], v[178:181], v[206:209], v[16:19]
	v_mfma_f32_16x16x32_bf16 v[4:7], v[170:173], v[214:217], v[4:7]
	v_mfma_f32_16x16x32_bf16 v[0:3], v[178:181], v[214:217], v[0:3]
	s_setprio 0
	s_barrier
	s_add_u32 s8, s8, 0x100
	s_addc_u32 s9, s9, 0
	s_add_u32 s42, s42, 0x100
	s_addc_u32 s43, s43, 0
	s_cmp_ge_i32 s68, s58
	s_mov_b32 s40, s68
	s_cbranch_scc0 .LBB0_1236

; #define PG8_STAGE(bufoff, gbase, voff) do { _Pragma("unroll") for (int _i = 0; _i < 2; ++_i) \
;         __builtin_amdgcn_global_load_lds((const unsigned*)((const char*)(gbase) + (voff)[_i]), (PG8_LAS unsigned*)(lds + (bufoff) + ldsw + _i * 8192), 16, 0, 0); } while (0)
; #define PG8_LDA(dst, b, h) do { _Pragma("unroll") for (int m = 0; m < 4; ++m) _Pragma("unroll") for (int k = 0; k < 2; ++k) dst[m][k] = *(const PG8_LAS bf16x8*)(lds + PG8_SA(b, h) + aoff + m * 2048 + k * 1024); } while (0)
; #define PG8_LDB(dst, b, h) do { _Pragma("unroll") for (int n = 0; n < 2; ++n) _Pragma("unroll") for (int k = 0; k < 2; ++k) dst[n][k] = *(const PG8_LAS bf16x8*)(lds + PG8_SB(b, h) + boff + n * 2048 + k * 1024); } while (0)
; #define PG8_MMA(ai, bj, At, Bt) do { __builtin_amdgcn_s_setprio(1); _Pragma("unroll") for (int m = 0; m < 4; ++m) _Pragma("unroll") for (int n = 0; n < 2; ++n) _Pragma("unroll") for (int k = 0; k < 2; ++k) \
;         acc[ai][bj][m][n] = __builtin_amdgcn_mfma_f32_16x16x32_bf16(Bt[n][k], At[m][k], acc[ai][bj][m][n], 0, 0, 0); __builtin_amdgcn_s_setprio(0); } while (0)
; #define PG8_WAIT_V(n) asm volatile("s_waitcnt vmcnt(" #n ")" ::: "memory")
; #define PG8_WAIT_L(n) asm volatile("s_waitcnt lgkmcnt(" #n ")" ::: "memory")
; template <class Epi, class Sched, bool ALIGN_EPI = false, bool SP2 = false>
; __device__ __forceinline__ void gemm_phase(PG8_LAS unsigned char* lds, const Gemm g, const Sched& S, const Epi& E) {
;     ...
;             const bool last = (t == nt - 2);
;             const char* a1 = cA + (size_t)(t + 1) * kstep;
;             const char* a2 = last ? nA : cA + (size_t)(t + 2) * kstep; const char* b2 = last ? nB : cB + (size_t)(t + 2) * kstep;
;             const char* a3 = a2 + kstep; const char* b3 = b2 + kstep;
;             if (last && has_next) S.a_ready(nxt);
;             if constexpr (SP2) {
;             PG8_LDB(B0, 0, 0); PG8_LDB(B1, 0, 1); PG8_SCHED; PG8_LDA(At, 0, 0); PG8_STAGE(PG8_SA(1, 1), a1 + hstepA, voffA);
;             PG8_WAIT_V(8); PG8_WAIT_L(0); PG8_BAR; PG8_MMA(0, 0, At, B0); PG8_MMA(0, 1, At, B1); PG8_BAR; PG8_SCHED;
;             PG8_LDA(At, 0, 1); PG8_STAGE(PG8_SB(0, 0), b2, voffB); PG8_STAGE(PG8_SB(0, 1), b2 + hstep, voffB); PG8_STAGE(PG8_SA(0, 0), a2, voffA);
;             PG8_WAIT_V(8); PG8_WAIT_L(0); PG8_BAR; PG8_MMA(1, 0, At, B0); PG8_MMA(1, 1, At, B1); PG8_BAR; PG8_SCHED;
.LBB0_1480:
	ds_read_b128 v[162:165], v159
	ds_read_b128 v[166:169], v159 offset:1024
	ds_read_b128 v[170:173], v159 offset:2048
	ds_read_b128 v[174:177], v159 offset:3072
	ds_read_b128 v[178:181], v160
	ds_read_b128 v[182:185], v160 offset:1024
	ds_read_b128 v[190:193], v160 offset:2048
	ds_read_b128 v[194:197], v160 offset:3072
	s_add_i32 s63, s36, 2
	s_add_u32 s64, s10, 0xfffe0080
	s_addc_u32 s37, s11, -1
	s_cmp_eq_u32 s56, s36
	s_cselect_b32 s36, s62, s64
	s_cselect_b32 s37, s29, s37
	s_cselect_b32 s65, s31, s39
	s_cselect_b32 s64, s30, s38
	s_add_i32 m0, s27, 0xc000
	ds_read_b128 v[198:201], v161
	ds_read_b128 v[202:205], v161 offset:1024
	ds_read_b128 v[206:209], v161 offset:2048
	ds_read_b128 v[210:213], v161 offset:3072
	ds_read_b128 v[214:217], v161 offset:4096
	ds_read_b128 v[218:221], v161 offset:5120
	ds_read_b128 v[222:225], v161 offset:6144
	global_load_lds_dwordx4 v138, s[10:11]
	s_add_i32 m0, s27, 0xe000
	ds_read_b128 v[226:229], v161 offset:7168
	global_load_lds_dwordx4 v140, s[10:11]
	s_waitcnt vmcnt(8) lgkmcnt(0)
	s_setprio 1
	s_barrier
	v_mfma_f32_16x16x32_bf16 v[124:127], v[162:165], v[198:201], v[124:127]
	v_mfma_f32_16x16x32_bf16 v[120:123], v[170:173], v[198:201], v[120:123]
	v_mfma_f32_16x16x32_bf16 v[108:111], v[162:165], v[206:209], v[108:111]
	v_mfma_f32_16x16x32_bf16 v[104:107], v[170:173], v[206:209], v[104:107]
	v_mfma_f32_16x16x32_bf16 v[92:95], v[162:165], v[214:217], v[92:95]
	v_mfma_f32_16x16x32_bf16 v[88:91], v[170:173], v[214:217], v[88:91]
	v_mfma_f32_16x16x32_bf16 v[76:79], v[162:165], v[222:225], v[76:79]
	v_mfma_f32_16x16x32_bf16 v[72:75], v[170:173], v[222:225], v[72:75]
	v_mfma_f32_16x16x32_bf16 v[124:127], v[166:169], v[202:205], v[124:127]
	v_mfma_f32_16x16x32_bf16 v[120:123], v[174:177], v[202:205], v[120:123]
	v_mfma_f32_16x16x32_bf16 v[108:111], v[166:169], v[210:213], v[108:111]
	v_mfma_f32_16x16x32_bf16 v[104:107], v[174:177], v[210:213], v[104:107]
	v_mfma_f32_16x16x32_bf16 v[92:95], v[166:169], v[218:221], v[92:95]
	v_mfma_f32_16x16x32_bf16 v[88:91], v[174:177], v[218:221], v[88:91]
	v_mfma_f32_16x16x32_bf16 v[76:79], v[166:169], v[226:229], v[76:79]
	v_mfma_f32_16x16x32_bf16 v[72:75], v[174:177], v[226:229], v[72:75]
	v_mfma_f32_16x16x32_bf16 v[116:119], v[178:181], v[198:201], v[116:119]
	v_mfma_f32_16x16x32_bf16 v[112:115], v[190:193], v[198:201], v[112:115]
	v_mfma_f32_16x16x32_bf16 v[100:103], v[178:181], v[206:209], v[100:103]
	v_mfma_f32_16x16x32_bf16 v[96:99], v[190:193], v[206:209], v[96:99]
	v_mfma_f32_16x16x32_bf16 v[84:87], v[178:181], v[214:217], v[84:87]
	v_mfma_f32_16x16x32_bf16 v[80:83], v[190:193], v[214:217], v[80:83]
	v_mfma_f32_16x16x32_bf16 v[68:71], v[178:181], v[222:225], v[68:71]
	v_mfma_f32_16x16x32_bf16 v[64:67], v[190:193], v[222:225], v[64:67]
	v_mfma_f32_16x16x32_bf16 v[116:119], v[182:185], v[202:205], v[116:119]
	v_mfma_f32_16x16x32_bf16 v[112:115], v[194:197], v[202:205], v[112:115]
	v_mfma_f32_16x16x32_bf16 v[100:103], v[182:185], v[210:213], v[100:103]
	v_mfma_f32_16x16x32_bf16 v[96:99], v[194:197], v[210:213], v[96:99]
	v_mfma_f32_16x16x32_bf16 v[84:87], v[182:185], v[218:221], v[84:87]
	v_mfma_f32_16x16x32_bf16 v[80:83], v[194:197], v[218:221], v[80:83]
	v_mfma_f32_16x16x32_bf16 v[68:71], v[182:185], v[226:229], v[68:71]
	v_mfma_f32_16x16x32_bf16 v[64:67], v[194:197], v[226:229], v[64:67]
	s_setprio 0
	s_barrier
	s_add_i32 s66, s57, s47
	s_mov_b32 m0, s66
	ds_read_b128 v[198:201], v161 offset:16384
	ds_read_b128 v[202:205], v161 offset:17408
	ds_read_b128 v[206:209], v161 offset:18432
	ds_read_b128 v[210:213], v161 offset:19456
	global_load_lds_dwordx4 v136, s[64:65]
	s_add_i32 m0, s66, 0x2000
	s_mov_b64 s[100:101], s[64:65]
	s_add_i32 s66, s58, s47
	global_load_lds_dwordx4 v134, s[64:65]
	s_add_u32 s64, s64, s16
	s_addc_u32 s65, s65, s17
	s_mov_b32 m0, s66
	ds_read_b128 v[226:229], v161 offset:23552
	global_load_lds_dwordx4 v136, s[64:65]
	s_add_i32 m0, s66, 0x2000
	ds_read_b128 v[222:225], v161 offset:22528
	global_load_lds_dwordx4 v134, s[64:65]
	s_mov_b32 m0, s27
	ds_read_b128 v[218:221], v161 offset:21504
	global_load_lds_dwordx4 v130, s[36:37]
	s_mov_b32 m0, s48
	ds_read_b128 v[214:217], v161 offset:20480
	global_load_lds_dwordx4 v132, s[36:37]
	s_waitcnt vmcnt(8) lgkmcnt(0)
	s_setprio 1
	s_barrier
	v_mfma_f32_16x16x32_bf16 v[60:63], v[162:165], v[198:201], v[60:63]
	v_mfma_f32_16x16x32_bf16 v[56:59], v[170:173], v[198:201], v[56:59]
	v_mfma_f32_16x16x32_bf16 v[44:47], v[162:165], v[206:209], v[44:47]
	v_mfma_f32_16x16x32_bf16 v[40:43], v[170:173], v[206:209], v[40:43]
	v_mfma_f32_16x16x32_bf16 v[28:31], v[162:165], v[214:217], v[28:31]
	v_mfma_f32_16x16x32_bf16 v[24:27], v[170:173], v[214:217], v[24:27]
	v_mfma_f32_16x16x32_bf16 v[12:15], v[162:165], v[222:225], v[12:15]
	v_mfma_f32_16x16x32_bf16 v[8:11], v[170:173], v[222:225], v[8:11]
	v_mfma_f32_16x16x32_bf16 v[60:63], v[166:169], v[202:205], v[60:63]
	v_mfma_f32_16x16x32_bf16 v[56:59], v[174:177], v[202:205], v[56:59]
	v_mfma_f32_16x16x32_bf16 v[44:47], v[166:169], v[210:213], v[44:47]
	v_mfma_f32_16x16x32_bf16 v[40:43], v[174:177], v[210:213], v[40:43]
	v_mfma_f32_16x16x32_bf16 v[28:31], v[166:169], v[218:221], v[28:31]
	v_mfma_f32_16x16x32_bf16 v[24:27], v[174:177], v[218:221], v[24:27]
	v_mfma_f32_16x16x32_bf16 v[12:15], v[166:169], v[226:229], v[12:15]
	v_mfma_f32_16x16x32_bf16 v[8:11], v[174:177], v[226:229], v[8:11]
	v_mfma_f32_16x16x32_bf16 v[52:55], v[178:181], v[198:201], v[52:55]
	v_mfma_f32_16x16x32_bf16 v[48:51], v[190:193], v[198:201], v[48:51]
	v_mfma_f32_16x16x32_bf16 v[36:39], v[178:181], v[206:209], v[36:39]
	v_mfma_f32_16x16x32_bf16 v[32:35], v[190:193], v[206:209], v[32:35]
	v_mfma_f32_16x16x32_bf16 v[20:23], v[178:181], v[214:217], v[20:23]
	v_mfma_f32_16x16x32_bf16 v[16:19], v[190:193], v[214:217], v[16:19]
	v_mfma_f32_16x16x32_bf16 v[4:7], v[178:181], v[222:225], v[4:7]
	v_mfma_f32_16x16x32_bf16 v[0:3], v[190:193], v[222:225], v[0:3]
	v_mfma_f32_16x16x32_bf16 v[52:55], v[182:185], v[202:205], v[52:55]
	v_mfma_f32_16x16x32_bf16 v[48:51], v[194:197], v[202:205], v[48:51]
	v_mfma_f32_16x16x32_bf16 v[36:39], v[182:185], v[210:213], v[36:39]
	v_mfma_f32_16x16x32_bf16 v[32:35], v[194:197], v[210:213], v[32:35]
	v_mfma_f32_16x16x32_bf16 v[20:23], v[182:185], v[218:221], v[20:23]
	v_mfma_f32_16x16x32_bf16 v[16:19], v[194:197], v[218:221], v[16:19]
	v_mfma_f32_16x16x32_bf16 v[4:7], v[182:185], v[226:229], v[4:7]
	v_mfma_f32_16x16x32_bf16 v[0:3], v[194:197], v[226:229], v[0:3]
	s_setprio 0
	s_barrier
; #define PG8_STAGE(bufoff, gbase, voff) do { _Pragma("unroll") for (int _i = 0; _i < 2; ++_i) \
;         __builtin_amdgcn_global_load_lds((const unsigned*)((const char*)(gbase) + (voff)[_i]), (PG8_LAS unsigned*)(lds + (bufoff) + ldsw + _i * 8192), 16, 0, 0); } while (0)
; #define PG8_LDA(dst, b, h) do { _Pragma("unroll") for (int m = 0; m < 4; ++m) _Pragma("unroll") for (int k = 0; k < 2; ++k) dst[m][k] = *(const PG8_LAS bf16x8*)(lds + PG8_SA(b, h) + aoff + m * 2048 + k * 1024); } while (0)
; #define PG8_LDB(dst, b, h) do { _Pragma("unroll") for (int n = 0; n < 2; ++n) _Pragma("unroll") for (int k = 0; k < 2; ++k) dst[n][k] = *(const PG8_LAS bf16x8*)(lds + PG8_SB(b, h) + boff + n * 2048 + k * 1024); } while (0)
; #define PG8_MMA(ai, bj, At, Bt) do { __builtin_amdgcn_s_setprio(1); _Pragma("unroll") for (int m = 0; m < 4; ++m) _Pragma("unroll") for (int n = 0; n < 2; ++n) _Pragma("unroll") for (int k = 0; k < 2; ++k) \
;         acc[ai][bj][m][n] = __builtin_amdgcn_mfma_f32_16x16x32_bf16(Bt[n][k], At[m][k], acc[ai][bj][m][n], 0, 0, 0); __builtin_amdgcn_s_setprio(0); } while (0)
; #define PG8_WAIT_V(n) asm volatile("s_waitcnt vmcnt(" #n ")" ::: "memory")
; #define PG8_WAIT_L(n) asm volatile("s_waitcnt lgkmcnt(" #n ")" ::: "memory")
; #define PG8_BAR __builtin_amdgcn_s_barrier()
; #define PG8_SCHED __builtin_amdgcn_sched_barrier(0)
; template <class Epi, class Sched, bool ALIGN_EPI = false, bool SP2 = false>
; __device__ __forceinline__ void gemm_phase(PG8_LAS unsigned char* lds, const Gemm g, const Sched& S, const Epi& E) {
;     ...
;             PG8_LDB(B0, 1, 0); PG8_LDB(B1, 1, 1); PG8_SCHED; PG8_LDA(At, 1, 0); PG8_STAGE(PG8_SA(0, 1), a2 + hstepA, voffA);
;             PG8_WAIT_V(8); PG8_WAIT_L(0); PG8_BAR; PG8_MMA(0, 0, At, B0); PG8_MMA(0, 1, At, B1); PG8_BAR; PG8_SCHED;
;             PG8_LDA(At, 1, 1); PG8_STAGE(PG8_SB(1, 0), b3, voffB); PG8_STAGE(PG8_SB(1, 1), b3 + hstep, voffB); PG8_STAGE(PG8_SA(1, 0), a3, voffA);
;             PG8_WAIT_V(8); PG8_WAIT_L(0); PG8_BAR; PG8_MMA(1, 0, At, B0); PG8_MMA(1, 1, At, B1); PG8_BAR; PG8_SCHED;
	s_add_i32 s64, 0, 0x18000
	s_add_i32 s65, 0, 0x1c000
	v_add_u32_e32 v174, s64, v157
	v_add_u32_e32 v194, s65, v157
	ds_read_b128 v[162:165], v174
	ds_read_b128 v[166:169], v174 offset:1024
	ds_read_b128 v[170:173], v174 offset:2048
	ds_read_b128 v[174:177], v174 offset:3072
	ds_read_b128 v[178:181], v194
	ds_read_b128 v[182:185], v194 offset:1024
	ds_read_b128 v[190:193], v194 offset:2048
	ds_read_b128 v[194:197], v194 offset:3072
	s_mov_b64 vcc, s[36:37]
	s_add_u32 s36, s36, 0x20000
	s_addc_u32 s37, s37, 0
	s_mov_b32 m0, s49
	ds_read_b128 v[198:201], v161 offset:32768
	ds_read_b128 v[202:205], v161 offset:33792
	ds_read_b128 v[206:209], v161 offset:34816
	ds_read_b128 v[210:213], v161 offset:35840
	ds_read_b128 v[214:217], v161 offset:36864
	ds_read_b128 v[218:221], v161 offset:37888
	ds_read_b128 v[222:225], v161 offset:38912
	global_load_lds_dwordx4 v130, s[36:37]
	s_mov_b32 m0, s50
	ds_read_b128 v[226:229], v161 offset:39936
	global_load_lds_dwordx4 v132, s[36:37]
	s_waitcnt vmcnt(8) lgkmcnt(0)
	s_setprio 1
	s_barrier
	v_mfma_f32_16x16x32_bf16 v[124:127], v[162:165], v[198:201], v[124:127]
	v_mfma_f32_16x16x32_bf16 v[120:123], v[170:173], v[198:201], v[120:123]
	v_mfma_f32_16x16x32_bf16 v[108:111], v[162:165], v[206:209], v[108:111]
	v_mfma_f32_16x16x32_bf16 v[104:107], v[170:173], v[206:209], v[104:107]
	v_mfma_f32_16x16x32_bf16 v[92:95], v[162:165], v[214:217], v[92:95]
	v_mfma_f32_16x16x32_bf16 v[88:91], v[170:173], v[214:217], v[88:91]
	v_mfma_f32_16x16x32_bf16 v[76:79], v[162:165], v[222:225], v[76:79]
	v_mfma_f32_16x16x32_bf16 v[72:75], v[170:173], v[222:225], v[72:75]
	v_mfma_f32_16x16x32_bf16 v[124:127], v[166:169], v[202:205], v[124:127]
	v_mfma_f32_16x16x32_bf16 v[120:123], v[174:177], v[202:205], v[120:123]
	v_mfma_f32_16x16x32_bf16 v[108:111], v[166:169], v[210:213], v[108:111]
	v_mfma_f32_16x16x32_bf16 v[104:107], v[174:177], v[210:213], v[104:107]
	v_mfma_f32_16x16x32_bf16 v[92:95], v[166:169], v[218:221], v[92:95]
	v_mfma_f32_16x16x32_bf16 v[88:91], v[174:177], v[218:221], v[88:91]
	v_mfma_f32_16x16x32_bf16 v[76:79], v[166:169], v[226:229], v[76:79]
	v_mfma_f32_16x16x32_bf16 v[72:75], v[174:177], v[226:229], v[72:75]
	v_mfma_f32_16x16x32_bf16 v[116:119], v[178:181], v[198:201], v[116:119]
	v_mfma_f32_16x16x32_bf16 v[112:115], v[190:193], v[198:201], v[112:115]
	v_mfma_f32_16x16x32_bf16 v[100:103], v[178:181], v[206:209], v[100:103]
	v_mfma_f32_16x16x32_bf16 v[96:99], v[190:193], v[206:209], v[96:99]
	v_mfma_f32_16x16x32_bf16 v[84:87], v[178:181], v[214:217], v[84:87]
	v_mfma_f32_16x16x32_bf16 v[80:83], v[190:193], v[214:217], v[80:83]
	v_mfma_f32_16x16x32_bf16 v[68:71], v[178:181], v[222:225], v[68:71]
	v_mfma_f32_16x16x32_bf16 v[64:67], v[190:193], v[222:225], v[64:67]
	v_mfma_f32_16x16x32_bf16 v[116:119], v[182:185], v[202:205], v[116:119]
	v_mfma_f32_16x16x32_bf16 v[112:115], v[194:197], v[202:205], v[112:115]
	v_mfma_f32_16x16x32_bf16 v[100:103], v[182:185], v[210:213], v[100:103]
	v_mfma_f32_16x16x32_bf16 v[96:99], v[194:197], v[210:213], v[96:99]
	v_mfma_f32_16x16x32_bf16 v[84:87], v[182:185], v[218:221], v[84:87]
	v_mfma_f32_16x16x32_bf16 v[80:83], v[194:197], v[218:221], v[80:83]
	v_mfma_f32_16x16x32_bf16 v[68:71], v[182:185], v[226:229], v[68:71]
	v_mfma_f32_16x16x32_bf16 v[64:67], v[194:197], v[226:229], v[64:67]
	s_setprio 0
	s_barrier
	s_add_i32 s36, s64, s47
	s_add_i32 m0, s36, 0xffffff80
	ds_read_b128 v[198:201], v161 offset:49152
	ds_read_b128 v[202:205], v161 offset:50176
	ds_read_b128 v[206:209], v161 offset:51200
	ds_read_b128 v[210:213], v161 offset:52224
	global_load_lds_dwordx4 v136, s[100:101] offset:128
	s_add_i32 m0, s36, 0x1f80
	s_add_i32 s36, s65, s47
	global_load_lds_dwordx4 v134, s[100:101] offset:128
	s_add_u32 s100, s100, s16
	s_addc_u32 s101, s101, s17
	s_add_i32 m0, s36, 0xffffff80
	ds_read_b128 v[226:229], v161 offset:56320
	global_load_lds_dwordx4 v136, s[100:101] offset:128
	s_add_i32 m0, s36, 0x1f80
	ds_read_b128 v[222:225], v161 offset:55296
	global_load_lds_dwordx4 v134, s[100:101] offset:128
	s_add_i32 m0, s51, 0xffffff80
	ds_read_b128 v[218:221], v161 offset:54272
	global_load_lds_dwordx4 v130, vcc offset:128
	s_add_i32 m0, s52, 0xffffff80
	ds_read_b128 v[214:217], v161 offset:53248
	global_load_lds_dwordx4 v132, vcc offset:128
	s_waitcnt vmcnt(8) lgkmcnt(0)
	s_setprio 1
	s_barrier
	v_mfma_f32_16x16x32_bf16 v[60:63], v[162:165], v[198:201], v[60:63]
	v_mfma_f32_16x16x32_bf16 v[56:59], v[170:173], v[198:201], v[56:59]
	v_mfma_f32_16x16x32_bf16 v[44:47], v[162:165], v[206:209], v[44:47]
	v_mfma_f32_16x16x32_bf16 v[40:43], v[170:173], v[206:209], v[40:43]
	v_mfma_f32_16x16x32_bf16 v[28:31], v[162:165], v[214:217], v[28:31]
	v_mfma_f32_16x16x32_bf16 v[24:27], v[170:173], v[214:217], v[24:27]
	v_mfma_f32_16x16x32_bf16 v[12:15], v[162:165], v[222:225], v[12:15]
	v_mfma_f32_16x16x32_bf16 v[8:11], v[170:173], v[222:225], v[8:11]
	v_mfma_f32_16x16x32_bf16 v[60:63], v[166:169], v[202:205], v[60:63]
	v_mfma_f32_16x16x32_bf16 v[56:59], v[174:177], v[202:205], v[56:59]
	v_mfma_f32_16x16x32_bf16 v[44:47], v[166:169], v[210:213], v[44:47]
	v_mfma_f32_16x16x32_bf16 v[40:43], v[174:177], v[210:213], v[40:43]
	v_mfma_f32_16x16x32_bf16 v[28:31], v[166:169], v[218:221], v[28:31]
	v_mfma_f32_16x16x32_bf16 v[24:27], v[174:177], v[218:221], v[24:27]
	v_mfma_f32_16x16x32_bf16 v[12:15], v[166:169], v[226:229], v[12:15]
	v_mfma_f32_16x16x32_bf16 v[8:11], v[174:177], v[226:229], v[8:11]
	v_mfma_f32_16x16x32_bf16 v[52:55], v[178:181], v[198:201], v[52:55]
	v_mfma_f32_16x16x32_bf16 v[48:51], v[190:193], v[198:201], v[48:51]
	v_mfma_f32_16x16x32_bf16 v[36:39], v[178:181], v[206:209], v[36:39]
	v_mfma_f32_16x16x32_bf16 v[32:35], v[190:193], v[206:209], v[32:35]
	v_mfma_f32_16x16x32_bf16 v[20:23], v[178:181], v[214:217], v[20:23]
	v_mfma_f32_16x16x32_bf16 v[16:19], v[190:193], v[214:217], v[16:19]
	v_mfma_f32_16x16x32_bf16 v[4:7], v[178:181], v[222:225], v[4:7]
	v_mfma_f32_16x16x32_bf16 v[0:3], v[190:193], v[222:225], v[0:3]
	v_mfma_f32_16x16x32_bf16 v[52:55], v[182:185], v[202:205], v[52:55]
	v_mfma_f32_16x16x32_bf16 v[48:51], v[194:197], v[202:205], v[48:51]
	v_mfma_f32_16x16x32_bf16 v[36:39], v[182:185], v[210:213], v[36:39]
	v_mfma_f32_16x16x32_bf16 v[32:35], v[194:197], v[210:213], v[32:35]
	v_mfma_f32_16x16x32_bf16 v[20:23], v[182:185], v[218:221], v[20:23]
	v_mfma_f32_16x16x32_bf16 v[16:19], v[194:197], v[218:221], v[16:19]
	v_mfma_f32_16x16x32_bf16 v[4:7], v[182:185], v[226:229], v[4:7]
	v_mfma_f32_16x16x32_bf16 v[0:3], v[194:197], v[226:229], v[0:3]
	s_setprio 0
	s_barrier
	s_add_u32 s10, s10, 0x100
	s_addc_u32 s11, s11, 0
	s_add_u32 s38, s38, 0x100
	s_addc_u32 s39, s39, 0
	s_cmp_ge_i32 s63, s53
	s_mov_b32 s36, s63
	s_cbranch_scc0 .LBB0_1480

; #define PG8_STAGE(bufoff, gbase, voff) do { _Pragma("unroll") for (int _i = 0; _i < 2; ++_i) \
;         __builtin_amdgcn_global_load_lds((const unsigned*)((const char*)(gbase) + (voff)[_i]), (PG8_LAS unsigned*)(lds + (bufoff) + ldsw + _i * 8192), 16, 0, 0); } while (0)
; #define PG8_LDA(dst, b, h) do { _Pragma("unroll") for (int m = 0; m < 4; ++m) _Pragma("unroll") for (int k = 0; k < 2; ++k) dst[m][k] = *(const PG8_LAS bf16x8*)(lds + PG8_SA(b, h) + aoff + m * 2048 + k * 1024); } while (0)
; #define PG8_LDB(dst, b, h) do { _Pragma("unroll") for (int n = 0; n < 2; ++n) _Pragma("unroll") for (int k = 0; k < 2; ++k) dst[n][k] = *(const PG8_LAS bf16x8*)(lds + PG8_SB(b, h) + boff + n * 2048 + k * 1024); } while (0)
; #define PG8_MMA(ai, bj, At, Bt) do { __builtin_amdgcn_s_setprio(1); _Pragma("unroll") for (int m = 0; m < 4; ++m) _Pragma("unroll") for (int n = 0; n < 2; ++n) _Pragma("unroll") for (int k = 0; k < 2; ++k) \
;         acc[ai][bj][m][n] = __builtin_amdgcn_mfma_f32_16x16x32_bf16(Bt[n][k], At[m][k], acc[ai][bj][m][n], 0, 0, 0); __builtin_amdgcn_s_setprio(0); } while (0)
; #define PG8_WAIT_V(n) asm volatile("s_waitcnt vmcnt(" #n ")" ::: "memory")
; #define PG8_WAIT_L(n) asm volatile("s_waitcnt lgkmcnt(" #n ")" ::: "memory")
; template <class Epi, class Sched, bool ALIGN_EPI = false, bool SP2 = false>
; __device__ __forceinline__ void gemm_phase(PG8_LAS unsigned char* lds, const Gemm g, const Sched& S, const Epi& E) {
;     ...
;             const bool last = (t == nt - 2);
;             const char* a1 = cA + (size_t)(t + 1) * kstep;
;             const char* a2 = last ? nA : cA + (size_t)(t + 2) * kstep; const char* b2 = last ? nB : cB + (size_t)(t + 2) * kstep;
;             const char* a3 = a2 + kstep; const char* b3 = b2 + kstep;
;             if (last && has_next) S.a_ready(nxt);
;             if constexpr (SP2) {
;             PG8_LDB(B0, 0, 0); PG8_LDB(B1, 0, 1); PG8_SCHED; PG8_LDA(At, 0, 0); PG8_STAGE(PG8_SA(1, 1), a1 + hstepA, voffA);
;             PG8_WAIT_V(8); PG8_WAIT_L(0); PG8_BAR; PG8_MMA(0, 0, At, B0); PG8_MMA(0, 1, At, B1); PG8_BAR; PG8_SCHED;
;             PG8_LDA(At, 0, 1); PG8_STAGE(PG8_SB(0, 0), b2, voffB); PG8_STAGE(PG8_SB(0, 1), b2 + hstep, voffB); PG8_STAGE(PG8_SA(0, 0), a2, voffA);
;             PG8_WAIT_V(8); PG8_WAIT_L(0); PG8_BAR; PG8_MMA(1, 0, At, B0); PG8_MMA(1, 1, At, B1); PG8_BAR; PG8_SCHED;
.LBB0_1501:
	ds_read_b128 v[68:71], v196
	ds_read_b128 v[72:75], v196 offset:1024
	ds_read_b128 v[76:79], v196 offset:2048
	ds_read_b128 v[80:83], v196 offset:3072
	ds_read_b128 v[84:87], v197
	ds_read_b128 v[88:91], v197 offset:1024
	ds_read_b128 v[182:185], v197 offset:2048
	ds_read_b128 v[202:205], v197 offset:3072
	s_add_i32 s38, s14, 2
	s_add_u32 s39, s4, 0xffff0080
	s_addc_u32 s15, s5, -1
	s_cmp_eq_u32 s58, s14
	s_cselect_b32 s14, s35, s39
	s_cselect_b32 s15, s27, s15
	s_cselect_b32 s73, s29, s37
	s_cselect_b32 s72, s28, s36
	s_add_i32 m0, s47, 0xc000
	ds_read_b128 v[206:209], v198
	ds_read_b128 v[210:213], v198 offset:1024
	ds_read_b128 v[214:217], v198 offset:2048
	ds_read_b128 v[218:221], v198 offset:3072
	ds_read_b128 v[222:225], v198 offset:4096
	ds_read_b128 v[226:229], v198 offset:5120
	ds_read_b128 v[230:233], v198 offset:6144
	global_load_lds_dwordx4 v174, s[4:5]
	s_add_i32 m0, s47, 0xe000
	ds_read_b128 v[234:237], v198 offset:7168
	global_load_lds_dwordx4 v176, s[4:5]
	s_waitcnt vmcnt(8) lgkmcnt(0)
	s_setprio 1
	s_barrier
	v_mfma_f32_16x16x32_bf16 v[152:155], v[68:71], v[206:209], v[152:155]
	v_mfma_f32_16x16x32_bf16 v[148:151], v[76:79], v[206:209], v[148:151]
	v_mfma_f32_16x16x32_bf16 v[136:139], v[68:71], v[214:217], v[136:139]
	v_mfma_f32_16x16x32_bf16 v[132:135], v[76:79], v[214:217], v[132:135]
	v_mfma_f32_16x16x32_bf16 v[120:123], v[68:71], v[222:225], v[120:123]
	v_mfma_f32_16x16x32_bf16 v[116:119], v[76:79], v[222:225], v[116:119]
	v_mfma_f32_16x16x32_bf16 v[104:107], v[68:71], v[230:233], v[104:107]
	v_mfma_f32_16x16x32_bf16 v[100:103], v[76:79], v[230:233], v[100:103]
	v_mfma_f32_16x16x32_bf16 v[152:155], v[72:75], v[210:213], v[152:155]
	v_mfma_f32_16x16x32_bf16 v[148:151], v[80:83], v[210:213], v[148:151]
	v_mfma_f32_16x16x32_bf16 v[136:139], v[72:75], v[218:221], v[136:139]
	v_mfma_f32_16x16x32_bf16 v[132:135], v[80:83], v[218:221], v[132:135]
	v_mfma_f32_16x16x32_bf16 v[120:123], v[72:75], v[226:229], v[120:123]
	v_mfma_f32_16x16x32_bf16 v[116:119], v[80:83], v[226:229], v[116:119]
	v_mfma_f32_16x16x32_bf16 v[104:107], v[72:75], v[234:237], v[104:107]
	v_mfma_f32_16x16x32_bf16 v[100:103], v[80:83], v[234:237], v[100:103]
	v_mfma_f32_16x16x32_bf16 v[144:147], v[84:87], v[206:209], v[144:147]
	v_mfma_f32_16x16x32_bf16 v[140:143], v[182:185], v[206:209], v[140:143]
	v_mfma_f32_16x16x32_bf16 v[128:131], v[84:87], v[214:217], v[128:131]
	v_mfma_f32_16x16x32_bf16 v[124:127], v[182:185], v[214:217], v[124:127]
	v_mfma_f32_16x16x32_bf16 v[112:115], v[84:87], v[222:225], v[112:115]
	v_mfma_f32_16x16x32_bf16 v[108:111], v[182:185], v[222:225], v[108:111]
	v_mfma_f32_16x16x32_bf16 v[96:99], v[84:87], v[230:233], v[96:99]
	v_mfma_f32_16x16x32_bf16 v[92:95], v[182:185], v[230:233], v[92:95]
	v_mfma_f32_16x16x32_bf16 v[144:147], v[88:91], v[210:213], v[144:147]
	v_mfma_f32_16x16x32_bf16 v[140:143], v[202:205], v[210:213], v[140:143]
	v_mfma_f32_16x16x32_bf16 v[128:131], v[88:91], v[218:221], v[128:131]
	v_mfma_f32_16x16x32_bf16 v[124:127], v[202:205], v[218:221], v[124:127]
	v_mfma_f32_16x16x32_bf16 v[112:115], v[88:91], v[226:229], v[112:115]
	v_mfma_f32_16x16x32_bf16 v[108:111], v[202:205], v[226:229], v[108:111]
	v_mfma_f32_16x16x32_bf16 v[96:99], v[88:91], v[234:237], v[96:99]
	v_mfma_f32_16x16x32_bf16 v[92:95], v[202:205], v[234:237], v[92:95]
	s_setprio 0
	s_barrier
	s_add_i32 s39, s61, s45
	s_mov_b32 m0, s39
	ds_read_b128 v[206:209], v198 offset:16384
	ds_read_b128 v[210:213], v198 offset:17408
	ds_read_b128 v[214:217], v198 offset:18432
	ds_read_b128 v[218:221], v198 offset:19456
	global_load_lds_dwordx4 v156, s[72:73]
	s_add_i32 m0, s39, 0x2000
	s_mov_b64 s[100:101], s[72:73]
	s_add_i32 s39, s62, s45
	global_load_lds_dwordx4 v158, s[72:73]
	s_add_u32 s72, s72, s16
	s_addc_u32 s73, s73, s17
	s_mov_b32 m0, s39
	ds_read_b128 v[234:237], v198 offset:23552
	global_load_lds_dwordx4 v156, s[72:73]
	s_add_i32 m0, s39, 0x2000
	ds_read_b128 v[230:233], v198 offset:22528
	global_load_lds_dwordx4 v158, s[72:73]
	s_mov_b32 m0, s47
	ds_read_b128 v[226:229], v198 offset:21504
	global_load_lds_dwordx4 v160, s[14:15]
	s_mov_b32 m0, s48
	ds_read_b128 v[222:225], v198 offset:20480
	global_load_lds_dwordx4 v162, s[14:15]
	s_waitcnt vmcnt(8) lgkmcnt(0)
	s_setprio 1
	s_barrier
	v_mfma_f32_16x16x32_bf16 v[64:67], v[68:71], v[206:209], v[64:67]
	v_mfma_f32_16x16x32_bf16 v[60:63], v[76:79], v[206:209], v[60:63]
	v_mfma_f32_16x16x32_bf16 v[48:51], v[68:71], v[214:217], v[48:51]
	v_mfma_f32_16x16x32_bf16 v[44:47], v[76:79], v[214:217], v[44:47]
	v_mfma_f32_16x16x32_bf16 v[32:35], v[68:71], v[222:225], v[32:35]
	v_mfma_f32_16x16x32_bf16 v[28:31], v[76:79], v[222:225], v[28:31]
	v_mfma_f32_16x16x32_bf16 v[16:19], v[68:71], v[230:233], v[16:19]
	v_mfma_f32_16x16x32_bf16 v[12:15], v[76:79], v[230:233], v[12:15]
	v_mfma_f32_16x16x32_bf16 v[64:67], v[72:75], v[210:213], v[64:67]
	v_mfma_f32_16x16x32_bf16 v[60:63], v[80:83], v[210:213], v[60:63]
	v_mfma_f32_16x16x32_bf16 v[48:51], v[72:75], v[218:221], v[48:51]
	v_mfma_f32_16x16x32_bf16 v[44:47], v[80:83], v[218:221], v[44:47]
	v_mfma_f32_16x16x32_bf16 v[32:35], v[72:75], v[226:229], v[32:35]
	v_mfma_f32_16x16x32_bf16 v[28:31], v[80:83], v[226:229], v[28:31]
	v_mfma_f32_16x16x32_bf16 v[16:19], v[72:75], v[234:237], v[16:19]
	v_mfma_f32_16x16x32_bf16 v[12:15], v[80:83], v[234:237], v[12:15]
	v_mfma_f32_16x16x32_bf16 v[56:59], v[84:87], v[206:209], v[56:59]
	v_mfma_f32_16x16x32_bf16 v[52:55], v[182:185], v[206:209], v[52:55]
	v_mfma_f32_16x16x32_bf16 v[40:43], v[84:87], v[214:217], v[40:43]
	v_mfma_f32_16x16x32_bf16 v[36:39], v[182:185], v[214:217], v[36:39]
	v_mfma_f32_16x16x32_bf16 v[24:27], v[84:87], v[222:225], v[24:27]
	v_mfma_f32_16x16x32_bf16 v[20:23], v[182:185], v[222:225], v[20:23]
	v_mfma_f32_16x16x32_bf16 v[8:11], v[84:87], v[230:233], v[8:11]
	v_mfma_f32_16x16x32_bf16 v[4:7], v[182:185], v[230:233], v[4:7]
	v_mfma_f32_16x16x32_bf16 v[56:59], v[88:91], v[210:213], v[56:59]
	v_mfma_f32_16x16x32_bf16 v[52:55], v[202:205], v[210:213], v[52:55]
	v_mfma_f32_16x16x32_bf16 v[40:43], v[88:91], v[218:221], v[40:43]
	v_mfma_f32_16x16x32_bf16 v[36:39], v[202:205], v[218:221], v[36:39]
	v_mfma_f32_16x16x32_bf16 v[24:27], v[88:91], v[226:229], v[24:27]
	v_mfma_f32_16x16x32_bf16 v[20:23], v[202:205], v[226:229], v[20:23]
	v_mfma_f32_16x16x32_bf16 v[8:11], v[88:91], v[234:237], v[8:11]
	v_mfma_f32_16x16x32_bf16 v[4:7], v[202:205], v[234:237], v[4:7]
	s_setprio 0
	s_barrier
; #define PG8_STAGE(bufoff, gbase, voff) do { _Pragma("unroll") for (int _i = 0; _i < 2; ++_i) \
;         __builtin_amdgcn_global_load_lds((const unsigned*)((const char*)(gbase) + (voff)[_i]), (PG8_LAS unsigned*)(lds + (bufoff) + ldsw + _i * 8192), 16, 0, 0); } while (0)
; #define PG8_LDA(dst, b, h) do { _Pragma("unroll") for (int m = 0; m < 4; ++m) _Pragma("unroll") for (int k = 0; k < 2; ++k) dst[m][k] = *(const PG8_LAS bf16x8*)(lds + PG8_SA(b, h) + aoff + m * 2048 + k * 1024); } while (0)
; #define PG8_LDB(dst, b, h) do { _Pragma("unroll") for (int n = 0; n < 2; ++n) _Pragma("unroll") for (int k = 0; k < 2; ++k) dst[n][k] = *(const PG8_LAS bf16x8*)(lds + PG8_SB(b, h) + boff + n * 2048 + k * 1024); } while (0)
; #define PG8_MMA(ai, bj, At, Bt) do { __builtin_amdgcn_s_setprio(1); _Pragma("unroll") for (int m = 0; m < 4; ++m) _Pragma("unroll") for (int n = 0; n < 2; ++n) _Pragma("unroll") for (int k = 0; k < 2; ++k) \
;         acc[ai][bj][m][n] = __builtin_amdgcn_mfma_f32_16x16x32_bf16(Bt[n][k], At[m][k], acc[ai][bj][m][n], 0, 0, 0); __builtin_amdgcn_s_setprio(0); } while (0)
; #define PG8_WAIT_V(n) asm volatile("s_waitcnt vmcnt(" #n ")" ::: "memory")
; #define PG8_WAIT_L(n) asm volatile("s_waitcnt lgkmcnt(" #n ")" ::: "memory")
; #define PG8_BAR __builtin_amdgcn_s_barrier()
; #define PG8_SCHED __builtin_amdgcn_sched_barrier(0)
; template <class Epi, class Sched, bool ALIGN_EPI = false, bool SP2 = false>
; __device__ __forceinline__ void gemm_phase(PG8_LAS unsigned char* lds, const Gemm g, const Sched& S, const Epi& E) {
;     ...
;             PG8_LDB(B0, 1, 0); PG8_LDB(B1, 1, 1); PG8_SCHED; PG8_LDA(At, 1, 0); PG8_STAGE(PG8_SA(0, 1), a2 + hstepA, voffA);
;             PG8_WAIT_V(8); PG8_WAIT_L(0); PG8_BAR; PG8_MMA(0, 0, At, B0); PG8_MMA(0, 1, At, B1); PG8_BAR; PG8_SCHED;
;             PG8_LDA(At, 1, 1); PG8_STAGE(PG8_SB(1, 0), b3, voffB); PG8_STAGE(PG8_SB(1, 1), b3 + hstep, voffB); PG8_STAGE(PG8_SA(1, 0), a3, voffA);
;             PG8_WAIT_V(8); PG8_WAIT_L(0); PG8_BAR; PG8_MMA(1, 0, At, B0); PG8_MMA(1, 1, At, B1); PG8_BAR; PG8_SCHED;
	s_add_i32 s39, 0, 0x18000
	s_add_i32 s71, 0, 0x1c000
	v_add_u32_e32 v80, s39, v191
	v_add_u32_e32 v164, s71, v191
	ds_read_b128 v[68:71], v80
	ds_read_b128 v[72:75], v80 offset:1024
	ds_read_b128 v[76:79], v80 offset:2048
	ds_read_b128 v[80:83], v80 offset:3072
	ds_read_b128 v[84:87], v164
	ds_read_b128 v[88:91], v164 offset:1024
	ds_read_b128 v[182:185], v164 offset:2048
	ds_read_b128 v[202:205], v164 offset:3072
	s_mov_b64 vcc, s[14:15]
	s_add_u32 s14, s14, 0x10000
	s_addc_u32 s15, s15, 0
	s_mov_b32 m0, s49
	ds_read_b128 v[206:209], v198 offset:32768
	ds_read_b128 v[210:213], v198 offset:33792
	ds_read_b128 v[214:217], v198 offset:34816
	ds_read_b128 v[218:221], v198 offset:35840
	ds_read_b128 v[222:225], v198 offset:36864
	ds_read_b128 v[226:229], v198 offset:37888
	ds_read_b128 v[230:233], v198 offset:38912
	global_load_lds_dwordx4 v160, s[14:15]
	s_mov_b32 m0, s50
	ds_read_b128 v[234:237], v198 offset:39936
	global_load_lds_dwordx4 v162, s[14:15]
	s_waitcnt vmcnt(8) lgkmcnt(0)
	s_setprio 1
	s_barrier
	v_mfma_f32_16x16x32_bf16 v[152:155], v[68:71], v[206:209], v[152:155]
	v_mfma_f32_16x16x32_bf16 v[148:151], v[76:79], v[206:209], v[148:151]
	v_mfma_f32_16x16x32_bf16 v[136:139], v[68:71], v[214:217], v[136:139]
	v_mfma_f32_16x16x32_bf16 v[132:135], v[76:79], v[214:217], v[132:135]
	v_mfma_f32_16x16x32_bf16 v[120:123], v[68:71], v[222:225], v[120:123]
	v_mfma_f32_16x16x32_bf16 v[116:119], v[76:79], v[222:225], v[116:119]
	v_mfma_f32_16x16x32_bf16 v[104:107], v[68:71], v[230:233], v[104:107]
	v_mfma_f32_16x16x32_bf16 v[100:103], v[76:79], v[230:233], v[100:103]
	v_mfma_f32_16x16x32_bf16 v[152:155], v[72:75], v[210:213], v[152:155]
	v_mfma_f32_16x16x32_bf16 v[148:151], v[80:83], v[210:213], v[148:151]
	v_mfma_f32_16x16x32_bf16 v[136:139], v[72:75], v[218:221], v[136:139]
	v_mfma_f32_16x16x32_bf16 v[132:135], v[80:83], v[218:221], v[132:135]
	v_mfma_f32_16x16x32_bf16 v[120:123], v[72:75], v[226:229], v[120:123]
	v_mfma_f32_16x16x32_bf16 v[116:119], v[80:83], v[226:229], v[116:119]
	v_mfma_f32_16x16x32_bf16 v[104:107], v[72:75], v[234:237], v[104:107]
	v_mfma_f32_16x16x32_bf16 v[100:103], v[80:83], v[234:237], v[100:103]
	v_mfma_f32_16x16x32_bf16 v[144:147], v[84:87], v[206:209], v[144:147]
	v_mfma_f32_16x16x32_bf16 v[140:143], v[182:185], v[206:209], v[140:143]
	v_mfma_f32_16x16x32_bf16 v[128:131], v[84:87], v[214:217], v[128:131]
	v_mfma_f32_16x16x32_bf16 v[124:127], v[182:185], v[214:217], v[124:127]
	v_mfma_f32_16x16x32_bf16 v[112:115], v[84:87], v[222:225], v[112:115]
	v_mfma_f32_16x16x32_bf16 v[108:111], v[182:185], v[222:225], v[108:111]
	v_mfma_f32_16x16x32_bf16 v[96:99], v[84:87], v[230:233], v[96:99]
	v_mfma_f32_16x16x32_bf16 v[92:95], v[182:185], v[230:233], v[92:95]
	v_mfma_f32_16x16x32_bf16 v[144:147], v[88:91], v[210:213], v[144:147]
	v_mfma_f32_16x16x32_bf16 v[140:143], v[202:205], v[210:213], v[140:143]
	v_mfma_f32_16x16x32_bf16 v[128:131], v[88:91], v[218:221], v[128:131]
	v_mfma_f32_16x16x32_bf16 v[124:127], v[202:205], v[218:221], v[124:127]
	v_mfma_f32_16x16x32_bf16 v[112:115], v[88:91], v[226:229], v[112:115]
	v_mfma_f32_16x16x32_bf16 v[108:111], v[202:205], v[226:229], v[108:111]
	v_mfma_f32_16x16x32_bf16 v[96:99], v[88:91], v[234:237], v[96:99]
	v_mfma_f32_16x16x32_bf16 v[92:95], v[202:205], v[234:237], v[92:95]
	s_setprio 0
	s_barrier
	s_add_i32 s14, s39, s45
	s_add_i32 m0, s14, 0xffffff80
	ds_read_b128 v[206:209], v198 offset:49152
	ds_read_b128 v[210:213], v198 offset:50176
	ds_read_b128 v[214:217], v198 offset:51200
	ds_read_b128 v[218:221], v198 offset:52224
	global_load_lds_dwordx4 v156, s[100:101] offset:128
	s_add_i32 m0, s14, 0x1f80
	s_add_i32 s14, s71, s45
	global_load_lds_dwordx4 v158, s[100:101] offset:128
	s_add_i32 m0, s14, 0xffffff80
	ds_read_b128 v[234:237], v198 offset:56320
	global_load_lds_dwordx4 v156, s[72:73] offset:128
	s_add_i32 m0, s14, 0x1f80
	ds_read_b128 v[230:233], v198 offset:55296
	global_load_lds_dwordx4 v158, s[72:73] offset:128
	s_add_i32 m0, s56, 0xffffff80
	ds_read_b128 v[226:229], v198 offset:54272
	global_load_lds_dwordx4 v160, vcc offset:128
	s_add_i32 m0, s57, 0xffffff80
	ds_read_b128 v[222:225], v198 offset:53248
	global_load_lds_dwordx4 v162, vcc offset:128
	s_waitcnt vmcnt(8) lgkmcnt(0)
	s_setprio 1
	s_barrier
	v_mfma_f32_16x16x32_bf16 v[64:67], v[68:71], v[206:209], v[64:67]
	v_mfma_f32_16x16x32_bf16 v[60:63], v[76:79], v[206:209], v[60:63]
	v_mfma_f32_16x16x32_bf16 v[48:51], v[68:71], v[214:217], v[48:51]
	v_mfma_f32_16x16x32_bf16 v[44:47], v[76:79], v[214:217], v[44:47]
	v_mfma_f32_16x16x32_bf16 v[32:35], v[68:71], v[222:225], v[32:35]
	v_mfma_f32_16x16x32_bf16 v[28:31], v[76:79], v[222:225], v[28:31]
	v_mfma_f32_16x16x32_bf16 v[16:19], v[68:71], v[230:233], v[16:19]
	v_mfma_f32_16x16x32_bf16 v[12:15], v[76:79], v[230:233], v[12:15]
	v_mfma_f32_16x16x32_bf16 v[64:67], v[72:75], v[210:213], v[64:67]
	v_mfma_f32_16x16x32_bf16 v[60:63], v[80:83], v[210:213], v[60:63]
	v_mfma_f32_16x16x32_bf16 v[48:51], v[72:75], v[218:221], v[48:51]
	v_mfma_f32_16x16x32_bf16 v[44:47], v[80:83], v[218:221], v[44:47]
	v_mfma_f32_16x16x32_bf16 v[32:35], v[72:75], v[226:229], v[32:35]
	v_mfma_f32_16x16x32_bf16 v[28:31], v[80:83], v[226:229], v[28:31]
	v_mfma_f32_16x16x32_bf16 v[16:19], v[72:75], v[234:237], v[16:19]
	v_mfma_f32_16x16x32_bf16 v[12:15], v[80:83], v[234:237], v[12:15]
	v_mfma_f32_16x16x32_bf16 v[56:59], v[84:87], v[206:209], v[56:59]
	v_mfma_f32_16x16x32_bf16 v[52:55], v[182:185], v[206:209], v[52:55]
	v_mfma_f32_16x16x32_bf16 v[40:43], v[84:87], v[214:217], v[40:43]
	v_mfma_f32_16x16x32_bf16 v[36:39], v[182:185], v[214:217], v[36:39]
	v_mfma_f32_16x16x32_bf16 v[24:27], v[84:87], v[222:225], v[24:27]
	v_mfma_f32_16x16x32_bf16 v[20:23], v[182:185], v[222:225], v[20:23]
	v_mfma_f32_16x16x32_bf16 v[8:11], v[84:87], v[230:233], v[8:11]
	v_mfma_f32_16x16x32_bf16 v[4:7], v[182:185], v[230:233], v[4:7]
	v_mfma_f32_16x16x32_bf16 v[56:59], v[88:91], v[210:213], v[56:59]
	v_mfma_f32_16x16x32_bf16 v[52:55], v[202:205], v[210:213], v[52:55]
	v_mfma_f32_16x16x32_bf16 v[40:43], v[88:91], v[218:221], v[40:43]
	v_mfma_f32_16x16x32_bf16 v[36:39], v[202:205], v[218:221], v[36:39]
	v_mfma_f32_16x16x32_bf16 v[24:27], v[88:91], v[226:229], v[24:27]
	v_mfma_f32_16x16x32_bf16 v[20:23], v[202:205], v[226:229], v[20:23]
	v_mfma_f32_16x16x32_bf16 v[8:11], v[88:91], v[234:237], v[8:11]
	v_mfma_f32_16x16x32_bf16 v[4:7], v[202:205], v[234:237], v[4:7]
	s_setprio 0
	s_barrier
	s_add_u32 s4, s4, 0x100
	s_addc_u32 s5, s5, 0
	s_add_u32 s36, s36, 0x100
	s_addc_u32 s37, s37, 0
	s_cmp_ge_i32 s38, s54
	s_mov_b32 s14, s38
	s_cbranch_scc0 .LBB0_1501

; #define PG8_STAGE(bufoff, gbase, voff) do { _Pragma("unroll") for (int _i = 0; _i < 2; ++_i) \
;         __builtin_amdgcn_global_load_lds((const unsigned*)((const char*)(gbase) + (voff)[_i]), (PG8_LAS unsigned*)(lds + (bufoff) + ldsw + _i * 8192), 16, 0, 0); } while (0)
; #define PG8_LDA(dst, b, h) do { _Pragma("unroll") for (int m = 0; m < 4; ++m) _Pragma("unroll") for (int k = 0; k < 2; ++k) dst[m][k] = *(const PG8_LAS bf16x8*)(lds + PG8_SA(b, h) + aoff + m * 2048 + k * 1024); } while (0)
; #define PG8_LDB(dst, b, h) do { _Pragma("unroll") for (int n = 0; n < 2; ++n) _Pragma("unroll") for (int k = 0; k < 2; ++k) dst[n][k] = *(const PG8_LAS bf16x8*)(lds + PG8_SB(b, h) + boff + n * 2048 + k * 1024); } while (0)
; #define PG8_MMA(ai, bj, At, Bt) do { __builtin_amdgcn_s_setprio(1); _Pragma("unroll") for (int m = 0; m < 4; ++m) _Pragma("unroll") for (int n = 0; n < 2; ++n) _Pragma("unroll") for (int k = 0; k < 2; ++k) \
;         acc[ai][bj][m][n] = __builtin_amdgcn_mfma_f32_16x16x32_bf16(Bt[n][k], At[m][k], acc[ai][bj][m][n], 0, 0, 0); __builtin_amdgcn_s_setprio(0); } while (0)
; #define PG8_WAIT_V(n) asm volatile("s_waitcnt vmcnt(" #n ")" ::: "memory")
; #define PG8_WAIT_L(n) asm volatile("s_waitcnt lgkmcnt(" #n ")" ::: "memory")
; template <class Epi, class Sched, bool ALIGN_EPI = false, bool SP2 = false>
; __device__ __forceinline__ void gemm_phase(PG8_LAS unsigned char* lds, const Gemm g, const Sched& S, const Epi& E) {
;     ...
;             const bool last = (t == nt - 2);
;             const char* a1 = cA + (size_t)(t + 1) * kstep;
;             const char* a2 = last ? nA : cA + (size_t)(t + 2) * kstep; const char* b2 = last ? nB : cB + (size_t)(t + 2) * kstep;
;             const char* a3 = a2 + kstep; const char* b3 = b2 + kstep;
;             if (last && has_next) S.a_ready(nxt);
;             if constexpr (SP2) {
;             PG8_LDB(B0, 0, 0); PG8_LDB(B1, 0, 1); PG8_SCHED; PG8_LDA(At, 0, 0); PG8_STAGE(PG8_SA(1, 1), a1 + hstepA, voffA);
;             PG8_WAIT_V(8); PG8_WAIT_L(0); PG8_BAR; PG8_MMA(0, 0, At, B0); PG8_MMA(0, 1, At, B1); PG8_BAR; PG8_SCHED;
;             PG8_LDA(At, 0, 1); PG8_STAGE(PG8_SB(0, 0), b2, voffB); PG8_STAGE(PG8_SB(0, 1), b2 + hstep, voffB); PG8_STAGE(PG8_SA(0, 0), a2, voffA);
;             PG8_WAIT_V(8); PG8_WAIT_L(0); PG8_BAR; PG8_MMA(1, 0, At, B0); PG8_MMA(1, 1, At, B1); PG8_BAR; PG8_SCHED;
.LBB0_1679:
	ds_read_b128 v[120:123], v169
	ds_read_b128 v[128:131], v169 offset:1024
	ds_read_b128 v[136:139], v169 offset:2048
	ds_read_b128 v[140:143], v169 offset:3072
	ds_read_b128 v[160:163], v170
	ds_read_b128 v[172:175], v170 offset:1024
	ds_read_b128 v[176:179], v170 offset:2048
	ds_read_b128 v[180:183], v170 offset:3072
	s_add_i32 s90, s68, 2
	s_add_u32 s91, s8, 0xfffc0080
	s_addc_u32 s69, s9, -1
	s_cmp_eq_u32 s84, s68
	s_cselect_b32 s68, s89, s91
	s_cselect_b32 s69, s61, s69
	s_cselect_b32 s93, s63, s71
	s_cselect_b32 s92, s62, s70
	s_add_i32 m0, s67, 0xc000
	ds_read_b128 v[184:187], v171
	ds_read_b128 v[190:193], v171 offset:1024
	ds_read_b128 v[194:197], v171 offset:2048
	ds_read_b128 v[198:201], v171 offset:3072
	ds_read_b128 v[202:205], v171 offset:4096
	ds_read_b128 v[206:209], v171 offset:5120
	ds_read_b128 v[210:213], v171 offset:6144
	global_load_lds_dwordx4 v152, s[8:9]
	s_add_i32 m0, s67, 0xe000
	ds_read_b128 v[214:217], v171 offset:7168
	global_load_lds_dwordx4 v154, s[8:9]
	s_waitcnt vmcnt(8) lgkmcnt(0)
	s_setprio 1
	s_barrier
	v_mfma_f32_16x16x32_bf16 v[132:135], v[120:123], v[184:187], v[132:135]
	v_mfma_f32_16x16x32_bf16 v[124:127], v[136:139], v[184:187], v[124:127]
	v_mfma_f32_16x16x32_bf16 v[108:111], v[120:123], v[194:197], v[108:111]
	v_mfma_f32_16x16x32_bf16 v[104:107], v[136:139], v[194:197], v[104:107]
	v_mfma_f32_16x16x32_bf16 v[92:95], v[120:123], v[202:205], v[92:95]
	v_mfma_f32_16x16x32_bf16 v[88:91], v[136:139], v[202:205], v[88:91]
	v_mfma_f32_16x16x32_bf16 v[76:79], v[120:123], v[210:213], v[76:79]
	v_mfma_f32_16x16x32_bf16 v[72:75], v[136:139], v[210:213], v[72:75]
	v_mfma_f32_16x16x32_bf16 v[132:135], v[128:131], v[190:193], v[132:135]
	v_mfma_f32_16x16x32_bf16 v[124:127], v[140:143], v[190:193], v[124:127]
	v_mfma_f32_16x16x32_bf16 v[108:111], v[128:131], v[198:201], v[108:111]
	v_mfma_f32_16x16x32_bf16 v[104:107], v[140:143], v[198:201], v[104:107]
	v_mfma_f32_16x16x32_bf16 v[92:95], v[128:131], v[206:209], v[92:95]
	v_mfma_f32_16x16x32_bf16 v[88:91], v[140:143], v[206:209], v[88:91]
	v_mfma_f32_16x16x32_bf16 v[76:79], v[128:131], v[214:217], v[76:79]
	v_mfma_f32_16x16x32_bf16 v[72:75], v[140:143], v[214:217], v[72:75]
	v_mfma_f32_16x16x32_bf16 v[116:119], v[160:163], v[184:187], v[116:119]
	v_mfma_f32_16x16x32_bf16 v[112:115], v[176:179], v[184:187], v[112:115]
	v_mfma_f32_16x16x32_bf16 v[100:103], v[160:163], v[194:197], v[100:103]
	v_mfma_f32_16x16x32_bf16 v[96:99], v[176:179], v[194:197], v[96:99]
	v_mfma_f32_16x16x32_bf16 v[84:87], v[160:163], v[202:205], v[84:87]
	v_mfma_f32_16x16x32_bf16 v[80:83], v[176:179], v[202:205], v[80:83]
	v_mfma_f32_16x16x32_bf16 v[68:71], v[160:163], v[210:213], v[68:71]
	v_mfma_f32_16x16x32_bf16 v[64:67], v[176:179], v[210:213], v[64:67]
	v_mfma_f32_16x16x32_bf16 v[116:119], v[172:175], v[190:193], v[116:119]
	v_mfma_f32_16x16x32_bf16 v[112:115], v[180:183], v[190:193], v[112:115]
	v_mfma_f32_16x16x32_bf16 v[100:103], v[172:175], v[198:201], v[100:103]
	v_mfma_f32_16x16x32_bf16 v[96:99], v[180:183], v[198:201], v[96:99]
	v_mfma_f32_16x16x32_bf16 v[84:87], v[172:175], v[206:209], v[84:87]
	v_mfma_f32_16x16x32_bf16 v[80:83], v[180:183], v[206:209], v[80:83]
	v_mfma_f32_16x16x32_bf16 v[68:71], v[172:175], v[214:217], v[68:71]
	v_mfma_f32_16x16x32_bf16 v[64:67], v[180:183], v[214:217], v[64:67]
	s_setprio 0
	s_barrier
	s_add_i32 s91, s85, s73
	s_mov_b32 m0, s91
	ds_read_b128 v[184:187], v171 offset:16384
	ds_read_b128 v[190:193], v171 offset:17408
	ds_read_b128 v[194:197], v171 offset:18432
	ds_read_b128 v[198:201], v171 offset:19456
	global_load_lds_dwordx4 v150, s[92:93]
	s_add_i32 m0, s91, 0x2000
	s_mov_b64 s[100:101], s[92:93]
	s_add_i32 s91, s86, s73
	global_load_lds_dwordx4 v148, s[92:93]
	s_add_u32 s92, s92, s10
	s_addc_u32 s93, s93, s11
	s_mov_b32 m0, s91
	ds_read_b128 v[214:217], v171 offset:23552
	global_load_lds_dwordx4 v150, s[92:93]
	s_add_i32 m0, s91, 0x2000
	ds_read_b128 v[210:213], v171 offset:22528
	global_load_lds_dwordx4 v148, s[92:93]
	s_mov_b32 m0, s67
	ds_read_b128 v[206:209], v171 offset:21504
	global_load_lds_dwordx4 v144, s[68:69]
	s_mov_b32 m0, s75
	ds_read_b128 v[202:205], v171 offset:20480
	global_load_lds_dwordx4 v146, s[68:69]
	s_waitcnt vmcnt(8) lgkmcnt(0)
	s_setprio 1
	s_barrier
	v_mfma_f32_16x16x32_bf16 v[60:63], v[120:123], v[184:187], v[60:63]
	v_mfma_f32_16x16x32_bf16 v[56:59], v[136:139], v[184:187], v[56:59]
	v_mfma_f32_16x16x32_bf16 v[44:47], v[120:123], v[194:197], v[44:47]
	v_mfma_f32_16x16x32_bf16 v[40:43], v[136:139], v[194:197], v[40:43]
	v_mfma_f32_16x16x32_bf16 v[28:31], v[120:123], v[202:205], v[28:31]
	v_mfma_f32_16x16x32_bf16 v[24:27], v[136:139], v[202:205], v[24:27]
	v_mfma_f32_16x16x32_bf16 v[12:15], v[120:123], v[210:213], v[12:15]
	v_mfma_f32_16x16x32_bf16 v[8:11], v[136:139], v[210:213], v[8:11]
	v_mfma_f32_16x16x32_bf16 v[60:63], v[128:131], v[190:193], v[60:63]
	v_mfma_f32_16x16x32_bf16 v[56:59], v[140:143], v[190:193], v[56:59]
	v_mfma_f32_16x16x32_bf16 v[44:47], v[128:131], v[198:201], v[44:47]
	v_mfma_f32_16x16x32_bf16 v[40:43], v[140:143], v[198:201], v[40:43]
	v_mfma_f32_16x16x32_bf16 v[28:31], v[128:131], v[206:209], v[28:31]
	v_mfma_f32_16x16x32_bf16 v[24:27], v[140:143], v[206:209], v[24:27]
	v_mfma_f32_16x16x32_bf16 v[12:15], v[128:131], v[214:217], v[12:15]
	v_mfma_f32_16x16x32_bf16 v[8:11], v[140:143], v[214:217], v[8:11]
	v_mfma_f32_16x16x32_bf16 v[52:55], v[160:163], v[184:187], v[52:55]
	v_mfma_f32_16x16x32_bf16 v[48:51], v[176:179], v[184:187], v[48:51]
	v_mfma_f32_16x16x32_bf16 v[36:39], v[160:163], v[194:197], v[36:39]
	v_mfma_f32_16x16x32_bf16 v[32:35], v[176:179], v[194:197], v[32:35]
	v_mfma_f32_16x16x32_bf16 v[20:23], v[160:163], v[202:205], v[20:23]
	v_mfma_f32_16x16x32_bf16 v[16:19], v[176:179], v[202:205], v[16:19]
	v_mfma_f32_16x16x32_bf16 v[4:7], v[160:163], v[210:213], v[4:7]
	v_mfma_f32_16x16x32_bf16 v[0:3], v[176:179], v[210:213], v[0:3]
	v_mfma_f32_16x16x32_bf16 v[52:55], v[172:175], v[190:193], v[52:55]
	v_mfma_f32_16x16x32_bf16 v[48:51], v[180:183], v[190:193], v[48:51]
	v_mfma_f32_16x16x32_bf16 v[36:39], v[172:175], v[198:201], v[36:39]
	v_mfma_f32_16x16x32_bf16 v[32:35], v[180:183], v[198:201], v[32:35]
	v_mfma_f32_16x16x32_bf16 v[20:23], v[172:175], v[206:209], v[20:23]
	v_mfma_f32_16x16x32_bf16 v[16:19], v[180:183], v[206:209], v[16:19]
	v_mfma_f32_16x16x32_bf16 v[4:7], v[172:175], v[214:217], v[4:7]
	v_mfma_f32_16x16x32_bf16 v[0:3], v[180:183], v[214:217], v[0:3]
	s_setprio 0
	s_barrier
; #define PG8_STAGE(bufoff, gbase, voff) do { _Pragma("unroll") for (int _i = 0; _i < 2; ++_i) \
;         __builtin_amdgcn_global_load_lds((const unsigned*)((const char*)(gbase) + (voff)[_i]), (PG8_LAS unsigned*)(lds + (bufoff) + ldsw + _i * 8192), 16, 0, 0); } while (0)
; #define PG8_LDA(dst, b, h) do { _Pragma("unroll") for (int m = 0; m < 4; ++m) _Pragma("unroll") for (int k = 0; k < 2; ++k) dst[m][k] = *(const PG8_LAS bf16x8*)(lds + PG8_SA(b, h) + aoff + m * 2048 + k * 1024); } while (0)
; #define PG8_LDB(dst, b, h) do { _Pragma("unroll") for (int n = 0; n < 2; ++n) _Pragma("unroll") for (int k = 0; k < 2; ++k) dst[n][k] = *(const PG8_LAS bf16x8*)(lds + PG8_SB(b, h) + boff + n * 2048 + k * 1024); } while (0)
; #define PG8_MMA(ai, bj, At, Bt) do { __builtin_amdgcn_s_setprio(1); _Pragma("unroll") for (int m = 0; m < 4; ++m) _Pragma("unroll") for (int n = 0; n < 2; ++n) _Pragma("unroll") for (int k = 0; k < 2; ++k) \
;         acc[ai][bj][m][n] = __builtin_amdgcn_mfma_f32_16x16x32_bf16(Bt[n][k], At[m][k], acc[ai][bj][m][n], 0, 0, 0); __builtin_amdgcn_s_setprio(0); } while (0)
; #define PG8_WAIT_V(n) asm volatile("s_waitcnt vmcnt(" #n ")" ::: "memory")
; #define PG8_WAIT_L(n) asm volatile("s_waitcnt lgkmcnt(" #n ")" ::: "memory")
; #define PG8_BAR __builtin_amdgcn_s_barrier()
; #define PG8_SCHED __builtin_amdgcn_sched_barrier(0)
; template <class Epi, class Sched, bool ALIGN_EPI = false, bool SP2 = false>
; __device__ __forceinline__ void gemm_phase(PG8_LAS unsigned char* lds, const Gemm g, const Sched& S, const Epi& E) {
;     ...
;             PG8_LDB(B0, 1, 0); PG8_LDB(B1, 1, 1); PG8_SCHED; PG8_LDA(At, 1, 0); PG8_STAGE(PG8_SA(0, 1), a2 + hstepA, voffA);
;             PG8_WAIT_V(8); PG8_WAIT_L(0); PG8_BAR; PG8_MMA(0, 0, At, B0); PG8_MMA(0, 1, At, B1); PG8_BAR; PG8_SCHED;
;             PG8_LDA(At, 1, 1); PG8_STAGE(PG8_SB(1, 0), b3, voffB); PG8_STAGE(PG8_SB(1, 1), b3 + hstep, voffB); PG8_STAGE(PG8_SA(1, 0), a3, voffA);
;             PG8_WAIT_V(8); PG8_WAIT_L(0); PG8_BAR; PG8_MMA(1, 0, At, B0); PG8_MMA(1, 1, At, B1); PG8_BAR; PG8_SCHED;
	s_add_i32 s91, 0, 0x18000
	s_add_i32 s92, 0, 0x1c000
	v_add_u32_e32 v140, s91, v167
	v_add_u32_e32 v180, s92, v167
	ds_read_b128 v[120:123], v140
	ds_read_b128 v[128:131], v140 offset:1024
	ds_read_b128 v[136:139], v140 offset:2048
	ds_read_b128 v[140:143], v140 offset:3072
	ds_read_b128 v[160:163], v180
	ds_read_b128 v[172:175], v180 offset:1024
	ds_read_b128 v[176:179], v180 offset:2048
	ds_read_b128 v[180:183], v180 offset:3072
	s_mov_b64 vcc, s[68:69]
	s_add_u32 s68, s68, 0x40000
	s_addc_u32 s69, s69, 0
	s_mov_b32 m0, s76
	ds_read_b128 v[184:187], v171 offset:32768
	ds_read_b128 v[190:193], v171 offset:33792
	ds_read_b128 v[194:197], v171 offset:34816
	ds_read_b128 v[198:201], v171 offset:35840
	ds_read_b128 v[202:205], v171 offset:36864
	ds_read_b128 v[206:209], v171 offset:37888
	ds_read_b128 v[210:213], v171 offset:38912
	global_load_lds_dwordx4 v144, s[68:69]
	s_mov_b32 m0, s77
	ds_read_b128 v[214:217], v171 offset:39936
	global_load_lds_dwordx4 v146, s[68:69]
	s_waitcnt vmcnt(8) lgkmcnt(0)
	s_setprio 1
	s_barrier
	v_mfma_f32_16x16x32_bf16 v[132:135], v[120:123], v[184:187], v[132:135]
	v_mfma_f32_16x16x32_bf16 v[124:127], v[136:139], v[184:187], v[124:127]
	v_mfma_f32_16x16x32_bf16 v[108:111], v[120:123], v[194:197], v[108:111]
	v_mfma_f32_16x16x32_bf16 v[104:107], v[136:139], v[194:197], v[104:107]
	v_mfma_f32_16x16x32_bf16 v[92:95], v[120:123], v[202:205], v[92:95]
	v_mfma_f32_16x16x32_bf16 v[88:91], v[136:139], v[202:205], v[88:91]
	v_mfma_f32_16x16x32_bf16 v[76:79], v[120:123], v[210:213], v[76:79]
	v_mfma_f32_16x16x32_bf16 v[72:75], v[136:139], v[210:213], v[72:75]
	v_mfma_f32_16x16x32_bf16 v[132:135], v[128:131], v[190:193], v[132:135]
	v_mfma_f32_16x16x32_bf16 v[124:127], v[140:143], v[190:193], v[124:127]
	v_mfma_f32_16x16x32_bf16 v[108:111], v[128:131], v[198:201], v[108:111]
	v_mfma_f32_16x16x32_bf16 v[104:107], v[140:143], v[198:201], v[104:107]
	v_mfma_f32_16x16x32_bf16 v[92:95], v[128:131], v[206:209], v[92:95]
	v_mfma_f32_16x16x32_bf16 v[88:91], v[140:143], v[206:209], v[88:91]
	v_mfma_f32_16x16x32_bf16 v[76:79], v[128:131], v[214:217], v[76:79]
	v_mfma_f32_16x16x32_bf16 v[72:75], v[140:143], v[214:217], v[72:75]
	v_mfma_f32_16x16x32_bf16 v[116:119], v[160:163], v[184:187], v[116:119]
	v_mfma_f32_16x16x32_bf16 v[112:115], v[176:179], v[184:187], v[112:115]
	v_mfma_f32_16x16x32_bf16 v[100:103], v[160:163], v[194:197], v[100:103]
	v_mfma_f32_16x16x32_bf16 v[96:99], v[176:179], v[194:197], v[96:99]
	v_mfma_f32_16x16x32_bf16 v[84:87], v[160:163], v[202:205], v[84:87]
	v_mfma_f32_16x16x32_bf16 v[80:83], v[176:179], v[202:205], v[80:83]
	v_mfma_f32_16x16x32_bf16 v[68:71], v[160:163], v[210:213], v[68:71]
	v_mfma_f32_16x16x32_bf16 v[64:67], v[176:179], v[210:213], v[64:67]
	v_mfma_f32_16x16x32_bf16 v[116:119], v[172:175], v[190:193], v[116:119]
	v_mfma_f32_16x16x32_bf16 v[112:115], v[180:183], v[190:193], v[112:115]
	v_mfma_f32_16x16x32_bf16 v[100:103], v[172:175], v[198:201], v[100:103]
	v_mfma_f32_16x16x32_bf16 v[96:99], v[180:183], v[198:201], v[96:99]
	v_mfma_f32_16x16x32_bf16 v[84:87], v[172:175], v[206:209], v[84:87]
	v_mfma_f32_16x16x32_bf16 v[80:83], v[180:183], v[206:209], v[80:83]
	v_mfma_f32_16x16x32_bf16 v[68:71], v[172:175], v[214:217], v[68:71]
	v_mfma_f32_16x16x32_bf16 v[64:67], v[180:183], v[214:217], v[64:67]
	s_setprio 0
	s_barrier
	s_add_i32 s68, s91, s73
	s_add_i32 m0, s68, 0xffffff80
	ds_read_b128 v[184:187], v171 offset:49152
	ds_read_b128 v[190:193], v171 offset:50176
	ds_read_b128 v[194:197], v171 offset:51200
	ds_read_b128 v[198:201], v171 offset:52224
	global_load_lds_dwordx4 v150, s[100:101] offset:128
	s_add_i32 m0, s68, 0x1f80
	s_add_i32 s68, s92, s73
	global_load_lds_dwordx4 v148, s[100:101] offset:128
	s_add_u32 s100, s100, s10
	s_addc_u32 s101, s101, s11
	s_add_i32 m0, s68, 0xffffff80
	ds_read_b128 v[214:217], v171 offset:56320
	global_load_lds_dwordx4 v150, s[100:101] offset:128
	s_add_i32 m0, s68, 0x1f80
	ds_read_b128 v[210:213], v171 offset:55296
	global_load_lds_dwordx4 v148, s[100:101] offset:128
	s_add_i32 m0, s80, 0xffffff80
	ds_read_b128 v[206:209], v171 offset:54272
	global_load_lds_dwordx4 v144, vcc offset:128
	s_add_i32 m0, s81, 0xffffff80
	ds_read_b128 v[202:205], v171 offset:53248
	global_load_lds_dwordx4 v146, vcc offset:128
	s_waitcnt vmcnt(8) lgkmcnt(0)
	s_setprio 1
	s_barrier
	v_mfma_f32_16x16x32_bf16 v[60:63], v[120:123], v[184:187], v[60:63]
	v_mfma_f32_16x16x32_bf16 v[56:59], v[136:139], v[184:187], v[56:59]
	v_mfma_f32_16x16x32_bf16 v[44:47], v[120:123], v[194:197], v[44:47]
	v_mfma_f32_16x16x32_bf16 v[40:43], v[136:139], v[194:197], v[40:43]
	v_mfma_f32_16x16x32_bf16 v[28:31], v[120:123], v[202:205], v[28:31]
	v_mfma_f32_16x16x32_bf16 v[24:27], v[136:139], v[202:205], v[24:27]
	v_mfma_f32_16x16x32_bf16 v[12:15], v[120:123], v[210:213], v[12:15]
	v_mfma_f32_16x16x32_bf16 v[8:11], v[136:139], v[210:213], v[8:11]
	v_mfma_f32_16x16x32_bf16 v[60:63], v[128:131], v[190:193], v[60:63]
	v_mfma_f32_16x16x32_bf16 v[56:59], v[140:143], v[190:193], v[56:59]
	v_mfma_f32_16x16x32_bf16 v[44:47], v[128:131], v[198:201], v[44:47]
	v_mfma_f32_16x16x32_bf16 v[40:43], v[140:143], v[198:201], v[40:43]
	v_mfma_f32_16x16x32_bf16 v[28:31], v[128:131], v[206:209], v[28:31]
	v_mfma_f32_16x16x32_bf16 v[24:27], v[140:143], v[206:209], v[24:27]
	v_mfma_f32_16x16x32_bf16 v[12:15], v[128:131], v[214:217], v[12:15]
	v_mfma_f32_16x16x32_bf16 v[8:11], v[140:143], v[214:217], v[8:11]
	v_mfma_f32_16x16x32_bf16 v[52:55], v[160:163], v[184:187], v[52:55]
	v_mfma_f32_16x16x32_bf16 v[48:51], v[176:179], v[184:187], v[48:51]
	v_mfma_f32_16x16x32_bf16 v[36:39], v[160:163], v[194:197], v[36:39]
	v_mfma_f32_16x16x32_bf16 v[32:35], v[176:179], v[194:197], v[32:35]
	v_mfma_f32_16x16x32_bf16 v[20:23], v[160:163], v[202:205], v[20:23]
	v_mfma_f32_16x16x32_bf16 v[16:19], v[176:179], v[202:205], v[16:19]
	v_mfma_f32_16x16x32_bf16 v[4:7], v[160:163], v[210:213], v[4:7]
	v_mfma_f32_16x16x32_bf16 v[0:3], v[176:179], v[210:213], v[0:3]
	v_mfma_f32_16x16x32_bf16 v[52:55], v[172:175], v[190:193], v[52:55]
	v_mfma_f32_16x16x32_bf16 v[48:51], v[180:183], v[190:193], v[48:51]
	v_mfma_f32_16x16x32_bf16 v[36:39], v[172:175], v[198:201], v[36:39]
	v_mfma_f32_16x16x32_bf16 v[32:35], v[180:183], v[198:201], v[32:35]
	v_mfma_f32_16x16x32_bf16 v[20:23], v[172:175], v[206:209], v[20:23]
	v_mfma_f32_16x16x32_bf16 v[16:19], v[180:183], v[206:209], v[16:19]
	v_mfma_f32_16x16x32_bf16 v[4:7], v[172:175], v[214:217], v[4:7]
	v_mfma_f32_16x16x32_bf16 v[0:3], v[180:183], v[214:217], v[0:3]
	s_setprio 0
	s_barrier
	s_add_u32 s8, s8, 0x100
	s_addc_u32 s9, s9, 0
	s_add_u32 s70, s70, 0x100
	s_addc_u32 s71, s71, 0
	s_cmp_ge_i32 s90, s83
	s_mov_b32 s68, s90
	s_cbranch_scc0 .LBB0_1679

; #define PG8_STAGE(bufoff, gbase, voff) do { _Pragma("unroll") for (int _i = 0; _i < 2; ++_i) \
;         __builtin_amdgcn_global_load_lds((const unsigned*)((const char*)(gbase) + (voff)[_i]), (PG8_LAS unsigned*)(lds + (bufoff) + ldsw + _i * 8192), 16, 0, 0); } while (0)
; #define PG8_LDA(dst, b, h) do { _Pragma("unroll") for (int m = 0; m < 4; ++m) _Pragma("unroll") for (int k = 0; k < 2; ++k) dst[m][k] = *(const PG8_LAS bf16x8*)(lds + PG8_SA(b, h) + aoff + m * 2048 + k * 1024); } while (0)
; #define PG8_LDB(dst, b, h) do { _Pragma("unroll") for (int n = 0; n < 2; ++n) _Pragma("unroll") for (int k = 0; k < 2; ++k) dst[n][k] = *(const PG8_LAS bf16x8*)(lds + PG8_SB(b, h) + boff + n * 2048 + k * 1024); } while (0)
; #define PG8_MMA(ai, bj, At, Bt) do { __builtin_amdgcn_s_setprio(1); _Pragma("unroll") for (int m = 0; m < 4; ++m) _Pragma("unroll") for (int n = 0; n < 2; ++n) _Pragma("unroll") for (int k = 0; k < 2; ++k) \
;         acc[ai][bj][m][n] = __builtin_amdgcn_mfma_f32_16x16x32_bf16(Bt[n][k], At[m][k], acc[ai][bj][m][n], 0, 0, 0); __builtin_amdgcn_s_setprio(0); } while (0)
; #define PG8_WAIT_V(n) asm volatile("s_waitcnt vmcnt(" #n ")" ::: "memory")
; #define PG8_WAIT_L(n) asm volatile("s_waitcnt lgkmcnt(" #n ")" ::: "memory")
; template <class Epi, class Sched, bool ALIGN_EPI = false, bool SP2 = false>
; __device__ __forceinline__ void gemm_phase(PG8_LAS unsigned char* lds, const Gemm g, const Sched& S, const Epi& E) {
;     ...
;             const bool last = (t == nt - 2);
;             const char* a1 = cA + (size_t)(t + 1) * kstep;
;             const char* a2 = last ? nA : cA + (size_t)(t + 2) * kstep; const char* b2 = last ? nB : cB + (size_t)(t + 2) * kstep;
;             const char* a3 = a2 + kstep; const char* b3 = b2 + kstep;
;             if (last && has_next) S.a_ready(nxt);
;             if constexpr (SP2) {
;             PG8_LDB(B0, 0, 0); PG8_LDB(B1, 0, 1); PG8_SCHED; PG8_LDA(At, 0, 0); PG8_STAGE(PG8_SA(1, 1), a1 + hstepA, voffA);
;             PG8_WAIT_V(8); PG8_WAIT_L(0); PG8_BAR; PG8_MMA(0, 0, At, B0); PG8_MMA(0, 1, At, B1); PG8_BAR; PG8_SCHED;
;             PG8_LDA(At, 0, 1); PG8_STAGE(PG8_SB(0, 0), b2, voffB); PG8_STAGE(PG8_SB(0, 1), b2 + hstep, voffB); PG8_STAGE(PG8_SA(0, 0), a2, voffA);
;             PG8_WAIT_V(8); PG8_WAIT_L(0); PG8_BAR; PG8_MMA(1, 0, At, B0); PG8_MMA(1, 1, At, B1); PG8_BAR; PG8_SCHED;
.LBB0_1815:
	ds_read_b128 v[150:153], v147
	ds_read_b128 v[154:157], v147 offset:1024
	ds_read_b128 v[158:161], v147 offset:2048
	ds_read_b128 v[162:165], v147 offset:3072
	ds_read_b128 v[166:169], v148
	ds_read_b128 v[170:173], v148 offset:1024
	ds_read_b128 v[174:177], v148 offset:2048
	ds_read_b128 v[178:181], v148 offset:3072
	s_add_i32 s57, s30, 2
	s_add_u32 s58, s10, 0xfffc0080
	s_addc_u32 s31, s11, -1
	s_cmp_eq_u32 s50, s30
	s_cselect_b32 s30, s56, s58
	s_cselect_b32 s31, s23, s31
	s_cselect_b32 s59, s25, s35
	s_cselect_b32 s58, s24, s34
	s_add_i32 m0, s29, 0xc000
	ds_read_b128 v[182:185], v149
	ds_read_b128 v[190:193], v149 offset:1024
	ds_read_b128 v[194:197], v149 offset:2048
	ds_read_b128 v[198:201], v149 offset:3072
	ds_read_b128 v[202:205], v149 offset:4096
	ds_read_b128 v[206:209], v149 offset:5120
	ds_read_b128 v[210:213], v149 offset:6144
	global_load_lds_dwordx4 v136, s[10:11]
	s_add_i32 m0, s29, 0xe000
	ds_read_b128 v[214:217], v149 offset:7168
	global_load_lds_dwordx4 v138, s[10:11]
	s_waitcnt vmcnt(8) lgkmcnt(0)
	s_setprio 1
	s_barrier
	v_mfma_f32_16x16x32_bf16 v[124:127], v[150:153], v[182:185], v[124:127]
	v_mfma_f32_16x16x32_bf16 v[116:119], v[158:161], v[182:185], v[116:119]
	v_mfma_f32_16x16x32_bf16 v[108:111], v[150:153], v[194:197], v[108:111]
	v_mfma_f32_16x16x32_bf16 v[100:103], v[158:161], v[194:197], v[100:103]
	v_mfma_f32_16x16x32_bf16 v[92:95], v[150:153], v[202:205], v[92:95]
	v_mfma_f32_16x16x32_bf16 v[84:87], v[158:161], v[202:205], v[84:87]
	v_mfma_f32_16x16x32_bf16 v[76:79], v[150:153], v[210:213], v[76:79]
	v_mfma_f32_16x16x32_bf16 v[68:71], v[158:161], v[210:213], v[68:71]
	v_mfma_f32_16x16x32_bf16 v[124:127], v[154:157], v[190:193], v[124:127]
	v_mfma_f32_16x16x32_bf16 v[116:119], v[162:165], v[190:193], v[116:119]
	v_mfma_f32_16x16x32_bf16 v[108:111], v[154:157], v[198:201], v[108:111]
	v_mfma_f32_16x16x32_bf16 v[100:103], v[162:165], v[198:201], v[100:103]
	v_mfma_f32_16x16x32_bf16 v[92:95], v[154:157], v[206:209], v[92:95]
	v_mfma_f32_16x16x32_bf16 v[84:87], v[162:165], v[206:209], v[84:87]
	v_mfma_f32_16x16x32_bf16 v[76:79], v[154:157], v[214:217], v[76:79]
	v_mfma_f32_16x16x32_bf16 v[68:71], v[162:165], v[214:217], v[68:71]
	v_mfma_f32_16x16x32_bf16 v[120:123], v[166:169], v[182:185], v[120:123]
	v_mfma_f32_16x16x32_bf16 v[112:115], v[174:177], v[182:185], v[112:115]
	v_mfma_f32_16x16x32_bf16 v[104:107], v[166:169], v[194:197], v[104:107]
	v_mfma_f32_16x16x32_bf16 v[96:99], v[174:177], v[194:197], v[96:99]
	v_mfma_f32_16x16x32_bf16 v[88:91], v[166:169], v[202:205], v[88:91]
	v_mfma_f32_16x16x32_bf16 v[80:83], v[174:177], v[202:205], v[80:83]
	v_mfma_f32_16x16x32_bf16 v[72:75], v[166:169], v[210:213], v[72:75]
	v_mfma_f32_16x16x32_bf16 v[64:67], v[174:177], v[210:213], v[64:67]
	v_mfma_f32_16x16x32_bf16 v[120:123], v[170:173], v[190:193], v[120:123]
	v_mfma_f32_16x16x32_bf16 v[112:115], v[178:181], v[190:193], v[112:115]
	v_mfma_f32_16x16x32_bf16 v[104:107], v[170:173], v[198:201], v[104:107]
	v_mfma_f32_16x16x32_bf16 v[96:99], v[178:181], v[198:201], v[96:99]
	v_mfma_f32_16x16x32_bf16 v[88:91], v[170:173], v[206:209], v[88:91]
	v_mfma_f32_16x16x32_bf16 v[80:83], v[178:181], v[206:209], v[80:83]
	v_mfma_f32_16x16x32_bf16 v[72:75], v[170:173], v[214:217], v[72:75]
	v_mfma_f32_16x16x32_bf16 v[64:67], v[178:181], v[214:217], v[64:67]
	s_setprio 0
	s_barrier
	s_add_i32 s60, s51, s38
	s_mov_b32 m0, s60
	ds_read_b128 v[182:185], v149 offset:16384
	ds_read_b128 v[190:193], v149 offset:17408
	ds_read_b128 v[194:197], v149 offset:18432
	ds_read_b128 v[198:201], v149 offset:19456
	global_load_lds_dwordx4 v134, s[58:59]
	s_add_i32 m0, s60, 0x2000
	s_mov_b64 s[100:101], s[58:59]
	s_add_i32 s60, s52, s38
	global_load_lds_dwordx4 v132, s[58:59]
	s_add_u32 s58, s58, s4
	s_addc_u32 s59, s59, s5
	s_mov_b32 m0, s60
	ds_read_b128 v[214:217], v149 offset:23552
	global_load_lds_dwordx4 v134, s[58:59]
	s_add_i32 m0, s60, 0x2000
	ds_read_b128 v[210:213], v149 offset:22528
	global_load_lds_dwordx4 v132, s[58:59]
	s_mov_b32 m0, s29
	ds_read_b128 v[206:209], v149 offset:21504
	global_load_lds_dwordx4 v128, s[30:31]
	s_mov_b32 m0, s41
	ds_read_b128 v[202:205], v149 offset:20480
	global_load_lds_dwordx4 v130, s[30:31]
	s_waitcnt vmcnt(8) lgkmcnt(0)
	s_setprio 1
	s_barrier
	v_mfma_f32_16x16x32_bf16 v[60:63], v[150:153], v[182:185], v[60:63]
	v_mfma_f32_16x16x32_bf16 v[52:55], v[158:161], v[182:185], v[52:55]
	v_mfma_f32_16x16x32_bf16 v[44:47], v[150:153], v[194:197], v[44:47]
	v_mfma_f32_16x16x32_bf16 v[36:39], v[158:161], v[194:197], v[36:39]
	v_mfma_f32_16x16x32_bf16 v[28:31], v[150:153], v[202:205], v[28:31]
	v_mfma_f32_16x16x32_bf16 v[20:23], v[158:161], v[202:205], v[20:23]
	v_mfma_f32_16x16x32_bf16 v[12:15], v[150:153], v[210:213], v[12:15]
	v_mfma_f32_16x16x32_bf16 v[4:7], v[158:161], v[210:213], v[4:7]
	v_mfma_f32_16x16x32_bf16 v[60:63], v[154:157], v[190:193], v[60:63]
	v_mfma_f32_16x16x32_bf16 v[52:55], v[162:165], v[190:193], v[52:55]
	v_mfma_f32_16x16x32_bf16 v[44:47], v[154:157], v[198:201], v[44:47]
	v_mfma_f32_16x16x32_bf16 v[36:39], v[162:165], v[198:201], v[36:39]
	v_mfma_f32_16x16x32_bf16 v[28:31], v[154:157], v[206:209], v[28:31]
	v_mfma_f32_16x16x32_bf16 v[20:23], v[162:165], v[206:209], v[20:23]
	v_mfma_f32_16x16x32_bf16 v[12:15], v[154:157], v[214:217], v[12:15]
	v_mfma_f32_16x16x32_bf16 v[4:7], v[162:165], v[214:217], v[4:7]
	v_mfma_f32_16x16x32_bf16 v[56:59], v[166:169], v[182:185], v[56:59]
	v_mfma_f32_16x16x32_bf16 v[48:51], v[174:177], v[182:185], v[48:51]
	v_mfma_f32_16x16x32_bf16 v[40:43], v[166:169], v[194:197], v[40:43]
	v_mfma_f32_16x16x32_bf16 v[32:35], v[174:177], v[194:197], v[32:35]
	v_mfma_f32_16x16x32_bf16 v[24:27], v[166:169], v[202:205], v[24:27]
	v_mfma_f32_16x16x32_bf16 v[16:19], v[174:177], v[202:205], v[16:19]
	v_mfma_f32_16x16x32_bf16 v[8:11], v[166:169], v[210:213], v[8:11]
	v_mfma_f32_16x16x32_bf16 v[0:3], v[174:177], v[210:213], v[0:3]
	v_mfma_f32_16x16x32_bf16 v[56:59], v[170:173], v[190:193], v[56:59]
	v_mfma_f32_16x16x32_bf16 v[48:51], v[178:181], v[190:193], v[48:51]
	v_mfma_f32_16x16x32_bf16 v[40:43], v[170:173], v[198:201], v[40:43]
	v_mfma_f32_16x16x32_bf16 v[32:35], v[178:181], v[198:201], v[32:35]
	v_mfma_f32_16x16x32_bf16 v[24:27], v[170:173], v[206:209], v[24:27]
	v_mfma_f32_16x16x32_bf16 v[16:19], v[178:181], v[206:209], v[16:19]
	v_mfma_f32_16x16x32_bf16 v[8:11], v[170:173], v[214:217], v[8:11]
	v_mfma_f32_16x16x32_bf16 v[0:3], v[178:181], v[214:217], v[0:3]
	s_setprio 0
	s_barrier
; #define PG8_STAGE(bufoff, gbase, voff) do { _Pragma("unroll") for (int _i = 0; _i < 2; ++_i) \
;         __builtin_amdgcn_global_load_lds((const unsigned*)((const char*)(gbase) + (voff)[_i]), (PG8_LAS unsigned*)(lds + (bufoff) + ldsw + _i * 8192), 16, 0, 0); } while (0)
; #define PG8_LDA(dst, b, h) do { _Pragma("unroll") for (int m = 0; m < 4; ++m) _Pragma("unroll") for (int k = 0; k < 2; ++k) dst[m][k] = *(const PG8_LAS bf16x8*)(lds + PG8_SA(b, h) + aoff + m * 2048 + k * 1024); } while (0)
; #define PG8_LDB(dst, b, h) do { _Pragma("unroll") for (int n = 0; n < 2; ++n) _Pragma("unroll") for (int k = 0; k < 2; ++k) dst[n][k] = *(const PG8_LAS bf16x8*)(lds + PG8_SB(b, h) + boff + n * 2048 + k * 1024); } while (0)
; #define PG8_MMA(ai, bj, At, Bt) do { __builtin_amdgcn_s_setprio(1); _Pragma("unroll") for (int m = 0; m < 4; ++m) _Pragma("unroll") for (int n = 0; n < 2; ++n) _Pragma("unroll") for (int k = 0; k < 2; ++k) \
;         acc[ai][bj][m][n] = __builtin_amdgcn_mfma_f32_16x16x32_bf16(Bt[n][k], At[m][k], acc[ai][bj][m][n], 0, 0, 0); __builtin_amdgcn_s_setprio(0); } while (0)
; #define PG8_WAIT_V(n) asm volatile("s_waitcnt vmcnt(" #n ")" ::: "memory")
; #define PG8_WAIT_L(n) asm volatile("s_waitcnt lgkmcnt(" #n ")" ::: "memory")
; #define PG8_BAR __builtin_amdgcn_s_barrier()
; #define PG8_SCHED __builtin_amdgcn_sched_barrier(0)
; template <class Epi, class Sched, bool ALIGN_EPI = false, bool SP2 = false>
; __device__ __forceinline__ void gemm_phase(PG8_LAS unsigned char* lds, const Gemm g, const Sched& S, const Epi& E) {
;     ...
;             PG8_LDB(B0, 1, 0); PG8_LDB(B1, 1, 1); PG8_SCHED; PG8_LDA(At, 1, 0); PG8_STAGE(PG8_SA(0, 1), a2 + hstepA, voffA);
;             PG8_WAIT_V(8); PG8_WAIT_L(0); PG8_BAR; PG8_MMA(0, 0, At, B0); PG8_MMA(0, 1, At, B1); PG8_BAR; PG8_SCHED;
;             PG8_LDA(At, 1, 1); PG8_STAGE(PG8_SB(1, 0), b3, voffB); PG8_STAGE(PG8_SB(1, 1), b3 + hstep, voffB); PG8_STAGE(PG8_SA(1, 0), a3, voffA);
;             PG8_WAIT_V(8); PG8_WAIT_L(0); PG8_BAR; PG8_MMA(1, 0, At, B0); PG8_MMA(1, 1, At, B1); PG8_BAR; PG8_SCHED;
	s_add_i32 s58, 0, 0x18000
	s_add_i32 s59, 0, 0x1c000
	v_add_u32_e32 v162, s58, v145
	v_add_u32_e32 v178, s59, v145
	ds_read_b128 v[150:153], v162
	ds_read_b128 v[154:157], v162 offset:1024
	ds_read_b128 v[158:161], v162 offset:2048
	ds_read_b128 v[162:165], v162 offset:3072
	ds_read_b128 v[166:169], v178
	ds_read_b128 v[170:173], v178 offset:1024
	ds_read_b128 v[174:177], v178 offset:2048
	ds_read_b128 v[178:181], v178 offset:3072
	s_mov_b64 vcc, s[30:31]
	s_add_u32 s30, s30, 0x40000
	s_addc_u32 s31, s31, 0
	s_mov_b32 m0, s42
	ds_read_b128 v[182:185], v149 offset:32768
	ds_read_b128 v[190:193], v149 offset:33792
	ds_read_b128 v[194:197], v149 offset:34816
	ds_read_b128 v[198:201], v149 offset:35840
	ds_read_b128 v[202:205], v149 offset:36864
	ds_read_b128 v[206:209], v149 offset:37888
	ds_read_b128 v[210:213], v149 offset:38912
	global_load_lds_dwordx4 v128, s[30:31]
	s_mov_b32 m0, s43
	ds_read_b128 v[214:217], v149 offset:39936
	global_load_lds_dwordx4 v130, s[30:31]
	s_waitcnt vmcnt(8) lgkmcnt(0)
	s_setprio 1
	s_barrier
	v_mfma_f32_16x16x32_bf16 v[124:127], v[150:153], v[182:185], v[124:127]
	v_mfma_f32_16x16x32_bf16 v[116:119], v[158:161], v[182:185], v[116:119]
	v_mfma_f32_16x16x32_bf16 v[108:111], v[150:153], v[194:197], v[108:111]
	v_mfma_f32_16x16x32_bf16 v[100:103], v[158:161], v[194:197], v[100:103]
	v_mfma_f32_16x16x32_bf16 v[92:95], v[150:153], v[202:205], v[92:95]
	v_mfma_f32_16x16x32_bf16 v[84:87], v[158:161], v[202:205], v[84:87]
	v_mfma_f32_16x16x32_bf16 v[76:79], v[150:153], v[210:213], v[76:79]
	v_mfma_f32_16x16x32_bf16 v[68:71], v[158:161], v[210:213], v[68:71]
	v_mfma_f32_16x16x32_bf16 v[124:127], v[154:157], v[190:193], v[124:127]
	v_mfma_f32_16x16x32_bf16 v[116:119], v[162:165], v[190:193], v[116:119]
	v_mfma_f32_16x16x32_bf16 v[108:111], v[154:157], v[198:201], v[108:111]
	v_mfma_f32_16x16x32_bf16 v[100:103], v[162:165], v[198:201], v[100:103]
	v_mfma_f32_16x16x32_bf16 v[92:95], v[154:157], v[206:209], v[92:95]
	v_mfma_f32_16x16x32_bf16 v[84:87], v[162:165], v[206:209], v[84:87]
	v_mfma_f32_16x16x32_bf16 v[76:79], v[154:157], v[214:217], v[76:79]
	v_mfma_f32_16x16x32_bf16 v[68:71], v[162:165], v[214:217], v[68:71]
	v_mfma_f32_16x16x32_bf16 v[120:123], v[166:169], v[182:185], v[120:123]
	v_mfma_f32_16x16x32_bf16 v[112:115], v[174:177], v[182:185], v[112:115]
	v_mfma_f32_16x16x32_bf16 v[104:107], v[166:169], v[194:197], v[104:107]
	v_mfma_f32_16x16x32_bf16 v[96:99], v[174:177], v[194:197], v[96:99]
	v_mfma_f32_16x16x32_bf16 v[88:91], v[166:169], v[202:205], v[88:91]
	v_mfma_f32_16x16x32_bf16 v[80:83], v[174:177], v[202:205], v[80:83]
	v_mfma_f32_16x16x32_bf16 v[72:75], v[166:169], v[210:213], v[72:75]
	v_mfma_f32_16x16x32_bf16 v[64:67], v[174:177], v[210:213], v[64:67]
	v_mfma_f32_16x16x32_bf16 v[120:123], v[170:173], v[190:193], v[120:123]
	v_mfma_f32_16x16x32_bf16 v[112:115], v[178:181], v[190:193], v[112:115]
	v_mfma_f32_16x16x32_bf16 v[104:107], v[170:173], v[198:201], v[104:107]
	v_mfma_f32_16x16x32_bf16 v[96:99], v[178:181], v[198:201], v[96:99]
	v_mfma_f32_16x16x32_bf16 v[88:91], v[170:173], v[206:209], v[88:91]
	v_mfma_f32_16x16x32_bf16 v[80:83], v[178:181], v[206:209], v[80:83]
	v_mfma_f32_16x16x32_bf16 v[72:75], v[170:173], v[214:217], v[72:75]
	v_mfma_f32_16x16x32_bf16 v[64:67], v[178:181], v[214:217], v[64:67]
	s_setprio 0
	s_barrier
	s_add_i32 s30, s58, s38
	s_add_i32 m0, s30, 0xffffff80
	ds_read_b128 v[182:185], v149 offset:49152
	ds_read_b128 v[190:193], v149 offset:50176
	ds_read_b128 v[194:197], v149 offset:51200
	ds_read_b128 v[198:201], v149 offset:52224
	global_load_lds_dwordx4 v134, s[100:101] offset:128
	s_add_i32 m0, s30, 0x1f80
	s_add_i32 s30, s59, s38
	global_load_lds_dwordx4 v132, s[100:101] offset:128
	s_add_u32 s100, s100, s4
	s_addc_u32 s101, s101, s5
	s_add_i32 m0, s30, 0xffffff80
	ds_read_b128 v[214:217], v149 offset:56320
	global_load_lds_dwordx4 v134, s[100:101] offset:128
	s_add_i32 m0, s30, 0x1f80
	ds_read_b128 v[210:213], v149 offset:55296
	global_load_lds_dwordx4 v132, s[100:101] offset:128
	s_add_i32 m0, s46, 0xffffff80
	ds_read_b128 v[206:209], v149 offset:54272
	global_load_lds_dwordx4 v128, vcc offset:128
	s_add_i32 m0, s47, 0xffffff80
	ds_read_b128 v[202:205], v149 offset:53248
	global_load_lds_dwordx4 v130, vcc offset:128
	s_waitcnt vmcnt(8) lgkmcnt(0)
	s_setprio 1
	s_barrier
	v_mfma_f32_16x16x32_bf16 v[60:63], v[150:153], v[182:185], v[60:63]
	v_mfma_f32_16x16x32_bf16 v[52:55], v[158:161], v[182:185], v[52:55]
	v_mfma_f32_16x16x32_bf16 v[44:47], v[150:153], v[194:197], v[44:47]
	v_mfma_f32_16x16x32_bf16 v[36:39], v[158:161], v[194:197], v[36:39]
	v_mfma_f32_16x16x32_bf16 v[28:31], v[150:153], v[202:205], v[28:31]
	v_mfma_f32_16x16x32_bf16 v[20:23], v[158:161], v[202:205], v[20:23]
	v_mfma_f32_16x16x32_bf16 v[12:15], v[150:153], v[210:213], v[12:15]
	v_mfma_f32_16x16x32_bf16 v[4:7], v[158:161], v[210:213], v[4:7]
	v_mfma_f32_16x16x32_bf16 v[60:63], v[154:157], v[190:193], v[60:63]
	v_mfma_f32_16x16x32_bf16 v[52:55], v[162:165], v[190:193], v[52:55]
	v_mfma_f32_16x16x32_bf16 v[44:47], v[154:157], v[198:201], v[44:47]
	v_mfma_f32_16x16x32_bf16 v[36:39], v[162:165], v[198:201], v[36:39]
	v_mfma_f32_16x16x32_bf16 v[28:31], v[154:157], v[206:209], v[28:31]
	v_mfma_f32_16x16x32_bf16 v[20:23], v[162:165], v[206:209], v[20:23]
	v_mfma_f32_16x16x32_bf16 v[12:15], v[154:157], v[214:217], v[12:15]
	v_mfma_f32_16x16x32_bf16 v[4:7], v[162:165], v[214:217], v[4:7]
	v_mfma_f32_16x16x32_bf16 v[56:59], v[166:169], v[182:185], v[56:59]
	v_mfma_f32_16x16x32_bf16 v[48:51], v[174:177], v[182:185], v[48:51]
	v_mfma_f32_16x16x32_bf16 v[40:43], v[166:169], v[194:197], v[40:43]
	v_mfma_f32_16x16x32_bf16 v[32:35], v[174:177], v[194:197], v[32:35]
	v_mfma_f32_16x16x32_bf16 v[24:27], v[166:169], v[202:205], v[24:27]
	v_mfma_f32_16x16x32_bf16 v[16:19], v[174:177], v[202:205], v[16:19]
	v_mfma_f32_16x16x32_bf16 v[8:11], v[166:169], v[210:213], v[8:11]
	v_mfma_f32_16x16x32_bf16 v[0:3], v[174:177], v[210:213], v[0:3]
	v_mfma_f32_16x16x32_bf16 v[56:59], v[170:173], v[190:193], v[56:59]
	v_mfma_f32_16x16x32_bf16 v[48:51], v[178:181], v[190:193], v[48:51]
	v_mfma_f32_16x16x32_bf16 v[40:43], v[170:173], v[198:201], v[40:43]
	v_mfma_f32_16x16x32_bf16 v[32:35], v[178:181], v[198:201], v[32:35]
	v_mfma_f32_16x16x32_bf16 v[24:27], v[170:173], v[206:209], v[24:27]
	v_mfma_f32_16x16x32_bf16 v[16:19], v[178:181], v[206:209], v[16:19]
	v_mfma_f32_16x16x32_bf16 v[8:11], v[170:173], v[214:217], v[8:11]
	v_mfma_f32_16x16x32_bf16 v[0:3], v[178:181], v[214:217], v[0:3]
	s_setprio 0
	s_barrier
	s_add_u32 s10, s10, 0x100
	s_addc_u32 s11, s11, 0
	s_add_u32 s34, s34, 0x100
	s_addc_u32 s35, s35, 0
	s_cmp_ge_i32 s57, s49
	s_mov_b32 s30, s57
	s_cbranch_scc0 .LBB0_1815

; #define PG8_STAGE(bufoff, gbase, voff) do { _Pragma("unroll") for (int _i = 0; _i < 2; ++_i) \
;         __builtin_amdgcn_global_load_lds((const unsigned*)((const char*)(gbase) + (voff)[_i]), (PG8_LAS unsigned*)(lds + (bufoff) + ldsw + _i * 8192), 16, 0, 0); } while (0)
; #define PG8_LDA(dst, b, h) do { _Pragma("unroll") for (int m = 0; m < 4; ++m) _Pragma("unroll") for (int k = 0; k < 2; ++k) dst[m][k] = *(const PG8_LAS bf16x8*)(lds + PG8_SA(b, h) + aoff + m * 2048 + k * 1024); } while (0)
; #define PG8_LDB(dst, b, h) do { _Pragma("unroll") for (int n = 0; n < 2; ++n) _Pragma("unroll") for (int k = 0; k < 2; ++k) dst[n][k] = *(const PG8_LAS bf16x8*)(lds + PG8_SB(b, h) + boff + n * 2048 + k * 1024); } while (0)
; #define PG8_MMA(ai, bj, At, Bt) do { __builtin_amdgcn_s_setprio(1); _Pragma("unroll") for (int m = 0; m < 4; ++m) _Pragma("unroll") for (int n = 0; n < 2; ++n) _Pragma("unroll") for (int k = 0; k < 2; ++k) \
;         acc[ai][bj][m][n] = __builtin_amdgcn_mfma_f32_16x16x32_bf16(Bt[n][k], At[m][k], acc[ai][bj][m][n], 0, 0, 0); __builtin_amdgcn_s_setprio(0); } while (0)
; #define PG8_WAIT_V(n) asm volatile("s_waitcnt vmcnt(" #n ")" ::: "memory")
; #define PG8_WAIT_L(n) asm volatile("s_waitcnt lgkmcnt(" #n ")" ::: "memory")
; template <class Epi, class Sched, bool ALIGN_EPI = false, bool SP2 = false>
; __device__ __forceinline__ void gemm_phase(PG8_LAS unsigned char* lds, const Gemm g, const Sched& S, const Epi& E) {
;     ...
;             const bool last = (t == nt - 2);
;             const char* a1 = cA + (size_t)(t + 1) * kstep;
;             const char* a2 = last ? nA : cA + (size_t)(t + 2) * kstep; const char* b2 = last ? nB : cB + (size_t)(t + 2) * kstep;
;             const char* a3 = a2 + kstep; const char* b3 = b2 + kstep;
;             if (last && has_next) S.a_ready(nxt);
;             if constexpr (SP2) {
;             PG8_LDB(B0, 0, 0); PG8_LDB(B1, 0, 1); PG8_SCHED; PG8_LDA(At, 0, 0); PG8_STAGE(PG8_SA(1, 1), a1 + hstepA, voffA);
;             PG8_WAIT_V(8); PG8_WAIT_L(0); PG8_BAR; PG8_MMA(0, 0, At, B0); PG8_MMA(0, 1, At, B1); PG8_BAR; PG8_SCHED;
;             PG8_LDA(At, 0, 1); PG8_STAGE(PG8_SB(0, 0), b2, voffB); PG8_STAGE(PG8_SB(0, 1), b2 + hstep, voffB); PG8_STAGE(PG8_SA(0, 0), a2, voffA);
;             PG8_WAIT_V(8); PG8_WAIT_L(0); PG8_BAR; PG8_MMA(1, 0, At, B0); PG8_MMA(1, 1, At, B1); PG8_BAR; PG8_SCHED;
.LBB0_1897:
	ds_read_b128 v[128:131], v169
	ds_read_b128 v[132:135], v169 offset:1024
	ds_read_b128 v[136:139], v169 offset:2048
	ds_read_b128 v[140:143], v169 offset:3072
	ds_read_b128 v[160:163], v170
	ds_read_b128 v[172:175], v170 offset:1024
	ds_read_b128 v[176:179], v170 offset:2048
	ds_read_b128 v[180:183], v170 offset:3072
	s_add_i32 s63, s38, 2
	s_add_u32 s64, s36, 0xfff50080
	s_addc_u32 s39, s37, -1
	s_cmp_eq_u32 s53, s38
	s_cselect_b32 s38, s4, s64
	s_cselect_b32 s39, s5, s39
	s_cselect_b32 s65, s35, s62
	s_cselect_b32 s64, s34, s61
	s_add_i32 m0, s44, 0xc000
	ds_read_b128 v[184:187], v171
	ds_read_b128 v[188:191], v171 offset:1024
	ds_read_b128 v[192:195], v171 offset:2048
	ds_read_b128 v[196:199], v171 offset:3072
	ds_read_b128 v[200:203], v171 offset:4096
	ds_read_b128 v[204:207], v171 offset:5120
	ds_read_b128 v[208:211], v171 offset:6144
	global_load_lds_dwordx4 v152, s[36:37]
	s_add_i32 m0, s44, 0xe000
	ds_read_b128 v[212:215], v171 offset:7168
	global_load_lds_dwordx4 v154, s[36:37]
	s_waitcnt vmcnt(8) lgkmcnt(0)
	s_setprio 1
	s_barrier
	v_mfma_f32_16x16x32_bf16 v[124:127], v[128:131], v[184:187], v[124:127]
	v_mfma_f32_16x16x32_bf16 v[120:123], v[136:139], v[184:187], v[120:123]
	v_mfma_f32_16x16x32_bf16 v[108:111], v[128:131], v[192:195], v[108:111]
	v_mfma_f32_16x16x32_bf16 v[104:107], v[136:139], v[192:195], v[104:107]
	v_mfma_f32_16x16x32_bf16 v[92:95], v[128:131], v[200:203], v[92:95]
	v_mfma_f32_16x16x32_bf16 v[88:91], v[136:139], v[200:203], v[88:91]
	v_mfma_f32_16x16x32_bf16 v[76:79], v[128:131], v[208:211], v[76:79]
	v_mfma_f32_16x16x32_bf16 v[72:75], v[136:139], v[208:211], v[72:75]
	v_mfma_f32_16x16x32_bf16 v[124:127], v[132:135], v[188:191], v[124:127]
	v_mfma_f32_16x16x32_bf16 v[120:123], v[140:143], v[188:191], v[120:123]
	v_mfma_f32_16x16x32_bf16 v[108:111], v[132:135], v[196:199], v[108:111]
	v_mfma_f32_16x16x32_bf16 v[104:107], v[140:143], v[196:199], v[104:107]
	v_mfma_f32_16x16x32_bf16 v[92:95], v[132:135], v[204:207], v[92:95]
	v_mfma_f32_16x16x32_bf16 v[88:91], v[140:143], v[204:207], v[88:91]
	v_mfma_f32_16x16x32_bf16 v[76:79], v[132:135], v[212:215], v[76:79]
	v_mfma_f32_16x16x32_bf16 v[72:75], v[140:143], v[212:215], v[72:75]
	v_mfma_f32_16x16x32_bf16 v[116:119], v[160:163], v[184:187], v[116:119]
	v_mfma_f32_16x16x32_bf16 v[112:115], v[176:179], v[184:187], v[112:115]
	v_mfma_f32_16x16x32_bf16 v[100:103], v[160:163], v[192:195], v[100:103]
	v_mfma_f32_16x16x32_bf16 v[96:99], v[176:179], v[192:195], v[96:99]
	v_mfma_f32_16x16x32_bf16 v[84:87], v[160:163], v[200:203], v[84:87]
	v_mfma_f32_16x16x32_bf16 v[80:83], v[176:179], v[200:203], v[80:83]
	v_mfma_f32_16x16x32_bf16 v[68:71], v[160:163], v[208:211], v[68:71]
	v_mfma_f32_16x16x32_bf16 v[64:67], v[176:179], v[208:211], v[64:67]
	v_mfma_f32_16x16x32_bf16 v[116:119], v[172:175], v[188:191], v[116:119]
	v_mfma_f32_16x16x32_bf16 v[112:115], v[180:183], v[188:191], v[112:115]
	v_mfma_f32_16x16x32_bf16 v[100:103], v[172:175], v[196:199], v[100:103]
	v_mfma_f32_16x16x32_bf16 v[96:99], v[180:183], v[196:199], v[96:99]
	v_mfma_f32_16x16x32_bf16 v[84:87], v[172:175], v[204:207], v[84:87]
	v_mfma_f32_16x16x32_bf16 v[80:83], v[180:183], v[204:207], v[80:83]
	v_mfma_f32_16x16x32_bf16 v[68:71], v[172:175], v[212:215], v[68:71]
	v_mfma_f32_16x16x32_bf16 v[64:67], v[180:183], v[212:215], v[64:67]
	s_setprio 0
	s_barrier
	s_add_i32 s66, s54, s42
	s_mov_b32 m0, s66
	ds_read_b128 v[184:187], v171 offset:16384
	ds_read_b128 v[188:191], v171 offset:17408
	ds_read_b128 v[192:195], v171 offset:18432
	ds_read_b128 v[196:199], v171 offset:19456
	global_load_lds_dwordx4 v150, s[64:65]
	s_add_i32 m0, s66, 0x2000
	s_mov_b64 s[100:101], s[64:65]
	s_add_i32 s66, s55, s42
	global_load_lds_dwordx4 v148, s[64:65]
	s_add_u32 s64, s64, s6
	s_addc_u32 s65, s65, s7
	s_mov_b32 m0, s66
	ds_read_b128 v[212:215], v171 offset:23552
	global_load_lds_dwordx4 v150, s[64:65]
	s_add_i32 m0, s66, 0x2000
	ds_read_b128 v[208:211], v171 offset:22528
	global_load_lds_dwordx4 v148, s[64:65]
	s_mov_b32 m0, s44
	ds_read_b128 v[204:207], v171 offset:21504
	global_load_lds_dwordx4 v144, s[38:39]
	s_mov_b32 m0, s45
	ds_read_b128 v[200:203], v171 offset:20480
	global_load_lds_dwordx4 v146, s[38:39]
	s_waitcnt vmcnt(8) lgkmcnt(0)
	s_setprio 1
	s_barrier
	v_mfma_f32_16x16x32_bf16 v[60:63], v[128:131], v[184:187], v[60:63]
	v_mfma_f32_16x16x32_bf16 v[56:59], v[136:139], v[184:187], v[56:59]
	v_mfma_f32_16x16x32_bf16 v[44:47], v[128:131], v[192:195], v[44:47]
	v_mfma_f32_16x16x32_bf16 v[40:43], v[136:139], v[192:195], v[40:43]
	v_mfma_f32_16x16x32_bf16 v[28:31], v[128:131], v[200:203], v[28:31]
	v_mfma_f32_16x16x32_bf16 v[24:27], v[136:139], v[200:203], v[24:27]
	v_mfma_f32_16x16x32_bf16 v[12:15], v[128:131], v[208:211], v[12:15]
	v_mfma_f32_16x16x32_bf16 v[8:11], v[136:139], v[208:211], v[8:11]
	v_mfma_f32_16x16x32_bf16 v[60:63], v[132:135], v[188:191], v[60:63]
	v_mfma_f32_16x16x32_bf16 v[56:59], v[140:143], v[188:191], v[56:59]
	v_mfma_f32_16x16x32_bf16 v[44:47], v[132:135], v[196:199], v[44:47]
	v_mfma_f32_16x16x32_bf16 v[40:43], v[140:143], v[196:199], v[40:43]
	v_mfma_f32_16x16x32_bf16 v[28:31], v[132:135], v[204:207], v[28:31]
	v_mfma_f32_16x16x32_bf16 v[24:27], v[140:143], v[204:207], v[24:27]
	v_mfma_f32_16x16x32_bf16 v[12:15], v[132:135], v[212:215], v[12:15]
	v_mfma_f32_16x16x32_bf16 v[8:11], v[140:143], v[212:215], v[8:11]
	v_mfma_f32_16x16x32_bf16 v[52:55], v[160:163], v[184:187], v[52:55]
	v_mfma_f32_16x16x32_bf16 v[48:51], v[176:179], v[184:187], v[48:51]
	v_mfma_f32_16x16x32_bf16 v[36:39], v[160:163], v[192:195], v[36:39]
	v_mfma_f32_16x16x32_bf16 v[32:35], v[176:179], v[192:195], v[32:35]
	v_mfma_f32_16x16x32_bf16 v[20:23], v[160:163], v[200:203], v[20:23]
	v_mfma_f32_16x16x32_bf16 v[16:19], v[176:179], v[200:203], v[16:19]
	v_mfma_f32_16x16x32_bf16 v[4:7], v[160:163], v[208:211], v[4:7]
	v_mfma_f32_16x16x32_bf16 v[0:3], v[176:179], v[208:211], v[0:3]
	v_mfma_f32_16x16x32_bf16 v[52:55], v[172:175], v[188:191], v[52:55]
	v_mfma_f32_16x16x32_bf16 v[48:51], v[180:183], v[188:191], v[48:51]
	v_mfma_f32_16x16x32_bf16 v[36:39], v[172:175], v[196:199], v[36:39]
	v_mfma_f32_16x16x32_bf16 v[32:35], v[180:183], v[196:199], v[32:35]
	v_mfma_f32_16x16x32_bf16 v[20:23], v[172:175], v[204:207], v[20:23]
	v_mfma_f32_16x16x32_bf16 v[16:19], v[180:183], v[204:207], v[16:19]
	v_mfma_f32_16x16x32_bf16 v[4:7], v[172:175], v[212:215], v[4:7]
	v_mfma_f32_16x16x32_bf16 v[0:3], v[180:183], v[212:215], v[0:3]
	s_setprio 0
	s_barrier
; #define PG8_STAGE(bufoff, gbase, voff) do { _Pragma("unroll") for (int _i = 0; _i < 2; ++_i) \
;         __builtin_amdgcn_global_load_lds((const unsigned*)((const char*)(gbase) + (voff)[_i]), (PG8_LAS unsigned*)(lds + (bufoff) + ldsw + _i * 8192), 16, 0, 0); } while (0)
; #define PG8_LDA(dst, b, h) do { _Pragma("unroll") for (int m = 0; m < 4; ++m) _Pragma("unroll") for (int k = 0; k < 2; ++k) dst[m][k] = *(const PG8_LAS bf16x8*)(lds + PG8_SA(b, h) + aoff + m * 2048 + k * 1024); } while (0)
; #define PG8_LDB(dst, b, h) do { _Pragma("unroll") for (int n = 0; n < 2; ++n) _Pragma("unroll") for (int k = 0; k < 2; ++k) dst[n][k] = *(const PG8_LAS bf16x8*)(lds + PG8_SB(b, h) + boff + n * 2048 + k * 1024); } while (0)
; #define PG8_MMA(ai, bj, At, Bt) do { __builtin_amdgcn_s_setprio(1); _Pragma("unroll") for (int m = 0; m < 4; ++m) _Pragma("unroll") for (int n = 0; n < 2; ++n) _Pragma("unroll") for (int k = 0; k < 2; ++k) \
;         acc[ai][bj][m][n] = __builtin_amdgcn_mfma_f32_16x16x32_bf16(Bt[n][k], At[m][k], acc[ai][bj][m][n], 0, 0, 0); __builtin_amdgcn_s_setprio(0); } while (0)
; #define PG8_WAIT_V(n) asm volatile("s_waitcnt vmcnt(" #n ")" ::: "memory")
; #define PG8_WAIT_L(n) asm volatile("s_waitcnt lgkmcnt(" #n ")" ::: "memory")
; #define PG8_BAR __builtin_amdgcn_s_barrier()
; #define PG8_SCHED __builtin_amdgcn_sched_barrier(0)
; template <class Epi, class Sched, bool ALIGN_EPI = false, bool SP2 = false>
; __device__ __forceinline__ void gemm_phase(PG8_LAS unsigned char* lds, const Gemm g, const Sched& S, const Epi& E) {
;     ...
;             PG8_LDB(B0, 1, 0); PG8_LDB(B1, 1, 1); PG8_SCHED; PG8_LDA(At, 1, 0); PG8_STAGE(PG8_SA(0, 1), a2 + hstepA, voffA);
;             PG8_WAIT_V(8); PG8_WAIT_L(0); PG8_BAR; PG8_MMA(0, 0, At, B0); PG8_MMA(0, 1, At, B1); PG8_BAR; PG8_SCHED;
;             PG8_LDA(At, 1, 1); PG8_STAGE(PG8_SB(1, 0), b3, voffB); PG8_STAGE(PG8_SB(1, 1), b3 + hstep, voffB); PG8_STAGE(PG8_SA(1, 0), a3, voffA);
;             PG8_WAIT_V(8); PG8_WAIT_L(0); PG8_BAR; PG8_MMA(1, 0, At, B0); PG8_MMA(1, 1, At, B1); PG8_BAR; PG8_SCHED;
	s_add_i32 s64, 0, 0x18000
	s_add_i32 s65, 0, 0x1c000
	v_add_u32_e32 v140, s64, v167
	v_add_u32_e32 v180, s65, v167
	ds_read_b128 v[128:131], v140
	ds_read_b128 v[132:135], v140 offset:1024
	ds_read_b128 v[136:139], v140 offset:2048
	ds_read_b128 v[140:143], v140 offset:3072
	ds_read_b128 v[160:163], v180
	ds_read_b128 v[172:175], v180 offset:1024
	ds_read_b128 v[176:179], v180 offset:2048
	ds_read_b128 v[180:183], v180 offset:3072
	s_mov_b64 vcc, s[38:39]
	s_add_u32 s38, s38, 0xb0000
	s_addc_u32 s39, s39, 0
	s_mov_b32 m0, s46
	ds_read_b128 v[184:187], v171 offset:32768
	ds_read_b128 v[188:191], v171 offset:33792
	ds_read_b128 v[192:195], v171 offset:34816
	ds_read_b128 v[196:199], v171 offset:35840
	ds_read_b128 v[200:203], v171 offset:36864
	ds_read_b128 v[204:207], v171 offset:37888
	ds_read_b128 v[208:211], v171 offset:38912
	global_load_lds_dwordx4 v144, s[38:39]
	s_mov_b32 m0, s47
	ds_read_b128 v[212:215], v171 offset:39936
	global_load_lds_dwordx4 v146, s[38:39]
	s_waitcnt vmcnt(8) lgkmcnt(0)
	s_setprio 1
	s_barrier
	v_mfma_f32_16x16x32_bf16 v[124:127], v[128:131], v[184:187], v[124:127]
	v_mfma_f32_16x16x32_bf16 v[120:123], v[136:139], v[184:187], v[120:123]
	v_mfma_f32_16x16x32_bf16 v[108:111], v[128:131], v[192:195], v[108:111]
	v_mfma_f32_16x16x32_bf16 v[104:107], v[136:139], v[192:195], v[104:107]
	v_mfma_f32_16x16x32_bf16 v[92:95], v[128:131], v[200:203], v[92:95]
	v_mfma_f32_16x16x32_bf16 v[88:91], v[136:139], v[200:203], v[88:91]
	v_mfma_f32_16x16x32_bf16 v[76:79], v[128:131], v[208:211], v[76:79]
	v_mfma_f32_16x16x32_bf16 v[72:75], v[136:139], v[208:211], v[72:75]
	v_mfma_f32_16x16x32_bf16 v[124:127], v[132:135], v[188:191], v[124:127]
	v_mfma_f32_16x16x32_bf16 v[120:123], v[140:143], v[188:191], v[120:123]
	v_mfma_f32_16x16x32_bf16 v[108:111], v[132:135], v[196:199], v[108:111]
	v_mfma_f32_16x16x32_bf16 v[104:107], v[140:143], v[196:199], v[104:107]
	v_mfma_f32_16x16x32_bf16 v[92:95], v[132:135], v[204:207], v[92:95]
	v_mfma_f32_16x16x32_bf16 v[88:91], v[140:143], v[204:207], v[88:91]
	v_mfma_f32_16x16x32_bf16 v[76:79], v[132:135], v[212:215], v[76:79]
	v_mfma_f32_16x16x32_bf16 v[72:75], v[140:143], v[212:215], v[72:75]
	v_mfma_f32_16x16x32_bf16 v[116:119], v[160:163], v[184:187], v[116:119]
	v_mfma_f32_16x16x32_bf16 v[112:115], v[176:179], v[184:187], v[112:115]
	v_mfma_f32_16x16x32_bf16 v[100:103], v[160:163], v[192:195], v[100:103]
	v_mfma_f32_16x16x32_bf16 v[96:99], v[176:179], v[192:195], v[96:99]
	v_mfma_f32_16x16x32_bf16 v[84:87], v[160:163], v[200:203], v[84:87]
	v_mfma_f32_16x16x32_bf16 v[80:83], v[176:179], v[200:203], v[80:83]
	v_mfma_f32_16x16x32_bf16 v[68:71], v[160:163], v[208:211], v[68:71]
	v_mfma_f32_16x16x32_bf16 v[64:67], v[176:179], v[208:211], v[64:67]
	v_mfma_f32_16x16x32_bf16 v[116:119], v[172:175], v[188:191], v[116:119]
	v_mfma_f32_16x16x32_bf16 v[112:115], v[180:183], v[188:191], v[112:115]
	v_mfma_f32_16x16x32_bf16 v[100:103], v[172:175], v[196:199], v[100:103]
	v_mfma_f32_16x16x32_bf16 v[96:99], v[180:183], v[196:199], v[96:99]
	v_mfma_f32_16x16x32_bf16 v[84:87], v[172:175], v[204:207], v[84:87]
	v_mfma_f32_16x16x32_bf16 v[80:83], v[180:183], v[204:207], v[80:83]
	v_mfma_f32_16x16x32_bf16 v[68:71], v[172:175], v[212:215], v[68:71]
	v_mfma_f32_16x16x32_bf16 v[64:67], v[180:183], v[212:215], v[64:67]
	s_setprio 0
	s_barrier
	s_add_i32 s38, s64, s42
	s_add_i32 m0, s38, 0xffffff80
	ds_read_b128 v[184:187], v171 offset:49152
	ds_read_b128 v[188:191], v171 offset:50176
	ds_read_b128 v[192:195], v171 offset:51200
	ds_read_b128 v[196:199], v171 offset:52224
	global_load_lds_dwordx4 v150, s[100:101] offset:128
	s_add_i32 m0, s38, 0x1f80
	s_add_i32 s38, s65, s42
	global_load_lds_dwordx4 v148, s[100:101] offset:128
	s_add_u32 s100, s100, s6
	s_addc_u32 s101, s101, s7
	s_add_i32 m0, s38, 0xffffff80
	ds_read_b128 v[212:215], v171 offset:56320
	global_load_lds_dwordx4 v150, s[100:101] offset:128
	s_add_i32 m0, s38, 0x1f80
	ds_read_b128 v[208:211], v171 offset:55296
	global_load_lds_dwordx4 v148, s[100:101] offset:128
	s_add_i32 m0, s50, 0xffffff80
	ds_read_b128 v[204:207], v171 offset:54272
	global_load_lds_dwordx4 v144, vcc offset:128
	s_add_i32 m0, s51, 0xffffff80
	ds_read_b128 v[200:203], v171 offset:53248
	global_load_lds_dwordx4 v146, vcc offset:128
	s_waitcnt vmcnt(8) lgkmcnt(0)
	s_setprio 1
	s_barrier
	v_mfma_f32_16x16x32_bf16 v[60:63], v[128:131], v[184:187], v[60:63]
	v_mfma_f32_16x16x32_bf16 v[56:59], v[136:139], v[184:187], v[56:59]
	v_mfma_f32_16x16x32_bf16 v[44:47], v[128:131], v[192:195], v[44:47]
	v_mfma_f32_16x16x32_bf16 v[40:43], v[136:139], v[192:195], v[40:43]
	v_mfma_f32_16x16x32_bf16 v[28:31], v[128:131], v[200:203], v[28:31]
	v_mfma_f32_16x16x32_bf16 v[24:27], v[136:139], v[200:203], v[24:27]
	v_mfma_f32_16x16x32_bf16 v[12:15], v[128:131], v[208:211], v[12:15]
	v_mfma_f32_16x16x32_bf16 v[8:11], v[136:139], v[208:211], v[8:11]
	v_mfma_f32_16x16x32_bf16 v[60:63], v[132:135], v[188:191], v[60:63]
	v_mfma_f32_16x16x32_bf16 v[56:59], v[140:143], v[188:191], v[56:59]
	v_mfma_f32_16x16x32_bf16 v[44:47], v[132:135], v[196:199], v[44:47]
	v_mfma_f32_16x16x32_bf16 v[40:43], v[140:143], v[196:199], v[40:43]
	v_mfma_f32_16x16x32_bf16 v[28:31], v[132:135], v[204:207], v[28:31]
	v_mfma_f32_16x16x32_bf16 v[24:27], v[140:143], v[204:207], v[24:27]
	v_mfma_f32_16x16x32_bf16 v[12:15], v[132:135], v[212:215], v[12:15]
	v_mfma_f32_16x16x32_bf16 v[8:11], v[140:143], v[212:215], v[8:11]
	v_mfma_f32_16x16x32_bf16 v[52:55], v[160:163], v[184:187], v[52:55]
	v_mfma_f32_16x16x32_bf16 v[48:51], v[176:179], v[184:187], v[48:51]
	v_mfma_f32_16x16x32_bf16 v[36:39], v[160:163], v[192:195], v[36:39]
	v_mfma_f32_16x16x32_bf16 v[32:35], v[176:179], v[192:195], v[32:35]
	v_mfma_f32_16x16x32_bf16 v[20:23], v[160:163], v[200:203], v[20:23]
	v_mfma_f32_16x16x32_bf16 v[16:19], v[176:179], v[200:203], v[16:19]
	v_mfma_f32_16x16x32_bf16 v[4:7], v[160:163], v[208:211], v[4:7]
	v_mfma_f32_16x16x32_bf16 v[0:3], v[176:179], v[208:211], v[0:3]
	v_mfma_f32_16x16x32_bf16 v[52:55], v[172:175], v[188:191], v[52:55]
	v_mfma_f32_16x16x32_bf16 v[48:51], v[180:183], v[188:191], v[48:51]
	v_mfma_f32_16x16x32_bf16 v[36:39], v[172:175], v[196:199], v[36:39]
	v_mfma_f32_16x16x32_bf16 v[32:35], v[180:183], v[196:199], v[32:35]
	v_mfma_f32_16x16x32_bf16 v[20:23], v[172:175], v[204:207], v[20:23]
	v_mfma_f32_16x16x32_bf16 v[16:19], v[180:183], v[204:207], v[16:19]
	v_mfma_f32_16x16x32_bf16 v[4:7], v[172:175], v[212:215], v[4:7]
	v_mfma_f32_16x16x32_bf16 v[0:3], v[180:183], v[212:215], v[0:3]
	s_setprio 0
	s_barrier
	s_add_u32 s36, s36, 0x100
	s_addc_u32 s37, s37, 0
	s_add_u32 s61, s61, 0x100
	s_addc_u32 s62, s62, 0
	s_cmp_ge_i32 s63, s52
	s_mov_b32 s38, s63
	s_cbranch_scc0 .LBB0_1897
